# nt hint on all dwordx4 global stores (all phases), on top of v37
# baseline (speedup 1.0000x reference)
; __device__ __forceinline__ void prologue(const Params& p, LAS unsigned char* lds) {
;     ...
;         for (int it = gwv; it < 2 * 1024; it += NGWV) {
;             const int l = it >> 10, r = it & 1023, nblk = r & 15, kg = r >> 4, g = kg >> 4, c0 = (kg & 15) * 8, n = nblk * 64 + lane;
;             const float* wp = p.w_pool + ((size_t)l * 4 + g) * 128 * 128 + (size_t)c0 * 128;
;             const float* sc = p.pool_scale + l * 512 + g * 128;
;             const float* wb = p.w_br_pool + (size_t)l * 512 * DM + (size_t)(g * 128) * DM + n;
;             float a[8];
; #pragma unroll
;             for (int i = 0; i < 8; ++i) a[i] = 0.f;
; #pragma unroll 8
;             for (int d = 0; d < 128; ++d) { const float x = wb[(size_t)d * DM] * sc[d];
; #pragma unroll
;                 for (int i = 0; i < 8; ++i) a[i] += wp[i * 128 + d] * x; }
.LBB0_49:
	v_lshlrev_b32_e32 v78, 2, v39
	s_add_u32 s70, s11, -28
	s_addc_u32 s71, s25, -1
	s_mov_b32 s68, 0x1000
	s_mov_b32 s69, 0
	global_load_dword v76, v78, s[26:27]
	global_load_dword v77, v78, s[26:27] offset:256
	global_load_dword v60, v78, s[70:71] offset:0
	global_load_dword v61, v78, s[70:71] offset:256
	global_load_dword v62, v78, s[70:71] offset:512
	global_load_dword v63, v78, s[70:71] offset:768
	global_load_dword v64, v78, s[70:71] offset:1024
	global_load_dword v65, v78, s[70:71] offset:1280
	global_load_dword v66, v78, s[70:71] offset:1536
	global_load_dword v67, v78, s[70:71] offset:1792
	global_load_dword v68, v78, s[70:71] offset:2048
	global_load_dword v69, v78, s[70:71] offset:2304
	global_load_dword v70, v78, s[70:71] offset:2560
	global_load_dword v71, v78, s[70:71] offset:2816
	global_load_dword v72, v78, s[70:71] offset:3072
	global_load_dword v73, v78, s[70:71] offset:3328
	global_load_dword v74, v78, s[70:71] offset:3584
	global_load_dword v75, v78, s[70:71] offset:3840
	v_lshl_add_u64 v[80:81], v[2:3], 0, s[68:69]
	s_mov_b32 s68, 0x2000
	global_load_dword v92, v[80:81], off offset:-4096
	global_load_dword v93, v[80:81], off
	v_lshl_add_u64 v[80:81], v[80:81], 0, s[68:69]
	global_load_dword v94, v[80:81], off offset:-4096
	global_load_dword v95, v[80:81], off
	v_lshl_add_u64 v[80:81], v[80:81], 0, s[68:69]
	global_load_dword v96, v[80:81], off offset:-4096
	global_load_dword v97, v[80:81], off
	v_lshl_add_u64 v[80:81], v[80:81], 0, s[68:69]
	global_load_dword v98, v[80:81], off offset:-4096
	global_load_dword v99, v[80:81], off
	v_lshl_add_u64 v[80:81], v[80:81], 0, s[68:69]
	global_load_dword v100, v[80:81], off offset:-4096
	global_load_dword v101, v[80:81], off
	v_lshl_add_u64 v[80:81], v[80:81], 0, s[68:69]
	global_load_dword v102, v[80:81], off offset:-4096
	global_load_dword v103, v[80:81], off
	v_lshl_add_u64 v[80:81], v[80:81], 0, s[68:69]
	global_load_dword v104, v[80:81], off offset:-4096
	global_load_dword v105, v[80:81], off
	v_lshl_add_u64 v[80:81], v[80:81], 0, s[68:69]
	global_load_dword v106, v[80:81], off offset:-4096
	global_load_dword v107, v[80:81], off
	v_lshl_add_u64 v[80:81], v[80:81], 0, s[68:69]
	global_load_dword v108, v[80:81], off offset:-4096
	global_load_dword v109, v[80:81], off
	v_lshl_add_u64 v[80:81], v[80:81], 0, s[68:69]
	global_load_dword v110, v[80:81], off offset:-4096
	global_load_dword v111, v[80:81], off
	v_lshl_add_u64 v[80:81], v[80:81], 0, s[68:69]
	global_load_dword v112, v[80:81], off offset:-4096
	global_load_dword v113, v[80:81], off
	v_lshl_add_u64 v[80:81], v[80:81], 0, s[68:69]
	global_load_dword v114, v[80:81], off offset:-4096
	global_load_dword v115, v[80:81], off
	v_lshl_add_u64 v[80:81], v[80:81], 0, s[68:69]
	global_load_dword v116, v[80:81], off offset:-4096
	global_load_dword v117, v[80:81], off
	v_lshl_add_u64 v[80:81], v[80:81], 0, s[68:69]
	global_load_dword v118, v[80:81], off offset:-4096
	global_load_dword v119, v[80:81], off
	v_lshl_add_u64 v[80:81], v[80:81], 0, s[68:69]
	global_load_dword v120, v[80:81], off offset:-4096
	global_load_dword v121, v[80:81], off
	v_lshl_add_u64 v[80:81], v[80:81], 0, s[68:69]
	global_load_dword v122, v[80:81], off offset:-4096
	global_load_dword v123, v[80:81], off
	v_lshl_add_u64 v[80:81], v[80:81], 0, s[68:69]
	global_load_dword v124, v[80:81], off offset:-4096
	global_load_dword v125, v[80:81], off
	v_lshl_add_u64 v[80:81], v[80:81], 0, s[68:69]
	global_load_dword v126, v[80:81], off offset:-4096
	global_load_dword v127, v[80:81], off
	v_lshl_add_u64 v[80:81], v[80:81], 0, s[68:69]
	global_load_dword v128, v[80:81], off offset:-4096
	global_load_dword v129, v[80:81], off
	v_lshl_add_u64 v[80:81], v[80:81], 0, s[68:69]
	global_load_dword v130, v[80:81], off offset:-4096
	global_load_dword v131, v[80:81], off
	v_lshl_add_u64 v[80:81], v[80:81], 0, s[68:69]
	s_waitcnt vmcnt(32)
	v_readlane_b32 s72, v76, 0
	v_readlane_b32 s73, v60, 0
	v_readlane_b32 s74, v62, 0
	v_readlane_b32 s75, v64, 0
	v_readlane_b32 s76, v66, 0
	v_readlane_b32 s77, v68, 0
	v_readlane_b32 s78, v70, 0
	v_readlane_b32 s79, v72, 0
	v_readlane_b32 s80, v74, 0
	v_mul_f32_e32 v82, s72, v92
	v_fmac_f32_e32 v10, s73, v82
	v_fmac_f32_e32 v11, s74, v82
	v_fmac_f32_e32 v8, s75, v82
	v_fmac_f32_e32 v9, s76, v82
	v_fmac_f32_e32 v6, s77, v82
	v_fmac_f32_e32 v7, s78, v82
	v_fmac_f32_e32 v4, s79, v82
	v_fmac_f32_e32 v5, s80, v82
	v_readlane_b32 s82, v76, 1
	v_readlane_b32 s83, v60, 1
	v_readlane_b32 s84, v62, 1
	v_readlane_b32 s85, v64, 1
	v_readlane_b32 s86, v66, 1
	v_readlane_b32 s87, v68, 1
	v_readlane_b32 s88, v70, 1
	v_readlane_b32 s89, v72, 1
	v_readlane_b32 s90, v74, 1
	v_mul_f32_e32 v83, s82, v93
	v_fmac_f32_e32 v10, s83, v83
	v_fmac_f32_e32 v11, s84, v83
	v_fmac_f32_e32 v8, s85, v83
	v_fmac_f32_e32 v9, s86, v83
	v_fmac_f32_e32 v6, s87, v83
	v_fmac_f32_e32 v7, s88, v83
	v_fmac_f32_e32 v4, s89, v83
	v_fmac_f32_e32 v5, s90, v83
	v_readlane_b32 s72, v76, 2
	v_readlane_b32 s73, v60, 2
	v_readlane_b32 s74, v62, 2
	v_readlane_b32 s75, v64, 2
	v_readlane_b32 s76, v66, 2
	v_readlane_b32 s77, v68, 2
	v_readlane_b32 s78, v70, 2
	v_readlane_b32 s79, v72, 2
	v_readlane_b32 s80, v74, 2
	v_mul_f32_e32 v82, s72, v94
	v_fmac_f32_e32 v10, s73, v82
	v_fmac_f32_e32 v11, s74, v82
	v_fmac_f32_e32 v8, s75, v82
	v_fmac_f32_e32 v9, s76, v82
	v_fmac_f32_e32 v6, s77, v82
	v_fmac_f32_e32 v7, s78, v82
	v_fmac_f32_e32 v4, s79, v82
	v_fmac_f32_e32 v5, s80, v82
	v_readlane_b32 s82, v76, 3
	v_readlane_b32 s83, v60, 3
	v_readlane_b32 s84, v62, 3
	v_readlane_b32 s85, v64, 3
	v_readlane_b32 s86, v66, 3
	v_readlane_b32 s87, v68, 3
	v_readlane_b32 s88, v70, 3
	v_readlane_b32 s89, v72, 3
; __device__ __forceinline__ void prologue(const Params& p, LAS unsigned char* lds) {
;     ...
;             for (int d = 0; d < 128; ++d) { const float x = wb[(size_t)d * DM] * sc[d];
; #pragma unroll
;                 for (int i = 0; i < 8; ++i) a[i] += wp[i * 128 + d] * x; }
	v_readlane_b32 s90, v74, 3
	v_mul_f32_e32 v83, s82, v95
	v_fmac_f32_e32 v10, s83, v83
	v_fmac_f32_e32 v11, s84, v83
	v_fmac_f32_e32 v8, s85, v83
	v_fmac_f32_e32 v9, s86, v83
	v_fmac_f32_e32 v6, s87, v83
	v_fmac_f32_e32 v7, s88, v83
	v_fmac_f32_e32 v4, s89, v83
	v_fmac_f32_e32 v5, s90, v83
	v_readlane_b32 s72, v76, 4
	v_readlane_b32 s73, v60, 4
	v_readlane_b32 s74, v62, 4
	v_readlane_b32 s75, v64, 4
	v_readlane_b32 s76, v66, 4
	v_readlane_b32 s77, v68, 4
	v_readlane_b32 s78, v70, 4
	v_readlane_b32 s79, v72, 4
	v_readlane_b32 s80, v74, 4
	v_mul_f32_e32 v82, s72, v96
	v_fmac_f32_e32 v10, s73, v82
	v_fmac_f32_e32 v11, s74, v82
	v_fmac_f32_e32 v8, s75, v82
	v_fmac_f32_e32 v9, s76, v82
	v_fmac_f32_e32 v6, s77, v82
	v_fmac_f32_e32 v7, s78, v82
	v_fmac_f32_e32 v4, s79, v82
	v_fmac_f32_e32 v5, s80, v82
	v_readlane_b32 s82, v76, 5
	v_readlane_b32 s83, v60, 5
	v_readlane_b32 s84, v62, 5
	v_readlane_b32 s85, v64, 5
	v_readlane_b32 s86, v66, 5
	v_readlane_b32 s87, v68, 5
	v_readlane_b32 s88, v70, 5
	v_readlane_b32 s89, v72, 5
	v_readlane_b32 s90, v74, 5
	v_mul_f32_e32 v83, s82, v97
	v_fmac_f32_e32 v10, s83, v83
	v_fmac_f32_e32 v11, s84, v83
	v_fmac_f32_e32 v8, s85, v83
	v_fmac_f32_e32 v9, s86, v83
	v_fmac_f32_e32 v6, s87, v83
	v_fmac_f32_e32 v7, s88, v83
	v_fmac_f32_e32 v4, s89, v83
	v_fmac_f32_e32 v5, s90, v83
	v_readlane_b32 s72, v76, 6
	v_readlane_b32 s73, v60, 6
	v_readlane_b32 s74, v62, 6
	v_readlane_b32 s75, v64, 6
	v_readlane_b32 s76, v66, 6
	v_readlane_b32 s77, v68, 6
	v_readlane_b32 s78, v70, 6
	v_readlane_b32 s79, v72, 6
	v_readlane_b32 s80, v74, 6
	v_mul_f32_e32 v82, s72, v98
	v_fmac_f32_e32 v10, s73, v82
	v_fmac_f32_e32 v11, s74, v82
	v_fmac_f32_e32 v8, s75, v82
	v_fmac_f32_e32 v9, s76, v82
	v_fmac_f32_e32 v6, s77, v82
	v_fmac_f32_e32 v7, s78, v82
	v_fmac_f32_e32 v4, s79, v82
	v_fmac_f32_e32 v5, s80, v82
	v_readlane_b32 s82, v76, 7
	v_readlane_b32 s83, v60, 7
	v_readlane_b32 s84, v62, 7
	v_readlane_b32 s85, v64, 7
	v_readlane_b32 s86, v66, 7
	v_readlane_b32 s87, v68, 7
	v_readlane_b32 s88, v70, 7
	v_readlane_b32 s89, v72, 7
	v_readlane_b32 s90, v74, 7
	v_mul_f32_e32 v83, s82, v99
	v_fmac_f32_e32 v10, s83, v83
	v_fmac_f32_e32 v11, s84, v83
	v_fmac_f32_e32 v8, s85, v83
	v_fmac_f32_e32 v9, s86, v83
	v_fmac_f32_e32 v6, s87, v83
	v_fmac_f32_e32 v7, s88, v83
	v_fmac_f32_e32 v4, s89, v83
	v_fmac_f32_e32 v5, s90, v83
	global_load_dword v132, v[80:81], off offset:-4096
	global_load_dword v133, v[80:81], off
	v_lshl_add_u64 v[80:81], v[80:81], 0, s[68:69]
	global_load_dword v134, v[80:81], off offset:-4096
	global_load_dword v135, v[80:81], off
	v_lshl_add_u64 v[80:81], v[80:81], 0, s[68:69]
	global_load_dword v136, v[80:81], off offset:-4096
	global_load_dword v137, v[80:81], off
	v_lshl_add_u64 v[80:81], v[80:81], 0, s[68:69]
	global_load_dword v138, v[80:81], off offset:-4096
	global_load_dword v139, v[80:81], off
	v_lshl_add_u64 v[80:81], v[80:81], 0, s[68:69]
	s_waitcnt vmcnt(32)
	v_readlane_b32 s72, v76, 8
	v_readlane_b32 s73, v60, 8
	v_readlane_b32 s74, v62, 8
	v_readlane_b32 s75, v64, 8
	v_readlane_b32 s76, v66, 8
	v_readlane_b32 s77, v68, 8
	v_readlane_b32 s78, v70, 8
	v_readlane_b32 s79, v72, 8
	v_readlane_b32 s80, v74, 8
	v_mul_f32_e32 v82, s72, v100
	v_fmac_f32_e32 v10, s73, v82
	v_fmac_f32_e32 v11, s74, v82
	v_fmac_f32_e32 v8, s75, v82
	v_fmac_f32_e32 v9, s76, v82
	v_fmac_f32_e32 v6, s77, v82
	v_fmac_f32_e32 v7, s78, v82
	v_fmac_f32_e32 v4, s79, v82
	v_fmac_f32_e32 v5, s80, v82
	v_readlane_b32 s82, v76, 9
	v_readlane_b32 s83, v60, 9
	v_readlane_b32 s84, v62, 9
	v_readlane_b32 s85, v64, 9
	v_readlane_b32 s86, v66, 9
	v_readlane_b32 s87, v68, 9
	v_readlane_b32 s88, v70, 9
	v_readlane_b32 s89, v72, 9
	v_readlane_b32 s90, v74, 9
	v_mul_f32_e32 v83, s82, v101
	v_fmac_f32_e32 v10, s83, v83
	v_fmac_f32_e32 v11, s84, v83
	v_fmac_f32_e32 v8, s85, v83
	v_fmac_f32_e32 v9, s86, v83
	v_fmac_f32_e32 v6, s87, v83
	v_fmac_f32_e32 v7, s88, v83
	v_fmac_f32_e32 v4, s89, v83
	v_fmac_f32_e32 v5, s90, v83
	v_readlane_b32 s72, v76, 10
	v_readlane_b32 s73, v60, 10
	v_readlane_b32 s74, v62, 10
	v_readlane_b32 s75, v64, 10
	v_readlane_b32 s76, v66, 10
	v_readlane_b32 s77, v68, 10
	v_readlane_b32 s78, v70, 10
	v_readlane_b32 s79, v72, 10
	v_readlane_b32 s80, v74, 10
	v_mul_f32_e32 v82, s72, v102
	v_fmac_f32_e32 v10, s73, v82
	v_fmac_f32_e32 v11, s74, v82
	v_fmac_f32_e32 v8, s75, v82
	v_fmac_f32_e32 v9, s76, v82
	v_fmac_f32_e32 v6, s77, v82
	v_fmac_f32_e32 v7, s78, v82
	v_fmac_f32_e32 v4, s79, v82
	v_fmac_f32_e32 v5, s80, v82
	v_readlane_b32 s82, v76, 11
	v_readlane_b32 s83, v60, 11
	v_readlane_b32 s84, v62, 11
	v_readlane_b32 s85, v64, 11
	v_readlane_b32 s86, v66, 11
	v_readlane_b32 s87, v68, 11
	v_readlane_b32 s88, v70, 11
	v_readlane_b32 s89, v72, 11
	v_readlane_b32 s90, v74, 11
	v_mul_f32_e32 v83, s82, v103
	v_fmac_f32_e32 v10, s83, v83
	v_fmac_f32_e32 v11, s84, v83
	v_fmac_f32_e32 v8, s85, v83
	v_fmac_f32_e32 v9, s86, v83
	v_fmac_f32_e32 v6, s87, v83
	v_fmac_f32_e32 v7, s88, v83
	v_fmac_f32_e32 v4, s89, v83
	v_fmac_f32_e32 v5, s90, v83
	v_readlane_b32 s72, v76, 12
	v_readlane_b32 s73, v60, 12
	v_readlane_b32 s74, v62, 12
	v_readlane_b32 s75, v64, 12
	v_readlane_b32 s76, v66, 12
	v_readlane_b32 s77, v68, 12
	v_readlane_b32 s78, v70, 12
	v_readlane_b32 s79, v72, 12
	v_readlane_b32 s80, v74, 12
	v_mul_f32_e32 v82, s72, v104
	v_fmac_f32_e32 v10, s73, v82
	v_fmac_f32_e32 v11, s74, v82
	v_fmac_f32_e32 v8, s75, v82
	v_fmac_f32_e32 v9, s76, v82
	v_fmac_f32_e32 v6, s77, v82
	v_fmac_f32_e32 v7, s78, v82
	v_fmac_f32_e32 v4, s79, v82
	v_fmac_f32_e32 v5, s80, v82
	v_readlane_b32 s82, v76, 13
	v_readlane_b32 s83, v60, 13
	v_readlane_b32 s84, v62, 13
	v_readlane_b32 s85, v64, 13
; __device__ __forceinline__ void prologue(const Params& p, LAS unsigned char* lds) {
;     ...
;             for (int d = 0; d < 128; ++d) { const float x = wb[(size_t)d * DM] * sc[d];
; #pragma unroll
;                 for (int i = 0; i < 8; ++i) a[i] += wp[i * 128 + d] * x; }
	v_readlane_b32 s86, v66, 13
	v_readlane_b32 s87, v68, 13
	v_readlane_b32 s88, v70, 13
	v_readlane_b32 s89, v72, 13
	v_readlane_b32 s90, v74, 13
	v_mul_f32_e32 v83, s82, v105
	v_fmac_f32_e32 v10, s83, v83
	v_fmac_f32_e32 v11, s84, v83
	v_fmac_f32_e32 v8, s85, v83
	v_fmac_f32_e32 v9, s86, v83
	v_fmac_f32_e32 v6, s87, v83
	v_fmac_f32_e32 v7, s88, v83
	v_fmac_f32_e32 v4, s89, v83
	v_fmac_f32_e32 v5, s90, v83
	v_readlane_b32 s72, v76, 14
	v_readlane_b32 s73, v60, 14
	v_readlane_b32 s74, v62, 14
	v_readlane_b32 s75, v64, 14
	v_readlane_b32 s76, v66, 14
	v_readlane_b32 s77, v68, 14
	v_readlane_b32 s78, v70, 14
	v_readlane_b32 s79, v72, 14
	v_readlane_b32 s80, v74, 14
	v_mul_f32_e32 v82, s72, v106
	v_fmac_f32_e32 v10, s73, v82
	v_fmac_f32_e32 v11, s74, v82
	v_fmac_f32_e32 v8, s75, v82
	v_fmac_f32_e32 v9, s76, v82
	v_fmac_f32_e32 v6, s77, v82
	v_fmac_f32_e32 v7, s78, v82
	v_fmac_f32_e32 v4, s79, v82
	v_fmac_f32_e32 v5, s80, v82
	v_readlane_b32 s82, v76, 15
	v_readlane_b32 s83, v60, 15
	v_readlane_b32 s84, v62, 15
	v_readlane_b32 s85, v64, 15
	v_readlane_b32 s86, v66, 15
	v_readlane_b32 s87, v68, 15
	v_readlane_b32 s88, v70, 15
	v_readlane_b32 s89, v72, 15
	v_readlane_b32 s90, v74, 15
	v_mul_f32_e32 v83, s82, v107
	v_fmac_f32_e32 v10, s83, v83
	v_fmac_f32_e32 v11, s84, v83
	v_fmac_f32_e32 v8, s85, v83
	v_fmac_f32_e32 v9, s86, v83
	v_fmac_f32_e32 v6, s87, v83
	v_fmac_f32_e32 v7, s88, v83
	v_fmac_f32_e32 v4, s89, v83
	v_fmac_f32_e32 v5, s90, v83
	global_load_dword v140, v[80:81], off offset:-4096
	global_load_dword v141, v[80:81], off
	v_lshl_add_u64 v[80:81], v[80:81], 0, s[68:69]
	global_load_dword v142, v[80:81], off offset:-4096
	global_load_dword v143, v[80:81], off
	v_lshl_add_u64 v[80:81], v[80:81], 0, s[68:69]
	global_load_dword v144, v[80:81], off offset:-4096
	global_load_dword v145, v[80:81], off
	v_lshl_add_u64 v[80:81], v[80:81], 0, s[68:69]
	global_load_dword v146, v[80:81], off offset:-4096
	global_load_dword v147, v[80:81], off
	v_lshl_add_u64 v[80:81], v[80:81], 0, s[68:69]
	s_waitcnt vmcnt(32)
	v_readlane_b32 s72, v76, 16
	v_readlane_b32 s73, v60, 16
	v_readlane_b32 s74, v62, 16
	v_readlane_b32 s75, v64, 16
	v_readlane_b32 s76, v66, 16
	v_readlane_b32 s77, v68, 16
	v_readlane_b32 s78, v70, 16
	v_readlane_b32 s79, v72, 16
	v_readlane_b32 s80, v74, 16
	v_mul_f32_e32 v82, s72, v108
	v_fmac_f32_e32 v10, s73, v82
	v_fmac_f32_e32 v11, s74, v82
	v_fmac_f32_e32 v8, s75, v82
	v_fmac_f32_e32 v9, s76, v82
	v_fmac_f32_e32 v6, s77, v82
	v_fmac_f32_e32 v7, s78, v82
	v_fmac_f32_e32 v4, s79, v82
	v_fmac_f32_e32 v5, s80, v82
	v_readlane_b32 s82, v76, 17
	v_readlane_b32 s83, v60, 17
	v_readlane_b32 s84, v62, 17
	v_readlane_b32 s85, v64, 17
	v_readlane_b32 s86, v66, 17
	v_readlane_b32 s87, v68, 17
	v_readlane_b32 s88, v70, 17
	v_readlane_b32 s89, v72, 17
	v_readlane_b32 s90, v74, 17
	v_mul_f32_e32 v83, s82, v109
	v_fmac_f32_e32 v10, s83, v83
	v_fmac_f32_e32 v11, s84, v83
	v_fmac_f32_e32 v8, s85, v83
	v_fmac_f32_e32 v9, s86, v83
	v_fmac_f32_e32 v6, s87, v83
	v_fmac_f32_e32 v7, s88, v83
	v_fmac_f32_e32 v4, s89, v83
	v_fmac_f32_e32 v5, s90, v83
	v_readlane_b32 s72, v76, 18
	v_readlane_b32 s73, v60, 18
	v_readlane_b32 s74, v62, 18
	v_readlane_b32 s75, v64, 18
	v_readlane_b32 s76, v66, 18
	v_readlane_b32 s77, v68, 18
	v_readlane_b32 s78, v70, 18
	v_readlane_b32 s79, v72, 18
	v_readlane_b32 s80, v74, 18
	v_mul_f32_e32 v82, s72, v110
	v_fmac_f32_e32 v10, s73, v82
	v_fmac_f32_e32 v11, s74, v82
	v_fmac_f32_e32 v8, s75, v82
	v_fmac_f32_e32 v9, s76, v82
	v_fmac_f32_e32 v6, s77, v82
	v_fmac_f32_e32 v7, s78, v82
	v_fmac_f32_e32 v4, s79, v82
	v_fmac_f32_e32 v5, s80, v82
	v_readlane_b32 s82, v76, 19
	v_readlane_b32 s83, v60, 19
	v_readlane_b32 s84, v62, 19
	v_readlane_b32 s85, v64, 19
	v_readlane_b32 s86, v66, 19
	v_readlane_b32 s87, v68, 19
	v_readlane_b32 s88, v70, 19
	v_readlane_b32 s89, v72, 19
	v_readlane_b32 s90, v74, 19
	v_mul_f32_e32 v83, s82, v111
	v_fmac_f32_e32 v10, s83, v83
	v_fmac_f32_e32 v11, s84, v83
	v_fmac_f32_e32 v8, s85, v83
	v_fmac_f32_e32 v9, s86, v83
	v_fmac_f32_e32 v6, s87, v83
	v_fmac_f32_e32 v7, s88, v83
	v_fmac_f32_e32 v4, s89, v83
	v_fmac_f32_e32 v5, s90, v83
	v_readlane_b32 s72, v76, 20
	v_readlane_b32 s73, v60, 20
	v_readlane_b32 s74, v62, 20
	v_readlane_b32 s75, v64, 20
	v_readlane_b32 s76, v66, 20
	v_readlane_b32 s77, v68, 20
	v_readlane_b32 s78, v70, 20
	v_readlane_b32 s79, v72, 20
	v_readlane_b32 s80, v74, 20
	v_mul_f32_e32 v82, s72, v112
	v_fmac_f32_e32 v10, s73, v82
	v_fmac_f32_e32 v11, s74, v82
	v_fmac_f32_e32 v8, s75, v82
	v_fmac_f32_e32 v9, s76, v82
	v_fmac_f32_e32 v6, s77, v82
	v_fmac_f32_e32 v7, s78, v82
	v_fmac_f32_e32 v4, s79, v82
	v_fmac_f32_e32 v5, s80, v82
	v_readlane_b32 s82, v76, 21
	v_readlane_b32 s83, v60, 21
	v_readlane_b32 s84, v62, 21
	v_readlane_b32 s85, v64, 21
	v_readlane_b32 s86, v66, 21
	v_readlane_b32 s87, v68, 21
	v_readlane_b32 s88, v70, 21
	v_readlane_b32 s89, v72, 21
	v_readlane_b32 s90, v74, 21
	v_mul_f32_e32 v83, s82, v113
	v_fmac_f32_e32 v10, s83, v83
	v_fmac_f32_e32 v11, s84, v83
	v_fmac_f32_e32 v8, s85, v83
	v_fmac_f32_e32 v9, s86, v83
	v_fmac_f32_e32 v6, s87, v83
	v_fmac_f32_e32 v7, s88, v83
	v_fmac_f32_e32 v4, s89, v83
	v_fmac_f32_e32 v5, s90, v83
	v_readlane_b32 s72, v76, 22
	v_readlane_b32 s73, v60, 22
	v_readlane_b32 s74, v62, 22
	v_readlane_b32 s75, v64, 22
	v_readlane_b32 s76, v66, 22
	v_readlane_b32 s77, v68, 22
	v_readlane_b32 s78, v70, 22
	v_readlane_b32 s79, v72, 22
	v_readlane_b32 s80, v74, 22
	v_mul_f32_e32 v82, s72, v114
	v_fmac_f32_e32 v10, s73, v82
	v_fmac_f32_e32 v11, s74, v82
	v_fmac_f32_e32 v8, s75, v82
	v_fmac_f32_e32 v9, s76, v82
	v_fmac_f32_e32 v6, s77, v82
	v_fmac_f32_e32 v7, s78, v82
	v_fmac_f32_e32 v4, s79, v82
	v_fmac_f32_e32 v5, s80, v82
	v_readlane_b32 s82, v76, 23
	v_readlane_b32 s83, v60, 23
	v_readlane_b32 s84, v62, 23
	v_readlane_b32 s85, v64, 23
	v_readlane_b32 s86, v66, 23
	v_readlane_b32 s87, v68, 23
	v_readlane_b32 s88, v70, 23
	v_readlane_b32 s89, v72, 23
	v_readlane_b32 s90, v74, 23
	v_mul_f32_e32 v83, s82, v115
	v_fmac_f32_e32 v10, s83, v83
	v_fmac_f32_e32 v11, s84, v83
	v_fmac_f32_e32 v8, s85, v83
	v_fmac_f32_e32 v9, s86, v83
	v_fmac_f32_e32 v6, s87, v83
	v_fmac_f32_e32 v7, s88, v83
	v_fmac_f32_e32 v4, s89, v83
	v_fmac_f32_e32 v5, s90, v83
	global_load_dword v148, v[80:81], off offset:-4096
	global_load_dword v149, v[80:81], off
	v_lshl_add_u64 v[80:81], v[80:81], 0, s[68:69]
	global_load_dword v150, v[80:81], off offset:-4096
	global_load_dword v151, v[80:81], off
	v_lshl_add_u64 v[80:81], v[80:81], 0, s[68:69]
	global_load_dword v152, v[80:81], off offset:-4096
	global_load_dword v153, v[80:81], off
	v_lshl_add_u64 v[80:81], v[80:81], 0, s[68:69]
	global_load_dword v154, v[80:81], off offset:-4096
	global_load_dword v155, v[80:81], off
	v_lshl_add_u64 v[80:81], v[80:81], 0, s[68:69]
	s_waitcnt vmcnt(32)
; __device__ __forceinline__ void prologue(const Params& p, LAS unsigned char* lds) {
;     ...
;             for (int d = 0; d < 128; ++d) { const float x = wb[(size_t)d * DM] * sc[d];
; #pragma unroll
;                 for (int i = 0; i < 8; ++i) a[i] += wp[i * 128 + d] * x; }
	v_readlane_b32 s72, v76, 24
	v_readlane_b32 s73, v60, 24
	v_readlane_b32 s74, v62, 24
	v_readlane_b32 s75, v64, 24
	v_readlane_b32 s76, v66, 24
	v_readlane_b32 s77, v68, 24
	v_readlane_b32 s78, v70, 24
	v_readlane_b32 s79, v72, 24
	v_readlane_b32 s80, v74, 24
	v_mul_f32_e32 v82, s72, v116
	v_fmac_f32_e32 v10, s73, v82
	v_fmac_f32_e32 v11, s74, v82
	v_fmac_f32_e32 v8, s75, v82
	v_fmac_f32_e32 v9, s76, v82
	v_fmac_f32_e32 v6, s77, v82
	v_fmac_f32_e32 v7, s78, v82
	v_fmac_f32_e32 v4, s79, v82
	v_fmac_f32_e32 v5, s80, v82
	v_readlane_b32 s82, v76, 25
	v_readlane_b32 s83, v60, 25
	v_readlane_b32 s84, v62, 25
	v_readlane_b32 s85, v64, 25
	v_readlane_b32 s86, v66, 25
	v_readlane_b32 s87, v68, 25
	v_readlane_b32 s88, v70, 25
	v_readlane_b32 s89, v72, 25
	v_readlane_b32 s90, v74, 25
	v_mul_f32_e32 v83, s82, v117
	v_fmac_f32_e32 v10, s83, v83
	v_fmac_f32_e32 v11, s84, v83
	v_fmac_f32_e32 v8, s85, v83
	v_fmac_f32_e32 v9, s86, v83
	v_fmac_f32_e32 v6, s87, v83
	v_fmac_f32_e32 v7, s88, v83
	v_fmac_f32_e32 v4, s89, v83
	v_fmac_f32_e32 v5, s90, v83
	v_readlane_b32 s72, v76, 26
	v_readlane_b32 s73, v60, 26
	v_readlane_b32 s74, v62, 26
	v_readlane_b32 s75, v64, 26
	v_readlane_b32 s76, v66, 26
	v_readlane_b32 s77, v68, 26
	v_readlane_b32 s78, v70, 26
	v_readlane_b32 s79, v72, 26
	v_readlane_b32 s80, v74, 26
	v_mul_f32_e32 v82, s72, v118
	v_fmac_f32_e32 v10, s73, v82
	v_fmac_f32_e32 v11, s74, v82
	v_fmac_f32_e32 v8, s75, v82
	v_fmac_f32_e32 v9, s76, v82
	v_fmac_f32_e32 v6, s77, v82
	v_fmac_f32_e32 v7, s78, v82
	v_fmac_f32_e32 v4, s79, v82
	v_fmac_f32_e32 v5, s80, v82
	v_readlane_b32 s82, v76, 27
	v_readlane_b32 s83, v60, 27
	v_readlane_b32 s84, v62, 27
	v_readlane_b32 s85, v64, 27
	v_readlane_b32 s86, v66, 27
	v_readlane_b32 s87, v68, 27
	v_readlane_b32 s88, v70, 27
	v_readlane_b32 s89, v72, 27
	v_readlane_b32 s90, v74, 27
	v_mul_f32_e32 v83, s82, v119
	v_fmac_f32_e32 v10, s83, v83
	v_fmac_f32_e32 v11, s84, v83
	v_fmac_f32_e32 v8, s85, v83
	v_fmac_f32_e32 v9, s86, v83
	v_fmac_f32_e32 v6, s87, v83
	v_fmac_f32_e32 v7, s88, v83
	v_fmac_f32_e32 v4, s89, v83
	v_fmac_f32_e32 v5, s90, v83
	v_readlane_b32 s72, v76, 28
	v_readlane_b32 s73, v60, 28
	v_readlane_b32 s74, v62, 28
	v_readlane_b32 s75, v64, 28
	v_readlane_b32 s76, v66, 28
	v_readlane_b32 s77, v68, 28
	v_readlane_b32 s78, v70, 28
	v_readlane_b32 s79, v72, 28
	v_readlane_b32 s80, v74, 28
	v_mul_f32_e32 v82, s72, v120
	v_fmac_f32_e32 v10, s73, v82
	v_fmac_f32_e32 v11, s74, v82
	v_fmac_f32_e32 v8, s75, v82
	v_fmac_f32_e32 v9, s76, v82
	v_fmac_f32_e32 v6, s77, v82
	v_fmac_f32_e32 v7, s78, v82
	v_fmac_f32_e32 v4, s79, v82
	v_fmac_f32_e32 v5, s80, v82
	v_readlane_b32 s82, v76, 29
	v_readlane_b32 s83, v60, 29
	v_readlane_b32 s84, v62, 29
	v_readlane_b32 s85, v64, 29
	v_readlane_b32 s86, v66, 29
	v_readlane_b32 s87, v68, 29
	v_readlane_b32 s88, v70, 29
	v_readlane_b32 s89, v72, 29
	v_readlane_b32 s90, v74, 29
	v_mul_f32_e32 v83, s82, v121
	v_fmac_f32_e32 v10, s83, v83
	v_fmac_f32_e32 v11, s84, v83
	v_fmac_f32_e32 v8, s85, v83
	v_fmac_f32_e32 v9, s86, v83
	v_fmac_f32_e32 v6, s87, v83
	v_fmac_f32_e32 v7, s88, v83
	v_fmac_f32_e32 v4, s89, v83
	v_fmac_f32_e32 v5, s90, v83
	v_readlane_b32 s72, v76, 30
	v_readlane_b32 s73, v60, 30
	v_readlane_b32 s74, v62, 30
	v_readlane_b32 s75, v64, 30
	v_readlane_b32 s76, v66, 30
	v_readlane_b32 s77, v68, 30
	v_readlane_b32 s78, v70, 30
	v_readlane_b32 s79, v72, 30
	v_readlane_b32 s80, v74, 30
	v_mul_f32_e32 v82, s72, v122
	v_fmac_f32_e32 v10, s73, v82
	v_fmac_f32_e32 v11, s74, v82
	v_fmac_f32_e32 v8, s75, v82
	v_fmac_f32_e32 v9, s76, v82
	v_fmac_f32_e32 v6, s77, v82
	v_fmac_f32_e32 v7, s78, v82
	v_fmac_f32_e32 v4, s79, v82
	v_fmac_f32_e32 v5, s80, v82
	v_readlane_b32 s82, v76, 31
	v_readlane_b32 s83, v60, 31
	v_readlane_b32 s84, v62, 31
	v_readlane_b32 s85, v64, 31
	v_readlane_b32 s86, v66, 31
	v_readlane_b32 s87, v68, 31
	v_readlane_b32 s88, v70, 31
	v_readlane_b32 s89, v72, 31
	v_readlane_b32 s90, v74, 31
	v_mul_f32_e32 v83, s82, v123
	v_fmac_f32_e32 v10, s83, v83
	v_fmac_f32_e32 v11, s84, v83
	v_fmac_f32_e32 v8, s85, v83
	v_fmac_f32_e32 v9, s86, v83
	v_fmac_f32_e32 v6, s87, v83
	v_fmac_f32_e32 v7, s88, v83
	v_fmac_f32_e32 v4, s89, v83
	v_fmac_f32_e32 v5, s90, v83
	global_load_dword v156, v[80:81], off offset:-4096
	global_load_dword v157, v[80:81], off
	v_lshl_add_u64 v[80:81], v[80:81], 0, s[68:69]
	global_load_dword v158, v[80:81], off offset:-4096
	global_load_dword v159, v[80:81], off
	v_lshl_add_u64 v[80:81], v[80:81], 0, s[68:69]
	global_load_dword v160, v[80:81], off offset:-4096
	global_load_dword v161, v[80:81], off
	v_lshl_add_u64 v[80:81], v[80:81], 0, s[68:69]
	global_load_dword v162, v[80:81], off offset:-4096
	global_load_dword v163, v[80:81], off
	v_lshl_add_u64 v[80:81], v[80:81], 0, s[68:69]
	s_waitcnt vmcnt(32)
; __device__ __forceinline__ void prologue(const Params& p, LAS unsigned char* lds) {
;     ...
;             for (int d = 0; d < 128; ++d) { const float x = wb[(size_t)d * DM] * sc[d];
; #pragma unroll
;                 for (int i = 0; i < 8; ++i) a[i] += wp[i * 128 + d] * x; }
	v_readlane_b32 s72, v76, 32
	v_readlane_b32 s73, v60, 32
	v_readlane_b32 s74, v62, 32
	v_readlane_b32 s75, v64, 32
	v_readlane_b32 s76, v66, 32
	v_readlane_b32 s77, v68, 32
	v_readlane_b32 s78, v70, 32
	v_readlane_b32 s79, v72, 32
	v_readlane_b32 s80, v74, 32
	v_mul_f32_e32 v82, s72, v124
	v_fmac_f32_e32 v10, s73, v82
	v_fmac_f32_e32 v11, s74, v82
	v_fmac_f32_e32 v8, s75, v82
	v_fmac_f32_e32 v9, s76, v82
	v_fmac_f32_e32 v6, s77, v82
	v_fmac_f32_e32 v7, s78, v82
	v_fmac_f32_e32 v4, s79, v82
	v_fmac_f32_e32 v5, s80, v82
	v_readlane_b32 s82, v76, 33
	v_readlane_b32 s83, v60, 33
	v_readlane_b32 s84, v62, 33
	v_readlane_b32 s85, v64, 33
	v_readlane_b32 s86, v66, 33
	v_readlane_b32 s87, v68, 33
	v_readlane_b32 s88, v70, 33
	v_readlane_b32 s89, v72, 33
	v_readlane_b32 s90, v74, 33
	v_mul_f32_e32 v83, s82, v125
	v_fmac_f32_e32 v10, s83, v83
	v_fmac_f32_e32 v11, s84, v83
	v_fmac_f32_e32 v8, s85, v83
	v_fmac_f32_e32 v9, s86, v83
	v_fmac_f32_e32 v6, s87, v83
	v_fmac_f32_e32 v7, s88, v83
	v_fmac_f32_e32 v4, s89, v83
	v_fmac_f32_e32 v5, s90, v83
	v_readlane_b32 s72, v76, 34
	v_readlane_b32 s73, v60, 34
	v_readlane_b32 s74, v62, 34
	v_readlane_b32 s75, v64, 34
	v_readlane_b32 s76, v66, 34
	v_readlane_b32 s77, v68, 34
	v_readlane_b32 s78, v70, 34
	v_readlane_b32 s79, v72, 34
	v_readlane_b32 s80, v74, 34
	v_mul_f32_e32 v82, s72, v126
	v_fmac_f32_e32 v10, s73, v82
	v_fmac_f32_e32 v11, s74, v82
	v_fmac_f32_e32 v8, s75, v82
	v_fmac_f32_e32 v9, s76, v82
	v_fmac_f32_e32 v6, s77, v82
	v_fmac_f32_e32 v7, s78, v82
	v_fmac_f32_e32 v4, s79, v82
	v_fmac_f32_e32 v5, s80, v82
	v_readlane_b32 s82, v76, 35
	v_readlane_b32 s83, v60, 35
	v_readlane_b32 s84, v62, 35
	v_readlane_b32 s85, v64, 35
	v_readlane_b32 s86, v66, 35
	v_readlane_b32 s87, v68, 35
	v_readlane_b32 s88, v70, 35
	v_readlane_b32 s89, v72, 35
	v_readlane_b32 s90, v74, 35
	v_mul_f32_e32 v83, s82, v127
	v_fmac_f32_e32 v10, s83, v83
	v_fmac_f32_e32 v11, s84, v83
	v_fmac_f32_e32 v8, s85, v83
	v_fmac_f32_e32 v9, s86, v83
	v_fmac_f32_e32 v6, s87, v83
	v_fmac_f32_e32 v7, s88, v83
	v_fmac_f32_e32 v4, s89, v83
	v_fmac_f32_e32 v5, s90, v83
	v_readlane_b32 s72, v76, 36
	v_readlane_b32 s73, v60, 36
	v_readlane_b32 s74, v62, 36
	v_readlane_b32 s75, v64, 36
	v_readlane_b32 s76, v66, 36
	v_readlane_b32 s77, v68, 36
	v_readlane_b32 s78, v70, 36
	v_readlane_b32 s79, v72, 36
	v_readlane_b32 s80, v74, 36
	v_mul_f32_e32 v82, s72, v128
	v_fmac_f32_e32 v10, s73, v82
	v_fmac_f32_e32 v11, s74, v82
	v_fmac_f32_e32 v8, s75, v82
	v_fmac_f32_e32 v9, s76, v82
	v_fmac_f32_e32 v6, s77, v82
	v_fmac_f32_e32 v7, s78, v82
	v_fmac_f32_e32 v4, s79, v82
	v_fmac_f32_e32 v5, s80, v82
	v_readlane_b32 s82, v76, 37
	v_readlane_b32 s83, v60, 37
	v_readlane_b32 s84, v62, 37
	v_readlane_b32 s85, v64, 37
	v_readlane_b32 s86, v66, 37
	v_readlane_b32 s87, v68, 37
	v_readlane_b32 s88, v70, 37
	v_readlane_b32 s89, v72, 37
	v_readlane_b32 s90, v74, 37
	v_mul_f32_e32 v83, s82, v129
	v_fmac_f32_e32 v10, s83, v83
	v_fmac_f32_e32 v11, s84, v83
	v_fmac_f32_e32 v8, s85, v83
	v_fmac_f32_e32 v9, s86, v83
	v_fmac_f32_e32 v6, s87, v83
	v_fmac_f32_e32 v7, s88, v83
	v_fmac_f32_e32 v4, s89, v83
	v_fmac_f32_e32 v5, s90, v83
	v_readlane_b32 s72, v76, 38
	v_readlane_b32 s73, v60, 38
	v_readlane_b32 s74, v62, 38
	v_readlane_b32 s75, v64, 38
	v_readlane_b32 s76, v66, 38
	v_readlane_b32 s77, v68, 38
	v_readlane_b32 s78, v70, 38
	v_readlane_b32 s79, v72, 38
	v_readlane_b32 s80, v74, 38
	v_mul_f32_e32 v82, s72, v130
	v_fmac_f32_e32 v10, s73, v82
	v_fmac_f32_e32 v11, s74, v82
	v_fmac_f32_e32 v8, s75, v82
	v_fmac_f32_e32 v9, s76, v82
	v_fmac_f32_e32 v6, s77, v82
	v_fmac_f32_e32 v7, s78, v82
	v_fmac_f32_e32 v4, s79, v82
	v_fmac_f32_e32 v5, s80, v82
	v_readlane_b32 s82, v76, 39
	v_readlane_b32 s83, v60, 39
	v_readlane_b32 s84, v62, 39
	v_readlane_b32 s85, v64, 39
	v_readlane_b32 s86, v66, 39
	v_readlane_b32 s87, v68, 39
	v_readlane_b32 s88, v70, 39
	v_readlane_b32 s89, v72, 39
	v_readlane_b32 s90, v74, 39
	v_mul_f32_e32 v83, s82, v131
	v_fmac_f32_e32 v10, s83, v83
	v_fmac_f32_e32 v11, s84, v83
	v_fmac_f32_e32 v8, s85, v83
	v_fmac_f32_e32 v9, s86, v83
	v_fmac_f32_e32 v6, s87, v83
	v_fmac_f32_e32 v7, s88, v83
	v_fmac_f32_e32 v4, s89, v83
	v_fmac_f32_e32 v5, s90, v83
	global_load_dword v164, v[80:81], off offset:-4096
	global_load_dword v165, v[80:81], off
	v_lshl_add_u64 v[80:81], v[80:81], 0, s[68:69]
	global_load_dword v166, v[80:81], off offset:-4096
	global_load_dword v167, v[80:81], off
	v_lshl_add_u64 v[80:81], v[80:81], 0, s[68:69]
	global_load_dword v168, v[80:81], off offset:-4096
	global_load_dword v169, v[80:81], off
	v_lshl_add_u64 v[80:81], v[80:81], 0, s[68:69]
	global_load_dword v170, v[80:81], off offset:-4096
	global_load_dword v171, v[80:81], off
	v_lshl_add_u64 v[80:81], v[80:81], 0, s[68:69]
	s_waitcnt vmcnt(32)
; __device__ __forceinline__ void prologue(const Params& p, LAS unsigned char* lds) {
;     ...
;             for (int d = 0; d < 128; ++d) { const float x = wb[(size_t)d * DM] * sc[d];
; #pragma unroll
;                 for (int i = 0; i < 8; ++i) a[i] += wp[i * 128 + d] * x; }
	v_readlane_b32 s72, v76, 40
	v_readlane_b32 s73, v60, 40
	v_readlane_b32 s74, v62, 40
	v_readlane_b32 s75, v64, 40
	v_readlane_b32 s76, v66, 40
	v_readlane_b32 s77, v68, 40
	v_readlane_b32 s78, v70, 40
	v_readlane_b32 s79, v72, 40
	v_readlane_b32 s80, v74, 40
	v_mul_f32_e32 v82, s72, v132
	v_fmac_f32_e32 v10, s73, v82
	v_fmac_f32_e32 v11, s74, v82
	v_fmac_f32_e32 v8, s75, v82
	v_fmac_f32_e32 v9, s76, v82
	v_fmac_f32_e32 v6, s77, v82
	v_fmac_f32_e32 v7, s78, v82
	v_fmac_f32_e32 v4, s79, v82
	v_fmac_f32_e32 v5, s80, v82
	v_readlane_b32 s82, v76, 41
	v_readlane_b32 s83, v60, 41
	v_readlane_b32 s84, v62, 41
	v_readlane_b32 s85, v64, 41
	v_readlane_b32 s86, v66, 41
	v_readlane_b32 s87, v68, 41
	v_readlane_b32 s88, v70, 41
	v_readlane_b32 s89, v72, 41
	v_readlane_b32 s90, v74, 41
	v_mul_f32_e32 v83, s82, v133
	v_fmac_f32_e32 v10, s83, v83
	v_fmac_f32_e32 v11, s84, v83
	v_fmac_f32_e32 v8, s85, v83
	v_fmac_f32_e32 v9, s86, v83
	v_fmac_f32_e32 v6, s87, v83
	v_fmac_f32_e32 v7, s88, v83
	v_fmac_f32_e32 v4, s89, v83
	v_fmac_f32_e32 v5, s90, v83
	v_readlane_b32 s72, v76, 42
	v_readlane_b32 s73, v60, 42
	v_readlane_b32 s74, v62, 42
	v_readlane_b32 s75, v64, 42
	v_readlane_b32 s76, v66, 42
	v_readlane_b32 s77, v68, 42
	v_readlane_b32 s78, v70, 42
	v_readlane_b32 s79, v72, 42
	v_readlane_b32 s80, v74, 42
	v_mul_f32_e32 v82, s72, v134
	v_fmac_f32_e32 v10, s73, v82
	v_fmac_f32_e32 v11, s74, v82
	v_fmac_f32_e32 v8, s75, v82
	v_fmac_f32_e32 v9, s76, v82
	v_fmac_f32_e32 v6, s77, v82
	v_fmac_f32_e32 v7, s78, v82
	v_fmac_f32_e32 v4, s79, v82
	v_fmac_f32_e32 v5, s80, v82
	v_readlane_b32 s82, v76, 43
	v_readlane_b32 s83, v60, 43
	v_readlane_b32 s84, v62, 43
	v_readlane_b32 s85, v64, 43
	v_readlane_b32 s86, v66, 43
	v_readlane_b32 s87, v68, 43
	v_readlane_b32 s88, v70, 43
	v_readlane_b32 s89, v72, 43
	v_readlane_b32 s90, v74, 43
	v_mul_f32_e32 v83, s82, v135
	v_fmac_f32_e32 v10, s83, v83
	v_fmac_f32_e32 v11, s84, v83
	v_fmac_f32_e32 v8, s85, v83
	v_fmac_f32_e32 v9, s86, v83
	v_fmac_f32_e32 v6, s87, v83
	v_fmac_f32_e32 v7, s88, v83
	v_fmac_f32_e32 v4, s89, v83
	v_fmac_f32_e32 v5, s90, v83
	v_readlane_b32 s72, v76, 44
	v_readlane_b32 s73, v60, 44
	v_readlane_b32 s74, v62, 44
	v_readlane_b32 s75, v64, 44
	v_readlane_b32 s76, v66, 44
	v_readlane_b32 s77, v68, 44
	v_readlane_b32 s78, v70, 44
	v_readlane_b32 s79, v72, 44
	v_readlane_b32 s80, v74, 44
	v_mul_f32_e32 v82, s72, v136
	v_fmac_f32_e32 v10, s73, v82
	v_fmac_f32_e32 v11, s74, v82
	v_fmac_f32_e32 v8, s75, v82
	v_fmac_f32_e32 v9, s76, v82
	v_fmac_f32_e32 v6, s77, v82
	v_fmac_f32_e32 v7, s78, v82
	v_fmac_f32_e32 v4, s79, v82
	v_fmac_f32_e32 v5, s80, v82
	v_readlane_b32 s82, v76, 45
	v_readlane_b32 s83, v60, 45
	v_readlane_b32 s84, v62, 45
	v_readlane_b32 s85, v64, 45
	v_readlane_b32 s86, v66, 45
	v_readlane_b32 s87, v68, 45
	v_readlane_b32 s88, v70, 45
	v_readlane_b32 s89, v72, 45
	v_readlane_b32 s90, v74, 45
	v_mul_f32_e32 v83, s82, v137
	v_fmac_f32_e32 v10, s83, v83
	v_fmac_f32_e32 v11, s84, v83
	v_fmac_f32_e32 v8, s85, v83
	v_fmac_f32_e32 v9, s86, v83
	v_fmac_f32_e32 v6, s87, v83
	v_fmac_f32_e32 v7, s88, v83
	v_fmac_f32_e32 v4, s89, v83
	v_fmac_f32_e32 v5, s90, v83
	v_readlane_b32 s72, v76, 46
	v_readlane_b32 s73, v60, 46
	v_readlane_b32 s74, v62, 46
	v_readlane_b32 s75, v64, 46
	v_readlane_b32 s76, v66, 46
	v_readlane_b32 s77, v68, 46
	v_readlane_b32 s78, v70, 46
	v_readlane_b32 s79, v72, 46
	v_readlane_b32 s80, v74, 46
	v_mul_f32_e32 v82, s72, v138
	v_fmac_f32_e32 v10, s73, v82
	v_fmac_f32_e32 v11, s74, v82
	v_fmac_f32_e32 v8, s75, v82
	v_fmac_f32_e32 v9, s76, v82
	v_fmac_f32_e32 v6, s77, v82
	v_fmac_f32_e32 v7, s78, v82
	v_fmac_f32_e32 v4, s79, v82
	v_fmac_f32_e32 v5, s80, v82
	v_readlane_b32 s82, v76, 47
	v_readlane_b32 s83, v60, 47
	v_readlane_b32 s84, v62, 47
	v_readlane_b32 s85, v64, 47
	v_readlane_b32 s86, v66, 47
	v_readlane_b32 s87, v68, 47
	v_readlane_b32 s88, v70, 47
	v_readlane_b32 s89, v72, 47
	v_readlane_b32 s90, v74, 47
	v_mul_f32_e32 v83, s82, v139
	v_fmac_f32_e32 v10, s83, v83
	v_fmac_f32_e32 v11, s84, v83
	v_fmac_f32_e32 v8, s85, v83
	v_fmac_f32_e32 v9, s86, v83
	v_fmac_f32_e32 v6, s87, v83
	v_fmac_f32_e32 v7, s88, v83
	v_fmac_f32_e32 v4, s89, v83
	v_fmac_f32_e32 v5, s90, v83
	global_load_dword v172, v[80:81], off offset:-4096
	global_load_dword v173, v[80:81], off
	v_lshl_add_u64 v[80:81], v[80:81], 0, s[68:69]
	global_load_dword v174, v[80:81], off offset:-4096
	global_load_dword v175, v[80:81], off
	v_lshl_add_u64 v[80:81], v[80:81], 0, s[68:69]
	global_load_dword v176, v[80:81], off offset:-4096
	global_load_dword v177, v[80:81], off
	v_lshl_add_u64 v[80:81], v[80:81], 0, s[68:69]
	global_load_dword v178, v[80:81], off offset:-4096
	global_load_dword v179, v[80:81], off
	v_lshl_add_u64 v[80:81], v[80:81], 0, s[68:69]
	s_waitcnt vmcnt(32)
; __device__ __forceinline__ void prologue(const Params& p, LAS unsigned char* lds) {
;     ...
;             for (int d = 0; d < 128; ++d) { const float x = wb[(size_t)d * DM] * sc[d];
; #pragma unroll
;                 for (int i = 0; i < 8; ++i) a[i] += wp[i * 128 + d] * x; }
	v_readlane_b32 s72, v76, 48
	v_readlane_b32 s73, v60, 48
	v_readlane_b32 s74, v62, 48
	v_readlane_b32 s75, v64, 48
	v_readlane_b32 s76, v66, 48
	v_readlane_b32 s77, v68, 48
	v_readlane_b32 s78, v70, 48
	v_readlane_b32 s79, v72, 48
	v_readlane_b32 s80, v74, 48
	v_mul_f32_e32 v82, s72, v140
	v_fmac_f32_e32 v10, s73, v82
	v_fmac_f32_e32 v11, s74, v82
	v_fmac_f32_e32 v8, s75, v82
	v_fmac_f32_e32 v9, s76, v82
	v_fmac_f32_e32 v6, s77, v82
	v_fmac_f32_e32 v7, s78, v82
	v_fmac_f32_e32 v4, s79, v82
	v_fmac_f32_e32 v5, s80, v82
	v_readlane_b32 s82, v76, 49
	v_readlane_b32 s83, v60, 49
	v_readlane_b32 s84, v62, 49
	v_readlane_b32 s85, v64, 49
	v_readlane_b32 s86, v66, 49
	v_readlane_b32 s87, v68, 49
	v_readlane_b32 s88, v70, 49
	v_readlane_b32 s89, v72, 49
	v_readlane_b32 s90, v74, 49
	v_mul_f32_e32 v83, s82, v141
	v_fmac_f32_e32 v10, s83, v83
	v_fmac_f32_e32 v11, s84, v83
	v_fmac_f32_e32 v8, s85, v83
	v_fmac_f32_e32 v9, s86, v83
	v_fmac_f32_e32 v6, s87, v83
	v_fmac_f32_e32 v7, s88, v83
	v_fmac_f32_e32 v4, s89, v83
	v_fmac_f32_e32 v5, s90, v83
	v_readlane_b32 s72, v76, 50
	v_readlane_b32 s73, v60, 50
	v_readlane_b32 s74, v62, 50
	v_readlane_b32 s75, v64, 50
	v_readlane_b32 s76, v66, 50
	v_readlane_b32 s77, v68, 50
	v_readlane_b32 s78, v70, 50
	v_readlane_b32 s79, v72, 50
	v_readlane_b32 s80, v74, 50
	v_mul_f32_e32 v82, s72, v142
	v_fmac_f32_e32 v10, s73, v82
	v_fmac_f32_e32 v11, s74, v82
	v_fmac_f32_e32 v8, s75, v82
	v_fmac_f32_e32 v9, s76, v82
	v_fmac_f32_e32 v6, s77, v82
	v_fmac_f32_e32 v7, s78, v82
	v_fmac_f32_e32 v4, s79, v82
	v_fmac_f32_e32 v5, s80, v82
	v_readlane_b32 s82, v76, 51
	v_readlane_b32 s83, v60, 51
	v_readlane_b32 s84, v62, 51
	v_readlane_b32 s85, v64, 51
	v_readlane_b32 s86, v66, 51
	v_readlane_b32 s87, v68, 51
	v_readlane_b32 s88, v70, 51
	v_readlane_b32 s89, v72, 51
	v_readlane_b32 s90, v74, 51
	v_mul_f32_e32 v83, s82, v143
	v_fmac_f32_e32 v10, s83, v83
	v_fmac_f32_e32 v11, s84, v83
	v_fmac_f32_e32 v8, s85, v83
	v_fmac_f32_e32 v9, s86, v83
	v_fmac_f32_e32 v6, s87, v83
	v_fmac_f32_e32 v7, s88, v83
	v_fmac_f32_e32 v4, s89, v83
	v_fmac_f32_e32 v5, s90, v83
	v_readlane_b32 s72, v76, 52
	v_readlane_b32 s73, v60, 52
	v_readlane_b32 s74, v62, 52
	v_readlane_b32 s75, v64, 52
	v_readlane_b32 s76, v66, 52
	v_readlane_b32 s77, v68, 52
	v_readlane_b32 s78, v70, 52
	v_readlane_b32 s79, v72, 52
	v_readlane_b32 s80, v74, 52
	v_mul_f32_e32 v82, s72, v144
	v_fmac_f32_e32 v10, s73, v82
	v_fmac_f32_e32 v11, s74, v82
	v_fmac_f32_e32 v8, s75, v82
	v_fmac_f32_e32 v9, s76, v82
	v_fmac_f32_e32 v6, s77, v82
	v_fmac_f32_e32 v7, s78, v82
	v_fmac_f32_e32 v4, s79, v82
	v_fmac_f32_e32 v5, s80, v82
	v_readlane_b32 s82, v76, 53
	v_readlane_b32 s83, v60, 53
	v_readlane_b32 s84, v62, 53
	v_readlane_b32 s85, v64, 53
	v_readlane_b32 s86, v66, 53
	v_readlane_b32 s87, v68, 53
	v_readlane_b32 s88, v70, 53
	v_readlane_b32 s89, v72, 53
	v_readlane_b32 s90, v74, 53
	v_mul_f32_e32 v83, s82, v145
	v_fmac_f32_e32 v10, s83, v83
	v_fmac_f32_e32 v11, s84, v83
	v_fmac_f32_e32 v8, s85, v83
	v_fmac_f32_e32 v9, s86, v83
	v_fmac_f32_e32 v6, s87, v83
	v_fmac_f32_e32 v7, s88, v83
	v_fmac_f32_e32 v4, s89, v83
	v_fmac_f32_e32 v5, s90, v83
	v_readlane_b32 s72, v76, 54
	v_readlane_b32 s73, v60, 54
	v_readlane_b32 s74, v62, 54
	v_readlane_b32 s75, v64, 54
	v_readlane_b32 s76, v66, 54
	v_readlane_b32 s77, v68, 54
	v_readlane_b32 s78, v70, 54
	v_readlane_b32 s79, v72, 54
	v_readlane_b32 s80, v74, 54
	v_mul_f32_e32 v82, s72, v146
	v_fmac_f32_e32 v10, s73, v82
	v_fmac_f32_e32 v11, s74, v82
	v_fmac_f32_e32 v8, s75, v82
	v_fmac_f32_e32 v9, s76, v82
	v_fmac_f32_e32 v6, s77, v82
	v_fmac_f32_e32 v7, s78, v82
	v_fmac_f32_e32 v4, s79, v82
	v_fmac_f32_e32 v5, s80, v82
	v_readlane_b32 s82, v76, 55
	v_readlane_b32 s83, v60, 55
	v_readlane_b32 s84, v62, 55
	v_readlane_b32 s85, v64, 55
	v_readlane_b32 s86, v66, 55
	v_readlane_b32 s87, v68, 55
	v_readlane_b32 s88, v70, 55
	v_readlane_b32 s89, v72, 55
	v_readlane_b32 s90, v74, 55
	v_mul_f32_e32 v83, s82, v147
	v_fmac_f32_e32 v10, s83, v83
	v_fmac_f32_e32 v11, s84, v83
	v_fmac_f32_e32 v8, s85, v83
	v_fmac_f32_e32 v9, s86, v83
	v_fmac_f32_e32 v6, s87, v83
	v_fmac_f32_e32 v7, s88, v83
	v_fmac_f32_e32 v4, s89, v83
	v_fmac_f32_e32 v5, s90, v83
	global_load_dword v180, v[80:81], off offset:-4096
	global_load_dword v181, v[80:81], off
	v_lshl_add_u64 v[80:81], v[80:81], 0, s[68:69]
	global_load_dword v182, v[80:81], off offset:-4096
	global_load_dword v183, v[80:81], off
	v_lshl_add_u64 v[80:81], v[80:81], 0, s[68:69]
	global_load_dword v184, v[80:81], off offset:-4096
	global_load_dword v185, v[80:81], off
	v_lshl_add_u64 v[80:81], v[80:81], 0, s[68:69]
	global_load_dword v186, v[80:81], off offset:-4096
	global_load_dword v187, v[80:81], off
	v_lshl_add_u64 v[80:81], v[80:81], 0, s[68:69]
	s_waitcnt vmcnt(32)
; __device__ __forceinline__ void prologue(const Params& p, LAS unsigned char* lds) {
;     ...
;             for (int d = 0; d < 128; ++d) { const float x = wb[(size_t)d * DM] * sc[d];
; #pragma unroll
;                 for (int i = 0; i < 8; ++i) a[i] += wp[i * 128 + d] * x; }
	v_readlane_b32 s72, v76, 56
	v_readlane_b32 s73, v60, 56
	v_readlane_b32 s74, v62, 56
	v_readlane_b32 s75, v64, 56
	v_readlane_b32 s76, v66, 56
	v_readlane_b32 s77, v68, 56
	v_readlane_b32 s78, v70, 56
	v_readlane_b32 s79, v72, 56
	v_readlane_b32 s80, v74, 56
	v_mul_f32_e32 v82, s72, v148
	v_fmac_f32_e32 v10, s73, v82
	v_fmac_f32_e32 v11, s74, v82
	v_fmac_f32_e32 v8, s75, v82
	v_fmac_f32_e32 v9, s76, v82
	v_fmac_f32_e32 v6, s77, v82
	v_fmac_f32_e32 v7, s78, v82
	v_fmac_f32_e32 v4, s79, v82
	v_fmac_f32_e32 v5, s80, v82
	v_readlane_b32 s82, v76, 57
	v_readlane_b32 s83, v60, 57
	v_readlane_b32 s84, v62, 57
	v_readlane_b32 s85, v64, 57
	v_readlane_b32 s86, v66, 57
	v_readlane_b32 s87, v68, 57
	v_readlane_b32 s88, v70, 57
	v_readlane_b32 s89, v72, 57
	v_readlane_b32 s90, v74, 57
	v_mul_f32_e32 v83, s82, v149
	v_fmac_f32_e32 v10, s83, v83
	v_fmac_f32_e32 v11, s84, v83
	v_fmac_f32_e32 v8, s85, v83
	v_fmac_f32_e32 v9, s86, v83
	v_fmac_f32_e32 v6, s87, v83
	v_fmac_f32_e32 v7, s88, v83
	v_fmac_f32_e32 v4, s89, v83
	v_fmac_f32_e32 v5, s90, v83
	v_readlane_b32 s72, v76, 58
	v_readlane_b32 s73, v60, 58
	v_readlane_b32 s74, v62, 58
	v_readlane_b32 s75, v64, 58
	v_readlane_b32 s76, v66, 58
	v_readlane_b32 s77, v68, 58
	v_readlane_b32 s78, v70, 58
	v_readlane_b32 s79, v72, 58
	v_readlane_b32 s80, v74, 58
	v_mul_f32_e32 v82, s72, v150
	v_fmac_f32_e32 v10, s73, v82
	v_fmac_f32_e32 v11, s74, v82
	v_fmac_f32_e32 v8, s75, v82
	v_fmac_f32_e32 v9, s76, v82
	v_fmac_f32_e32 v6, s77, v82
	v_fmac_f32_e32 v7, s78, v82
	v_fmac_f32_e32 v4, s79, v82
	v_fmac_f32_e32 v5, s80, v82
	v_readlane_b32 s82, v76, 59
	v_readlane_b32 s83, v60, 59
	v_readlane_b32 s84, v62, 59
	v_readlane_b32 s85, v64, 59
	v_readlane_b32 s86, v66, 59
	v_readlane_b32 s87, v68, 59
	v_readlane_b32 s88, v70, 59
	v_readlane_b32 s89, v72, 59
	v_readlane_b32 s90, v74, 59
	v_mul_f32_e32 v83, s82, v151
	v_fmac_f32_e32 v10, s83, v83
	v_fmac_f32_e32 v11, s84, v83
	v_fmac_f32_e32 v8, s85, v83
	v_fmac_f32_e32 v9, s86, v83
	v_fmac_f32_e32 v6, s87, v83
	v_fmac_f32_e32 v7, s88, v83
	v_fmac_f32_e32 v4, s89, v83
	v_fmac_f32_e32 v5, s90, v83
	v_readlane_b32 s72, v76, 60
	v_readlane_b32 s73, v60, 60
	v_readlane_b32 s74, v62, 60
	v_readlane_b32 s75, v64, 60
	v_readlane_b32 s76, v66, 60
	v_readlane_b32 s77, v68, 60
	v_readlane_b32 s78, v70, 60
	v_readlane_b32 s79, v72, 60
	v_readlane_b32 s80, v74, 60
	v_mul_f32_e32 v82, s72, v152
	v_fmac_f32_e32 v10, s73, v82
	v_fmac_f32_e32 v11, s74, v82
	v_fmac_f32_e32 v8, s75, v82
	v_fmac_f32_e32 v9, s76, v82
	v_fmac_f32_e32 v6, s77, v82
	v_fmac_f32_e32 v7, s78, v82
	v_fmac_f32_e32 v4, s79, v82
	v_fmac_f32_e32 v5, s80, v82
	v_readlane_b32 s82, v76, 61
	v_readlane_b32 s83, v60, 61
	v_readlane_b32 s84, v62, 61
	v_readlane_b32 s85, v64, 61
	v_readlane_b32 s86, v66, 61
	v_readlane_b32 s87, v68, 61
	v_readlane_b32 s88, v70, 61
	v_readlane_b32 s89, v72, 61
	v_readlane_b32 s90, v74, 61
	v_mul_f32_e32 v83, s82, v153
	v_fmac_f32_e32 v10, s83, v83
	v_fmac_f32_e32 v11, s84, v83
	v_fmac_f32_e32 v8, s85, v83
	v_fmac_f32_e32 v9, s86, v83
	v_fmac_f32_e32 v6, s87, v83
	v_fmac_f32_e32 v7, s88, v83
	v_fmac_f32_e32 v4, s89, v83
	v_fmac_f32_e32 v5, s90, v83
	v_readlane_b32 s72, v76, 62
	v_readlane_b32 s73, v60, 62
	v_readlane_b32 s74, v62, 62
	v_readlane_b32 s75, v64, 62
	v_readlane_b32 s76, v66, 62
	v_readlane_b32 s77, v68, 62
	v_readlane_b32 s78, v70, 62
	v_readlane_b32 s79, v72, 62
	v_readlane_b32 s80, v74, 62
	v_mul_f32_e32 v82, s72, v154
	v_fmac_f32_e32 v10, s73, v82
	v_fmac_f32_e32 v11, s74, v82
	v_fmac_f32_e32 v8, s75, v82
	v_fmac_f32_e32 v9, s76, v82
	v_fmac_f32_e32 v6, s77, v82
	v_fmac_f32_e32 v7, s78, v82
	v_fmac_f32_e32 v4, s79, v82
	v_fmac_f32_e32 v5, s80, v82
	v_readlane_b32 s82, v76, 63
	v_readlane_b32 s83, v60, 63
	v_readlane_b32 s84, v62, 63
	v_readlane_b32 s85, v64, 63
	v_readlane_b32 s86, v66, 63
	v_readlane_b32 s87, v68, 63
	v_readlane_b32 s88, v70, 63
	v_readlane_b32 s89, v72, 63
	v_readlane_b32 s90, v74, 63
	v_mul_f32_e32 v83, s82, v155
	v_fmac_f32_e32 v10, s83, v83
	v_fmac_f32_e32 v11, s84, v83
	v_fmac_f32_e32 v8, s85, v83
	v_fmac_f32_e32 v9, s86, v83
	v_fmac_f32_e32 v6, s87, v83
	v_fmac_f32_e32 v7, s88, v83
	v_fmac_f32_e32 v4, s89, v83
	v_fmac_f32_e32 v5, s90, v83
	global_load_dword v188, v[80:81], off offset:-4096
	global_load_dword v189, v[80:81], off
	v_lshl_add_u64 v[80:81], v[80:81], 0, s[68:69]
	global_load_dword v190, v[80:81], off offset:-4096
	global_load_dword v191, v[80:81], off
	v_lshl_add_u64 v[80:81], v[80:81], 0, s[68:69]
	global_load_dword v192, v[80:81], off offset:-4096
	global_load_dword v193, v[80:81], off
	v_lshl_add_u64 v[80:81], v[80:81], 0, s[68:69]
	global_load_dword v194, v[80:81], off offset:-4096
	global_load_dword v195, v[80:81], off
	v_lshl_add_u64 v[80:81], v[80:81], 0, s[68:69]
	s_waitcnt vmcnt(32)
; __device__ __forceinline__ void prologue(const Params& p, LAS unsigned char* lds) {
;     ...
;             for (int d = 0; d < 128; ++d) { const float x = wb[(size_t)d * DM] * sc[d];
; #pragma unroll
;                 for (int i = 0; i < 8; ++i) a[i] += wp[i * 128 + d] * x; }
	v_readlane_b32 s72, v77, 0
	v_readlane_b32 s73, v61, 0
	v_readlane_b32 s74, v63, 0
	v_readlane_b32 s75, v65, 0
	v_readlane_b32 s76, v67, 0
	v_readlane_b32 s77, v69, 0
	v_readlane_b32 s78, v71, 0
	v_readlane_b32 s79, v73, 0
	v_readlane_b32 s80, v75, 0
	v_mul_f32_e32 v82, s72, v156
	v_fmac_f32_e32 v10, s73, v82
	v_fmac_f32_e32 v11, s74, v82
	v_fmac_f32_e32 v8, s75, v82
	v_fmac_f32_e32 v9, s76, v82
	v_fmac_f32_e32 v6, s77, v82
	v_fmac_f32_e32 v7, s78, v82
	v_fmac_f32_e32 v4, s79, v82
	v_fmac_f32_e32 v5, s80, v82
	v_readlane_b32 s82, v77, 1
	v_readlane_b32 s83, v61, 1
	v_readlane_b32 s84, v63, 1
	v_readlane_b32 s85, v65, 1
	v_readlane_b32 s86, v67, 1
	v_readlane_b32 s87, v69, 1
	v_readlane_b32 s88, v71, 1
	v_readlane_b32 s89, v73, 1
	v_readlane_b32 s90, v75, 1
	v_mul_f32_e32 v83, s82, v157
	v_fmac_f32_e32 v10, s83, v83
	v_fmac_f32_e32 v11, s84, v83
	v_fmac_f32_e32 v8, s85, v83
	v_fmac_f32_e32 v9, s86, v83
	v_fmac_f32_e32 v6, s87, v83
	v_fmac_f32_e32 v7, s88, v83
	v_fmac_f32_e32 v4, s89, v83
	v_fmac_f32_e32 v5, s90, v83
	v_readlane_b32 s72, v77, 2
	v_readlane_b32 s73, v61, 2
	v_readlane_b32 s74, v63, 2
	v_readlane_b32 s75, v65, 2
	v_readlane_b32 s76, v67, 2
	v_readlane_b32 s77, v69, 2
	v_readlane_b32 s78, v71, 2
	v_readlane_b32 s79, v73, 2
	v_readlane_b32 s80, v75, 2
	v_mul_f32_e32 v82, s72, v158
	v_fmac_f32_e32 v10, s73, v82
	v_fmac_f32_e32 v11, s74, v82
	v_fmac_f32_e32 v8, s75, v82
	v_fmac_f32_e32 v9, s76, v82
	v_fmac_f32_e32 v6, s77, v82
	v_fmac_f32_e32 v7, s78, v82
	v_fmac_f32_e32 v4, s79, v82
	v_fmac_f32_e32 v5, s80, v82
	v_readlane_b32 s82, v77, 3
	v_readlane_b32 s83, v61, 3
	v_readlane_b32 s84, v63, 3
	v_readlane_b32 s85, v65, 3
	v_readlane_b32 s86, v67, 3
	v_readlane_b32 s87, v69, 3
	v_readlane_b32 s88, v71, 3
	v_readlane_b32 s89, v73, 3
	v_readlane_b32 s90, v75, 3
	v_mul_f32_e32 v83, s82, v159
	v_fmac_f32_e32 v10, s83, v83
	v_fmac_f32_e32 v11, s84, v83
	v_fmac_f32_e32 v8, s85, v83
	v_fmac_f32_e32 v9, s86, v83
	v_fmac_f32_e32 v6, s87, v83
	v_fmac_f32_e32 v7, s88, v83
	v_fmac_f32_e32 v4, s89, v83
	v_fmac_f32_e32 v5, s90, v83
	v_readlane_b32 s72, v77, 4
	v_readlane_b32 s73, v61, 4
	v_readlane_b32 s74, v63, 4
	v_readlane_b32 s75, v65, 4
	v_readlane_b32 s76, v67, 4
	v_readlane_b32 s77, v69, 4
	v_readlane_b32 s78, v71, 4
	v_readlane_b32 s79, v73, 4
	v_readlane_b32 s80, v75, 4
	v_mul_f32_e32 v82, s72, v160
	v_fmac_f32_e32 v10, s73, v82
	v_fmac_f32_e32 v11, s74, v82
	v_fmac_f32_e32 v8, s75, v82
	v_fmac_f32_e32 v9, s76, v82
	v_fmac_f32_e32 v6, s77, v82
	v_fmac_f32_e32 v7, s78, v82
	v_fmac_f32_e32 v4, s79, v82
	v_fmac_f32_e32 v5, s80, v82
	v_readlane_b32 s82, v77, 5
	v_readlane_b32 s83, v61, 5
	v_readlane_b32 s84, v63, 5
	v_readlane_b32 s85, v65, 5
	v_readlane_b32 s86, v67, 5
	v_readlane_b32 s87, v69, 5
	v_readlane_b32 s88, v71, 5
	v_readlane_b32 s89, v73, 5
	v_readlane_b32 s90, v75, 5
	v_mul_f32_e32 v83, s82, v161
	v_fmac_f32_e32 v10, s83, v83
	v_fmac_f32_e32 v11, s84, v83
	v_fmac_f32_e32 v8, s85, v83
	v_fmac_f32_e32 v9, s86, v83
	v_fmac_f32_e32 v6, s87, v83
	v_fmac_f32_e32 v7, s88, v83
	v_fmac_f32_e32 v4, s89, v83
	v_fmac_f32_e32 v5, s90, v83
	v_readlane_b32 s72, v77, 6
	v_readlane_b32 s73, v61, 6
	v_readlane_b32 s74, v63, 6
	v_readlane_b32 s75, v65, 6
	v_readlane_b32 s76, v67, 6
	v_readlane_b32 s77, v69, 6
	v_readlane_b32 s78, v71, 6
	v_readlane_b32 s79, v73, 6
	v_readlane_b32 s80, v75, 6
	v_mul_f32_e32 v82, s72, v162
	v_fmac_f32_e32 v10, s73, v82
	v_fmac_f32_e32 v11, s74, v82
	v_fmac_f32_e32 v8, s75, v82
	v_fmac_f32_e32 v9, s76, v82
	v_fmac_f32_e32 v6, s77, v82
	v_fmac_f32_e32 v7, s78, v82
	v_fmac_f32_e32 v4, s79, v82
	v_fmac_f32_e32 v5, s80, v82
	v_readlane_b32 s82, v77, 7
	v_readlane_b32 s83, v61, 7
	v_readlane_b32 s84, v63, 7
	v_readlane_b32 s85, v65, 7
	v_readlane_b32 s86, v67, 7
	v_readlane_b32 s87, v69, 7
	v_readlane_b32 s88, v71, 7
	v_readlane_b32 s89, v73, 7
	v_readlane_b32 s90, v75, 7
	v_mul_f32_e32 v83, s82, v163
	v_fmac_f32_e32 v10, s83, v83
	v_fmac_f32_e32 v11, s84, v83
	v_fmac_f32_e32 v8, s85, v83
	v_fmac_f32_e32 v9, s86, v83
	v_fmac_f32_e32 v6, s87, v83
	v_fmac_f32_e32 v7, s88, v83
	v_fmac_f32_e32 v4, s89, v83
	v_fmac_f32_e32 v5, s90, v83
	global_load_dword v196, v[80:81], off offset:-4096
	global_load_dword v197, v[80:81], off
	v_lshl_add_u64 v[80:81], v[80:81], 0, s[68:69]
	global_load_dword v198, v[80:81], off offset:-4096
	global_load_dword v199, v[80:81], off
	v_lshl_add_u64 v[80:81], v[80:81], 0, s[68:69]
	global_load_dword v200, v[80:81], off offset:-4096
	global_load_dword v201, v[80:81], off
	v_lshl_add_u64 v[80:81], v[80:81], 0, s[68:69]
	global_load_dword v202, v[80:81], off offset:-4096
	global_load_dword v203, v[80:81], off
	v_lshl_add_u64 v[80:81], v[80:81], 0, s[68:69]
	s_waitcnt vmcnt(32)
; __device__ __forceinline__ void prologue(const Params& p, LAS unsigned char* lds) {
;     ...
;             for (int d = 0; d < 128; ++d) { const float x = wb[(size_t)d * DM] * sc[d];
; #pragma unroll
;                 for (int i = 0; i < 8; ++i) a[i] += wp[i * 128 + d] * x; }
	v_readlane_b32 s72, v77, 8
	v_readlane_b32 s73, v61, 8
	v_readlane_b32 s74, v63, 8
	v_readlane_b32 s75, v65, 8
	v_readlane_b32 s76, v67, 8
	v_readlane_b32 s77, v69, 8
	v_readlane_b32 s78, v71, 8
	v_readlane_b32 s79, v73, 8
	v_readlane_b32 s80, v75, 8
	v_mul_f32_e32 v82, s72, v164
	v_fmac_f32_e32 v10, s73, v82
	v_fmac_f32_e32 v11, s74, v82
	v_fmac_f32_e32 v8, s75, v82
	v_fmac_f32_e32 v9, s76, v82
	v_fmac_f32_e32 v6, s77, v82
	v_fmac_f32_e32 v7, s78, v82
	v_fmac_f32_e32 v4, s79, v82
	v_fmac_f32_e32 v5, s80, v82
	v_readlane_b32 s82, v77, 9
	v_readlane_b32 s83, v61, 9
	v_readlane_b32 s84, v63, 9
	v_readlane_b32 s85, v65, 9
	v_readlane_b32 s86, v67, 9
	v_readlane_b32 s87, v69, 9
	v_readlane_b32 s88, v71, 9
	v_readlane_b32 s89, v73, 9
	v_readlane_b32 s90, v75, 9
	v_mul_f32_e32 v83, s82, v165
	v_fmac_f32_e32 v10, s83, v83
	v_fmac_f32_e32 v11, s84, v83
	v_fmac_f32_e32 v8, s85, v83
	v_fmac_f32_e32 v9, s86, v83
	v_fmac_f32_e32 v6, s87, v83
	v_fmac_f32_e32 v7, s88, v83
	v_fmac_f32_e32 v4, s89, v83
	v_fmac_f32_e32 v5, s90, v83
	v_readlane_b32 s72, v77, 10
	v_readlane_b32 s73, v61, 10
	v_readlane_b32 s74, v63, 10
	v_readlane_b32 s75, v65, 10
	v_readlane_b32 s76, v67, 10
	v_readlane_b32 s77, v69, 10
	v_readlane_b32 s78, v71, 10
	v_readlane_b32 s79, v73, 10
	v_readlane_b32 s80, v75, 10
	v_mul_f32_e32 v82, s72, v166
	v_fmac_f32_e32 v10, s73, v82
	v_fmac_f32_e32 v11, s74, v82
	v_fmac_f32_e32 v8, s75, v82
	v_fmac_f32_e32 v9, s76, v82
	v_fmac_f32_e32 v6, s77, v82
	v_fmac_f32_e32 v7, s78, v82
	v_fmac_f32_e32 v4, s79, v82
	v_fmac_f32_e32 v5, s80, v82
	v_readlane_b32 s82, v77, 11
	v_readlane_b32 s83, v61, 11
	v_readlane_b32 s84, v63, 11
	v_readlane_b32 s85, v65, 11
	v_readlane_b32 s86, v67, 11
	v_readlane_b32 s87, v69, 11
	v_readlane_b32 s88, v71, 11
	v_readlane_b32 s89, v73, 11
	v_readlane_b32 s90, v75, 11
	v_mul_f32_e32 v83, s82, v167
	v_fmac_f32_e32 v10, s83, v83
	v_fmac_f32_e32 v11, s84, v83
	v_fmac_f32_e32 v8, s85, v83
	v_fmac_f32_e32 v9, s86, v83
	v_fmac_f32_e32 v6, s87, v83
	v_fmac_f32_e32 v7, s88, v83
	v_fmac_f32_e32 v4, s89, v83
	v_fmac_f32_e32 v5, s90, v83
	v_readlane_b32 s72, v77, 12
	v_readlane_b32 s73, v61, 12
	v_readlane_b32 s74, v63, 12
	v_readlane_b32 s75, v65, 12
	v_readlane_b32 s76, v67, 12
	v_readlane_b32 s77, v69, 12
	v_readlane_b32 s78, v71, 12
	v_readlane_b32 s79, v73, 12
	v_readlane_b32 s80, v75, 12
	v_mul_f32_e32 v82, s72, v168
	v_fmac_f32_e32 v10, s73, v82
	v_fmac_f32_e32 v11, s74, v82
	v_fmac_f32_e32 v8, s75, v82
	v_fmac_f32_e32 v9, s76, v82
	v_fmac_f32_e32 v6, s77, v82
	v_fmac_f32_e32 v7, s78, v82
	v_fmac_f32_e32 v4, s79, v82
	v_fmac_f32_e32 v5, s80, v82
	v_readlane_b32 s82, v77, 13
	v_readlane_b32 s83, v61, 13
	v_readlane_b32 s84, v63, 13
	v_readlane_b32 s85, v65, 13
	v_readlane_b32 s86, v67, 13
	v_readlane_b32 s87, v69, 13
	v_readlane_b32 s88, v71, 13
	v_readlane_b32 s89, v73, 13
	v_readlane_b32 s90, v75, 13
	v_mul_f32_e32 v83, s82, v169
	v_fmac_f32_e32 v10, s83, v83
	v_fmac_f32_e32 v11, s84, v83
	v_fmac_f32_e32 v8, s85, v83
	v_fmac_f32_e32 v9, s86, v83
	v_fmac_f32_e32 v6, s87, v83
	v_fmac_f32_e32 v7, s88, v83
	v_fmac_f32_e32 v4, s89, v83
	v_fmac_f32_e32 v5, s90, v83
	v_readlane_b32 s72, v77, 14
	v_readlane_b32 s73, v61, 14
	v_readlane_b32 s74, v63, 14
	v_readlane_b32 s75, v65, 14
	v_readlane_b32 s76, v67, 14
	v_readlane_b32 s77, v69, 14
	v_readlane_b32 s78, v71, 14
	v_readlane_b32 s79, v73, 14
	v_readlane_b32 s80, v75, 14
	v_mul_f32_e32 v82, s72, v170
	v_fmac_f32_e32 v10, s73, v82
	v_fmac_f32_e32 v11, s74, v82
	v_fmac_f32_e32 v8, s75, v82
	v_fmac_f32_e32 v9, s76, v82
	v_fmac_f32_e32 v6, s77, v82
	v_fmac_f32_e32 v7, s78, v82
	v_fmac_f32_e32 v4, s79, v82
	v_fmac_f32_e32 v5, s80, v82
	v_readlane_b32 s82, v77, 15
	v_readlane_b32 s83, v61, 15
	v_readlane_b32 s84, v63, 15
	v_readlane_b32 s85, v65, 15
	v_readlane_b32 s86, v67, 15
	v_readlane_b32 s87, v69, 15
	v_readlane_b32 s88, v71, 15
	v_readlane_b32 s89, v73, 15
	v_readlane_b32 s90, v75, 15
	v_mul_f32_e32 v83, s82, v171
	v_fmac_f32_e32 v10, s83, v83
	v_fmac_f32_e32 v11, s84, v83
	v_fmac_f32_e32 v8, s85, v83
	v_fmac_f32_e32 v9, s86, v83
	v_fmac_f32_e32 v6, s87, v83
	v_fmac_f32_e32 v7, s88, v83
	v_fmac_f32_e32 v4, s89, v83
	v_fmac_f32_e32 v5, s90, v83
	global_load_dword v204, v[80:81], off offset:-4096
	global_load_dword v205, v[80:81], off
	v_lshl_add_u64 v[80:81], v[80:81], 0, s[68:69]
	global_load_dword v206, v[80:81], off offset:-4096
	global_load_dword v207, v[80:81], off
	v_lshl_add_u64 v[80:81], v[80:81], 0, s[68:69]
	global_load_dword v208, v[80:81], off offset:-4096
	global_load_dword v209, v[80:81], off
	v_lshl_add_u64 v[80:81], v[80:81], 0, s[68:69]
	global_load_dword v210, v[80:81], off offset:-4096
	global_load_dword v211, v[80:81], off
	v_lshl_add_u64 v[80:81], v[80:81], 0, s[68:69]
	s_waitcnt vmcnt(32)
; __device__ __forceinline__ void prologue(const Params& p, LAS unsigned char* lds) {
;     ...
;             for (int d = 0; d < 128; ++d) { const float x = wb[(size_t)d * DM] * sc[d];
; #pragma unroll
;                 for (int i = 0; i < 8; ++i) a[i] += wp[i * 128 + d] * x; }
	v_readlane_b32 s72, v77, 16
	v_readlane_b32 s73, v61, 16
	v_readlane_b32 s74, v63, 16
	v_readlane_b32 s75, v65, 16
	v_readlane_b32 s76, v67, 16
	v_readlane_b32 s77, v69, 16
	v_readlane_b32 s78, v71, 16
	v_readlane_b32 s79, v73, 16
	v_readlane_b32 s80, v75, 16
	v_mul_f32_e32 v82, s72, v172
	v_fmac_f32_e32 v10, s73, v82
	v_fmac_f32_e32 v11, s74, v82
	v_fmac_f32_e32 v8, s75, v82
	v_fmac_f32_e32 v9, s76, v82
	v_fmac_f32_e32 v6, s77, v82
	v_fmac_f32_e32 v7, s78, v82
	v_fmac_f32_e32 v4, s79, v82
	v_fmac_f32_e32 v5, s80, v82
	v_readlane_b32 s82, v77, 17
	v_readlane_b32 s83, v61, 17
	v_readlane_b32 s84, v63, 17
	v_readlane_b32 s85, v65, 17
	v_readlane_b32 s86, v67, 17
	v_readlane_b32 s87, v69, 17
	v_readlane_b32 s88, v71, 17
	v_readlane_b32 s89, v73, 17
	v_readlane_b32 s90, v75, 17
	v_mul_f32_e32 v83, s82, v173
	v_fmac_f32_e32 v10, s83, v83
	v_fmac_f32_e32 v11, s84, v83
	v_fmac_f32_e32 v8, s85, v83
	v_fmac_f32_e32 v9, s86, v83
	v_fmac_f32_e32 v6, s87, v83
	v_fmac_f32_e32 v7, s88, v83
	v_fmac_f32_e32 v4, s89, v83
	v_fmac_f32_e32 v5, s90, v83
	v_readlane_b32 s72, v77, 18
	v_readlane_b32 s73, v61, 18
	v_readlane_b32 s74, v63, 18
	v_readlane_b32 s75, v65, 18
	v_readlane_b32 s76, v67, 18
	v_readlane_b32 s77, v69, 18
	v_readlane_b32 s78, v71, 18
	v_readlane_b32 s79, v73, 18
	v_readlane_b32 s80, v75, 18
	v_mul_f32_e32 v82, s72, v174
	v_fmac_f32_e32 v10, s73, v82
	v_fmac_f32_e32 v11, s74, v82
	v_fmac_f32_e32 v8, s75, v82
	v_fmac_f32_e32 v9, s76, v82
	v_fmac_f32_e32 v6, s77, v82
	v_fmac_f32_e32 v7, s78, v82
	v_fmac_f32_e32 v4, s79, v82
	v_fmac_f32_e32 v5, s80, v82
	v_readlane_b32 s82, v77, 19
	v_readlane_b32 s83, v61, 19
	v_readlane_b32 s84, v63, 19
	v_readlane_b32 s85, v65, 19
	v_readlane_b32 s86, v67, 19
	v_readlane_b32 s87, v69, 19
	v_readlane_b32 s88, v71, 19
	v_readlane_b32 s89, v73, 19
	v_readlane_b32 s90, v75, 19
	v_mul_f32_e32 v83, s82, v175
	v_fmac_f32_e32 v10, s83, v83
	v_fmac_f32_e32 v11, s84, v83
	v_fmac_f32_e32 v8, s85, v83
	v_fmac_f32_e32 v9, s86, v83
	v_fmac_f32_e32 v6, s87, v83
	v_fmac_f32_e32 v7, s88, v83
	v_fmac_f32_e32 v4, s89, v83
	v_fmac_f32_e32 v5, s90, v83
	v_readlane_b32 s72, v77, 20
	v_readlane_b32 s73, v61, 20
	v_readlane_b32 s74, v63, 20
	v_readlane_b32 s75, v65, 20
	v_readlane_b32 s76, v67, 20
	v_readlane_b32 s77, v69, 20
	v_readlane_b32 s78, v71, 20
	v_readlane_b32 s79, v73, 20
	v_readlane_b32 s80, v75, 20
	v_mul_f32_e32 v82, s72, v176
	v_fmac_f32_e32 v10, s73, v82
	v_fmac_f32_e32 v11, s74, v82
	v_fmac_f32_e32 v8, s75, v82
	v_fmac_f32_e32 v9, s76, v82
	v_fmac_f32_e32 v6, s77, v82
	v_fmac_f32_e32 v7, s78, v82
	v_fmac_f32_e32 v4, s79, v82
	v_fmac_f32_e32 v5, s80, v82
	v_readlane_b32 s82, v77, 21
	v_readlane_b32 s83, v61, 21
	v_readlane_b32 s84, v63, 21
	v_readlane_b32 s85, v65, 21
	v_readlane_b32 s86, v67, 21
	v_readlane_b32 s87, v69, 21
	v_readlane_b32 s88, v71, 21
	v_readlane_b32 s89, v73, 21
	v_readlane_b32 s90, v75, 21
	v_mul_f32_e32 v83, s82, v177
	v_fmac_f32_e32 v10, s83, v83
	v_fmac_f32_e32 v11, s84, v83
	v_fmac_f32_e32 v8, s85, v83
	v_fmac_f32_e32 v9, s86, v83
	v_fmac_f32_e32 v6, s87, v83
	v_fmac_f32_e32 v7, s88, v83
	v_fmac_f32_e32 v4, s89, v83
	v_fmac_f32_e32 v5, s90, v83
	v_readlane_b32 s72, v77, 22
	v_readlane_b32 s73, v61, 22
	v_readlane_b32 s74, v63, 22
	v_readlane_b32 s75, v65, 22
	v_readlane_b32 s76, v67, 22
	v_readlane_b32 s77, v69, 22
	v_readlane_b32 s78, v71, 22
	v_readlane_b32 s79, v73, 22
	v_readlane_b32 s80, v75, 22
	v_mul_f32_e32 v82, s72, v178
	v_fmac_f32_e32 v10, s73, v82
	v_fmac_f32_e32 v11, s74, v82
	v_fmac_f32_e32 v8, s75, v82
	v_fmac_f32_e32 v9, s76, v82
	v_fmac_f32_e32 v6, s77, v82
	v_fmac_f32_e32 v7, s78, v82
	v_fmac_f32_e32 v4, s79, v82
	v_fmac_f32_e32 v5, s80, v82
	v_readlane_b32 s82, v77, 23
	v_readlane_b32 s83, v61, 23
	v_readlane_b32 s84, v63, 23
	v_readlane_b32 s85, v65, 23
	v_readlane_b32 s86, v67, 23
	v_readlane_b32 s87, v69, 23
	v_readlane_b32 s88, v71, 23
	v_readlane_b32 s89, v73, 23
	v_readlane_b32 s90, v75, 23
	v_mul_f32_e32 v83, s82, v179
	v_fmac_f32_e32 v10, s83, v83
	v_fmac_f32_e32 v11, s84, v83
	v_fmac_f32_e32 v8, s85, v83
	v_fmac_f32_e32 v9, s86, v83
	v_fmac_f32_e32 v6, s87, v83
	v_fmac_f32_e32 v7, s88, v83
	v_fmac_f32_e32 v4, s89, v83
	v_fmac_f32_e32 v5, s90, v83
	global_load_dword v212, v[80:81], off offset:-4096
	global_load_dword v213, v[80:81], off
	v_lshl_add_u64 v[80:81], v[80:81], 0, s[68:69]
	global_load_dword v214, v[80:81], off offset:-4096
	global_load_dword v215, v[80:81], off
	v_lshl_add_u64 v[80:81], v[80:81], 0, s[68:69]
	global_load_dword v216, v[80:81], off offset:-4096
	global_load_dword v217, v[80:81], off
	v_lshl_add_u64 v[80:81], v[80:81], 0, s[68:69]
	global_load_dword v218, v[80:81], off offset:-4096
	global_load_dword v219, v[80:81], off
	v_lshl_add_u64 v[80:81], v[80:81], 0, s[68:69]
	s_waitcnt vmcnt(32)
; __device__ __forceinline__ void prologue(const Params& p, LAS unsigned char* lds) {
;     ...
;             for (int d = 0; d < 128; ++d) { const float x = wb[(size_t)d * DM] * sc[d];
; #pragma unroll
;                 for (int i = 0; i < 8; ++i) a[i] += wp[i * 128 + d] * x; }
	v_readlane_b32 s72, v77, 24
	v_readlane_b32 s73, v61, 24
	v_readlane_b32 s74, v63, 24
	v_readlane_b32 s75, v65, 24
	v_readlane_b32 s76, v67, 24
	v_readlane_b32 s77, v69, 24
	v_readlane_b32 s78, v71, 24
	v_readlane_b32 s79, v73, 24
	v_readlane_b32 s80, v75, 24
	v_mul_f32_e32 v82, s72, v180
	v_fmac_f32_e32 v10, s73, v82
	v_fmac_f32_e32 v11, s74, v82
	v_fmac_f32_e32 v8, s75, v82
	v_fmac_f32_e32 v9, s76, v82
	v_fmac_f32_e32 v6, s77, v82
	v_fmac_f32_e32 v7, s78, v82
	v_fmac_f32_e32 v4, s79, v82
	v_fmac_f32_e32 v5, s80, v82
	v_readlane_b32 s82, v77, 25
	v_readlane_b32 s83, v61, 25
	v_readlane_b32 s84, v63, 25
	v_readlane_b32 s85, v65, 25
	v_readlane_b32 s86, v67, 25
	v_readlane_b32 s87, v69, 25
	v_readlane_b32 s88, v71, 25
	v_readlane_b32 s89, v73, 25
	v_readlane_b32 s90, v75, 25
	v_mul_f32_e32 v83, s82, v181
	v_fmac_f32_e32 v10, s83, v83
	v_fmac_f32_e32 v11, s84, v83
	v_fmac_f32_e32 v8, s85, v83
	v_fmac_f32_e32 v9, s86, v83
	v_fmac_f32_e32 v6, s87, v83
	v_fmac_f32_e32 v7, s88, v83
	v_fmac_f32_e32 v4, s89, v83
	v_fmac_f32_e32 v5, s90, v83
	v_readlane_b32 s72, v77, 26
	v_readlane_b32 s73, v61, 26
	v_readlane_b32 s74, v63, 26
	v_readlane_b32 s75, v65, 26
	v_readlane_b32 s76, v67, 26
	v_readlane_b32 s77, v69, 26
	v_readlane_b32 s78, v71, 26
	v_readlane_b32 s79, v73, 26
	v_readlane_b32 s80, v75, 26
	v_mul_f32_e32 v82, s72, v182
	v_fmac_f32_e32 v10, s73, v82
	v_fmac_f32_e32 v11, s74, v82
	v_fmac_f32_e32 v8, s75, v82
	v_fmac_f32_e32 v9, s76, v82
	v_fmac_f32_e32 v6, s77, v82
	v_fmac_f32_e32 v7, s78, v82
	v_fmac_f32_e32 v4, s79, v82
	v_fmac_f32_e32 v5, s80, v82
	v_readlane_b32 s82, v77, 27
	v_readlane_b32 s83, v61, 27
	v_readlane_b32 s84, v63, 27
	v_readlane_b32 s85, v65, 27
	v_readlane_b32 s86, v67, 27
	v_readlane_b32 s87, v69, 27
	v_readlane_b32 s88, v71, 27
	v_readlane_b32 s89, v73, 27
	v_readlane_b32 s90, v75, 27
	v_mul_f32_e32 v83, s82, v183
	v_fmac_f32_e32 v10, s83, v83
	v_fmac_f32_e32 v11, s84, v83
	v_fmac_f32_e32 v8, s85, v83
	v_fmac_f32_e32 v9, s86, v83
	v_fmac_f32_e32 v6, s87, v83
	v_fmac_f32_e32 v7, s88, v83
	v_fmac_f32_e32 v4, s89, v83
	v_fmac_f32_e32 v5, s90, v83
	v_readlane_b32 s72, v77, 28
	v_readlane_b32 s73, v61, 28
	v_readlane_b32 s74, v63, 28
	v_readlane_b32 s75, v65, 28
	v_readlane_b32 s76, v67, 28
	v_readlane_b32 s77, v69, 28
	v_readlane_b32 s78, v71, 28
	v_readlane_b32 s79, v73, 28
	v_readlane_b32 s80, v75, 28
	v_mul_f32_e32 v82, s72, v184
	v_fmac_f32_e32 v10, s73, v82
	v_fmac_f32_e32 v11, s74, v82
	v_fmac_f32_e32 v8, s75, v82
	v_fmac_f32_e32 v9, s76, v82
	v_fmac_f32_e32 v6, s77, v82
	v_fmac_f32_e32 v7, s78, v82
	v_fmac_f32_e32 v4, s79, v82
	v_fmac_f32_e32 v5, s80, v82
	v_readlane_b32 s82, v77, 29
	v_readlane_b32 s83, v61, 29
	v_readlane_b32 s84, v63, 29
	v_readlane_b32 s85, v65, 29
	v_readlane_b32 s86, v67, 29
	v_readlane_b32 s87, v69, 29
	v_readlane_b32 s88, v71, 29
	v_readlane_b32 s89, v73, 29
	v_readlane_b32 s90, v75, 29
	v_mul_f32_e32 v83, s82, v185
	v_fmac_f32_e32 v10, s83, v83
	v_fmac_f32_e32 v11, s84, v83
	v_fmac_f32_e32 v8, s85, v83
	v_fmac_f32_e32 v9, s86, v83
	v_fmac_f32_e32 v6, s87, v83
	v_fmac_f32_e32 v7, s88, v83
	v_fmac_f32_e32 v4, s89, v83
	v_fmac_f32_e32 v5, s90, v83
	v_readlane_b32 s72, v77, 30
	v_readlane_b32 s73, v61, 30
	v_readlane_b32 s74, v63, 30
	v_readlane_b32 s75, v65, 30
	v_readlane_b32 s76, v67, 30
	v_readlane_b32 s77, v69, 30
	v_readlane_b32 s78, v71, 30
	v_readlane_b32 s79, v73, 30
	v_readlane_b32 s80, v75, 30
	v_mul_f32_e32 v82, s72, v186
	v_fmac_f32_e32 v10, s73, v82
	v_fmac_f32_e32 v11, s74, v82
	v_fmac_f32_e32 v8, s75, v82
	v_fmac_f32_e32 v9, s76, v82
	v_fmac_f32_e32 v6, s77, v82
	v_fmac_f32_e32 v7, s78, v82
	v_fmac_f32_e32 v4, s79, v82
	v_fmac_f32_e32 v5, s80, v82
	v_readlane_b32 s82, v77, 31
	v_readlane_b32 s83, v61, 31
	v_readlane_b32 s84, v63, 31
	v_readlane_b32 s85, v65, 31
	v_readlane_b32 s86, v67, 31
	v_readlane_b32 s87, v69, 31
	v_readlane_b32 s88, v71, 31
	v_readlane_b32 s89, v73, 31
	v_readlane_b32 s90, v75, 31
	v_mul_f32_e32 v83, s82, v187
	v_fmac_f32_e32 v10, s83, v83
	v_fmac_f32_e32 v11, s84, v83
	v_fmac_f32_e32 v8, s85, v83
	v_fmac_f32_e32 v9, s86, v83
	v_fmac_f32_e32 v6, s87, v83
	v_fmac_f32_e32 v7, s88, v83
	v_fmac_f32_e32 v4, s89, v83
	v_fmac_f32_e32 v5, s90, v83
	s_waitcnt vmcnt(24)
	v_readlane_b32 s72, v77, 32
	v_readlane_b32 s73, v61, 32
	v_readlane_b32 s74, v63, 32
	v_readlane_b32 s75, v65, 32
	v_readlane_b32 s76, v67, 32
	v_readlane_b32 s77, v69, 32
	v_readlane_b32 s78, v71, 32
	v_readlane_b32 s79, v73, 32
	v_readlane_b32 s80, v75, 32
	v_mul_f32_e32 v82, s72, v188
	v_fmac_f32_e32 v10, s73, v82
	v_fmac_f32_e32 v11, s74, v82
	v_fmac_f32_e32 v8, s75, v82
	v_fmac_f32_e32 v9, s76, v82
	v_fmac_f32_e32 v6, s77, v82
	v_fmac_f32_e32 v7, s78, v82
	v_fmac_f32_e32 v4, s79, v82
	v_fmac_f32_e32 v5, s80, v82
	v_readlane_b32 s82, v77, 33
	v_readlane_b32 s83, v61, 33
	v_readlane_b32 s84, v63, 33
	v_readlane_b32 s85, v65, 33
	v_readlane_b32 s86, v67, 33
	v_readlane_b32 s87, v69, 33
	v_readlane_b32 s88, v71, 33
	v_readlane_b32 s89, v73, 33
	v_readlane_b32 s90, v75, 33
	v_mul_f32_e32 v83, s82, v189
	v_fmac_f32_e32 v10, s83, v83
	v_fmac_f32_e32 v11, s84, v83
	v_fmac_f32_e32 v8, s85, v83
	v_fmac_f32_e32 v9, s86, v83
	v_fmac_f32_e32 v6, s87, v83
	v_fmac_f32_e32 v7, s88, v83
	v_fmac_f32_e32 v4, s89, v83
	v_fmac_f32_e32 v5, s90, v83
	v_readlane_b32 s72, v77, 34
	v_readlane_b32 s73, v61, 34
	v_readlane_b32 s74, v63, 34
	v_readlane_b32 s75, v65, 34
	v_readlane_b32 s76, v67, 34
	v_readlane_b32 s77, v69, 34
	v_readlane_b32 s78, v71, 34
	v_readlane_b32 s79, v73, 34
	v_readlane_b32 s80, v75, 34
	v_mul_f32_e32 v82, s72, v190
	v_fmac_f32_e32 v10, s73, v82
	v_fmac_f32_e32 v11, s74, v82
	v_fmac_f32_e32 v8, s75, v82
; __device__ __forceinline__ void prologue(const Params& p, LAS unsigned char* lds) {
;     ...
;             for (int d = 0; d < 128; ++d) { const float x = wb[(size_t)d * DM] * sc[d];
; #pragma unroll
;                 for (int i = 0; i < 8; ++i) a[i] += wp[i * 128 + d] * x; }
	v_fmac_f32_e32 v9, s76, v82
	v_fmac_f32_e32 v6, s77, v82
	v_fmac_f32_e32 v7, s78, v82
	v_fmac_f32_e32 v4, s79, v82
	v_fmac_f32_e32 v5, s80, v82
	v_readlane_b32 s82, v77, 35
	v_readlane_b32 s83, v61, 35
	v_readlane_b32 s84, v63, 35
	v_readlane_b32 s85, v65, 35
	v_readlane_b32 s86, v67, 35
	v_readlane_b32 s87, v69, 35
	v_readlane_b32 s88, v71, 35
	v_readlane_b32 s89, v73, 35
	v_readlane_b32 s90, v75, 35
	v_mul_f32_e32 v83, s82, v191
	v_fmac_f32_e32 v10, s83, v83
	v_fmac_f32_e32 v11, s84, v83
	v_fmac_f32_e32 v8, s85, v83
	v_fmac_f32_e32 v9, s86, v83
	v_fmac_f32_e32 v6, s87, v83
	v_fmac_f32_e32 v7, s88, v83
	v_fmac_f32_e32 v4, s89, v83
	v_fmac_f32_e32 v5, s90, v83
	v_readlane_b32 s72, v77, 36
	v_readlane_b32 s73, v61, 36
	v_readlane_b32 s74, v63, 36
	v_readlane_b32 s75, v65, 36
	v_readlane_b32 s76, v67, 36
	v_readlane_b32 s77, v69, 36
	v_readlane_b32 s78, v71, 36
	v_readlane_b32 s79, v73, 36
	v_readlane_b32 s80, v75, 36
	v_mul_f32_e32 v82, s72, v192
	v_fmac_f32_e32 v10, s73, v82
	v_fmac_f32_e32 v11, s74, v82
	v_fmac_f32_e32 v8, s75, v82
	v_fmac_f32_e32 v9, s76, v82
	v_fmac_f32_e32 v6, s77, v82
	v_fmac_f32_e32 v7, s78, v82
	v_fmac_f32_e32 v4, s79, v82
	v_fmac_f32_e32 v5, s80, v82
	v_readlane_b32 s82, v77, 37
	v_readlane_b32 s83, v61, 37
	v_readlane_b32 s84, v63, 37
	v_readlane_b32 s85, v65, 37
	v_readlane_b32 s86, v67, 37
	v_readlane_b32 s87, v69, 37
	v_readlane_b32 s88, v71, 37
	v_readlane_b32 s89, v73, 37
	v_readlane_b32 s90, v75, 37
	v_mul_f32_e32 v83, s82, v193
	v_fmac_f32_e32 v10, s83, v83
	v_fmac_f32_e32 v11, s84, v83
	v_fmac_f32_e32 v8, s85, v83
	v_fmac_f32_e32 v9, s86, v83
	v_fmac_f32_e32 v6, s87, v83
	v_fmac_f32_e32 v7, s88, v83
	v_fmac_f32_e32 v4, s89, v83
	v_fmac_f32_e32 v5, s90, v83
	v_readlane_b32 s72, v77, 38
	v_readlane_b32 s73, v61, 38
	v_readlane_b32 s74, v63, 38
	v_readlane_b32 s75, v65, 38
	v_readlane_b32 s76, v67, 38
	v_readlane_b32 s77, v69, 38
	v_readlane_b32 s78, v71, 38
	v_readlane_b32 s79, v73, 38
	v_readlane_b32 s80, v75, 38
	v_mul_f32_e32 v82, s72, v194
	v_fmac_f32_e32 v10, s73, v82
	v_fmac_f32_e32 v11, s74, v82
	v_fmac_f32_e32 v8, s75, v82
	v_fmac_f32_e32 v9, s76, v82
	v_fmac_f32_e32 v6, s77, v82
	v_fmac_f32_e32 v7, s78, v82
	v_fmac_f32_e32 v4, s79, v82
	v_fmac_f32_e32 v5, s80, v82
	v_readlane_b32 s82, v77, 39
	v_readlane_b32 s83, v61, 39
	v_readlane_b32 s84, v63, 39
	v_readlane_b32 s85, v65, 39
	v_readlane_b32 s86, v67, 39
	v_readlane_b32 s87, v69, 39
	v_readlane_b32 s88, v71, 39
	v_readlane_b32 s89, v73, 39
	v_readlane_b32 s90, v75, 39
	v_mul_f32_e32 v83, s82, v195
	v_fmac_f32_e32 v10, s83, v83
	v_fmac_f32_e32 v11, s84, v83
	v_fmac_f32_e32 v8, s85, v83
	v_fmac_f32_e32 v9, s86, v83
	v_fmac_f32_e32 v6, s87, v83
	v_fmac_f32_e32 v7, s88, v83
	v_fmac_f32_e32 v4, s89, v83
	v_fmac_f32_e32 v5, s90, v83
	s_waitcnt vmcnt(16)
	v_readlane_b32 s72, v77, 40
	v_readlane_b32 s73, v61, 40
	v_readlane_b32 s74, v63, 40
	v_readlane_b32 s75, v65, 40
	v_readlane_b32 s76, v67, 40
	v_readlane_b32 s77, v69, 40
	v_readlane_b32 s78, v71, 40
	v_readlane_b32 s79, v73, 40
	v_readlane_b32 s80, v75, 40
	v_mul_f32_e32 v82, s72, v196
	v_fmac_f32_e32 v10, s73, v82
	v_fmac_f32_e32 v11, s74, v82
	v_fmac_f32_e32 v8, s75, v82
	v_fmac_f32_e32 v9, s76, v82
	v_fmac_f32_e32 v6, s77, v82
	v_fmac_f32_e32 v7, s78, v82
	v_fmac_f32_e32 v4, s79, v82
	v_fmac_f32_e32 v5, s80, v82
	v_readlane_b32 s82, v77, 41
	v_readlane_b32 s83, v61, 41
	v_readlane_b32 s84, v63, 41
	v_readlane_b32 s85, v65, 41
	v_readlane_b32 s86, v67, 41
	v_readlane_b32 s87, v69, 41
	v_readlane_b32 s88, v71, 41
	v_readlane_b32 s89, v73, 41
	v_readlane_b32 s90, v75, 41
	v_mul_f32_e32 v83, s82, v197
	v_fmac_f32_e32 v10, s83, v83
	v_fmac_f32_e32 v11, s84, v83
	v_fmac_f32_e32 v8, s85, v83
	v_fmac_f32_e32 v9, s86, v83
	v_fmac_f32_e32 v6, s87, v83
	v_fmac_f32_e32 v7, s88, v83
	v_fmac_f32_e32 v4, s89, v83
	v_fmac_f32_e32 v5, s90, v83
	v_readlane_b32 s72, v77, 42
	v_readlane_b32 s73, v61, 42
	v_readlane_b32 s74, v63, 42
	v_readlane_b32 s75, v65, 42
	v_readlane_b32 s76, v67, 42
	v_readlane_b32 s77, v69, 42
	v_readlane_b32 s78, v71, 42
	v_readlane_b32 s79, v73, 42
	v_readlane_b32 s80, v75, 42
	v_mul_f32_e32 v82, s72, v198
	v_fmac_f32_e32 v10, s73, v82
	v_fmac_f32_e32 v11, s74, v82
	v_fmac_f32_e32 v8, s75, v82
	v_fmac_f32_e32 v9, s76, v82
	v_fmac_f32_e32 v6, s77, v82
	v_fmac_f32_e32 v7, s78, v82
	v_fmac_f32_e32 v4, s79, v82
	v_fmac_f32_e32 v5, s80, v82
	v_readlane_b32 s82, v77, 43
	v_readlane_b32 s83, v61, 43
	v_readlane_b32 s84, v63, 43
	v_readlane_b32 s85, v65, 43
	v_readlane_b32 s86, v67, 43
	v_readlane_b32 s87, v69, 43
	v_readlane_b32 s88, v71, 43
	v_readlane_b32 s89, v73, 43
	v_readlane_b32 s90, v75, 43
	v_mul_f32_e32 v83, s82, v199
	v_fmac_f32_e32 v10, s83, v83
	v_fmac_f32_e32 v11, s84, v83
	v_fmac_f32_e32 v8, s85, v83
	v_fmac_f32_e32 v9, s86, v83
	v_fmac_f32_e32 v6, s87, v83
	v_fmac_f32_e32 v7, s88, v83
	v_fmac_f32_e32 v4, s89, v83
	v_fmac_f32_e32 v5, s90, v83
	v_readlane_b32 s72, v77, 44
	v_readlane_b32 s73, v61, 44
	v_readlane_b32 s74, v63, 44
	v_readlane_b32 s75, v65, 44
	v_readlane_b32 s76, v67, 44
	v_readlane_b32 s77, v69, 44
	v_readlane_b32 s78, v71, 44
	v_readlane_b32 s79, v73, 44
	v_readlane_b32 s80, v75, 44
	v_mul_f32_e32 v82, s72, v200
	v_fmac_f32_e32 v10, s73, v82
	v_fmac_f32_e32 v11, s74, v82
	v_fmac_f32_e32 v8, s75, v82
	v_fmac_f32_e32 v9, s76, v82
	v_fmac_f32_e32 v6, s77, v82
	v_fmac_f32_e32 v7, s78, v82
	v_fmac_f32_e32 v4, s79, v82
	v_fmac_f32_e32 v5, s80, v82
	v_readlane_b32 s82, v77, 45
	v_readlane_b32 s83, v61, 45
	v_readlane_b32 s84, v63, 45
	v_readlane_b32 s85, v65, 45
	v_readlane_b32 s86, v67, 45
	v_readlane_b32 s87, v69, 45
	v_readlane_b32 s88, v71, 45
	v_readlane_b32 s89, v73, 45
	v_readlane_b32 s90, v75, 45
	v_mul_f32_e32 v83, s82, v201
	v_fmac_f32_e32 v10, s83, v83
	v_fmac_f32_e32 v11, s84, v83
	v_fmac_f32_e32 v8, s85, v83
	v_fmac_f32_e32 v9, s86, v83
	v_fmac_f32_e32 v6, s87, v83
	v_fmac_f32_e32 v7, s88, v83
	v_fmac_f32_e32 v4, s89, v83
	v_fmac_f32_e32 v5, s90, v83
	v_readlane_b32 s72, v77, 46
	v_readlane_b32 s73, v61, 46
	v_readlane_b32 s74, v63, 46
	v_readlane_b32 s75, v65, 46
	v_readlane_b32 s76, v67, 46
	v_readlane_b32 s77, v69, 46
	v_readlane_b32 s78, v71, 46
	v_readlane_b32 s79, v73, 46
	v_readlane_b32 s80, v75, 46
	v_mul_f32_e32 v82, s72, v202
	v_fmac_f32_e32 v10, s73, v82
	v_fmac_f32_e32 v11, s74, v82
	v_fmac_f32_e32 v8, s75, v82
	v_fmac_f32_e32 v9, s76, v82
	v_fmac_f32_e32 v6, s77, v82
	v_fmac_f32_e32 v7, s78, v82
	v_fmac_f32_e32 v4, s79, v82
	v_fmac_f32_e32 v5, s80, v82
	v_readlane_b32 s82, v77, 47
	v_readlane_b32 s83, v61, 47
	v_readlane_b32 s84, v63, 47
	v_readlane_b32 s85, v65, 47
	v_readlane_b32 s86, v67, 47
	v_readlane_b32 s87, v69, 47
	v_readlane_b32 s88, v71, 47
	v_readlane_b32 s89, v73, 47
	v_readlane_b32 s90, v75, 47
	v_mul_f32_e32 v83, s82, v203
	v_fmac_f32_e32 v10, s83, v83
	v_fmac_f32_e32 v11, s84, v83
	v_fmac_f32_e32 v8, s85, v83
	v_fmac_f32_e32 v9, s86, v83
	v_fmac_f32_e32 v6, s87, v83
	v_fmac_f32_e32 v7, s88, v83
	v_fmac_f32_e32 v4, s89, v83
	v_fmac_f32_e32 v5, s90, v83
	s_waitcnt vmcnt(8)
; __device__ __forceinline__ void prologue(const Params& p, LAS unsigned char* lds) {
;     ...
;             for (int d = 0; d < 128; ++d) { const float x = wb[(size_t)d * DM] * sc[d];
; #pragma unroll
;                 for (int i = 0; i < 8; ++i) a[i] += wp[i * 128 + d] * x; }
	v_readlane_b32 s72, v77, 48
	v_readlane_b32 s73, v61, 48
	v_readlane_b32 s74, v63, 48
	v_readlane_b32 s75, v65, 48
	v_readlane_b32 s76, v67, 48
	v_readlane_b32 s77, v69, 48
	v_readlane_b32 s78, v71, 48
	v_readlane_b32 s79, v73, 48
	v_readlane_b32 s80, v75, 48
	v_mul_f32_e32 v82, s72, v204
	v_fmac_f32_e32 v10, s73, v82
	v_fmac_f32_e32 v11, s74, v82
	v_fmac_f32_e32 v8, s75, v82
	v_fmac_f32_e32 v9, s76, v82
	v_fmac_f32_e32 v6, s77, v82
	v_fmac_f32_e32 v7, s78, v82
	v_fmac_f32_e32 v4, s79, v82
	v_fmac_f32_e32 v5, s80, v82
	v_readlane_b32 s82, v77, 49
	v_readlane_b32 s83, v61, 49
	v_readlane_b32 s84, v63, 49
	v_readlane_b32 s85, v65, 49
	v_readlane_b32 s86, v67, 49
	v_readlane_b32 s87, v69, 49
	v_readlane_b32 s88, v71, 49
	v_readlane_b32 s89, v73, 49
	v_readlane_b32 s90, v75, 49
	v_mul_f32_e32 v83, s82, v205
	v_fmac_f32_e32 v10, s83, v83
	v_fmac_f32_e32 v11, s84, v83
	v_fmac_f32_e32 v8, s85, v83
	v_fmac_f32_e32 v9, s86, v83
	v_fmac_f32_e32 v6, s87, v83
	v_fmac_f32_e32 v7, s88, v83
	v_fmac_f32_e32 v4, s89, v83
	v_fmac_f32_e32 v5, s90, v83
	v_readlane_b32 s72, v77, 50
	v_readlane_b32 s73, v61, 50
	v_readlane_b32 s74, v63, 50
	v_readlane_b32 s75, v65, 50
	v_readlane_b32 s76, v67, 50
	v_readlane_b32 s77, v69, 50
	v_readlane_b32 s78, v71, 50
	v_readlane_b32 s79, v73, 50
	v_readlane_b32 s80, v75, 50
	v_mul_f32_e32 v82, s72, v206
	v_fmac_f32_e32 v10, s73, v82
	v_fmac_f32_e32 v11, s74, v82
	v_fmac_f32_e32 v8, s75, v82
	v_fmac_f32_e32 v9, s76, v82
	v_fmac_f32_e32 v6, s77, v82
	v_fmac_f32_e32 v7, s78, v82
	v_fmac_f32_e32 v4, s79, v82
	v_fmac_f32_e32 v5, s80, v82
	v_readlane_b32 s82, v77, 51
	v_readlane_b32 s83, v61, 51
	v_readlane_b32 s84, v63, 51
	v_readlane_b32 s85, v65, 51
	v_readlane_b32 s86, v67, 51
	v_readlane_b32 s87, v69, 51
	v_readlane_b32 s88, v71, 51
	v_readlane_b32 s89, v73, 51
	v_readlane_b32 s90, v75, 51
	v_mul_f32_e32 v83, s82, v207
	v_fmac_f32_e32 v10, s83, v83
	v_fmac_f32_e32 v11, s84, v83
	v_fmac_f32_e32 v8, s85, v83
	v_fmac_f32_e32 v9, s86, v83
	v_fmac_f32_e32 v6, s87, v83
	v_fmac_f32_e32 v7, s88, v83
	v_fmac_f32_e32 v4, s89, v83
	v_fmac_f32_e32 v5, s90, v83
	v_readlane_b32 s72, v77, 52
	v_readlane_b32 s73, v61, 52
	v_readlane_b32 s74, v63, 52
	v_readlane_b32 s75, v65, 52
	v_readlane_b32 s76, v67, 52
	v_readlane_b32 s77, v69, 52
	v_readlane_b32 s78, v71, 52
	v_readlane_b32 s79, v73, 52
	v_readlane_b32 s80, v75, 52
	v_mul_f32_e32 v82, s72, v208
	v_fmac_f32_e32 v10, s73, v82
	v_fmac_f32_e32 v11, s74, v82
	v_fmac_f32_e32 v8, s75, v82
	v_fmac_f32_e32 v9, s76, v82
	v_fmac_f32_e32 v6, s77, v82
	v_fmac_f32_e32 v7, s78, v82
	v_fmac_f32_e32 v4, s79, v82
	v_fmac_f32_e32 v5, s80, v82
	v_readlane_b32 s82, v77, 53
	v_readlane_b32 s83, v61, 53
	v_readlane_b32 s84, v63, 53
	v_readlane_b32 s85, v65, 53
	v_readlane_b32 s86, v67, 53
	v_readlane_b32 s87, v69, 53
	v_readlane_b32 s88, v71, 53
	v_readlane_b32 s89, v73, 53
	v_readlane_b32 s90, v75, 53
	v_mul_f32_e32 v83, s82, v209
	v_fmac_f32_e32 v10, s83, v83
	v_fmac_f32_e32 v11, s84, v83
	v_fmac_f32_e32 v8, s85, v83
	v_fmac_f32_e32 v9, s86, v83
	v_fmac_f32_e32 v6, s87, v83
	v_fmac_f32_e32 v7, s88, v83
	v_fmac_f32_e32 v4, s89, v83
	v_fmac_f32_e32 v5, s90, v83
	v_readlane_b32 s72, v77, 54
	v_readlane_b32 s73, v61, 54
	v_readlane_b32 s74, v63, 54
	v_readlane_b32 s75, v65, 54
	v_readlane_b32 s76, v67, 54
	v_readlane_b32 s77, v69, 54
	v_readlane_b32 s78, v71, 54
	v_readlane_b32 s79, v73, 54
	v_readlane_b32 s80, v75, 54
	v_mul_f32_e32 v82, s72, v210
	v_fmac_f32_e32 v10, s73, v82
	v_fmac_f32_e32 v11, s74, v82
	v_fmac_f32_e32 v8, s75, v82
	v_fmac_f32_e32 v9, s76, v82
	v_fmac_f32_e32 v6, s77, v82
	v_fmac_f32_e32 v7, s78, v82
	v_fmac_f32_e32 v4, s79, v82
	v_fmac_f32_e32 v5, s80, v82
	v_readlane_b32 s82, v77, 55
	v_readlane_b32 s83, v61, 55
	v_readlane_b32 s84, v63, 55
	v_readlane_b32 s85, v65, 55
	v_readlane_b32 s86, v67, 55
	v_readlane_b32 s87, v69, 55
	v_readlane_b32 s88, v71, 55
	v_readlane_b32 s89, v73, 55
	v_readlane_b32 s90, v75, 55
	v_mul_f32_e32 v83, s82, v211
	v_fmac_f32_e32 v10, s83, v83
	v_fmac_f32_e32 v11, s84, v83
	v_fmac_f32_e32 v8, s85, v83
	v_fmac_f32_e32 v9, s86, v83
	v_fmac_f32_e32 v6, s87, v83
	v_fmac_f32_e32 v7, s88, v83
	v_fmac_f32_e32 v4, s89, v83
	v_fmac_f32_e32 v5, s90, v83
	s_waitcnt vmcnt(0)
; __device__ __forceinline__ u32x4 pack8(const float* f) { u32x4 w; w.x = cvt_pk_bf16(f[0], f[1]); w.y = cvt_pk_bf16(f[2], f[3]); w.z = cvt_pk_bf16(f[4], f[5]); w.w = cvt_pk_bf16(f[6], f[7]); return w; }
; __device__ __forceinline__ void prologue(const Params& p, LAS unsigned char* lds) {
;     ...
;             for (int d = 0; d < 128; ++d) { const float x = wb[(size_t)d * DM] * sc[d];
; #pragma unroll
;                 for (int i = 0; i < 8; ++i) a[i] += wp[i * 128 + d] * x; }
;             bf16_t* dst = (bf16_t*)(p.ws + WS_W + (size_t)l * W_LAYER + WO_MIX) + (size_t)(1024 + n) * 512 + g * 128 + c0;
;             *(u32x4*)dst = pack8(a);
;         }
	v_readlane_b32 s72, v77, 56
	v_readlane_b32 s73, v61, 56
	v_readlane_b32 s74, v63, 56
	v_readlane_b32 s75, v65, 56
	v_readlane_b32 s76, v67, 56
	v_readlane_b32 s77, v69, 56
	v_readlane_b32 s78, v71, 56
	v_readlane_b32 s79, v73, 56
	v_readlane_b32 s80, v75, 56
	v_mul_f32_e32 v82, s72, v212
	v_fmac_f32_e32 v10, s73, v82
	v_fmac_f32_e32 v11, s74, v82
	v_fmac_f32_e32 v8, s75, v82
	v_fmac_f32_e32 v9, s76, v82
	v_fmac_f32_e32 v6, s77, v82
	v_fmac_f32_e32 v7, s78, v82
	v_fmac_f32_e32 v4, s79, v82
	v_fmac_f32_e32 v5, s80, v82
	v_readlane_b32 s82, v77, 57
	v_readlane_b32 s83, v61, 57
	v_readlane_b32 s84, v63, 57
	v_readlane_b32 s85, v65, 57
	v_readlane_b32 s86, v67, 57
	v_readlane_b32 s87, v69, 57
	v_readlane_b32 s88, v71, 57
	v_readlane_b32 s89, v73, 57
	v_readlane_b32 s90, v75, 57
	v_mul_f32_e32 v83, s82, v213
	v_fmac_f32_e32 v10, s83, v83
	v_fmac_f32_e32 v11, s84, v83
	v_fmac_f32_e32 v8, s85, v83
	v_fmac_f32_e32 v9, s86, v83
	v_fmac_f32_e32 v6, s87, v83
	v_fmac_f32_e32 v7, s88, v83
	v_fmac_f32_e32 v4, s89, v83
	v_fmac_f32_e32 v5, s90, v83
	v_readlane_b32 s72, v77, 58
	v_readlane_b32 s73, v61, 58
	v_readlane_b32 s74, v63, 58
	v_readlane_b32 s75, v65, 58
	v_readlane_b32 s76, v67, 58
	v_readlane_b32 s77, v69, 58
	v_readlane_b32 s78, v71, 58
	v_readlane_b32 s79, v73, 58
	v_readlane_b32 s80, v75, 58
	v_mul_f32_e32 v82, s72, v214
	v_fmac_f32_e32 v10, s73, v82
	v_fmac_f32_e32 v11, s74, v82
	v_fmac_f32_e32 v8, s75, v82
	v_fmac_f32_e32 v9, s76, v82
	v_fmac_f32_e32 v6, s77, v82
	v_fmac_f32_e32 v7, s78, v82
	v_fmac_f32_e32 v4, s79, v82
	v_fmac_f32_e32 v5, s80, v82
	v_readlane_b32 s82, v77, 59
	v_readlane_b32 s83, v61, 59
	v_readlane_b32 s84, v63, 59
	v_readlane_b32 s85, v65, 59
	v_readlane_b32 s86, v67, 59
	v_readlane_b32 s87, v69, 59
	v_readlane_b32 s88, v71, 59
	v_readlane_b32 s89, v73, 59
	v_readlane_b32 s90, v75, 59
	v_mul_f32_e32 v83, s82, v215
	v_fmac_f32_e32 v10, s83, v83
	v_fmac_f32_e32 v11, s84, v83
	v_fmac_f32_e32 v8, s85, v83
	v_fmac_f32_e32 v9, s86, v83
	v_fmac_f32_e32 v6, s87, v83
	v_fmac_f32_e32 v7, s88, v83
	v_fmac_f32_e32 v4, s89, v83
	v_fmac_f32_e32 v5, s90, v83
	v_readlane_b32 s72, v77, 60
	v_readlane_b32 s73, v61, 60
	v_readlane_b32 s74, v63, 60
	v_readlane_b32 s75, v65, 60
	v_readlane_b32 s76, v67, 60
	v_readlane_b32 s77, v69, 60
	v_readlane_b32 s78, v71, 60
	v_readlane_b32 s79, v73, 60
	v_readlane_b32 s80, v75, 60
	v_mul_f32_e32 v82, s72, v216
	v_fmac_f32_e32 v10, s73, v82
	v_fmac_f32_e32 v11, s74, v82
	v_fmac_f32_e32 v8, s75, v82
	v_fmac_f32_e32 v9, s76, v82
	v_fmac_f32_e32 v6, s77, v82
	v_fmac_f32_e32 v7, s78, v82
	v_fmac_f32_e32 v4, s79, v82
	v_fmac_f32_e32 v5, s80, v82
	v_readlane_b32 s82, v77, 61
	v_readlane_b32 s83, v61, 61
	v_readlane_b32 s84, v63, 61
	v_readlane_b32 s85, v65, 61
	v_readlane_b32 s86, v67, 61
	v_readlane_b32 s87, v69, 61
	v_readlane_b32 s88, v71, 61
	v_readlane_b32 s89, v73, 61
	v_readlane_b32 s90, v75, 61
	v_mul_f32_e32 v83, s82, v217
	v_fmac_f32_e32 v10, s83, v83
	v_fmac_f32_e32 v11, s84, v83
	v_fmac_f32_e32 v8, s85, v83
	v_fmac_f32_e32 v9, s86, v83
	v_fmac_f32_e32 v6, s87, v83
	v_fmac_f32_e32 v7, s88, v83
	v_fmac_f32_e32 v4, s89, v83
	v_fmac_f32_e32 v5, s90, v83
	v_readlane_b32 s72, v77, 62
	v_readlane_b32 s73, v61, 62
	v_readlane_b32 s74, v63, 62
	v_readlane_b32 s75, v65, 62
	v_readlane_b32 s76, v67, 62
	v_readlane_b32 s77, v69, 62
	v_readlane_b32 s78, v71, 62
	v_readlane_b32 s79, v73, 62
	v_readlane_b32 s80, v75, 62
	v_mul_f32_e32 v82, s72, v218
	v_fmac_f32_e32 v10, s73, v82
	v_fmac_f32_e32 v11, s74, v82
	v_fmac_f32_e32 v8, s75, v82
	v_fmac_f32_e32 v9, s76, v82
	v_fmac_f32_e32 v6, s77, v82
	v_fmac_f32_e32 v7, s78, v82
	v_fmac_f32_e32 v4, s79, v82
	v_fmac_f32_e32 v5, s80, v82
	v_readlane_b32 s82, v77, 63
	v_readlane_b32 s83, v61, 63
	v_readlane_b32 s84, v63, 63
	v_readlane_b32 s85, v65, 63
	v_readlane_b32 s86, v67, 63
	v_readlane_b32 s87, v69, 63
	v_readlane_b32 s88, v71, 63
	v_readlane_b32 s89, v73, 63
	v_readlane_b32 s90, v75, 63
	v_mul_f32_e32 v83, s82, v219
	v_fmac_f32_e32 v10, s83, v83
	v_fmac_f32_e32 v11, s84, v83
	v_fmac_f32_e32 v8, s85, v83
	v_fmac_f32_e32 v9, s86, v83
	v_fmac_f32_e32 v6, s87, v83
	v_fmac_f32_e32 v7, s88, v83
	v_fmac_f32_e32 v4, s89, v83
	v_fmac_f32_e32 v5, s90, v83
	s_lshl_b32 s11, s24, 6
	s_and_b32 s11, s11, 0x3c0
	s_and_b32 s4, s4, 3
	v_or_b32_e32 v0, s11, v39
	s_mul_hi_i32 s11, s10, 0x1b00000
	s_mul_i32 s10, s10, 0x1b00000
	s_add_u32 s10, s50, s10
	s_addc_u32 s11, s51, s11
	v_lshlrev_b32_e32 v0, 10, v0
	v_lshl_add_u64 v[2:3], s[10:11], 0, v[0:1]
	s_lshl_b32 s4, s4, 8
	v_lshl_add_u64 v[2:3], v[2:3], 0, s[4:5]
	s_and_b32 s4, s24, 0xf0
	v_lshl_add_u64 v[2:3], v[2:3], 0, s[4:5]
	v_add_co_u32_e32 v2, vcc, 0x880000, v2
	s_add_i32 s24, s24, s32
	s_add_i32 s1, s1, s33
	v_addc_co_u32_e32 v3, vcc, 0, v3, vcc
	s_cmpk_gt_i32 s24, 0x7ff
	v_cvt_pk_bf16_f32 v10, v10, v11
	v_cvt_pk_bf16_f32 v11, v8, v9
	v_cvt_pk_bf16_f32 v12, v6, v7
	v_cvt_pk_bf16_f32 v13, v4, v5
	global_store_dwordx4 v[2:3], v[10:13], off nt
	s_cbranch_scc0 .LBB0_48

; #define LAS __attribute__((address_space(3)))
; __device__ __forceinline__ unsigned cvt_pk_bf16(float lo, float hi) { unsigned r; asm volatile("v_cvt_pk_bf16_f32 %0, %1, %2" : "=v"(r) : "v"(lo), "v"(hi)); return r; }
; __device__ __forceinline__ void transpose_item(const float* W, int N, const float* ks, bf16_t* WT, int ldo, int orow0, int k0, int n0, LAS float* scr, int lane) {
;     f32x4 v[8];
; #pragma unroll
;     for (int i = 0; i < 8; ++i) v[i] = *(const f32x4*)(W + (size_t)(k0 + i * 4 + (lane >> 4)) * N + n0 + 4 * (lane & 15));
; #pragma unroll
;     for (int i = 0; i < 8; ++i) { const int kk = i * 4 + (lane >> 4); const float sc = ks ? ks[k0 + kk] : 1.0f; LAS float* d = scr + kk * 65 + 4 * (lane & 15);
;         d[0] = v[i][0] * sc; d[1] = v[i][1] * sc; d[2] = v[i][2] * sc; d[3] = v[i][3] * sc; }
;     asm volatile("s_waitcnt lgkmcnt(0)" ::: "memory");
;     const int kc = lane & 3;
; #pragma unroll
;     for (int j = 0; j < 4; ++j) { const int n = (lane >> 2) + 16 * j; const LAS float* s = scr + (8 * kc) * 65 + n;
;         u32x4 o; o.x = cvt_pk_bf16(s[0 * 65], s[1 * 65]); o.y = cvt_pk_bf16(s[2 * 65], s[3 * 65]); o.z = cvt_pk_bf16(s[4 * 65], s[5 * 65]); o.w = cvt_pk_bf16(s[6 * 65], s[7 * 65]);
;         *(u32x4*)(WT + (size_t)(orow0 + n) * ldo + k0 + 8 * kc) = o; }
;     asm volatile("s_waitcnt lgkmcnt(0)" ::: "memory");
; }
; __device__ __forceinline__ void convert_weights(const Params& p, LAS unsigned char* lds, int first, int last, int worker, int nworkers) {
;     ...
;         if (r < WI_IN) { const int kb = r / 52, nb = r % 52; transpose_item(p.w_in + (size_t)l * DM * INW, INW, p.norm_mix + l * DM, (bf16_t*)(wb + WO_IN), DM, nb * 64, kb * 32, nb * 64, scr, lane); continue; } r -= WI_IN;
.LBB0_54:
	v_add_u32_e32 v9, 0x1450, v49
	ds_write2_b32 v9, v4, v5 offset1:1
	v_add_u32_e32 v4, 0x1458, v49
	ds_write2_b32 v4, v6, v7 offset1:1
	s_waitcnt vmcnt(0)
	v_pk_mul_f32 v[0:1], v[0:1], v[8:9] op_sel_hi:[1,0]
	v_add_u32_e32 v4, 0x1860, v49
	ds_write2_b32 v4, v0, v1 offset1:1
	v_pk_mul_f32 v[0:1], v[2:3], v[8:9] op_sel_hi:[1,0]
	v_add_u32_e32 v2, 0x1868, v49
	ds_write2_b32 v2, v0, v1 offset1:1
	s_waitcnt lgkmcnt(0)
	ds_read2_b32 v[0:1], v44 offset1:65
	s_waitcnt lgkmcnt(0)
	v_cvt_pk_bf16_f32 v0, v0, v1
	ds_read2_b32 v[2:3], v44 offset0:130 offset1:195
	v_add_u32_e32 v10, 0x400, v44
	s_mul_hi_i32 s5, s18, 0x1b00000
	s_mul_i32 s18, s18, 0x1b00000
	s_waitcnt lgkmcnt(0)
	v_cvt_pk_bf16_f32 v1, v2, v3
	ds_read2_b32 v[2:3], v10 offset0:4 offset1:69
	s_add_u32 s10, s1, s18
	s_addc_u32 s5, s12, s5
	s_waitcnt lgkmcnt(0)
	v_cvt_pk_bf16_f32 v2, v2, v3
	ds_read2_b32 v[4:5], v10 offset0:134 offset1:199
	s_lshl_b64 s[8:9], s[8:9], 1
	s_add_u32 s8, s10, s8
	s_waitcnt lgkmcnt(0)
	v_cvt_pk_bf16_f32 v3, v4, v5
	v_or_b32_e32 v4, s4, v43
	s_addc_u32 s9, s5, s9
	v_ashrrev_i32_e32 v5, 31, v4
	v_lshl_add_u64 v[6:7], s[8:9], 0, v[34:35]
	v_lshlrev_b64 v[4:5], 11, v[4:5]
	ds_read2_b32 v[8:9], v44 offset0:16 offset1:81
	v_lshl_add_u64 v[4:5], v[6:7], 0, v[4:5]
	global_store_dwordx4 v[4:5], v[0:3], off nt
	s_add_i32 s17, s17, s32
	s_cmpk_lt_i32 s17, 0x680
	s_waitcnt lgkmcnt(0)
	v_cvt_pk_bf16_f32 v0, v8, v9
	v_or_b32_e32 v8, s4, v45
	ds_read2_b32 v[2:3], v44 offset0:146 offset1:211
	v_ashrrev_i32_e32 v9, 31, v8
	s_waitcnt lgkmcnt(0)
	v_cvt_pk_bf16_f32 v1, v2, v3
	ds_read2_b32 v[2:3], v10 offset0:20 offset1:85
	v_lshlrev_b64 v[8:9], 11, v[8:9]
	s_waitcnt lgkmcnt(0)
	v_cvt_pk_bf16_f32 v2, v2, v3
	ds_read2_b32 v[4:5], v10 offset0:150 offset1:215
	s_waitcnt lgkmcnt(0)
	v_cvt_pk_bf16_f32 v3, v4, v5
	v_lshl_add_u64 v[8:9], v[6:7], 0, v[8:9]
	ds_read2_b32 v[4:5], v44 offset0:32 offset1:97
	global_store_dwordx4 v[8:9], v[0:3], off nt
	v_or_b32_e32 v8, s4, v46
	v_ashrrev_i32_e32 v9, 31, v8
	s_waitcnt lgkmcnt(0)
	v_cvt_pk_bf16_f32 v0, v4, v5
	ds_read2_b32 v[2:3], v44 offset0:162 offset1:227
	s_waitcnt lgkmcnt(0)
	v_cvt_pk_bf16_f32 v1, v2, v3
	ds_read2_b32 v[2:3], v10 offset0:36 offset1:101
	s_waitcnt lgkmcnt(0)
	v_cvt_pk_bf16_f32 v2, v2, v3
	ds_read2_b32 v[4:5], v10 offset0:166 offset1:231
	v_lshlrev_b64 v[8:9], 11, v[8:9]
	s_waitcnt lgkmcnt(0)
	v_cvt_pk_bf16_f32 v3, v4, v5
	ds_read2_b32 v[4:5], v44 offset0:48 offset1:113
	v_lshl_add_u64 v[8:9], v[6:7], 0, v[8:9]
	global_store_dwordx4 v[8:9], v[0:3], off nt
	s_waitcnt lgkmcnt(0)
	s_nop 0
	v_cvt_pk_bf16_f32 v0, v4, v5
	v_or_b32_e32 v4, s4, v47
	v_ashrrev_i32_e32 v5, 31, v4
	ds_read2_b32 v[2:3], v44 offset0:178 offset1:243
	v_lshlrev_b64 v[4:5], 11, v[4:5]
	s_waitcnt lgkmcnt(0)
	v_cvt_pk_bf16_f32 v1, v2, v3
	ds_read2_b32 v[2:3], v10 offset0:52 offset1:117
	v_lshl_add_u64 v[4:5], v[6:7], 0, v[4:5]
	s_waitcnt lgkmcnt(0)
	v_cvt_pk_bf16_f32 v2, v2, v3
	ds_read2_b32 v[8:9], v10 offset0:182 offset1:247
	s_waitcnt lgkmcnt(0)
	v_cvt_pk_bf16_f32 v3, v8, v9
	global_store_dwordx4 v[4:5], v[0:3], off nt
	s_waitcnt lgkmcnt(0)
	s_cbranch_scc0 .LBB0_65

; #define LAS __attribute__((address_space(3)))
; __device__ __forceinline__ unsigned cvt_pk_bf16(float lo, float hi) { unsigned r; asm volatile("v_cvt_pk_bf16_f32 %0, %1, %2" : "=v"(r) : "v"(lo), "v"(hi)); return r; }
; __device__ __forceinline__ void transpose_item(const float* W, int N, const float* ks, bf16_t* WT, int ldo, int orow0, int k0, int n0, LAS float* scr, int lane) {
;     f32x4 v[8];
; #pragma unroll
;     for (int i = 0; i < 8; ++i) v[i] = *(const f32x4*)(W + (size_t)(k0 + i * 4 + (lane >> 4)) * N + n0 + 4 * (lane & 15));
; #pragma unroll
;     for (int i = 0; i < 8; ++i) { const int kk = i * 4 + (lane >> 4); const float sc = ks ? ks[k0 + kk] : 1.0f; LAS float* d = scr + kk * 65 + 4 * (lane & 15);
;         d[0] = v[i][0] * sc; d[1] = v[i][1] * sc; d[2] = v[i][2] * sc; d[3] = v[i][3] * sc; }
;     asm volatile("s_waitcnt lgkmcnt(0)" ::: "memory");
;     const int kc = lane & 3;
; #pragma unroll
;     for (int j = 0; j < 4; ++j) { const int n = (lane >> 2) + 16 * j; const LAS float* s = scr + (8 * kc) * 65 + n;
;         u32x4 o; o.x = cvt_pk_bf16(s[0 * 65], s[1 * 65]); o.y = cvt_pk_bf16(s[2 * 65], s[3 * 65]); o.z = cvt_pk_bf16(s[4 * 65], s[5 * 65]); o.w = cvt_pk_bf16(s[6 * 65], s[7 * 65]);
;         *(u32x4*)(WT + (size_t)(orow0 + n) * ldo + k0 + 8 * kc) = o; }
;     asm volatile("s_waitcnt lgkmcnt(0)" ::: "memory");
; }
; __device__ __forceinline__ void convert_weights(const Params& p, LAS unsigned char* lds, int first, int last, int worker, int nworkers) {
;     ...
;         if (r < WI_IN) { const int kb = r / 52, nb = r % 52; transpose_item(p.w_in + (size_t)l * DM * INW, INW, p.norm_mix + l * DM, (bf16_t*)(wb + WO_IN), DM, nb * 64, kb * 32, nb * 64, scr, lane); continue; } r -= WI_IN;
.LBB0_194:
	v_add_u32_e32 v9, 0x1450, v24
	ds_write2_b32 v9, v4, v5 offset1:1
	v_add_u32_e32 v4, 0x1458, v24
	ds_write2_b32 v4, v6, v7 offset1:1
	v_pk_mul_f32 v[0:1], v[0:1], v[8:9] op_sel_hi:[1,0]
	v_add_u32_e32 v4, 0x1860, v24
	ds_write2_b32 v4, v0, v1 offset1:1
	v_pk_mul_f32 v[0:1], v[2:3], v[8:9] op_sel_hi:[1,0]
	v_add_u32_e32 v2, 0x1868, v24
	ds_write2_b32 v2, v0, v1 offset1:1
	s_waitcnt lgkmcnt(0)
	ds_read2_b32 v[0:1], v43 offset1:65
	s_waitcnt lgkmcnt(0)
	v_cvt_pk_bf16_f32 v0, v0, v1
	ds_read2_b32 v[2:3], v43 offset0:130 offset1:195
	v_add_u32_e32 v8, 0x400, v43
	s_waitcnt lgkmcnt(0)
	v_cvt_pk_bf16_f32 v1, v2, v3
	ds_read2_b32 v[2:3], v8 offset0:4 offset1:69
	s_lshl_b64 s[2:3], s[2:3], 1
	s_waitcnt lgkmcnt(0)
	v_cvt_pk_bf16_f32 v2, v2, v3
	ds_read2_b32 v[6:7], v8 offset0:134 offset1:199
	s_add_u32 s2, s14, s2
	s_waitcnt lgkmcnt(0)
	v_cvt_pk_bf16_f32 v3, v6, v7
	v_or_b32_e32 v6, s0, v39
	s_addc_u32 s3, s15, s3
	v_lshlrev_b32_e32 v96, 1, v36
	v_ashrrev_i32_e32 v7, 31, v6
	v_lshl_add_u64 v[4:5], s[2:3], 0, v[96:97]
	v_lshlrev_b64 v[6:7], 11, v[6:7]
	v_lshl_add_u64 v[6:7], v[4:5], 0, v[6:7]
	global_store_dwordx4 v[6:7], v[0:3], off nt
	ds_read2_b32 v[0:1], v43 offset0:16 offset1:81
	s_waitcnt lgkmcnt(0)
	v_cvt_pk_bf16_f32 v0, v0, v1
	ds_read2_b32 v[2:3], v43 offset0:146 offset1:211
	s_waitcnt lgkmcnt(0)
	v_cvt_pk_bf16_f32 v1, v2, v3
	ds_read2_b32 v[2:3], v8 offset0:20 offset1:85
	s_waitcnt lgkmcnt(0)
	v_cvt_pk_bf16_f32 v2, v2, v3
	ds_read2_b32 v[6:7], v8 offset0:150 offset1:215
	s_waitcnt lgkmcnt(0)
	v_cvt_pk_bf16_f32 v3, v6, v7
	v_or_b32_e32 v6, s0, v44
	v_ashrrev_i32_e32 v7, 31, v6
	v_lshlrev_b64 v[6:7], 11, v[6:7]
	v_lshl_add_u64 v[6:7], v[4:5], 0, v[6:7]
	global_store_dwordx4 v[6:7], v[0:3], off nt
	ds_read2_b32 v[0:1], v43 offset0:32 offset1:97
	s_waitcnt lgkmcnt(0)
	v_cvt_pk_bf16_f32 v0, v0, v1
	ds_read2_b32 v[2:3], v43 offset0:162 offset1:227
	s_waitcnt lgkmcnt(0)
	v_cvt_pk_bf16_f32 v1, v2, v3
	ds_read2_b32 v[2:3], v8 offset0:36 offset1:101
	s_waitcnt lgkmcnt(0)
	v_cvt_pk_bf16_f32 v2, v2, v3
	ds_read2_b32 v[6:7], v8 offset0:166 offset1:231
	s_waitcnt lgkmcnt(0)
	v_cvt_pk_bf16_f32 v3, v6, v7
	v_or_b32_e32 v6, s0, v45
	v_ashrrev_i32_e32 v7, 31, v6
	v_lshlrev_b64 v[6:7], 11, v[6:7]
	v_lshl_add_u64 v[6:7], v[4:5], 0, v[6:7]
	global_store_dwordx4 v[6:7], v[0:3], off nt
	ds_read2_b32 v[0:1], v43 offset0:48 offset1:113
	s_waitcnt lgkmcnt(0)
	v_cvt_pk_bf16_f32 v0, v0, v1
	ds_read2_b32 v[2:3], v43 offset0:178 offset1:243
	s_waitcnt lgkmcnt(0)
	v_cvt_pk_bf16_f32 v1, v2, v3
	ds_read2_b32 v[2:3], v8 offset0:52 offset1:117
	s_waitcnt lgkmcnt(0)
	v_cvt_pk_bf16_f32 v2, v2, v3
	ds_read2_b32 v[6:7], v8 offset0:182 offset1:247
	s_waitcnt lgkmcnt(0)
	v_cvt_pk_bf16_f32 v3, v6, v7
	v_or_b32_e32 v6, s0, v46
	v_ashrrev_i32_e32 v7, 31, v6
	v_lshlrev_b64 v[6:7], 11, v[6:7]
	v_lshl_add_u64 v[4:5], v[4:5], 0, v[6:7]
	global_store_dwordx4 v[4:5], v[0:3], off nt
	s_waitcnt lgkmcnt(0)

; #define LAS __attribute__((address_space(3)))
; __device__ __forceinline__ void transpose_item(const float* W, int N, const float* ks, bf16_t* WT, int ldo, int orow0, int k0, int n0, LAS float* scr, int lane) {
;     f32x4 v[8];
; #pragma unroll
;     for (int i = 0; i < 8; ++i) v[i] = *(const f32x4*)(W + (size_t)(k0 + i * 4 + (lane >> 4)) * N + n0 + 4 * (lane & 15));
; #pragma unroll
;     for (int i = 0; i < 8; ++i) { const int kk = i * 4 + (lane >> 4); const float sc = ks ? ks[k0 + kk] : 1.0f; LAS float* d = scr + kk * 65 + 4 * (lane & 15);
;         d[0] = v[i][0] * sc; d[1] = v[i][1] * sc; d[2] = v[i][2] * sc; d[3] = v[i][3] * sc; }
;     asm volatile("s_waitcnt lgkmcnt(0)" ::: "memory");
;     const int kc = lane & 3;
; #pragma unroll
;     for (int j = 0; j < 4; ++j) { const int n = (lane >> 2) + 16 * j; const LAS float* s = scr + (8 * kc) * 65 + n;
;         u32x4 o; o.x = cvt_pk_bf16(s[0 * 65], s[1 * 65]); o.y = cvt_pk_bf16(s[2 * 65], s[3 * 65]); o.z = cvt_pk_bf16(s[4 * 65], s[5 * 65]); o.w = cvt_pk_bf16(s[6 * 65], s[7 * 65]);
;         *(u32x4*)(WT + (size_t)(orow0 + n) * ldo + k0 + 8 * kc) = o; }
;     asm volatile("s_waitcnt lgkmcnt(0)" ::: "memory");
; }
; __device__ __forceinline__ void convert_weights(const Params& p, LAS unsigned char* lds, int first, int last, int worker, int nworkers) {
;     ...
;     for (int it = first + worker; it < last; it += nworkers) {
;         const int l = it / WI_L; int r = it % WI_L;
;         unsigned char* wb = p.ws + WS_W + (size_t)l * W_LAYER;
;         if (r < WI_IN) { const int kb = r / 52, nb = r % 52; transpose_item(p.w_in + (size_t)l * DM * INW, INW, p.norm_mix + l * DM, (bf16_t*)(wb + WO_IN), DM, nb * 64, kb * 32, nb * 64, scr, lane); continue; } r -= WI_IN;
;         if (r < WI_BA) { const int kb = r / 16, nb = r % 16; transpose_item(p.w_br_attn + (size_t)l * 512 * DM, DM, nullptr, (bf16_t*)(wb + WO_MIX), 512, nb * 64, kb * 32, nb * 64, scr, lane); continue; } r -= WI_BA;
;         if (r < WI_OUT) { const int kb = r / 16, nb = r % 16; transpose_item(p.w_out + (size_t)l * DM * DM, DM, nullptr, (bf16_t*)(wb + WO_OUT), DM, nb * 64, kb * 32, nb * 64, scr, lane); continue; } r -= WI_OUT;
;         if (r < WI_UP) { const int kb = r / 88, nb = r % 88; const int n0 = nb * 64; const int nn = n0 < FF ? n0 : n0 - FF; const int orow = (nn >> 7) * 256 + (n0 < FF ? 0 : 128) + (nn & 127);
.LBB0_196:
	s_mul_hi_i32 s0, s7, 0x4ec4ec4f
	s_lshr_b32 s1, s0, 31
	s_ashr_i32 s0, s0, 11
	s_add_i32 s2, s0, s1
	s_mul_i32 s0, s2, 0xffffe600
	s_add_i32 s16, s7, s0
	s_ashr_i32 s3, s2, 31
	s_mul_i32 s1, s2, 0x1b00000
	s_mul_hi_i32 s0, s2, 0x1b00000
	s_add_u32 s14, s80, s1
	s_addc_u32 s15, s82, s0
	s_cmpk_gt_i32 s16, 0x67f
	s_mov_b64 s[0:1], -1
	s_cbranch_scc0 .LBB0_218
	s_cmpk_gt_u32 s16, 0x77f
	s_cbranch_scc0 .LBB0_215
	s_cmpk_gt_u32 s16, 0x97f
	s_cbranch_scc0 .LBB0_212
	s_cmpk_gt_u32 s16, 0x147f
	s_cbranch_scc0 .LBB0_201
	v_readlane_b32 s40, v248, 54
	s_mul_i32 s1, s2, 0xb00000
	v_readlane_b32 s50, v247, 0
	s_mul_hi_i32 s0, s2, 0xb00000
	v_readlane_b32 s51, v247, 1
	s_add_u32 s1, s50, s1
	s_mul_i32 s8, s2, 0xffffcc00
	s_addc_u32 s9, s51, s0
	s_add_i32 s8, s10, s8
	s_and_b32 s0, s12, 0x3c0
	s_and_b32 s8, s8, 0x7fffffe0
	s_add_i32 s96, s8, 0xffffd700
	s_lshl_b32 s8, s0, 2
	s_add_u32 s8, s1, s8
	v_or_b32_e32 v28, s96, v32
	s_addc_u32 s9, s9, 0
	v_lshlrev_b32_e32 v96, 2, v34
	v_mov_b32_e32 v29, v97
	v_lshl_add_u64 v[30:31], s[8:9], 0, v[96:97]
	v_lshlrev_b64 v[0:1], 12, v[28:29]
	v_or_b32_e32 v96, 4, v28
	v_lshl_add_u64 v[0:1], v[30:31], 0, v[0:1]
	v_lshlrev_b64 v[4:5], 12, v[96:97]
	global_load_dwordx4 v[0:3], v[0:1], off
	v_lshl_add_u64 v[4:5], v[30:31], 0, v[4:5]
	v_or_b32_e32 v96, 8, v28
	global_load_dwordx4 v[4:7], v[4:5], off
	v_lshlrev_b64 v[8:9], 12, v[96:97]
	v_lshl_add_u64 v[8:9], v[30:31], 0, v[8:9]
	v_or_b32_e32 v96, 12, v28
	global_load_dwordx4 v[8:11], v[8:9], off
	v_lshlrev_b64 v[12:13], 12, v[96:97]
	v_lshl_add_u64 v[12:13], v[30:31], 0, v[12:13]
	v_or_b32_e32 v96, 16, v28
	global_load_dwordx4 v[12:15], v[12:13], off
	v_lshlrev_b64 v[16:17], 12, v[96:97]
	v_lshl_add_u64 v[16:17], v[30:31], 0, v[16:17]
	v_or_b32_e32 v96, 20, v28
	global_load_dwordx4 v[16:19], v[16:17], off
	v_lshlrev_b64 v[20:21], 12, v[96:97]
	v_lshl_add_u64 v[20:21], v[30:31], 0, v[20:21]
	v_or_b32_e32 v96, 24, v28
	global_load_dwordx4 v[20:23], v[20:21], off
	v_lshlrev_b64 v[24:25], 12, v[96:97]
	v_lshl_add_u64 v[24:25], v[30:31], 0, v[24:25]
	v_or_b32_e32 v96, 28, v28
	global_load_dwordx4 v[24:27], v[24:25], off
	v_lshlrev_b64 v[28:29], 12, v[96:97]
	v_lshl_add_u64 v[28:29], v[30:31], 0, v[28:29]
	global_load_dwordx4 v[28:31], v[28:29], off
	v_add_u32_e32 v38, v35, v37
	s_lshl_b64 s[8:9], s[96:97], 1
	s_add_u32 s8, s14, s8
	s_addc_u32 s9, s15, s9
	v_lshlrev_b32_e32 v96, 1, v36
	v_readlane_b32 s41, v248, 55
	v_readlane_b32 s42, v248, 56
	v_readlane_b32 s43, v248, 57
	v_readlane_b32 s44, v248, 58
	v_readlane_b32 s45, v248, 59
	v_readlane_b32 s46, v248, 60
	v_readlane_b32 s47, v248, 61
	v_readlane_b32 s48, v248, 62
	v_readlane_b32 s49, v248, 63
	v_readlane_b32 s52, v247, 2
	v_readlane_b32 s53, v247, 3
	v_readlane_b32 s54, v247, 4
	v_readlane_b32 s55, v247, 5
	s_waitcnt vmcnt(0)
	ds_write2_b32 v38, v0, v1 offset1:1
	ds_write2_b32 v38, v2, v3 offset0:2 offset1:3
	v_add_u32_e32 v0, 0x410, v38
	ds_write2_b32 v0, v4, v5 offset1:1
	v_add_u32_e32 v0, 0x418, v38
	ds_write2_b32 v0, v6, v7 offset1:1
	v_add_u32_e32 v0, 0x820, v38
	ds_write2_b32 v0, v8, v9 offset1:1
	v_add_u32_e32 v0, 0x828, v38
	ds_write2_b32 v0, v10, v11 offset1:1
	v_add_u32_e32 v0, 0xc30, v38
	ds_write2_b32 v0, v12, v13 offset1:1
	v_add_u32_e32 v0, 0xc38, v38
	ds_write2_b32 v0, v14, v15 offset1:1
	v_add_u32_e32 v0, 0x1040, v38
	ds_write2_b32 v0, v16, v17 offset1:1
	v_add_u32_e32 v0, 0x1048, v38
	ds_write2_b32 v0, v18, v19 offset1:1
	v_add_u32_e32 v0, 0x1450, v38
	ds_write2_b32 v0, v20, v21 offset1:1
	v_add_u32_e32 v0, 0x1458, v38
	ds_write2_b32 v0, v22, v23 offset1:1
	v_add_u32_e32 v0, 0x1860, v38
	ds_write2_b32 v0, v24, v25 offset1:1
	v_add_u32_e32 v0, 0x1868, v38
	ds_write2_b32 v0, v26, v27 offset1:1
	v_add_u32_e32 v0, 0x1c70, v38
	ds_write2_b32 v0, v28, v29 offset1:1
	v_add_u32_e32 v0, 0x1c78, v38
	ds_write2_b32 v0, v30, v31 offset1:1
	s_waitcnt lgkmcnt(0)
	v_lshl_add_u64 v[0:1], s[8:9], 0, v[96:97]
	s_mov_b64 s[8:9], 0x1580000
	v_lshl_add_u64 v[4:5], v[0:1], 0, s[8:9]
	ds_read2_b32 v[0:1], v43 offset1:65
	s_waitcnt lgkmcnt(0)
	v_cvt_pk_bf16_f32 v0, v0, v1
	ds_read2_b32 v[2:3], v43 offset0:130 offset1:195
	v_add_u32_e32 v8, 0x400, v43
	s_waitcnt lgkmcnt(0)
	v_cvt_pk_bf16_f32 v1, v2, v3
	ds_read2_b32 v[2:3], v8 offset0:4 offset1:69
	s_waitcnt lgkmcnt(0)
	v_cvt_pk_bf16_f32 v2, v2, v3
	ds_read2_b32 v[6:7], v8 offset0:134 offset1:199
	s_waitcnt lgkmcnt(0)
	v_cvt_pk_bf16_f32 v3, v6, v7
	v_or_b32_e32 v6, s0, v39
	v_mul_u32_u24_e32 v6, 0xb00, v6
	v_lshlrev_b32_e32 v96, 1, v6
	v_lshl_add_u64 v[6:7], v[4:5], 0, v[96:97]
	global_store_dwordx4 v[6:7], v[0:3], off nt
	ds_read2_b32 v[0:1], v43 offset0:16 offset1:81
	s_waitcnt lgkmcnt(0)
	v_cvt_pk_bf16_f32 v0, v0, v1
	ds_read2_b32 v[2:3], v43 offset0:146 offset1:211
	s_waitcnt lgkmcnt(0)
	v_cvt_pk_bf16_f32 v1, v2, v3
	ds_read2_b32 v[2:3], v8 offset0:20 offset1:85
	s_waitcnt lgkmcnt(0)
	v_cvt_pk_bf16_f32 v2, v2, v3
	ds_read2_b32 v[6:7], v8 offset0:150 offset1:215
	s_waitcnt lgkmcnt(0)
	v_cvt_pk_bf16_f32 v3, v6, v7
	v_or_b32_e32 v6, s0, v44
	v_mul_u32_u24_e32 v6, 0xb00, v6
	v_lshlrev_b32_e32 v96, 1, v6
	v_lshl_add_u64 v[6:7], v[4:5], 0, v[96:97]
	global_store_dwordx4 v[6:7], v[0:3], off nt
	ds_read2_b32 v[0:1], v43 offset0:32 offset1:97
	s_waitcnt lgkmcnt(0)
	v_cvt_pk_bf16_f32 v0, v0, v1
	ds_read2_b32 v[2:3], v43 offset0:162 offset1:227
	s_waitcnt lgkmcnt(0)
	v_cvt_pk_bf16_f32 v1, v2, v3
	ds_read2_b32 v[2:3], v8 offset0:36 offset1:101
	s_waitcnt lgkmcnt(0)
	v_cvt_pk_bf16_f32 v2, v2, v3
	ds_read2_b32 v[6:7], v8 offset0:166 offset1:231
	s_waitcnt lgkmcnt(0)
	v_cvt_pk_bf16_f32 v3, v6, v7
	v_or_b32_e32 v6, s0, v45
	v_mul_u32_u24_e32 v6, 0xb00, v6
	v_lshlrev_b32_e32 v96, 1, v6
	v_lshl_add_u64 v[6:7], v[4:5], 0, v[96:97]
	global_store_dwordx4 v[6:7], v[0:3], off nt
	ds_read2_b32 v[0:1], v43 offset0:48 offset1:113
	s_waitcnt lgkmcnt(0)
	v_cvt_pk_bf16_f32 v0, v0, v1
	ds_read2_b32 v[2:3], v43 offset0:178 offset1:243
	s_waitcnt lgkmcnt(0)
	v_cvt_pk_bf16_f32 v1, v2, v3
	ds_read2_b32 v[2:3], v8 offset0:52 offset1:117
	s_waitcnt lgkmcnt(0)
	v_cvt_pk_bf16_f32 v2, v2, v3
	ds_read2_b32 v[6:7], v8 offset0:182 offset1:247
	s_waitcnt lgkmcnt(0)
	v_cvt_pk_bf16_f32 v3, v6, v7
	v_or_b32_e32 v6, s0, v46
	v_mul_u32_u24_e32 v6, 0xb00, v6
	v_lshlrev_b32_e32 v96, 1, v6
	v_lshl_add_u64 v[4:5], v[4:5], 0, v[96:97]
	global_store_dwordx4 v[4:5], v[0:3], off nt
	s_waitcnt lgkmcnt(0)
	s_mov_b64 s[0:1], 0

; #define LAS __attribute__((address_space(3)))
; __device__ __forceinline__ unsigned cvt_pk_bf16(float lo, float hi) { unsigned r; asm volatile("v_cvt_pk_bf16_f32 %0, %1, %2" : "=v"(r) : "v"(lo), "v"(hi)); return r; }
; __device__ __forceinline__ void transpose_item(const float* W, int N, const float* ks, bf16_t* WT, int ldo, int orow0, int k0, int n0, LAS float* scr, int lane) {
;     f32x4 v[8];
; #pragma unroll
;     for (int i = 0; i < 8; ++i) v[i] = *(const f32x4*)(W + (size_t)(k0 + i * 4 + (lane >> 4)) * N + n0 + 4 * (lane & 15));
; #pragma unroll
;     for (int i = 0; i < 8; ++i) { const int kk = i * 4 + (lane >> 4); const float sc = ks ? ks[k0 + kk] : 1.0f; LAS float* d = scr + kk * 65 + 4 * (lane & 15);
;         d[0] = v[i][0] * sc; d[1] = v[i][1] * sc; d[2] = v[i][2] * sc; d[3] = v[i][3] * sc; }
;     asm volatile("s_waitcnt lgkmcnt(0)" ::: "memory");
;     const int kc = lane & 3;
; #pragma unroll
;     for (int j = 0; j < 4; ++j) { const int n = (lane >> 2) + 16 * j; const LAS float* s = scr + (8 * kc) * 65 + n;
;         u32x4 o; o.x = cvt_pk_bf16(s[0 * 65], s[1 * 65]); o.y = cvt_pk_bf16(s[2 * 65], s[3 * 65]); o.z = cvt_pk_bf16(s[4 * 65], s[5 * 65]); o.w = cvt_pk_bf16(s[6 * 65], s[7 * 65]);
;         *(u32x4*)(WT + (size_t)(orow0 + n) * ldo + k0 + 8 * kc) = o; }
;     asm volatile("s_waitcnt lgkmcnt(0)" ::: "memory");
; }
; __device__ __forceinline__ void convert_weights(const Params& p, LAS unsigned char* lds, int first, int last, int worker, int nworkers) {
;     ...
;         if (r < WI_UP) { const int kb = r / 88, nb = r % 88; const int n0 = nb * 64; const int nn = n0 < FF ? n0 : n0 - FF; const int orow = (nn >> 7) * 256 + (n0 < FF ? 0 : 128) + (nn & 127);
;             transpose_item(p.w_up + (size_t)l * DM * FF2, FF2, p.norm_ffn + l * DM, (bf16_t*)(wb + WO_UP), DM, orow, kb * 32, n0, scr, lane); continue; } r -= WI_UP;
.LBB0_210:
	s_lshl_b32 s0, s18, 6
	s_and_b32 s0, 0xffff, s0
	s_and_b32 s1, 0xffff, s18
	s_add_i32 s8, s0, 0xfffff500
	s_cmp_lt_u32 s1, 44
	s_cselect_b32 s0, s0, s8
	s_cselect_b32 s1, 0, 0x80
	s_lshl_b32 s8, s0, 1
	s_and_b32 s0, s0, 64
	v_add_u32_e32 v8, 0x1450, v24
	s_and_b32 s8, s8, 0xffffff00
	s_or_b32 s0, s0, s1
	ds_write2_b32 v8, v4, v5 offset1:1
	v_add_u32_e32 v4, 0x1458, v24
	s_or_b32 s0, s0, s8
	ds_write2_b32 v4, v6, v7 offset1:1
	v_pk_mul_f32 v[0:1], v[0:1], v[16:17] op_sel_hi:[1,0]
	v_add_u32_e32 v4, 0x1860, v24
	s_lshl_b32 s1, s17, 1
	ds_write2_b32 v4, v0, v1 offset1:1
	v_pk_mul_f32 v[0:1], v[2:3], v[16:17] op_sel_hi:[1,0]
	v_add_u32_e32 v2, 0x1868, v24
	s_add_u32 s8, s14, s1
	ds_write2_b32 v2, v0, v1 offset1:1
	s_addc_u32 s9, s15, 0
	v_lshlrev_b32_e32 v96, 1, v36
	s_waitcnt lgkmcnt(0)
	v_lshl_add_u64 v[0:1], s[8:9], 0, v[96:97]
	s_mov_b64 s[8:9], 0xa80000
	v_lshl_add_u64 v[4:5], v[0:1], 0, s[8:9]
	ds_read2_b32 v[0:1], v43 offset1:65
	s_waitcnt lgkmcnt(0)
	v_cvt_pk_bf16_f32 v0, v0, v1
	ds_read2_b32 v[2:3], v43 offset0:130 offset1:195
	v_add_u32_e32 v8, 0x400, v43
	s_waitcnt lgkmcnt(0)
	v_cvt_pk_bf16_f32 v1, v2, v3
	ds_read2_b32 v[2:3], v8 offset0:4 offset1:69
	s_waitcnt lgkmcnt(0)
	v_cvt_pk_bf16_f32 v2, v2, v3
	ds_read2_b32 v[6:7], v8 offset0:134 offset1:199
	s_waitcnt lgkmcnt(0)
	v_cvt_pk_bf16_f32 v3, v6, v7
	v_or_b32_e32 v6, s0, v39
	v_ashrrev_i32_e32 v7, 31, v6
	v_lshlrev_b64 v[6:7], 11, v[6:7]
	v_lshl_add_u64 v[6:7], v[4:5], 0, v[6:7]
	global_store_dwordx4 v[6:7], v[0:3], off nt
	ds_read2_b32 v[0:1], v43 offset0:16 offset1:81
	s_waitcnt lgkmcnt(0)
	v_cvt_pk_bf16_f32 v0, v0, v1
	ds_read2_b32 v[2:3], v43 offset0:146 offset1:211
	s_waitcnt lgkmcnt(0)
	v_cvt_pk_bf16_f32 v1, v2, v3
	ds_read2_b32 v[2:3], v8 offset0:20 offset1:85
	s_waitcnt lgkmcnt(0)
	v_cvt_pk_bf16_f32 v2, v2, v3
	ds_read2_b32 v[6:7], v8 offset0:150 offset1:215
	s_waitcnt lgkmcnt(0)
	v_cvt_pk_bf16_f32 v3, v6, v7
	v_or_b32_e32 v6, s0, v44
	v_ashrrev_i32_e32 v7, 31, v6
	v_lshlrev_b64 v[6:7], 11, v[6:7]
	v_lshl_add_u64 v[6:7], v[4:5], 0, v[6:7]
	global_store_dwordx4 v[6:7], v[0:3], off nt
	ds_read2_b32 v[0:1], v43 offset0:32 offset1:97
	s_waitcnt lgkmcnt(0)
	v_cvt_pk_bf16_f32 v0, v0, v1
	ds_read2_b32 v[2:3], v43 offset0:162 offset1:227
	s_waitcnt lgkmcnt(0)
	v_cvt_pk_bf16_f32 v1, v2, v3
	ds_read2_b32 v[2:3], v8 offset0:36 offset1:101
	s_waitcnt lgkmcnt(0)
	v_cvt_pk_bf16_f32 v2, v2, v3
	ds_read2_b32 v[6:7], v8 offset0:166 offset1:231
	s_waitcnt lgkmcnt(0)
	v_cvt_pk_bf16_f32 v3, v6, v7
	v_or_b32_e32 v6, s0, v45
	v_ashrrev_i32_e32 v7, 31, v6
	v_lshlrev_b64 v[6:7], 11, v[6:7]
	v_lshl_add_u64 v[6:7], v[4:5], 0, v[6:7]
	global_store_dwordx4 v[6:7], v[0:3], off nt
	ds_read2_b32 v[0:1], v43 offset0:48 offset1:113
	s_waitcnt lgkmcnt(0)
	v_cvt_pk_bf16_f32 v0, v0, v1
	ds_read2_b32 v[2:3], v43 offset0:178 offset1:243
	s_waitcnt lgkmcnt(0)
	v_cvt_pk_bf16_f32 v1, v2, v3
	ds_read2_b32 v[2:3], v8 offset0:52 offset1:117
	s_waitcnt lgkmcnt(0)
	v_cvt_pk_bf16_f32 v2, v2, v3
	ds_read2_b32 v[6:7], v8 offset0:182 offset1:247
	s_waitcnt lgkmcnt(0)
	v_cvt_pk_bf16_f32 v3, v6, v7
	v_or_b32_e32 v6, s0, v46
	v_ashrrev_i32_e32 v7, 31, v6
	v_lshlrev_b64 v[6:7], 11, v[6:7]
	v_lshl_add_u64 v[4:5], v[4:5], 0, v[6:7]
	global_store_dwordx4 v[4:5], v[0:3], off nt
	s_waitcnt lgkmcnt(0)

; #define LAS __attribute__((address_space(3)))
; __device__ __forceinline__ unsigned cvt_pk_bf16(float lo, float hi) { unsigned r; asm volatile("v_cvt_pk_bf16_f32 %0, %1, %2" : "=v"(r) : "v"(lo), "v"(hi)); return r; }
; __device__ __forceinline__ void transpose_item(const float* W, int N, const float* ks, bf16_t* WT, int ldo, int orow0, int k0, int n0, LAS float* scr, int lane) {
;     f32x4 v[8];
; #pragma unroll
;     for (int i = 0; i < 8; ++i) v[i] = *(const f32x4*)(W + (size_t)(k0 + i * 4 + (lane >> 4)) * N + n0 + 4 * (lane & 15));
; #pragma unroll
;     for (int i = 0; i < 8; ++i) { const int kk = i * 4 + (lane >> 4); const float sc = ks ? ks[k0 + kk] : 1.0f; LAS float* d = scr + kk * 65 + 4 * (lane & 15);
;         d[0] = v[i][0] * sc; d[1] = v[i][1] * sc; d[2] = v[i][2] * sc; d[3] = v[i][3] * sc; }
;     asm volatile("s_waitcnt lgkmcnt(0)" ::: "memory");
;     const int kc = lane & 3;
; #pragma unroll
;     for (int j = 0; j < 4; ++j) { const int n = (lane >> 2) + 16 * j; const LAS float* s = scr + (8 * kc) * 65 + n;
;         u32x4 o; o.x = cvt_pk_bf16(s[0 * 65], s[1 * 65]); o.y = cvt_pk_bf16(s[2 * 65], s[3 * 65]); o.z = cvt_pk_bf16(s[4 * 65], s[5 * 65]); o.w = cvt_pk_bf16(s[6 * 65], s[7 * 65]);
;         *(u32x4*)(WT + (size_t)(orow0 + n) * ldo + k0 + 8 * kc) = o; }
;     asm volatile("s_waitcnt lgkmcnt(0)" ::: "memory");
; }
; __device__ __forceinline__ void convert_weights(const Params& p, LAS unsigned char* lds, int first, int last, int worker, int nworkers) {
;     ...
;         if (r < WI_OUT) { const int kb = r / 16, nb = r % 16; transpose_item(p.w_out + (size_t)l * DM * DM, DM, nullptr, (bf16_t*)(wb + WO_OUT), DM, nb * 64, kb * 32, nb * 64, scr, lane); continue; } r -= WI_OUT;
.LBB0_212:
	s_andn2_b64 vcc, exec, s[0:1]
	s_cbranch_vccnz .LBB0_214
	s_lshl_b64 s[0:1], s[2:3], 22
	v_readlane_b32 s40, v248, 54
	v_readlane_b32 s41, v248, 55
	s_add_u32 s8, s40, s0
	s_mul_i32 s9, s2, 0xffffcc00
	s_addc_u32 s1, s41, s1
	s_add_i32 s9, s10, s9
	s_and_b32 s0, s12, 0x3c0
	s_and_b32 s9, s9, 0x1fe0
	s_add_i32 s96, s9, 0xfffff100
	s_lshl_b32 s9, s0, 2
	s_add_u32 s8, s8, s9
	v_or_b32_e32 v28, s96, v32
	s_addc_u32 s9, s1, 0
	v_lshlrev_b32_e32 v96, 2, v34
	v_mov_b32_e32 v29, v97
	v_lshl_add_u64 v[30:31], s[8:9], 0, v[96:97]
	v_lshlrev_b64 v[0:1], 12, v[28:29]
	v_or_b32_e32 v96, 4, v28
	v_lshl_add_u64 v[0:1], v[30:31], 0, v[0:1]
	v_lshlrev_b64 v[4:5], 12, v[96:97]
	global_load_dwordx4 v[0:3], v[0:1], off
	v_lshl_add_u64 v[4:5], v[30:31], 0, v[4:5]
	v_or_b32_e32 v96, 8, v28
	global_load_dwordx4 v[4:7], v[4:5], off
	v_lshlrev_b64 v[8:9], 12, v[96:97]
	v_lshl_add_u64 v[8:9], v[30:31], 0, v[8:9]
	v_or_b32_e32 v96, 12, v28
	global_load_dwordx4 v[8:11], v[8:9], off
	v_lshlrev_b64 v[12:13], 12, v[96:97]
	v_lshl_add_u64 v[12:13], v[30:31], 0, v[12:13]
	v_or_b32_e32 v96, 16, v28
	global_load_dwordx4 v[12:15], v[12:13], off
	v_lshlrev_b64 v[16:17], 12, v[96:97]
	v_lshl_add_u64 v[16:17], v[30:31], 0, v[16:17]
	v_or_b32_e32 v96, 20, v28
	global_load_dwordx4 v[16:19], v[16:17], off
	v_lshlrev_b64 v[20:21], 12, v[96:97]
	v_lshl_add_u64 v[20:21], v[30:31], 0, v[20:21]
	v_or_b32_e32 v96, 24, v28
	global_load_dwordx4 v[20:23], v[20:21], off
	v_lshlrev_b64 v[24:25], 12, v[96:97]
	v_lshl_add_u64 v[24:25], v[30:31], 0, v[24:25]
	v_or_b32_e32 v96, 28, v28
	global_load_dwordx4 v[24:27], v[24:25], off
	v_lshlrev_b64 v[28:29], 12, v[96:97]
	v_lshl_add_u64 v[28:29], v[30:31], 0, v[28:29]
	global_load_dwordx4 v[28:31], v[28:29], off
	v_add_u32_e32 v38, v35, v37
	s_lshl_b64 s[8:9], s[96:97], 1
	s_add_u32 s8, s14, s8
	s_addc_u32 s9, s15, s9
	v_lshlrev_b32_e32 v96, 1, v36
	v_readlane_b32 s42, v248, 56
	v_readlane_b32 s43, v248, 57
	v_readlane_b32 s44, v248, 58
	v_readlane_b32 s45, v248, 59
	v_readlane_b32 s46, v248, 60
	v_readlane_b32 s47, v248, 61
	v_readlane_b32 s48, v248, 62
	v_readlane_b32 s49, v248, 63
	v_readlane_b32 s50, v247, 0
	v_readlane_b32 s51, v247, 1
	v_readlane_b32 s52, v247, 2
	v_readlane_b32 s53, v247, 3
	v_readlane_b32 s54, v247, 4
	v_readlane_b32 s55, v247, 5
	s_waitcnt vmcnt(0)
	ds_write2_b32 v38, v0, v1 offset1:1
	ds_write2_b32 v38, v2, v3 offset0:2 offset1:3
	v_add_u32_e32 v0, 0x410, v38
	ds_write2_b32 v0, v4, v5 offset1:1
	v_add_u32_e32 v0, 0x418, v38
	ds_write2_b32 v0, v6, v7 offset1:1
	v_add_u32_e32 v0, 0x820, v38
	ds_write2_b32 v0, v8, v9 offset1:1
	v_add_u32_e32 v0, 0x828, v38
	ds_write2_b32 v0, v10, v11 offset1:1
	v_add_u32_e32 v0, 0xc30, v38
	ds_write2_b32 v0, v12, v13 offset1:1
	v_add_u32_e32 v0, 0xc38, v38
	ds_write2_b32 v0, v14, v15 offset1:1
	v_add_u32_e32 v0, 0x1040, v38
	ds_write2_b32 v0, v16, v17 offset1:1
	v_add_u32_e32 v0, 0x1048, v38
	ds_write2_b32 v0, v18, v19 offset1:1
	v_add_u32_e32 v0, 0x1450, v38
	ds_write2_b32 v0, v20, v21 offset1:1
	v_add_u32_e32 v0, 0x1458, v38
	ds_write2_b32 v0, v22, v23 offset1:1
	v_add_u32_e32 v0, 0x1860, v38
	ds_write2_b32 v0, v24, v25 offset1:1
	v_add_u32_e32 v0, 0x1868, v38
	ds_write2_b32 v0, v26, v27 offset1:1
	v_add_u32_e32 v0, 0x1c70, v38
	ds_write2_b32 v0, v28, v29 offset1:1
	v_add_u32_e32 v0, 0x1c78, v38
	ds_write2_b32 v0, v30, v31 offset1:1
	s_waitcnt lgkmcnt(0)
	v_lshl_add_u64 v[0:1], s[8:9], 0, v[96:97]
	s_mov_b64 s[8:9], 0x880000
	v_lshl_add_u64 v[4:5], v[0:1], 0, s[8:9]
	ds_read2_b32 v[0:1], v43 offset1:65
	s_waitcnt lgkmcnt(0)
	v_cvt_pk_bf16_f32 v0, v0, v1
	ds_read2_b32 v[2:3], v43 offset0:130 offset1:195
	v_add_u32_e32 v8, 0x400, v43
	s_waitcnt lgkmcnt(0)
	v_cvt_pk_bf16_f32 v1, v2, v3
	ds_read2_b32 v[2:3], v8 offset0:4 offset1:69
	s_waitcnt lgkmcnt(0)
	v_cvt_pk_bf16_f32 v2, v2, v3
	ds_read2_b32 v[6:7], v8 offset0:134 offset1:199
	s_waitcnt lgkmcnt(0)
	v_cvt_pk_bf16_f32 v3, v6, v7
	v_or_b32_e32 v6, s0, v39
	v_lshlrev_b32_e32 v96, 11, v6
	v_lshl_add_u64 v[6:7], v[4:5], 0, v[96:97]
	global_store_dwordx4 v[6:7], v[0:3], off nt
	ds_read2_b32 v[0:1], v43 offset0:16 offset1:81
	s_waitcnt lgkmcnt(0)
	v_cvt_pk_bf16_f32 v0, v0, v1
	ds_read2_b32 v[2:3], v43 offset0:146 offset1:211
	s_waitcnt lgkmcnt(0)
	v_cvt_pk_bf16_f32 v1, v2, v3
	ds_read2_b32 v[2:3], v8 offset0:20 offset1:85
	s_waitcnt lgkmcnt(0)
	v_cvt_pk_bf16_f32 v2, v2, v3
	ds_read2_b32 v[6:7], v8 offset0:150 offset1:215
	s_waitcnt lgkmcnt(0)
	v_cvt_pk_bf16_f32 v3, v6, v7
	v_or_b32_e32 v6, s0, v44
	v_lshlrev_b32_e32 v96, 11, v6
	v_lshl_add_u64 v[6:7], v[4:5], 0, v[96:97]
	global_store_dwordx4 v[6:7], v[0:3], off nt
	ds_read2_b32 v[0:1], v43 offset0:32 offset1:97
	s_waitcnt lgkmcnt(0)
	v_cvt_pk_bf16_f32 v0, v0, v1
	ds_read2_b32 v[2:3], v43 offset0:162 offset1:227
	s_waitcnt lgkmcnt(0)
	v_cvt_pk_bf16_f32 v1, v2, v3
	ds_read2_b32 v[2:3], v8 offset0:36 offset1:101
	s_waitcnt lgkmcnt(0)
	v_cvt_pk_bf16_f32 v2, v2, v3
	ds_read2_b32 v[6:7], v8 offset0:166 offset1:231
	s_waitcnt lgkmcnt(0)
	v_cvt_pk_bf16_f32 v3, v6, v7
	v_or_b32_e32 v6, s0, v45
	v_lshlrev_b32_e32 v96, 11, v6
	v_lshl_add_u64 v[6:7], v[4:5], 0, v[96:97]
	global_store_dwordx4 v[6:7], v[0:3], off nt
	ds_read2_b32 v[0:1], v43 offset0:48 offset1:113
	s_waitcnt lgkmcnt(0)
	v_cvt_pk_bf16_f32 v0, v0, v1
	ds_read2_b32 v[2:3], v43 offset0:178 offset1:243
	s_waitcnt lgkmcnt(0)
	v_cvt_pk_bf16_f32 v1, v2, v3
	ds_read2_b32 v[2:3], v8 offset0:52 offset1:117
	s_waitcnt lgkmcnt(0)
	v_cvt_pk_bf16_f32 v2, v2, v3
	ds_read2_b32 v[6:7], v8 offset0:182 offset1:247
	s_waitcnt lgkmcnt(0)
	v_cvt_pk_bf16_f32 v3, v6, v7
	v_or_b32_e32 v6, s0, v46
	v_lshlrev_b32_e32 v96, 11, v6
	v_lshl_add_u64 v[4:5], v[4:5], 0, v[96:97]
	global_store_dwordx4 v[4:5], v[0:3], off nt
	s_waitcnt lgkmcnt(0)

; #define LAS __attribute__((address_space(3)))
; __device__ __forceinline__ unsigned cvt_pk_bf16(float lo, float hi) { unsigned r; asm volatile("v_cvt_pk_bf16_f32 %0, %1, %2" : "=v"(r) : "v"(lo), "v"(hi)); return r; }
; __device__ __forceinline__ void transpose_item(const float* W, int N, const float* ks, bf16_t* WT, int ldo, int orow0, int k0, int n0, LAS float* scr, int lane) {
;     f32x4 v[8];
; #pragma unroll
;     for (int i = 0; i < 8; ++i) v[i] = *(const f32x4*)(W + (size_t)(k0 + i * 4 + (lane >> 4)) * N + n0 + 4 * (lane & 15));
; #pragma unroll
;     for (int i = 0; i < 8; ++i) { const int kk = i * 4 + (lane >> 4); const float sc = ks ? ks[k0 + kk] : 1.0f; LAS float* d = scr + kk * 65 + 4 * (lane & 15);
;         d[0] = v[i][0] * sc; d[1] = v[i][1] * sc; d[2] = v[i][2] * sc; d[3] = v[i][3] * sc; }
;     asm volatile("s_waitcnt lgkmcnt(0)" ::: "memory");
;     const int kc = lane & 3;
; #pragma unroll
;     for (int j = 0; j < 4; ++j) { const int n = (lane >> 2) + 16 * j; const LAS float* s = scr + (8 * kc) * 65 + n;
;         u32x4 o; o.x = cvt_pk_bf16(s[0 * 65], s[1 * 65]); o.y = cvt_pk_bf16(s[2 * 65], s[3 * 65]); o.z = cvt_pk_bf16(s[4 * 65], s[5 * 65]); o.w = cvt_pk_bf16(s[6 * 65], s[7 * 65]);
;         *(u32x4*)(WT + (size_t)(orow0 + n) * ldo + k0 + 8 * kc) = o; }
;     asm volatile("s_waitcnt lgkmcnt(0)" ::: "memory");
; }
; __device__ __forceinline__ void convert_weights(const Params& p, LAS unsigned char* lds, int first, int last, int worker, int nworkers) {
;     ...
;         if (r < WI_BA) { const int kb = r / 16, nb = r % 16; transpose_item(p.w_br_attn + (size_t)l * 512 * DM, DM, nullptr, (bf16_t*)(wb + WO_MIX), 512, nb * 64, kb * 32, nb * 64, scr, lane); continue; } r -= WI_BA;
.LBB0_215:
	s_andn2_b64 vcc, exec, s[0:1]
	s_cbranch_vccnz .LBB0_217
	v_readlane_b32 s40, v249, 20
	s_lshl_b64 s[0:1], s[2:3], 21
	v_readlane_b32 s50, v249, 30
	v_readlane_b32 s51, v249, 31
	s_add_u32 s3, s50, s0
	s_addc_u32 s1, s51, s1
	s_lshl_b32 s8, s2, 10
	s_sub_i32 s8, s10, s8
	s_and_b32 s0, s12, 0x3c0
	s_and_b32 s8, s8, 0xfe0
	s_add_i32 s96, s8, 0xfffff300
	s_lshl_b32 s8, s0, 2
	s_add_u32 s8, s3, s8
	v_or_b32_e32 v28, s96, v32
	s_addc_u32 s9, s1, 0
	v_lshlrev_b32_e32 v96, 2, v34
	v_mov_b32_e32 v29, v97
	v_lshl_add_u64 v[30:31], s[8:9], 0, v[96:97]
	v_lshlrev_b64 v[0:1], 12, v[28:29]
	v_or_b32_e32 v96, 4, v28
	v_lshl_add_u64 v[0:1], v[30:31], 0, v[0:1]
	v_lshlrev_b64 v[4:5], 12, v[96:97]
	global_load_dwordx4 v[0:3], v[0:1], off
	v_lshl_add_u64 v[4:5], v[30:31], 0, v[4:5]
	v_or_b32_e32 v96, 8, v28
	global_load_dwordx4 v[4:7], v[4:5], off
	v_lshlrev_b64 v[8:9], 12, v[96:97]
	v_lshl_add_u64 v[8:9], v[30:31], 0, v[8:9]
	v_or_b32_e32 v96, 12, v28
	global_load_dwordx4 v[8:11], v[8:9], off
	v_lshlrev_b64 v[12:13], 12, v[96:97]
	v_lshl_add_u64 v[12:13], v[30:31], 0, v[12:13]
	v_or_b32_e32 v96, 16, v28
	global_load_dwordx4 v[12:15], v[12:13], off
	v_lshlrev_b64 v[16:17], 12, v[96:97]
	v_lshl_add_u64 v[16:17], v[30:31], 0, v[16:17]
	v_or_b32_e32 v96, 20, v28
	global_load_dwordx4 v[16:19], v[16:17], off
	v_lshlrev_b64 v[20:21], 12, v[96:97]
	v_lshl_add_u64 v[20:21], v[30:31], 0, v[20:21]
	v_or_b32_e32 v96, 24, v28
	global_load_dwordx4 v[20:23], v[20:21], off
	v_lshlrev_b64 v[24:25], 12, v[96:97]
	v_lshl_add_u64 v[24:25], v[30:31], 0, v[24:25]
	v_or_b32_e32 v96, 28, v28
	global_load_dwordx4 v[24:27], v[24:25], off
	v_lshlrev_b64 v[28:29], 12, v[96:97]
	v_lshl_add_u64 v[28:29], v[30:31], 0, v[28:29]
	global_load_dwordx4 v[28:31], v[28:29], off
	v_add_u32_e32 v38, v35, v37
	s_lshl_b64 s[8:9], s[96:97], 1
	s_add_u32 s8, s14, s8
	s_addc_u32 s9, s15, s9
	v_lshlrev_b32_e32 v96, 1, v36
	v_readlane_b32 s41, v249, 21
	v_readlane_b32 s42, v249, 22
	v_readlane_b32 s43, v249, 23
	v_readlane_b32 s44, v249, 24
	v_readlane_b32 s45, v249, 25
	v_readlane_b32 s46, v249, 26
	v_readlane_b32 s47, v249, 27
	v_readlane_b32 s48, v249, 28
	v_readlane_b32 s49, v249, 29
	v_readlane_b32 s52, v249, 32
	v_readlane_b32 s53, v249, 33
	v_readlane_b32 s54, v249, 34
	v_readlane_b32 s55, v249, 35
	s_waitcnt vmcnt(0)
	ds_write2_b32 v38, v0, v1 offset1:1
	ds_write2_b32 v38, v2, v3 offset0:2 offset1:3
	v_add_u32_e32 v0, 0x410, v38
	ds_write2_b32 v0, v4, v5 offset1:1
	v_add_u32_e32 v0, 0x418, v38
	ds_write2_b32 v0, v6, v7 offset1:1
	v_add_u32_e32 v0, 0x820, v38
	ds_write2_b32 v0, v8, v9 offset1:1
	v_add_u32_e32 v0, 0x828, v38
	ds_write2_b32 v0, v10, v11 offset1:1
	v_add_u32_e32 v0, 0xc30, v38
	ds_write2_b32 v0, v12, v13 offset1:1
	v_add_u32_e32 v0, 0xc38, v38
	ds_write2_b32 v0, v14, v15 offset1:1
	v_add_u32_e32 v0, 0x1040, v38
	ds_write2_b32 v0, v16, v17 offset1:1
	v_add_u32_e32 v0, 0x1048, v38
	ds_write2_b32 v0, v18, v19 offset1:1
	v_add_u32_e32 v0, 0x1450, v38
	ds_write2_b32 v0, v20, v21 offset1:1
	v_add_u32_e32 v0, 0x1458, v38
	ds_write2_b32 v0, v22, v23 offset1:1
	v_add_u32_e32 v0, 0x1860, v38
	ds_write2_b32 v0, v24, v25 offset1:1
	v_add_u32_e32 v0, 0x1868, v38
	ds_write2_b32 v0, v26, v27 offset1:1
	v_add_u32_e32 v0, 0x1c70, v38
	ds_write2_b32 v0, v28, v29 offset1:1
	v_add_u32_e32 v0, 0x1c78, v38
	ds_write2_b32 v0, v30, v31 offset1:1
	s_waitcnt lgkmcnt(0)
	v_lshl_add_u64 v[0:1], s[8:9], 0, v[96:97]
	s_mov_b64 s[8:9], 0x680000
	v_lshl_add_u64 v[4:5], v[0:1], 0, s[8:9]
	ds_read2_b32 v[0:1], v43 offset1:65
	s_waitcnt lgkmcnt(0)
	v_cvt_pk_bf16_f32 v0, v0, v1
	ds_read2_b32 v[2:3], v43 offset0:130 offset1:195
	v_add_u32_e32 v8, 0x400, v43
	s_waitcnt lgkmcnt(0)
	v_cvt_pk_bf16_f32 v1, v2, v3
	ds_read2_b32 v[2:3], v8 offset0:4 offset1:69
	s_waitcnt lgkmcnt(0)
	v_cvt_pk_bf16_f32 v2, v2, v3
	ds_read2_b32 v[6:7], v8 offset0:134 offset1:199
	s_waitcnt lgkmcnt(0)
	v_cvt_pk_bf16_f32 v3, v6, v7
	v_or_b32_e32 v6, s0, v39
	v_lshlrev_b32_e32 v96, 10, v6
	v_lshl_add_u64 v[6:7], v[4:5], 0, v[96:97]
	global_store_dwordx4 v[6:7], v[0:3], off nt
	ds_read2_b32 v[0:1], v43 offset0:16 offset1:81
	s_waitcnt lgkmcnt(0)
	v_cvt_pk_bf16_f32 v0, v0, v1
	ds_read2_b32 v[2:3], v43 offset0:146 offset1:211
	s_waitcnt lgkmcnt(0)
	v_cvt_pk_bf16_f32 v1, v2, v3
	ds_read2_b32 v[2:3], v8 offset0:20 offset1:85
	s_waitcnt lgkmcnt(0)
	v_cvt_pk_bf16_f32 v2, v2, v3
	ds_read2_b32 v[6:7], v8 offset0:150 offset1:215
	s_waitcnt lgkmcnt(0)
	v_cvt_pk_bf16_f32 v3, v6, v7
	v_or_b32_e32 v6, s0, v44
	v_lshlrev_b32_e32 v96, 10, v6
	v_lshl_add_u64 v[6:7], v[4:5], 0, v[96:97]
	global_store_dwordx4 v[6:7], v[0:3], off nt
	ds_read2_b32 v[0:1], v43 offset0:32 offset1:97
	s_waitcnt lgkmcnt(0)
	v_cvt_pk_bf16_f32 v0, v0, v1
	ds_read2_b32 v[2:3], v43 offset0:162 offset1:227
	s_waitcnt lgkmcnt(0)
	v_cvt_pk_bf16_f32 v1, v2, v3
	ds_read2_b32 v[2:3], v8 offset0:36 offset1:101
	s_waitcnt lgkmcnt(0)
	v_cvt_pk_bf16_f32 v2, v2, v3
	ds_read2_b32 v[6:7], v8 offset0:166 offset1:231
	s_waitcnt lgkmcnt(0)
	v_cvt_pk_bf16_f32 v3, v6, v7
	v_or_b32_e32 v6, s0, v45
	v_lshlrev_b32_e32 v96, 10, v6
	v_lshl_add_u64 v[6:7], v[4:5], 0, v[96:97]
	global_store_dwordx4 v[6:7], v[0:3], off nt
	ds_read2_b32 v[0:1], v43 offset0:48 offset1:113
	s_waitcnt lgkmcnt(0)
	v_cvt_pk_bf16_f32 v0, v0, v1
	ds_read2_b32 v[2:3], v43 offset0:178 offset1:243
	s_waitcnt lgkmcnt(0)
	v_cvt_pk_bf16_f32 v1, v2, v3
	ds_read2_b32 v[2:3], v8 offset0:52 offset1:117
	s_waitcnt lgkmcnt(0)
	v_cvt_pk_bf16_f32 v2, v2, v3
	ds_read2_b32 v[6:7], v8 offset0:182 offset1:247
	s_waitcnt lgkmcnt(0)
	v_cvt_pk_bf16_f32 v3, v6, v7
	v_or_b32_e32 v6, s0, v46
	v_lshlrev_b32_e32 v96, 10, v6
	v_lshl_add_u64 v[4:5], v[4:5], 0, v[96:97]
	global_store_dwordx4 v[4:5], v[0:3], off nt
	s_waitcnt lgkmcnt(0)

; #define LAS __attribute__((address_space(3)))
; __device__ __forceinline__ unsigned cvt_pk_bf16(float lo, float hi) { unsigned r; asm volatile("v_cvt_pk_bf16_f32 %0, %1, %2" : "=v"(r) : "v"(lo), "v"(hi)); return r; }
; __device__ __forceinline__ void unpack8(const u32x4 w, float* f) { f[0] = bf_lo(w.x); f[1] = bf_hi(w.x); f[2] = bf_lo(w.y); f[3] = bf_hi(w.y); f[4] = bf_lo(w.z); f[5] = bf_hi(w.z); f[6] = bf_lo(w.w); f[7] = bf_hi(w.w); }
; __device__ __forceinline__ u32x4 pack8(const float* f) { u32x4 w; w.x = cvt_pk_bf16(f[0], f[1]); w.y = cvt_pk_bf16(f[2], f[3]); w.z = cvt_pk_bf16(f[4], f[5]); w.w = cvt_pk_bf16(f[6], f[7]); return w; }
; __device__ __forceinline__ void attn_macro(const Params& p, int l, LAS unsigned char* lds, int b, int cg, int kvh) {
;     ...
;     for (int it = 0; it < 6; ++it) {
;         const int idx = it * 512 + tid, j = idx >> 3, ch = idx & 7;
;         float kf[8], vf[8]; unpack8(kraw[it], kf); unpack8(vraw[it], vf);
;         float ss = 0.f;
; #pragma unroll
;         for (int i = 0; i < 8; ++i) ss += kf[i] * kf[i];
;         ss += __shfl_xor(ss, 1); ss += __shfl_xor(ss, 2); ss += __shfl_xor(ss, 4);
;         const float sc = __builtin_amdgcn_rsqf(ss * (1.0f / 64.0f) + EPS);
; #pragma unroll
;         for (int i = 0; i < 8; ++i) kf[i] = kf[i] * sc * knorm[ch * 8 + i];
;         *(LAS u32x4*)(Ks + j * MK_LD + ch * 8) = pack8(kf);
;         const int js = j ^ (ch << 3);
; #pragma unroll
;         for (int i = 0; i < 8; i += 2) { const unsigned w = cvt_pk_bf16(vf[i], vf[i + 1]); Vt[(ch * 8 + i) * MV_LD + js] = (bf16_t)(w & 0xffffu); Vt[(ch * 8 + i + 1) * MV_LD + js] = (bf16_t)(w >> 16); }
;         if (cg == 63 && j >= 256) {
;             const size_t o = ((((size_t)l * 2 + b) * 128 + (j - 256)) * 2 + kvh) * 64 + ch * 8; float* kd = p.out + O_KP + o; float* vd = p.out + O_VP + o;
;             *(f32x4*)kd = (f32x4){kf[0], kf[1], kf[2], kf[3]}; *(f32x4*)(kd + 4) = (f32x4){kf[4], kf[5], kf[6], kf[7]};
;             *(f32x4*)vd = (f32x4){vf[0], vf[1], vf[2], vf[3]}; *(f32x4*)(vd + 4) = (f32x4){vf[4], vf[5], vf[6], vf[7]};
;         }
.LBB0_300:
	s_or_b64 exec, exec, s[8:9]
	v_lshlrev_b32_e32 v96, 2, v57
	global_load_dwordx4 v[52:55], v96, s[50:51]
	global_load_dwordx4 v[74:77], v96, s[50:51] offset:16
	v_and_b32_e32 v60, 64, v225
	v_xor_b32_e32 v63, 1, v225
	s_waitcnt vmcnt(0) lgkmcnt(0)
	v_lshlrev_b32_e32 v78, 16, v40
	v_and_b32_e32 v79, 0xffff0000, v40
	v_add_u32_e32 v60, 64, v60
	v_lshlrev_b32_e32 v40, 16, v41
	v_and_b32_e32 v41, 0xffff0000, v41
	v_pk_mul_f32 v[66:67], v[78:79], v[78:79]
	v_cmp_lt_i32_e32 vcc, v63, v60
	v_pk_mul_f32 v[68:69], v[40:41], v[40:41]
	v_add_f32_e32 v66, v66, v67
	v_cndmask_b32_e32 v63, v225, v63, vcc
	v_lshlrev_b32_e32 v80, 16, v42
	v_and_b32_e32 v81, 0xffff0000, v42
	v_lshlrev_b32_e32 v64, 2, v63
	v_add_f32_e32 v63, v68, v66
	v_pk_mul_f32 v[82:83], v[80:81], v[80:81]
	v_add_f32_e32 v63, v69, v63
	v_lshlrev_b32_e32 v42, 16, v43
	v_and_b32_e32 v43, 0xffff0000, v43
	v_add_f32_e32 v63, v82, v63
	v_pk_mul_f32 v[84:85], v[42:43], v[42:43]
	v_add_f32_e32 v63, v83, v63
	v_add_f32_e32 v63, v84, v63
	v_add_f32_e32 v63, v85, v63
	ds_bpermute_b32 v67, v64, v63
	v_xor_b32_e32 v70, 2, v225
	v_cmp_lt_i32_e32 vcc, v70, v60
	v_xor_b32_e32 v86, 4, v225
	s_lshl_b32 s8, s12, 6
	v_cndmask_b32_e32 v66, v225, v70, vcc
	v_lshlrev_b32_e32 v66, 2, v66
	s_waitcnt lgkmcnt(0)
	v_add_f32_e32 v67, v63, v67
	ds_bpermute_b32 v69, v66, v67
	v_cmp_lt_i32_e32 vcc, v86, v60
	v_lshl_add_u32 v58, v57, 1, 0
	v_or_b32_e32 v62, s8, v57
	v_cndmask_b32_e32 v68, v225, v86, vcc
	v_lshlrev_b32_e32 v68, 2, v68
	s_waitcnt lgkmcnt(0)
	v_add_f32_e32 v67, v67, v69
	ds_bpermute_b32 v69, v68, v67
	v_mad_u64_u32 v[82:83], s[8:9], v73, s83, v[58:59]
	v_xor_b32_e32 v87, v57, v73
	s_movk_i32 s8, 0x30e
	s_waitcnt lgkmcnt(0)
	v_add_f32_e32 v67, v67, v69
	v_fmamk_f32 v67, v67, 0x3c800000, v223
	v_rsq_f32_e32 v70, v67
	v_mad_u32_u24 v63, v57, s8, v58
	v_lshlrev_b32_e32 v83, 1, v87
	v_lshlrev_b32_e32 v48, 16, v44
	v_pk_mul_f32 v[78:79], v[70:71], v[78:79] op_sel_hi:[0,1]
	v_pk_mul_f32 v[40:41], v[70:71], v[40:41] op_sel_hi:[0,1]
	v_pk_mul_f32 v[80:81], v[70:71], v[80:81] op_sel_hi:[0,1]
	v_pk_mul_f32 v[42:43], v[70:71], v[42:43] op_sel_hi:[0,1]
	v_and_b32_e32 v49, 0xffff0000, v44
	v_add_u32_e32 v84, v63, v83
	v_add_u32_e32 v67, 0x620, v63
	v_lshlrev_b32_e32 v50, 16, v45
	v_and_b32_e32 v51, 0xffff0000, v45
	v_add_u32_e32 v69, v67, v83
	s_cmp_eq_u32 s11, 63
	v_lshlrev_b32_e32 v44, 16, v46
	v_and_b32_e32 v45, 0xffff0000, v46
	s_cselect_b64 s[8:9], -1, 0
	s_and_b32 s15, s10, 0xffffff80
	s_movk_i32 s10, 0xff
	v_cmp_lt_i32_e32 vcc, s10, v73
	v_lshlrev_b32_e32 v46, 16, v47
	v_and_b32_e32 v47, 0xffff0000, v47
	s_add_i32 s15, s15, s18
	s_and_b64 s[40:41], s[8:9], vcc
	v_pk_mul_f32 v[52:53], v[52:53], v[78:79]
	v_pk_mul_f32 v[54:55], v[54:55], v[40:41]
	v_pk_mul_f32 v[40:41], v[74:75], v[80:81]
	v_pk_mul_f32 v[42:43], v[42:43], v[76:77]
	v_cvt_pk_bf16_f32 v74, v52, v53
	v_cvt_pk_bf16_f32 v75, v54, v55
	v_cvt_pk_bf16_f32 v76, v40, v41
	s_nop 0
	v_cvt_pk_bf16_f32 v77, v42, v43
	ds_write_b128 v82, v[74:77]
	v_cvt_pk_bf16_f32 v70, v48, v49
	ds_write_b16 v84, v70 offset:55296
	ds_write_b16_d16_hi v84, v70 offset:56080
	v_cvt_pk_bf16_f32 v70, v50, v51
	ds_write_b16 v69, v70 offset:55296
	ds_write_b16_d16_hi v69, v70 offset:56080
	v_add_u32_e32 v69, 0xc40, v63
	v_cvt_pk_bf16_f32 v70, v44, v45
	v_add_u32_e32 v74, v69, v83
	ds_write_b16 v74, v70 offset:55296
	ds_write_b16_d16_hi v74, v70 offset:56080
	v_add_u32_e32 v70, 0x1260, v63
	v_cvt_pk_bf16_f32 v74, v46, v47
	v_add_u32_e32 v75, v70, v83
	ds_write_b16 v75, v74 offset:55296
	ds_write_b16_d16_hi v75, v74 offset:56080
	s_and_saveexec_b64 s[10:11], s[40:41]
	s_cbranch_execz .LBB0_302
	v_add_u32_e32 v73, s15, v73
	v_add_u32_e32 v74, 0xffffff00, v73
	v_mov_b32_e32 v75, v97
	v_lshlrev_b64 v[74:75], 9, v[74:75]
	v_lshl_or_b32 v74, v62, 2, v74
	v_lshl_add_u64 v[76:77], s[54:55], 0, v[74:75]
	v_lshl_add_u64 v[74:75], s[56:57], 0, v[74:75]
	global_store_dwordx4 v[76:77], v[52:55], off nt
	global_store_dwordx4 v[76:77], v[40:43], off offset:16 nt
	global_store_dwordx4 v[74:75], v[48:51], off nt
	global_store_dwordx4 v[74:75], v[44:47], off offset:16 nt
.LBB0_302:
	s_or_b64 exec, exec, s[10:11]
	v_lshl_add_u64 v[48:49], s[50:51], 0, v[96:97]
	global_load_dwordx4 v[44:47], v[48:49], off
	global_load_dwordx4 v[50:53], v[48:49], off offset:16
	v_lshlrev_b32_e32 v54, 16, v36
	v_and_b32_e32 v55, 0xffff0000, v36
	v_lshlrev_b32_e32 v36, 16, v37
	v_and_b32_e32 v37, 0xffff0000, v37
	v_pk_mul_f32 v[42:43], v[54:55], v[54:55]
	v_lshlrev_b32_e32 v40, 16, v32
	v_and_b32_e32 v41, 0xffff0000, v32
	v_pk_mul_f32 v[76:77], v[36:37], v[36:37]
	v_add_f32_e32 v32, v42, v43
	v_lshlrev_b32_e32 v74, 16, v38
	v_and_b32_e32 v75, 0xffff0000, v38
	v_add_f32_e32 v32, v76, v32
	v_pk_mul_f32 v[78:79], v[74:75], v[74:75]
	v_add_f32_e32 v32, v77, v32
	v_lshlrev_b32_e32 v38, 16, v39
	v_and_b32_e32 v39, 0xffff0000, v39
	v_add_f32_e32 v32, v78, v32
	v_pk_mul_f32 v[80:81], v[38:39], v[38:39]
	v_add_f32_e32 v32, v79, v32
	v_add_f32_e32 v32, v80, v32
	v_add_f32_e32 v73, v81, v32
	ds_bpermute_b32 v76, v64, v73
	v_lshlrev_b32_e32 v42, 16, v33
	v_and_b32_e32 v43, 0xffff0000, v33
	v_lshlrev_b32_e32 v32, 16, v34
	v_and_b32_e32 v33, 0xffff0000, v34
	s_waitcnt lgkmcnt(0)
	v_add_f32_e32 v73, v73, v76
	ds_bpermute_b32 v78, v66, v73
	v_mad_u64_u32 v[76:77], s[10:11], v72, s83, v[58:59]
	s_movk_i32 s10, 0xff
	s_nop 0
	v_cmp_lt_i32_e32 vcc, s10, v72
	s_waitcnt lgkmcnt(0)
	v_add_f32_e32 v73, v73, v78
	ds_bpermute_b32 v77, v68, v73
	v_xor_b32_e32 v78, v72, v57
	v_lshlrev_b32_e32 v79, 1, v78
	v_add_u32_e32 v80, v63, v79
	v_lshlrev_b32_e32 v34, 16, v35
	s_waitcnt lgkmcnt(0)
	v_add_f32_e32 v73, v73, v77
	v_fmamk_f32 v73, v73, 0x3c800000, v223
	v_rsq_f32_e32 v78, v73
	v_add_u32_e32 v73, v67, v79
	v_add_u32_e32 v77, v69, v79
	v_add_u32_e32 v79, v70, v79
	v_pk_mul_f32 v[54:55], v[78:79], v[54:55] op_sel_hi:[0,1]
	v_pk_mul_f32 v[36:37], v[78:79], v[36:37] op_sel_hi:[0,1]
	v_pk_mul_f32 v[74:75], v[78:79], v[74:75] op_sel_hi:[0,1]
	v_pk_mul_f32 v[38:39], v[78:79], v[38:39] op_sel_hi:[0,1]
	v_and_b32_e32 v35, 0xffff0000, v35
	s_and_b64 s[40:41], s[8:9], vcc
	s_waitcnt vmcnt(0)
	v_pk_mul_f32 v[44:45], v[44:45], v[54:55]
	v_pk_mul_f32 v[46:47], v[46:47], v[36:37]
	v_pk_mul_f32 v[36:37], v[50:51], v[74:75]
	v_cvt_pk_bf16_f32 v50, v44, v45
	v_pk_mul_f32 v[38:39], v[38:39], v[52:53]
	v_cvt_pk_bf16_f32 v51, v46, v47
	v_cvt_pk_bf16_f32 v52, v36, v37
	s_nop 0
	v_cvt_pk_bf16_f32 v53, v38, v39
	ds_write_b128 v76, v[50:53]
	v_cvt_pk_bf16_f32 v50, v40, v41
	ds_write_b16 v80, v50 offset:55296
	ds_write_b16_d16_hi v80, v50 offset:56080
	v_cvt_pk_bf16_f32 v50, v42, v43
	ds_write_b16 v73, v50 offset:55296
	ds_write_b16_d16_hi v73, v50 offset:56080
	v_cvt_pk_bf16_f32 v50, v32, v33
	ds_write_b16 v77, v50 offset:55296
	ds_write_b16_d16_hi v77, v50 offset:56080
	v_cvt_pk_bf16_f32 v50, v34, v35
	ds_write_b16 v79, v50 offset:55296
	ds_write_b16_d16_hi v79, v50 offset:56080
	s_and_saveexec_b64 s[10:11], s[40:41]
	s_cbranch_execz .LBB0_304
; #define LAS __attribute__((address_space(3)))
; __device__ __forceinline__ unsigned cvt_pk_bf16(float lo, float hi) { unsigned r; asm volatile("v_cvt_pk_bf16_f32 %0, %1, %2" : "=v"(r) : "v"(lo), "v"(hi)); return r; }
; __device__ __forceinline__ void unpack8(const u32x4 w, float* f) { f[0] = bf_lo(w.x); f[1] = bf_hi(w.x); f[2] = bf_lo(w.y); f[3] = bf_hi(w.y); f[4] = bf_lo(w.z); f[5] = bf_hi(w.z); f[6] = bf_lo(w.w); f[7] = bf_hi(w.w); }
; __device__ __forceinline__ u32x4 pack8(const float* f) { u32x4 w; w.x = cvt_pk_bf16(f[0], f[1]); w.y = cvt_pk_bf16(f[2], f[3]); w.z = cvt_pk_bf16(f[4], f[5]); w.w = cvt_pk_bf16(f[6], f[7]); return w; }
; __device__ __forceinline__ void attn_macro(const Params& p, int l, LAS unsigned char* lds, int b, int cg, int kvh) {
;     ...
;     for (int it = 0; it < 6; ++it) {
;         const int idx = it * 512 + tid, j = idx >> 3, ch = idx & 7;
;         float kf[8], vf[8]; unpack8(kraw[it], kf); unpack8(vraw[it], vf);
;         float ss = 0.f;
; #pragma unroll
;         for (int i = 0; i < 8; ++i) ss += kf[i] * kf[i];
;         ss += __shfl_xor(ss, 1); ss += __shfl_xor(ss, 2); ss += __shfl_xor(ss, 4);
;         const float sc = __builtin_amdgcn_rsqf(ss * (1.0f / 64.0f) + EPS);
; #pragma unroll
;         for (int i = 0; i < 8; ++i) kf[i] = kf[i] * sc * knorm[ch * 8 + i];
;         *(LAS u32x4*)(Ks + j * MK_LD + ch * 8) = pack8(kf);
;         const int js = j ^ (ch << 3);
; #pragma unroll
;         for (int i = 0; i < 8; i += 2) { const unsigned w = cvt_pk_bf16(vf[i], vf[i + 1]); Vt[(ch * 8 + i) * MV_LD + js] = (bf16_t)(w & 0xffffu); Vt[(ch * 8 + i + 1) * MV_LD + js] = (bf16_t)(w >> 16); }
;         if (cg == 63 && j >= 256) {
;             const size_t o = ((((size_t)l * 2 + b) * 128 + (j - 256)) * 2 + kvh) * 64 + ch * 8; float* kd = p.out + O_KP + o; float* vd = p.out + O_VP + o;
;             *(f32x4*)kd = (f32x4){kf[0], kf[1], kf[2], kf[3]}; *(f32x4*)(kd + 4) = (f32x4){kf[4], kf[5], kf[6], kf[7]};
;             *(f32x4*)vd = (f32x4){vf[0], vf[1], vf[2], vf[3]}; *(f32x4*)(vd + 4) = (f32x4){vf[4], vf[5], vf[6], vf[7]};
;         }
	v_add_u32_e32 v50, s15, v72
	v_add_u32_e32 v96, 0xffffff00, v50
	v_lshlrev_b64 v[50:51], 9, v[96:97]
	v_lshl_or_b32 v50, v62, 2, v50
	v_lshl_add_u64 v[52:53], s[54:55], 0, v[50:51]
	v_lshl_add_u64 v[50:51], s[56:57], 0, v[50:51]
	global_store_dwordx4 v[52:53], v[44:47], off nt
	global_store_dwordx4 v[52:53], v[36:39], off offset:16 nt
	global_store_dwordx4 v[50:51], v[40:43], off nt
	global_store_dwordx4 v[50:51], v[32:35], off offset:16 nt
.LBB0_304:
	s_or_b64 exec, exec, s[10:11]
	global_load_dwordx4 v[36:39], v[48:49], off
	global_load_dwordx4 v[40:43], v[48:49], off offset:16
	v_lshlrev_b32_e32 v44, 16, v28
	v_and_b32_e32 v45, 0xffff0000, v28
	v_lshlrev_b32_e32 v28, 16, v29
	v_and_b32_e32 v29, 0xffff0000, v29
	v_pk_mul_f32 v[34:35], v[44:45], v[44:45]
	v_lshlrev_b32_e32 v32, 16, v24
	v_and_b32_e32 v33, 0xffff0000, v24
	v_pk_mul_f32 v[50:51], v[28:29], v[28:29]
	v_add_f32_e32 v24, v34, v35
	v_lshlrev_b32_e32 v46, 16, v30
	v_and_b32_e32 v47, 0xffff0000, v30
	v_add_f32_e32 v24, v50, v24
	v_pk_mul_f32 v[52:53], v[46:47], v[46:47]
	v_add_f32_e32 v24, v51, v24
	v_lshlrev_b32_e32 v30, 16, v31
	v_and_b32_e32 v31, 0xffff0000, v31
	v_add_f32_e32 v24, v52, v24
	v_pk_mul_f32 v[54:55], v[30:31], v[30:31]
	v_add_f32_e32 v24, v53, v24
	v_add_f32_e32 v24, v54, v24
	v_add_f32_e32 v50, v55, v24
	ds_bpermute_b32 v51, v64, v50
	v_lshlrev_b32_e32 v34, 16, v25
	v_and_b32_e32 v35, 0xffff0000, v25
	v_lshlrev_b32_e32 v24, 16, v26
	v_and_b32_e32 v25, 0xffff0000, v26
	s_waitcnt lgkmcnt(0)
	v_add_f32_e32 v52, v50, v51
	ds_bpermute_b32 v53, v66, v52
	v_mad_u64_u32 v[50:51], s[10:11], v71, s83, v[58:59]
	s_movk_i32 s10, 0xff
	s_nop 0
	v_cmp_lt_i32_e32 vcc, s10, v71
	s_waitcnt lgkmcnt(0)
	v_add_f32_e32 v51, v52, v53
	ds_bpermute_b32 v52, v68, v51
	v_xor_b32_e32 v53, v71, v57
	v_lshlrev_b32_e32 v53, 1, v53
	v_add_u32_e32 v54, v63, v53
	v_add_u32_e32 v55, v69, v53
	s_waitcnt lgkmcnt(0)
	v_add_f32_e32 v51, v51, v52
	v_fmamk_f32 v51, v51, 0x3c800000, v223
	v_rsq_f32_e32 v52, v51
	v_add_u32_e32 v51, v67, v53
	v_add_u32_e32 v53, v70, v53
	v_lshlrev_b32_e32 v26, 16, v27
	v_pk_mul_f32 v[44:45], v[52:53], v[44:45] op_sel_hi:[0,1]
	v_pk_mul_f32 v[28:29], v[52:53], v[28:29] op_sel_hi:[0,1]
	v_pk_mul_f32 v[46:47], v[52:53], v[46:47] op_sel_hi:[0,1]
	v_pk_mul_f32 v[30:31], v[52:53], v[30:31] op_sel_hi:[0,1]
	v_and_b32_e32 v27, 0xffff0000, v27
	s_and_b64 s[40:41], s[8:9], vcc
	s_waitcnt vmcnt(0)
	v_pk_mul_f32 v[36:37], v[36:37], v[44:45]
	v_pk_mul_f32 v[38:39], v[38:39], v[28:29]
	v_pk_mul_f32 v[28:29], v[40:41], v[46:47]
	v_cvt_pk_bf16_f32 v40, v36, v37
	v_pk_mul_f32 v[30:31], v[30:31], v[42:43]
	v_cvt_pk_bf16_f32 v41, v38, v39
	v_cvt_pk_bf16_f32 v42, v28, v29
	s_nop 0
	v_cvt_pk_bf16_f32 v43, v30, v31
	ds_write_b128 v50, v[40:43]
	v_cvt_pk_bf16_f32 v40, v32, v33
	ds_write_b16 v54, v40 offset:55296
	ds_write_b16_d16_hi v54, v40 offset:56080
	v_cvt_pk_bf16_f32 v40, v34, v35
	ds_write_b16 v51, v40 offset:55296
	ds_write_b16_d16_hi v51, v40 offset:56080
	v_cvt_pk_bf16_f32 v40, v24, v25
	ds_write_b16 v55, v40 offset:55296
	ds_write_b16_d16_hi v55, v40 offset:56080
	v_cvt_pk_bf16_f32 v40, v26, v27
	ds_write_b16 v53, v40 offset:55296
	ds_write_b16_d16_hi v53, v40 offset:56080
	s_and_saveexec_b64 s[10:11], s[40:41]
	s_cbranch_execz .LBB0_306
	v_add_u32_e32 v40, s15, v71
	v_add_u32_e32 v96, 0xffffff00, v40
	v_lshlrev_b64 v[40:41], 9, v[96:97]
	v_lshl_or_b32 v40, v62, 2, v40
	v_lshl_add_u64 v[42:43], s[54:55], 0, v[40:41]
	v_lshl_add_u64 v[40:41], s[56:57], 0, v[40:41]
	global_store_dwordx4 v[42:43], v[36:39], off nt
	global_store_dwordx4 v[42:43], v[28:31], off offset:16 nt
	global_store_dwordx4 v[40:41], v[32:35], off nt
	global_store_dwordx4 v[40:41], v[24:27], off offset:16 nt
.LBB0_306:
	s_or_b64 exec, exec, s[10:11]
	global_load_dwordx4 v[28:31], v[48:49], off
	global_load_dwordx4 v[32:35], v[48:49], off offset:16
	v_lshlrev_b32_e32 v36, 16, v20
	v_and_b32_e32 v37, 0xffff0000, v20
	v_lshlrev_b32_e32 v20, 16, v21
	v_and_b32_e32 v21, 0xffff0000, v21
	v_pk_mul_f32 v[26:27], v[36:37], v[36:37]
	v_lshlrev_b32_e32 v24, 16, v16
	v_and_b32_e32 v25, 0xffff0000, v16
	v_pk_mul_f32 v[40:41], v[20:21], v[20:21]
	v_add_f32_e32 v16, v26, v27
	v_lshlrev_b32_e32 v38, 16, v22
	v_and_b32_e32 v39, 0xffff0000, v22
	v_add_f32_e32 v16, v40, v16
	v_pk_mul_f32 v[42:43], v[38:39], v[38:39]
	v_add_f32_e32 v16, v41, v16
	v_lshlrev_b32_e32 v22, 16, v23
	v_and_b32_e32 v23, 0xffff0000, v23
	v_add_f32_e32 v16, v42, v16
	v_pk_mul_f32 v[44:45], v[22:23], v[22:23]
	v_add_f32_e32 v16, v43, v16
	v_add_f32_e32 v16, v44, v16
	v_add_f32_e32 v40, v45, v16
	ds_bpermute_b32 v41, v64, v40
	v_lshlrev_b32_e32 v26, 16, v17
	v_and_b32_e32 v27, 0xffff0000, v17
	v_lshlrev_b32_e32 v16, 16, v18
	v_and_b32_e32 v17, 0xffff0000, v18
	s_waitcnt lgkmcnt(0)
	v_add_f32_e32 v42, v40, v41
	ds_bpermute_b32 v43, v66, v42
	v_mad_u64_u32 v[40:41], s[10:11], v65, s83, v[58:59]
	s_movk_i32 s10, 0xff
	s_nop 0
	v_cmp_lt_i32_e32 vcc, s10, v65
	s_waitcnt lgkmcnt(0)
	v_add_f32_e32 v41, v42, v43
	ds_bpermute_b32 v42, v68, v41
	v_xor_b32_e32 v43, v65, v57
	v_lshlrev_b32_e32 v43, 1, v43
	v_add_u32_e32 v44, v63, v43
	v_add_u32_e32 v45, v69, v43
	s_waitcnt lgkmcnt(0)
	v_add_f32_e32 v41, v41, v42
	v_fmamk_f32 v41, v41, 0x3c800000, v223
	v_rsq_f32_e32 v42, v41
	v_add_u32_e32 v41, v67, v43
	v_add_u32_e32 v43, v70, v43
	v_lshlrev_b32_e32 v18, 16, v19
	v_pk_mul_f32 v[36:37], v[42:43], v[36:37] op_sel_hi:[0,1]
	v_pk_mul_f32 v[20:21], v[42:43], v[20:21] op_sel_hi:[0,1]
	v_pk_mul_f32 v[38:39], v[42:43], v[38:39] op_sel_hi:[0,1]
	v_pk_mul_f32 v[22:23], v[42:43], v[22:23] op_sel_hi:[0,1]
	v_and_b32_e32 v19, 0xffff0000, v19
	s_and_b64 s[40:41], s[8:9], vcc
	s_waitcnt vmcnt(0)
	v_pk_mul_f32 v[28:29], v[28:29], v[36:37]
	v_pk_mul_f32 v[30:31], v[30:31], v[20:21]
	v_pk_mul_f32 v[20:21], v[32:33], v[38:39]
	v_cvt_pk_bf16_f32 v32, v28, v29
	v_pk_mul_f32 v[22:23], v[22:23], v[34:35]
	v_cvt_pk_bf16_f32 v33, v30, v31
	v_cvt_pk_bf16_f32 v34, v20, v21
	s_nop 0
	v_cvt_pk_bf16_f32 v35, v22, v23
	ds_write_b128 v40, v[32:35]
	v_cvt_pk_bf16_f32 v32, v24, v25
	ds_write_b16 v44, v32 offset:55296
	ds_write_b16_d16_hi v44, v32 offset:56080
	v_cvt_pk_bf16_f32 v32, v26, v27
	ds_write_b16 v41, v32 offset:55296
	ds_write_b16_d16_hi v41, v32 offset:56080
	v_cvt_pk_bf16_f32 v32, v16, v17
	ds_write_b16 v45, v32 offset:55296
	ds_write_b16_d16_hi v45, v32 offset:56080
	v_cvt_pk_bf16_f32 v32, v18, v19
	ds_write_b16 v43, v32 offset:55296
	ds_write_b16_d16_hi v43, v32 offset:56080
	s_and_saveexec_b64 s[10:11], s[40:41]
	s_cbranch_execz .LBB0_308
	v_add_u32_e32 v32, s15, v65
	v_add_u32_e32 v96, 0xffffff00, v32
	v_lshlrev_b64 v[32:33], 9, v[96:97]
	v_lshl_or_b32 v32, v62, 2, v32
	v_lshl_add_u64 v[34:35], s[54:55], 0, v[32:33]
	v_lshl_add_u64 v[32:33], s[56:57], 0, v[32:33]
	global_store_dwordx4 v[34:35], v[28:31], off nt
	global_store_dwordx4 v[34:35], v[20:23], off offset:16 nt
	global_store_dwordx4 v[32:33], v[24:27], off nt
	global_store_dwordx4 v[32:33], v[16:19], off offset:16 nt
; #define LAS __attribute__((address_space(3)))
; __device__ __forceinline__ unsigned cvt_pk_bf16(float lo, float hi) { unsigned r; asm volatile("v_cvt_pk_bf16_f32 %0, %1, %2" : "=v"(r) : "v"(lo), "v"(hi)); return r; }
; __device__ __forceinline__ void unpack8(const u32x4 w, float* f) { f[0] = bf_lo(w.x); f[1] = bf_hi(w.x); f[2] = bf_lo(w.y); f[3] = bf_hi(w.y); f[4] = bf_lo(w.z); f[5] = bf_hi(w.z); f[6] = bf_lo(w.w); f[7] = bf_hi(w.w); }
; __device__ __forceinline__ u32x4 pack8(const float* f) { u32x4 w; w.x = cvt_pk_bf16(f[0], f[1]); w.y = cvt_pk_bf16(f[2], f[3]); w.z = cvt_pk_bf16(f[4], f[5]); w.w = cvt_pk_bf16(f[6], f[7]); return w; }
; __device__ __forceinline__ void attn_macro(const Params& p, int l, LAS unsigned char* lds, int b, int cg, int kvh) {
;     ...
;     for (int it = 0; it < 6; ++it) {
;         const int idx = it * 512 + tid, j = idx >> 3, ch = idx & 7;
;         float kf[8], vf[8]; unpack8(kraw[it], kf); unpack8(vraw[it], vf);
;         float ss = 0.f;
; #pragma unroll
;         for (int i = 0; i < 8; ++i) ss += kf[i] * kf[i];
;         ss += __shfl_xor(ss, 1); ss += __shfl_xor(ss, 2); ss += __shfl_xor(ss, 4);
;         const float sc = __builtin_amdgcn_rsqf(ss * (1.0f / 64.0f) + EPS);
; #pragma unroll
;         for (int i = 0; i < 8; ++i) kf[i] = kf[i] * sc * knorm[ch * 8 + i];
;         *(LAS u32x4*)(Ks + j * MK_LD + ch * 8) = pack8(kf);
;         const int js = j ^ (ch << 3);
; #pragma unroll
;         for (int i = 0; i < 8; i += 2) { const unsigned w = cvt_pk_bf16(vf[i], vf[i + 1]); Vt[(ch * 8 + i) * MV_LD + js] = (bf16_t)(w & 0xffffu); Vt[(ch * 8 + i + 1) * MV_LD + js] = (bf16_t)(w >> 16); }
;         if (cg == 63 && j >= 256) {
;             const size_t o = ((((size_t)l * 2 + b) * 128 + (j - 256)) * 2 + kvh) * 64 + ch * 8; float* kd = p.out + O_KP + o; float* vd = p.out + O_VP + o;
;             *(f32x4*)kd = (f32x4){kf[0], kf[1], kf[2], kf[3]}; *(f32x4*)(kd + 4) = (f32x4){kf[4], kf[5], kf[6], kf[7]};
;             *(f32x4*)vd = (f32x4){vf[0], vf[1], vf[2], vf[3]}; *(f32x4*)(vd + 4) = (f32x4){vf[4], vf[5], vf[6], vf[7]};
;         }
.LBB0_308:
	s_or_b64 exec, exec, s[10:11]
	global_load_dwordx4 v[20:23], v[48:49], off
	global_load_dwordx4 v[24:27], v[48:49], off offset:16
	v_lshlrev_b32_e32 v28, 16, v12
	v_and_b32_e32 v29, 0xffff0000, v12
	v_lshlrev_b32_e32 v12, 16, v13
	v_and_b32_e32 v13, 0xffff0000, v13
	v_pk_mul_f32 v[18:19], v[28:29], v[28:29]
	v_lshlrev_b32_e32 v16, 16, v8
	v_and_b32_e32 v17, 0xffff0000, v8
	v_pk_mul_f32 v[32:33], v[12:13], v[12:13]
	v_add_f32_e32 v8, v18, v19
	v_lshlrev_b32_e32 v30, 16, v14
	v_and_b32_e32 v31, 0xffff0000, v14
	v_add_f32_e32 v8, v32, v8
	v_pk_mul_f32 v[34:35], v[30:31], v[30:31]
	v_add_f32_e32 v8, v33, v8
	v_lshlrev_b32_e32 v14, 16, v15
	v_and_b32_e32 v15, 0xffff0000, v15
	v_add_f32_e32 v8, v34, v8
	v_pk_mul_f32 v[36:37], v[14:15], v[14:15]
	v_add_f32_e32 v8, v35, v8
	v_add_f32_e32 v8, v36, v8
	v_add_f32_e32 v32, v37, v8
	ds_bpermute_b32 v33, v64, v32
	v_lshlrev_b32_e32 v18, 16, v9
	v_and_b32_e32 v19, 0xffff0000, v9
	v_lshlrev_b32_e32 v8, 16, v10
	v_and_b32_e32 v9, 0xffff0000, v10
	s_waitcnt lgkmcnt(0)
	v_add_f32_e32 v34, v32, v33
	ds_bpermute_b32 v35, v66, v34
	v_mad_u64_u32 v[32:33], s[10:11], v61, s83, v[58:59]
	s_movk_i32 s10, 0xff
	s_nop 0
	v_cmp_lt_i32_e32 vcc, s10, v61
	s_waitcnt lgkmcnt(0)
	v_add_f32_e32 v33, v34, v35
	ds_bpermute_b32 v34, v68, v33
	v_xor_b32_e32 v35, v61, v57
	v_lshlrev_b32_e32 v35, 1, v35
	v_add_u32_e32 v36, v63, v35
	v_add_u32_e32 v37, v69, v35
	s_waitcnt lgkmcnt(0)
	v_add_f32_e32 v33, v33, v34
	v_fmamk_f32 v33, v33, 0x3c800000, v223
	v_rsq_f32_e32 v34, v33
	v_add_u32_e32 v33, v67, v35
	v_add_u32_e32 v35, v70, v35
	v_lshlrev_b32_e32 v10, 16, v11
	v_pk_mul_f32 v[28:29], v[34:35], v[28:29] op_sel_hi:[0,1]
	v_pk_mul_f32 v[12:13], v[34:35], v[12:13] op_sel_hi:[0,1]
	v_pk_mul_f32 v[30:31], v[34:35], v[30:31] op_sel_hi:[0,1]
	v_pk_mul_f32 v[14:15], v[34:35], v[14:15] op_sel_hi:[0,1]
	v_and_b32_e32 v11, 0xffff0000, v11
	s_and_b64 s[40:41], s[8:9], vcc
	s_waitcnt vmcnt(0)
	v_pk_mul_f32 v[20:21], v[20:21], v[28:29]
	v_pk_mul_f32 v[22:23], v[22:23], v[12:13]
	v_pk_mul_f32 v[12:13], v[24:25], v[30:31]
	v_cvt_pk_bf16_f32 v24, v20, v21
	v_pk_mul_f32 v[14:15], v[14:15], v[26:27]
	v_cvt_pk_bf16_f32 v25, v22, v23
	v_cvt_pk_bf16_f32 v26, v12, v13
	s_nop 0
	v_cvt_pk_bf16_f32 v27, v14, v15
	ds_write_b128 v32, v[24:27]
	v_cvt_pk_bf16_f32 v24, v16, v17
	ds_write_b16 v36, v24 offset:55296
	ds_write_b16_d16_hi v36, v24 offset:56080
	v_cvt_pk_bf16_f32 v24, v18, v19
	ds_write_b16 v33, v24 offset:55296
	ds_write_b16_d16_hi v33, v24 offset:56080
	v_cvt_pk_bf16_f32 v24, v8, v9
	ds_write_b16 v37, v24 offset:55296
	ds_write_b16_d16_hi v37, v24 offset:56080
	v_cvt_pk_bf16_f32 v24, v10, v11
	ds_write_b16 v35, v24 offset:55296
	ds_write_b16_d16_hi v35, v24 offset:56080
	s_and_saveexec_b64 s[10:11], s[40:41]
	s_cbranch_execz .LBB0_310
	v_add_u32_e32 v24, s15, v61
	v_add_u32_e32 v96, 0xffffff00, v24
	v_lshlrev_b64 v[24:25], 9, v[96:97]
	v_lshl_or_b32 v24, v62, 2, v24
	v_lshl_add_u64 v[26:27], s[54:55], 0, v[24:25]
	v_lshl_add_u64 v[24:25], s[56:57], 0, v[24:25]
	global_store_dwordx4 v[26:27], v[20:23], off nt
	global_store_dwordx4 v[26:27], v[12:15], off offset:16 nt
	global_store_dwordx4 v[24:25], v[16:19], off nt
	global_store_dwordx4 v[24:25], v[8:11], off offset:16 nt
.LBB0_310:
	s_or_b64 exec, exec, s[10:11]
	global_load_dwordx4 v[12:15], v[48:49], off
	global_load_dwordx4 v[16:19], v[48:49], off offset:16
	v_lshlrev_b32_e32 v20, 16, v4
	v_and_b32_e32 v21, 0xffff0000, v4
	v_lshlrev_b32_e32 v4, 16, v5
	v_and_b32_e32 v5, 0xffff0000, v5
	v_pk_mul_f32 v[10:11], v[20:21], v[20:21]
	v_lshlrev_b32_e32 v8, 16, v0
	v_and_b32_e32 v9, 0xffff0000, v0
	v_pk_mul_f32 v[24:25], v[4:5], v[4:5]
	v_add_f32_e32 v0, v10, v11
	v_lshlrev_b32_e32 v22, 16, v6
	v_and_b32_e32 v23, 0xffff0000, v6
	v_add_f32_e32 v0, v24, v0
	v_pk_mul_f32 v[26:27], v[22:23], v[22:23]
	v_add_f32_e32 v0, v25, v0
	v_lshlrev_b32_e32 v6, 16, v7
	v_and_b32_e32 v7, 0xffff0000, v7
	v_add_f32_e32 v0, v26, v0
	v_pk_mul_f32 v[28:29], v[6:7], v[6:7]
	v_add_f32_e32 v0, v27, v0
	v_add_f32_e32 v0, v28, v0
	v_add_f32_e32 v24, v29, v0
	ds_bpermute_b32 v25, v64, v24
	v_lshlrev_b32_e32 v10, 16, v1
	v_and_b32_e32 v11, 0xffff0000, v1
	v_lshlrev_b32_e32 v0, 16, v2
	v_and_b32_e32 v1, 0xffff0000, v2
	s_waitcnt lgkmcnt(0)
	v_add_f32_e32 v26, v24, v25
	ds_bpermute_b32 v27, v66, v26
	v_mad_u64_u32 v[24:25], s[10:11], v59, s83, v[58:59]
	s_movk_i32 s10, 0xff
	s_nop 0
	v_cmp_lt_i32_e32 vcc, s10, v59
	s_waitcnt lgkmcnt(0)
	v_add_f32_e32 v25, v26, v27
	ds_bpermute_b32 v26, v68, v25
	v_xor_b32_e32 v27, v59, v57
	v_lshlrev_b32_e32 v27, 1, v27
	v_add_u32_e32 v28, v63, v27
	v_add_u32_e32 v29, v69, v27
	s_waitcnt lgkmcnt(0)
	v_add_f32_e32 v25, v25, v26
	v_fmamk_f32 v25, v25, 0x3c800000, v223
	v_rsq_f32_e32 v26, v25
	v_add_u32_e32 v25, v67, v27
	v_add_u32_e32 v27, v70, v27
	v_lshlrev_b32_e32 v2, 16, v3
	v_pk_mul_f32 v[20:21], v[26:27], v[20:21] op_sel_hi:[0,1]
	v_pk_mul_f32 v[4:5], v[26:27], v[4:5] op_sel_hi:[0,1]
	v_pk_mul_f32 v[22:23], v[26:27], v[22:23] op_sel_hi:[0,1]
	v_pk_mul_f32 v[6:7], v[26:27], v[6:7] op_sel_hi:[0,1]
	v_and_b32_e32 v3, 0xffff0000, v3
	s_and_b64 s[10:11], s[8:9], vcc
	s_waitcnt vmcnt(0)
	v_pk_mul_f32 v[12:13], v[12:13], v[20:21]
	v_pk_mul_f32 v[14:15], v[14:15], v[4:5]
	v_pk_mul_f32 v[4:5], v[16:17], v[22:23]
	v_cvt_pk_bf16_f32 v16, v12, v13
	v_pk_mul_f32 v[6:7], v[6:7], v[18:19]
	v_cvt_pk_bf16_f32 v17, v14, v15
	v_cvt_pk_bf16_f32 v18, v4, v5
	s_nop 0
	v_cvt_pk_bf16_f32 v19, v6, v7
	ds_write_b128 v24, v[16:19]
	v_cvt_pk_bf16_f32 v16, v8, v9
	ds_write_b16 v28, v16 offset:55296
	ds_write_b16_d16_hi v28, v16 offset:56080
	v_cvt_pk_bf16_f32 v16, v10, v11
	ds_write_b16 v25, v16 offset:55296
	ds_write_b16_d16_hi v25, v16 offset:56080
	v_cvt_pk_bf16_f32 v16, v0, v1
	ds_write_b16 v29, v16 offset:55296
	ds_write_b16_d16_hi v29, v16 offset:56080
	v_cvt_pk_bf16_f32 v16, v2, v3
	ds_write_b16 v27, v16 offset:55296
	ds_write_b16_d16_hi v27, v16 offset:56080
	s_and_saveexec_b64 s[8:9], s[10:11]
	s_cbranch_execz .LBB0_312
	v_add_u32_e32 v16, s15, v59
	v_add_u32_e32 v96, 0xffffff00, v16
	v_lshlrev_b64 v[16:17], 9, v[96:97]
	v_lshl_or_b32 v16, v62, 2, v16
	v_lshl_add_u64 v[18:19], s[54:55], 0, v[16:17]
	v_lshl_add_u64 v[16:17], s[56:57], 0, v[16:17]
	global_store_dwordx4 v[18:19], v[12:15], off nt
	global_store_dwordx4 v[18:19], v[4:7], off offset:16 nt
	global_store_dwordx4 v[16:17], v[8:11], off nt
	global_store_dwordx4 v[16:17], v[0:3], off offset:16 nt

; #define LAS __attribute__((address_space(3)))
; __device__ __forceinline__ unsigned cvt_pk_bf16(float lo, float hi) { unsigned r; asm volatile("v_cvt_pk_bf16_f32 %0, %1, %2" : "=v"(r) : "v"(lo), "v"(hi)); return r; }
; __device__ __forceinline__ void attn_macro(const Params& p, int l, LAS unsigned char* lds, int b, int cg, int kvh) {
;     ...
;         f32x16 o[2]; o[0] = (f32x16){}; o[1] = (f32x16){};
; #pragma unroll
;         for (int kt = 0; kt < 6; ++kt)
; #pragma unroll
;             for (int jj = 0; jj < 2; ++jj) {
;                 u32x4 pw;
;                 pw.x = cvt_pk_bf16(s[kt][8 * jj + 0], s[kt][8 * jj + 1]); pw.y = cvt_pk_bf16(s[kt][8 * jj + 2], s[kt][8 * jj + 3]);
;                 pw.z = cvt_pk_bf16(s[kt][8 * jj + 4], s[kt][8 * jj + 5]); pw.w = cvt_pk_bf16(s[kt][8 * jj + 6], s[kt][8 * jj + 7]);
;                 const bf16x8 pa = __builtin_bit_cast(bf16x8, pw);
;                 const int e0 = 32 * kt + 16 * jj + 4 * hi;
; #pragma unroll
;                 for (int db = 0; db < 2; ++db) {
;                     const int sw = (((db * 32 + q32) >> 3) & 7) << 3;
;                     const LAS bf16_t* vrow = Vt + (db * 32 + q32) * MV_LD + ci * 64;
;                     const u32x2 lo = *(const LAS u32x2*)(vrow + (e0 ^ sw)), hi2 = *(const LAS u32x2*)(vrow + ((e0 + 8) ^ sw));
;                     const bf16x8 vb = __builtin_bit_cast(bf16x8, (u32x4){lo.x, lo.y, hi2.x, hi2.y});
;                     o[db] = __builtin_amdgcn_mfma_f32_32x32x16_bf16(pa, vb, o[db], 0, 0, 0);
;                 }
;                 __builtin_amdgcn_sched_barrier(0);
;             }
.LBB0_313:
	s_or_b64 exec, exec, s[2:3]
	v_or_b32_e32 v183, 32, v144
	v_bitop3_b32 v4, v183, v96, 56 bitop3:0x6c
	v_mul_u32_u24_e32 v182, 0x310, v144
	v_cvt_pk_bf16_f32 v16, v0, v1
	v_cvt_pk_bf16_f32 v17, v2, v3
	v_cvt_pk_bf16_f32 v18, v5, v6
	v_bitop3_b32 v0, v96, v145, 24 bitop3:0x78
	s_add_i32 s2, s25, 0
	v_bitop3_b32 v1, v83, v145, 24 bitop3:0x78
	v_lshlrev_b32_e32 v4, 1, v4
	v_bitop3_b32 v5, v183, v83, 56 bitop3:0x6c
	v_lshlrev_b32_e32 v0, 1, v0
	v_lshlrev_b32_e32 v1, 1, v1
	v_add3_u32 v4, v182, v4, s2
	v_lshlrev_b32_e32 v5, 1, v5
	v_add3_u32 v0, v182, v0, s2
	v_add3_u32 v2, v182, v1, s2
	v_add_u32_e32 v4, 0x13a00, v4
	v_add3_u32 v5, v182, v5, s2
	v_cvt_pk_bf16_f32 v19, v7, v12
	ds_read_b64 v[0:1], v0 offset:55296
	ds_read_b64 v[2:3], v2 offset:55296
	v_add_u32_e32 v5, 0x13a00, v5
	ds_read_b64 v[20:21], v4
	ds_read_b64 v[22:23], v5
	s_waitcnt lgkmcnt(0)
	v_mfma_f32_32x32x16_bf16 v[0:15], v[16:19], v[0:3], 0
	v_mfma_f32_32x32x16_bf16 v[16:31], v[16:19], v[20:23], 0
	v_cvt_pk_bf16_f32 v184, v42, v43
	v_bitop3_b32 v42, v81, v145, 24 bitop3:0x78
	v_lshlrev_b32_e32 v42, 1, v42
	v_add3_u32 v42, v182, v42, s2
	v_cvt_pk_bf16_f32 v185, v45, v53
	v_cvt_pk_bf16_f32 v186, v61, v70
	v_cvt_pk_bf16_f32 v187, v74, v86
	ds_read_b64 v[188:189], v42 offset:55296
	v_bitop3_b32 v42, v84, v145, 24 bitop3:0x78
	v_lshlrev_b32_e32 v42, 1, v42
	v_add3_u32 v42, v182, v42, s2
	ds_read_b64 v[190:191], v42 offset:55296
	v_bitop3_b32 v42, v183, v81, 56 bitop3:0x6c
	v_lshlrev_b32_e32 v42, 1, v42
	v_add3_u32 v42, v182, v42, s2
	v_add_u32_e32 v42, 0x13a00, v42
	s_waitcnt lgkmcnt(0)
	v_mfma_f32_32x32x16_bf16 v[0:15], v[184:187], v[188:191], v[0:15]
	ds_read_b64 v[188:189], v42
	v_bitop3_b32 v42, v183, v84, 56 bitop3:0x6c
	v_lshlrev_b32_e32 v42, 1, v42
	v_add3_u32 v42, v182, v42, s2
	v_add_u32_e32 v42, 0x13a00, v42
	ds_read_b64 v[190:191], v42
	s_waitcnt lgkmcnt(0)
	v_mfma_f32_32x32x16_bf16 v[16:31], v[184:187], v[188:191], v[16:31]
	v_cvt_pk_bf16_f32 v42, v44, v46
	v_bitop3_b32 v46, v82, v145, 24 bitop3:0x78
	v_lshlrev_b32_e32 v46, 1, v46
	v_add3_u32 v46, v182, v46, s2
	v_cvt_pk_bf16_f32 v43, v54, v57
	v_cvt_pk_bf16_f32 v44, v71, v77
	v_cvt_pk_bf16_f32 v45, v87, v94
	ds_read_b64 v[184:185], v46 offset:55296
	v_bitop3_b32 v46, v67, v145, 24 bitop3:0x78
	v_lshlrev_b32_e32 v46, 1, v46
	v_add3_u32 v46, v182, v46, s2
	ds_read_b64 v[186:187], v46 offset:55296
	v_bitop3_b32 v46, v183, v82, 56 bitop3:0x6c
	v_lshlrev_b32_e32 v46, 1, v46
	v_add3_u32 v46, v182, v46, s2
	v_add_u32_e32 v46, 0x13a00, v46
	s_waitcnt lgkmcnt(0)
	v_mfma_f32_32x32x16_bf16 v[0:15], v[42:45], v[184:187], v[0:15]
	ds_read_b64 v[184:185], v46
	v_bitop3_b32 v46, v183, v67, 56 bitop3:0x6c
	v_lshlrev_b32_e32 v46, 1, v46
	v_add3_u32 v46, v182, v46, s2
	v_add_u32_e32 v46, 0x13a00, v46
	ds_read_b64 v[186:187], v46
	s_waitcnt lgkmcnt(0)
	v_mfma_f32_32x32x16_bf16 v[16:31], v[42:45], v[184:187], v[16:31]
	v_bitop3_b32 v46, v65, v145, 24 bitop3:0x78
	v_lshlrev_b32_e32 v46, 1, v46
	v_add3_u32 v46, v182, v46, s2
	v_cvt_pk_bf16_f32 v42, v47, v55
	v_cvt_pk_bf16_f32 v43, v58, v62
	v_cvt_pk_bf16_f32 v44, v78, v90
	v_cvt_pk_bf16_f32 v45, v95, v120
	ds_read_b64 v[184:185], v46 offset:55296
	v_bitop3_b32 v46, v66, v145, 24 bitop3:0x78
	v_lshlrev_b32_e32 v46, 1, v46
	v_add3_u32 v46, v182, v46, s2
	ds_read_b64 v[186:187], v46 offset:55296
	v_bitop3_b32 v46, v183, v65, 56 bitop3:0x6c
	v_lshlrev_b32_e32 v46, 1, v46
	v_add3_u32 v46, v182, v46, s2
	v_add_u32_e32 v46, 0x13a00, v46
	s_waitcnt lgkmcnt(0)
	v_mfma_f32_32x32x16_bf16 v[0:15], v[42:45], v[184:187], v[0:15]
	ds_read_b64 v[184:185], v46
	v_bitop3_b32 v46, v183, v66, 56 bitop3:0x6c
	v_lshlrev_b32_e32 v46, 1, v46
	v_add3_u32 v46, v182, v46, s2
	v_add_u32_e32 v46, 0x13a00, v46
	ds_read_b64 v[186:187], v46
	s_waitcnt lgkmcnt(0)
	v_mfma_f32_32x32x16_bf16 v[16:31], v[42:45], v[184:187], v[16:31]
	v_bitop3_b32 v46, v64, v145, 24 bitop3:0x78
	v_lshlrev_b32_e32 v46, 1, v46
	v_add3_u32 v46, v182, v46, s2
	v_cvt_pk_bf16_f32 v42, v56, v59
	v_cvt_pk_bf16_f32 v43, v63, v72
	v_cvt_pk_bf16_f32 v44, v91, v116
	v_cvt_pk_bf16_f32 v45, v121, v148
	ds_read_b64 v[54:55], v46 offset:55296
	v_bitop3_b32 v46, v52, v145, 24 bitop3:0x78
	v_lshlrev_b32_e32 v46, 1, v46
	v_add3_u32 v46, v182, v46, s2
	ds_read_b64 v[56:57], v46 offset:55296
	v_bitop3_b32 v46, v183, v64, 56 bitop3:0x6c
	v_lshlrev_b32_e32 v46, 1, v46
	v_add3_u32 v46, v182, v46, s2
	v_add_u32_e32 v46, 0x13a00, v46
	s_waitcnt lgkmcnt(0)
	v_mfma_f32_32x32x16_bf16 v[0:15], v[42:45], v[54:57], v[0:15]
	ds_read_b64 v[54:55], v46
	v_bitop3_b32 v46, v183, v52, 56 bitop3:0x6c
	v_lshlrev_b32_e32 v46, 1, v46
	v_add3_u32 v46, v182, v46, s2
	v_add_u32_e32 v46, 0x13a00, v46
	ds_read_b64 v[56:57], v46
	s_waitcnt lgkmcnt(0)
	v_mfma_f32_32x32x16_bf16 v[16:31], v[42:45], v[54:57], v[16:31]
	v_bitop3_b32 v46, v49, v145, 24 bitop3:0x78
	v_lshlrev_b32_e32 v46, 1, v46
	v_add3_u32 v46, v182, v46, s2
	v_cvt_pk_bf16_f32 v42, v60, v68
	v_cvt_pk_bf16_f32 v43, v73, v79
	v_cvt_pk_bf16_f32 v44, v117, v124
	v_cvt_pk_bf16_f32 v45, v149, v156
	ds_read_b64 v[52:53], v46 offset:55296
	v_bitop3_b32 v46, v51, v145, 24 bitop3:0x78
	v_lshlrev_b32_e32 v46, 1, v46
	v_add3_u32 v46, v182, v46, s2
	ds_read_b64 v[54:55], v46 offset:55296
	v_bitop3_b32 v46, v183, v49, 56 bitop3:0x6c
	v_lshlrev_b32_e32 v46, 1, v46
	v_add3_u32 v46, v182, v46, s2
	v_add_u32_e32 v46, 0x13a00, v46
	s_waitcnt lgkmcnt(0)
	v_mfma_f32_32x32x16_bf16 v[0:15], v[42:45], v[52:55], v[0:15]
	ds_read_b64 v[52:53], v46
	v_bitop3_b32 v46, v183, v51, 56 bitop3:0x6c
	v_lshlrev_b32_e32 v46, 1, v46
	v_add3_u32 v46, v182, v46, s2
	v_add_u32_e32 v46, 0x13a00, v46
	ds_read_b64 v[54:55], v46
	s_waitcnt lgkmcnt(0)
; #define LAS __attribute__((address_space(3)))
; __device__ __forceinline__ unsigned cvt_pk_bf16(float lo, float hi) { unsigned r; asm volatile("v_cvt_pk_bf16_f32 %0, %1, %2" : "=v"(r) : "v"(lo), "v"(hi)); return r; }
; __device__ __forceinline__ void attn_macro(const Params& p, int l, LAS unsigned char* lds, int b, int cg, int kvh) {
;     ...
;         for (int kt = 0; kt < 6; ++kt)
; #pragma unroll
;             for (int jj = 0; jj < 2; ++jj) {
;                 u32x4 pw;
;                 pw.x = cvt_pk_bf16(s[kt][8 * jj + 0], s[kt][8 * jj + 1]); pw.y = cvt_pk_bf16(s[kt][8 * jj + 2], s[kt][8 * jj + 3]);
;                 pw.z = cvt_pk_bf16(s[kt][8 * jj + 4], s[kt][8 * jj + 5]); pw.w = cvt_pk_bf16(s[kt][8 * jj + 6], s[kt][8 * jj + 7]);
;                 const bf16x8 pa = __builtin_bit_cast(bf16x8, pw);
;                 const int e0 = 32 * kt + 16 * jj + 4 * hi;
; #pragma unroll
;                 for (int db = 0; db < 2; ++db) {
;                     const int sw = (((db * 32 + q32) >> 3) & 7) << 3;
;                     const LAS bf16_t* vrow = Vt + (db * 32 + q32) * MV_LD + ci * 64;
;                     const u32x2 lo = *(const LAS u32x2*)(vrow + (e0 ^ sw)), hi2 = *(const LAS u32x2*)(vrow + ((e0 + 8) ^ sw));
;                     const bf16x8 vb = __builtin_bit_cast(bf16x8, (u32x4){lo.x, lo.y, hi2.x, hi2.y});
;                     o[db] = __builtin_amdgcn_mfma_f32_32x32x16_bf16(pa, vb, o[db], 0, 0, 0);
;                 }
;                 __builtin_amdgcn_sched_barrier(0);
;             }
	v_mfma_f32_32x32x16_bf16 v[16:31], v[42:45], v[52:55], v[16:31]
	v_bitop3_b32 v46, v48, v145, 24 bitop3:0x78
	v_lshlrev_b32_e32 v46, 1, v46
	v_add3_u32 v46, v182, v46, s2
	v_cvt_pk_bf16_f32 v42, v69, v75
	v_cvt_pk_bf16_f32 v43, v85, v92
	v_cvt_pk_bf16_f32 v44, v125, v152
	v_cvt_pk_bf16_f32 v45, v157, v163
	ds_read_b64 v[52:53], v46 offset:55296
	v_bitop3_b32 v46, v50, v145, 24 bitop3:0x78
	v_lshlrev_b32_e32 v46, 1, v46
	v_add3_u32 v46, v182, v46, s2
	ds_read_b64 v[54:55], v46 offset:55296
	v_bitop3_b32 v46, v183, v48, 56 bitop3:0x6c
	v_bitop3_b32 v48, v183, v50, 56 bitop3:0x6c
	v_lshlrev_b32_e32 v46, 1, v46
	v_lshlrev_b32_e32 v48, 1, v48
	v_add3_u32 v46, v182, v46, s2
	v_add3_u32 v48, v182, v48, s2
	v_add_u32_e32 v46, 0x13a00, v46
	v_add_u32_e32 v48, 0x13a00, v48
	ds_read_b64 v[46:47], v46
	ds_read_b64 v[48:49], v48
	s_waitcnt lgkmcnt(0)
	v_mfma_f32_32x32x16_bf16 v[0:15], v[42:45], v[52:55], v[0:15]
	v_mfma_f32_32x32x16_bf16 v[16:31], v[42:45], v[46:49], v[16:31]
	v_bitop3_b32 v46, v39, v145, 24 bitop3:0x78
	v_bitop3_b32 v48, v41, v145, 24 bitop3:0x78
	v_lshlrev_b32_e32 v46, 1, v46
	v_lshlrev_b32_e32 v48, 1, v48
	v_add3_u32 v46, v182, v46, s2
	v_add3_u32 v48, v182, v48, s2
	v_cvt_pk_bf16_f32 v42, v76, v88
	v_cvt_pk_bf16_f32 v43, v93, v118
	v_cvt_pk_bf16_f32 v44, v153, v159
	v_cvt_pk_bf16_f32 v45, v164, v168
	ds_read_b64 v[46:47], v46 offset:55296
	ds_read_b64 v[48:49], v48 offset:55296
	v_bitop3_b32 v39, v183, v39, 56 bitop3:0x6c
	v_lshlrev_b32_e32 v39, 1, v39
	v_add3_u32 v39, v182, v39, s2
	v_add_u32_e32 v39, 0x13a00, v39
	s_waitcnt lgkmcnt(0)
	v_mfma_f32_32x32x16_bf16 v[0:15], v[42:45], v[46:49], v[0:15]
	ds_read_b64 v[46:47], v39
	v_bitop3_b32 v39, v183, v41, 56 bitop3:0x6c
	v_lshlrev_b32_e32 v39, 1, v39
	v_add3_u32 v39, v182, v39, s2
	v_add_u32_e32 v39, 0x13a00, v39
	ds_read_b64 v[48:49], v39
	s_waitcnt lgkmcnt(0)
	v_mfma_f32_32x32x16_bf16 v[16:31], v[42:45], v[46:49], v[16:31]
	v_bitop3_b32 v39, v37, v145, 24 bitop3:0x78
	v_lshlrev_b32_e32 v39, 1, v39
	v_add3_u32 v39, v182, v39, s2
	v_cvt_pk_bf16_f32 v42, v89, v114
	v_cvt_pk_bf16_f32 v43, v119, v146
	v_cvt_pk_bf16_f32 v44, v160, v165
	v_cvt_pk_bf16_f32 v45, v169, v172
	ds_read_b64 v[46:47], v39 offset:55296
	v_bitop3_b32 v39, v40, v145, 24 bitop3:0x78
	v_lshlrev_b32_e32 v39, 1, v39
	v_add3_u32 v39, v182, v39, s2
	ds_read_b64 v[48:49], v39 offset:55296
	v_bitop3_b32 v37, v183, v37, 56 bitop3:0x6c
	v_lshlrev_b32_e32 v37, 1, v37
	v_add3_u32 v37, v182, v37, s2
	v_add_u32_e32 v37, 0x13a00, v37
	s_waitcnt lgkmcnt(0)
	v_mfma_f32_32x32x16_bf16 v[0:15], v[42:45], v[46:49], v[0:15]
	ds_read_b64 v[46:47], v37
	v_bitop3_b32 v37, v183, v40, 56 bitop3:0x6c
	v_lshlrev_b32_e32 v37, 1, v37
	v_add3_u32 v37, v182, v37, s2
	v_add_u32_e32 v37, 0x13a00, v37
	ds_read_b64 v[48:49], v37
	s_waitcnt lgkmcnt(0)
	v_mfma_f32_32x32x16_bf16 v[16:31], v[42:45], v[46:49], v[16:31]
	v_bitop3_b32 v37, v35, v145, 24 bitop3:0x78
	v_lshlrev_b32_e32 v37, 1, v37
	v_add3_u32 v37, v182, v37, s2
	v_cvt_pk_bf16_f32 v40, v115, v122
	v_cvt_pk_bf16_f32 v41, v147, v154
	v_cvt_pk_bf16_f32 v42, v166, v170
	v_cvt_pk_bf16_f32 v43, v173, v176
	ds_read_b64 v[44:45], v37 offset:55296
	v_bitop3_b32 v37, v38, v145, 24 bitop3:0x78
	v_lshlrev_b32_e32 v37, 1, v37
	v_add3_u32 v37, v182, v37, s2
	ds_read_b64 v[46:47], v37 offset:55296
	v_bitop3_b32 v35, v183, v35, 56 bitop3:0x6c
	v_lshlrev_b32_e32 v35, 1, v35
	v_add3_u32 v35, v182, v35, s2
	v_add_u32_e32 v35, 0x13a00, v35
	s_waitcnt lgkmcnt(0)
	v_mfma_f32_32x32x16_bf16 v[0:15], v[40:43], v[44:47], v[0:15]
	ds_read_b64 v[44:45], v35
	v_bitop3_b32 v35, v183, v38, 56 bitop3:0x6c
	v_lshlrev_b32_e32 v35, 1, v35
	v_add3_u32 v35, v182, v35, s2
	v_add_u32_e32 v35, 0x13a00, v35
	ds_read_b64 v[46:47], v35
	s_waitcnt lgkmcnt(0)
	v_mfma_f32_32x32x16_bf16 v[16:31], v[40:43], v[44:47], v[16:31]
	v_bitop3_b32 v35, v33, v145, 24 bitop3:0x78
	v_lshlrev_b32_e32 v35, 1, v35
	v_add3_u32 v35, v182, v35, s2
	v_cvt_pk_bf16_f32 v38, v123, v150
	v_cvt_pk_bf16_f32 v39, v155, v161
	v_cvt_pk_bf16_f32 v40, v171, v174
	v_cvt_pk_bf16_f32 v41, v177, v179
	ds_read_b64 v[42:43], v35 offset:55296
	v_bitop3_b32 v35, v36, v145, 24 bitop3:0x78
	v_lshlrev_b32_e32 v35, 1, v35
	v_add3_u32 v35, v182, v35, s2
	ds_read_b64 v[44:45], v35 offset:55296
	v_bitop3_b32 v33, v183, v33, 56 bitop3:0x6c
	v_lshlrev_b32_e32 v33, 1, v33
	v_add3_u32 v33, v182, v33, s2
	v_add_u32_e32 v33, 0x13a00, v33
	s_waitcnt lgkmcnt(0)
	v_mfma_f32_32x32x16_bf16 v[0:15], v[38:41], v[42:45], v[0:15]
	ds_read_b64 v[42:43], v33
	v_bitop3_b32 v33, v183, v36, 56 bitop3:0x6c
	v_lshlrev_b32_e32 v33, 1, v33
	v_add3_u32 v33, v182, v33, s2
	v_add_u32_e32 v33, 0x13a00, v33
	ds_read_b64 v[44:45], v33
	s_waitcnt lgkmcnt(0)
	v_mfma_f32_32x32x16_bf16 v[16:31], v[38:41], v[42:45], v[16:31]
	v_bitop3_b32 v33, v32, v145, 24 bitop3:0x78
	v_lshlrev_b32_e32 v33, 1, v33
	v_add3_u32 v33, v182, v33, s2
	v_cvt_pk_bf16_f32 v36, v151, v158
	v_cvt_pk_bf16_f32 v37, v162, v167
	v_cvt_pk_bf16_f32 v38, v175, v178
	v_cvt_pk_bf16_f32 v39, v180, v181
	ds_read_b64 v[40:41], v33 offset:55296
	v_bitop3_b32 v33, v34, v145, 24 bitop3:0x78
	v_bitop3_b32 v32, v183, v32, 56 bitop3:0x6c
	v_bitop3_b32 v34, v183, v34, 56 bitop3:0x6c
	v_lshlrev_b32_e32 v32, 1, v32
	v_lshlrev_b32_e32 v34, 1, v34
	v_lshlrev_b32_e32 v33, 1, v33
	v_add3_u32 v32, v182, v32, s2
	v_add3_u32 v34, v182, v34, s2
	v_add3_u32 v33, v182, v33, s2
	v_add_u32_e32 v32, 0x13a00, v32
	v_add_u32_e32 v34, 0x13a00, v34
	ds_read_b64 v[42:43], v33 offset:55296
	ds_read_b64 v[32:33], v32
	ds_read_b64 v[34:35], v34
	s_waitcnt lgkmcnt(0)
; #define LAS __attribute__((address_space(3)))
; __device__ __forceinline__ unsigned cvt_pk_bf16(float lo, float hi) { unsigned r; asm volatile("v_cvt_pk_bf16_f32 %0, %1, %2" : "=v"(r) : "v"(lo), "v"(hi)); return r; }
; __device__ __forceinline__ int crow(int r, int hi) { return (r & 3) + 8 * (r >> 2) + 4 * hi; }
; __device__ __forceinline__ void attn_macro(const Params& p, int l, LAS unsigned char* lds, int b, int cg, int kvh) {
;     ...
;         asm volatile("s_waitcnt lgkmcnt(0)" ::: "memory");
;         LAS bf16_t* ost = (LAS bf16_t*)(lds + M_OST) + wid * (32 * 72);
; #pragma unroll
;         for (int r = 0; r < 16; ++r) {
;             const int qq = crow(r, hi);
;             const float inv = wsc[qq];
; #pragma unroll
;             for (int db = 0; db < 2; ++db) ost[qq * 72 + db * 32 + q32] = (bf16_t)(cvt_pk_bf16(o[db][r] * inv, 0.f) & 0xffffu);
;         }
;         asm volatile("s_waitcnt lgkmcnt(0)" ::: "memory");
; #pragma unroll
;         for (int i = 0; i < 4; ++i) {
;             const int row = i * 8 + (lane >> 3), chn = lane & 7;
;             const u32x4 v = *(const LAS u32x4*)(ost + row * 72 + chn * 8);
;             *(u32x4*)(AD + (size_t)(row0 + half * 32 + row) * DM + h * 64 + chn * 8) = v;
;         }
	v_mfma_f32_32x32x16_bf16 v[0:15], v[36:39], v[40:43], v[0:15]
	v_mfma_f32_32x32x16_bf16 v[16:31], v[36:39], v[32:35], v[16:31]
	s_waitcnt lgkmcnt(0)
	v_lshl_add_u32 v36, v96, 2, s9
	ds_read_b32 v33, v36
	v_lshl_add_u32 v32, v144, 1, s11
	s_movk_i32 s2, 0x240
	s_movk_i32 s27, 0x90
	s_add_i32 s96, s16, s17
	s_waitcnt lgkmcnt(0)
	s_nop 3
	v_mul_f32_e32 v0, v0, v33
	v_mad_u64_u32 v[34:35], s[2:3], v143, s2, v[32:33]
	v_cvt_pk_bf16_f32 v0, v0, v97
	ds_write_b16 v34, v0
	v_mul_f32_e32 v0, v16, v33
	v_cvt_pk_bf16_f32 v0, v0, v97
	ds_read_b32 v16, v36 offset:4
	ds_write_b16 v34, v0 offset:64
	v_mad_u64_u32 v[32:33], s[2:3], v80, s27, v[32:33]
	s_addk_i32 s25, 0x80
	s_waitcnt lgkmcnt(0)
	v_mul_f32_e32 v0, v1, v16
	v_cvt_pk_bf16_f32 v0, v0, v97
	ds_write_b16 v32, v0
	v_mul_f32_e32 v0, v17, v16
	v_cvt_pk_bf16_f32 v0, v0, v97
	ds_read_b32 v1, v36 offset:8
	ds_write_b16 v32, v0 offset:64
	s_add_i32 s17, s17, 64
	s_sub_i32 s13, s13, 64
	s_add_i32 s10, s10, 1
	s_waitcnt lgkmcnt(0)
	v_mul_f32_e32 v0, v2, v1
	v_cvt_pk_bf16_f32 v0, v0, v97
	ds_write_b16 v32, v0 offset:144
	v_mul_f32_e32 v0, v18, v1
	v_cvt_pk_bf16_f32 v0, v0, v97
	ds_read_b32 v1, v36 offset:12
	ds_write_b16 v32, v0 offset:208
	s_cmpk_eq_i32 s25, 0x200
	s_waitcnt lgkmcnt(0)
	v_mul_f32_e32 v0, v3, v1
	v_cvt_pk_bf16_f32 v0, v0, v97
	ds_write_b16 v32, v0 offset:288
	v_mul_f32_e32 v0, v19, v1
	v_cvt_pk_bf16_f32 v0, v0, v97
	ds_read_b32 v1, v36 offset:32
	ds_write_b16 v32, v0 offset:352
	s_waitcnt lgkmcnt(0)
	v_mul_f32_e32 v0, v4, v1
	v_cvt_pk_bf16_f32 v0, v0, v97
	ds_write_b16 v32, v0 offset:1008
	v_mul_f32_e32 v0, v20, v1
	v_cvt_pk_bf16_f32 v0, v0, v97
	ds_read_b32 v1, v36 offset:36
	ds_write_b16 v32, v0 offset:1072
	s_waitcnt lgkmcnt(0)
	v_mul_f32_e32 v0, v5, v1
	v_cvt_pk_bf16_f32 v0, v0, v97
	ds_write_b16 v32, v0 offset:1152
	v_mul_f32_e32 v0, v21, v1
	v_cvt_pk_bf16_f32 v0, v0, v97
	ds_read_b32 v1, v36 offset:40
	ds_write_b16 v32, v0 offset:1216
	v_lshl_add_u64 v[4:5], s[96:97], 0, v[126:127]
	v_lshlrev_b64 v[4:5], 11, v[4:5]
	v_lshl_add_u64 v[4:5], v[128:129], 0, v[4:5]
	s_waitcnt lgkmcnt(0)
	v_mul_f32_e32 v0, v6, v1
	v_cvt_pk_bf16_f32 v0, v0, v97
	ds_write_b16 v32, v0 offset:1296
	v_mul_f32_e32 v0, v22, v1
	v_cvt_pk_bf16_f32 v0, v0, v97
	ds_read_b32 v1, v36 offset:44
	ds_write_b16 v32, v0 offset:1360
	s_waitcnt lgkmcnt(0)
	v_mul_f32_e32 v0, v7, v1
	v_cvt_pk_bf16_f32 v0, v0, v97
	ds_write_b16 v32, v0 offset:1440
	v_mul_f32_e32 v0, v23, v1
	v_cvt_pk_bf16_f32 v0, v0, v97
	ds_read_b32 v1, v36 offset:64
	ds_write_b16 v32, v0 offset:1504
	s_waitcnt lgkmcnt(0)
	v_mul_f32_e32 v0, v8, v1
	v_cvt_pk_bf16_f32 v0, v0, v97
	ds_write_b16 v32, v0 offset:2160
	v_mul_f32_e32 v0, v24, v1
	v_cvt_pk_bf16_f32 v0, v0, v97
	ds_read_b32 v1, v36 offset:68
	ds_write_b16 v32, v0 offset:2224
	s_waitcnt lgkmcnt(0)
	v_mul_f32_e32 v0, v9, v1
	v_cvt_pk_bf16_f32 v0, v0, v97
	ds_write_b16 v32, v0 offset:2304
	v_mul_f32_e32 v0, v25, v1
	v_cvt_pk_bf16_f32 v0, v0, v97
	ds_read_b32 v1, v36 offset:72
	ds_write_b16 v32, v0 offset:2368
	s_waitcnt lgkmcnt(0)
	v_mul_f32_e32 v0, v10, v1
	v_cvt_pk_bf16_f32 v0, v0, v97
	ds_write_b16 v32, v0 offset:2448
	v_mul_f32_e32 v0, v26, v1
	v_cvt_pk_bf16_f32 v0, v0, v97
	ds_read_b32 v1, v36 offset:76
	ds_write_b16 v32, v0 offset:2512
	s_waitcnt lgkmcnt(0)
	v_mul_f32_e32 v0, v11, v1
	v_cvt_pk_bf16_f32 v0, v0, v97
	ds_write_b16 v32, v0 offset:2592
	v_mul_f32_e32 v0, v27, v1
	v_cvt_pk_bf16_f32 v0, v0, v97
	ds_read_b32 v1, v36 offset:96
	ds_write_b16 v32, v0 offset:2656
	s_waitcnt lgkmcnt(0)
	v_mul_f32_e32 v0, v12, v1
	v_cvt_pk_bf16_f32 v0, v0, v97
	ds_write_b16 v32, v0 offset:3312
	v_mul_f32_e32 v0, v28, v1
	v_cvt_pk_bf16_f32 v0, v0, v97
	ds_read_b32 v1, v36 offset:100
	ds_write_b16 v32, v0 offset:3376
	s_waitcnt lgkmcnt(0)
	v_mul_f32_e32 v0, v13, v1
	v_cvt_pk_bf16_f32 v0, v0, v97
	ds_write_b16 v32, v0 offset:3456
	v_mul_f32_e32 v0, v29, v1
	v_cvt_pk_bf16_f32 v0, v0, v97
	ds_read_b32 v1, v36 offset:104
	ds_write_b16 v32, v0 offset:3520
	s_waitcnt lgkmcnt(0)
	v_mul_f32_e32 v0, v14, v1
	v_cvt_pk_bf16_f32 v0, v0, v97
	ds_write_b16 v32, v0 offset:3600
	v_mul_f32_e32 v0, v30, v1
	v_cvt_pk_bf16_f32 v0, v0, v97
	ds_read_b32 v1, v36 offset:108
	ds_write_b16 v32, v0 offset:3664
	s_waitcnt lgkmcnt(0)
	v_mul_f32_e32 v0, v15, v1
	v_cvt_pk_bf16_f32 v0, v0, v97
	ds_write_b16 v32, v0 offset:3744
	v_mul_f32_e32 v0, v31, v1
	v_cvt_pk_bf16_f32 v0, v0, v97
	ds_write_b16 v32, v0 offset:3808
	s_waitcnt lgkmcnt(0)
	ds_read_b128 v[0:3], v142
	s_waitcnt lgkmcnt(0)
	global_store_dwordx4 v[4:5], v[0:3], off nt
	ds_read_b128 v[0:3], v142 offset:1152
	v_lshl_add_u64 v[4:5], s[96:97], 0, v[130:131]
	v_lshlrev_b64 v[4:5], 11, v[4:5]
	v_lshl_add_u64 v[4:5], v[128:129], 0, v[4:5]
	s_waitcnt lgkmcnt(0)
	global_store_dwordx4 v[4:5], v[0:3], off nt
	ds_read_b128 v[0:3], v142 offset:2304
	v_lshl_add_u64 v[4:5], s[96:97], 0, v[132:133]
	v_lshlrev_b64 v[4:5], 11, v[4:5]
	v_lshl_add_u64 v[4:5], v[128:129], 0, v[4:5]
	s_waitcnt lgkmcnt(0)
	global_store_dwordx4 v[4:5], v[0:3], off nt
	ds_read_b128 v[0:3], v142 offset:3456
	v_lshl_add_u64 v[4:5], s[96:97], 0, v[134:135]
	v_lshlrev_b64 v[4:5], 11, v[4:5]
	v_lshl_add_u64 v[4:5], v[128:129], 0, v[4:5]
	s_waitcnt lgkmcnt(0)
	global_store_dwordx4 v[4:5], v[0:3], off nt
	s_waitcnt lgkmcnt(0)
	s_cbranch_scc1 .LBB0_318

; __device__ __forceinline__ void unpack8(const u32x4 w, float* f) { f[0] = bf_lo(w.x); f[1] = bf_hi(w.x); f[2] = bf_lo(w.y); f[3] = bf_hi(w.y); f[4] = bf_lo(w.z); f[5] = bf_hi(w.z); f[6] = bf_lo(w.w); f[7] = bf_hi(w.w); }
; __device__ __forceinline__ u32x4 pack8(const float* f) { u32x4 w; w.x = cvt_pk_bf16(f[0], f[1]); w.y = cvt_pk_bf16(f[2], f[3]); w.z = cvt_pk_bf16(f[4], f[5]); w.w = cvt_pk_bf16(f[6], f[7]); return w; }
; template <int W>
; __device__ __forceinline__ void pool_task_prompt(const Params& p, int l, int b, int c, int g, int rg, int ch, long row0) {
;     ...
;     const int col = g * 128 + ch * 8, tl0 = 4 * rg, t0 = c * 64 + tl0;
;     u32x4 raw[W + 3];
; #pragma unroll
;     for (int i = 0; i < W + 3; ++i) { const int tt = t0 - (W - 1) + i; raw[i] = (u32x4){0u, 0u, 0u, 0u};
;         if (tt >= 0) raw[i] = *(const u32x4*)(P + (size_t)((long)b * SEQ + tt) * INW + 768 + col); }
;     float a[4][8], cur[4][8];
; #pragma unroll
;     for (int k = 0; k < 8; ++k) a[0][k] = 0.f;
; #pragma unroll
;     for (int i = 0; i < W; ++i) { float x[8]; unpack8(raw[i], x);
; #pragma unroll
;         for (int k = 0; k < 8; ++k) { a[0][k] += x[k]; if (i == W - 1) cur[0][k] = x[k]; } }
; #pragma unroll
;     for (int r = 1; r < 4; ++r) { float xin[8], xout[8]; unpack8(raw[W - 1 + r], xin); unpack8(raw[r - 1], xout);
; #pragma unroll
;         for (int k = 0; k < 8; ++k) { a[r][k] = a[r - 1][k] + (xin[k] - xout[k]); cur[r][k] = xin[k]; } }
; #pragma unroll
;     for (int r = 0; r < 4; ++r) {
;         const int t = t0 + r;
;         const float inv = 1.0f / (float)((t + 1) < W ? (t + 1) : W);
;         float d[8];
; #pragma unroll
;         for (int k = 0; k < 8; ++k) d[k] = a[r][k] * inv - cur[r][k];
;         *(u32x4*)(AD + (size_t)(row0 + tl0 + r) * DM + 512 + col) = pack8(d);
;         if (t >= SEQ - 15) { float* pd = p.out + O_PP + (((size_t)l * 2 + b) * 15 + (t - (SEQ - 15))) * 512 + col;
;             *(f32x4*)pd = (f32x4){cur[r][0], cur[r][1], cur[r][2], cur[r][3]}; *(f32x4*)(pd + 4) = (f32x4){cur[r][4], cur[r][5], cur[r][6], cur[r][7]}; }
.LBB0_337:
	s_or_b64 exec, exec, s[14:15]
	v_lshl_add_u64 v[0:1], s[86:87], 0, v[96:97]
	v_mov_b32_e32 v41, v97
	v_lshl_add_u64 v[0:1], v[0:1], 0, v[40:41]
	v_add_co_u32_e32 v2, vcc, 0xfb00000, v0
	s_waitcnt vmcnt(0) lgkmcnt(0)
	v_lshlrev_b32_e32 v61, 16, v12
	v_addc_co_u32_e32 v3, vcc, 0, v1, vcc
	v_add_co_u32_e32 v8, vcc, 0xfb02000, v0
	v_and_b32_e32 v62, 0xffff0000, v12
	s_nop 0
	v_addc_co_u32_e32 v9, vcc, 0, v1, vcc
	global_load_dwordx4 v[64:67], v[2:3], off offset:1536
	global_load_dwordx4 v[24:27], v[8:9], off
	v_add_co_u32_e32 v2, vcc, 0xfb03000, v0
	v_lshlrev_b32_e32 v60, 16, v13
	s_nop 0
	v_addc_co_u32_e32 v3, vcc, 0, v1, vcc
	v_add_co_u32_e32 v0, vcc, 0xfb05000, v0
	v_and_b32_e32 v59, 0xffff0000, v13
	s_nop 0
	v_addc_co_u32_e32 v1, vcc, 0, v1, vcc
	global_load_dwordx4 v[8:11], v[2:3], off offset:2560
	s_nop 0
	global_load_dwordx4 v[0:3], v[0:1], off offset:1024
	v_lshlrev_b32_e32 v58, 16, v14
	v_and_b32_e32 v57, 0xffff0000, v14
	v_lshlrev_b32_e32 v56, 16, v15
	v_and_b32_e32 v55, 0xffff0000, v15
	v_add_f32_e32 v13, 0, v61
	v_add_f32_e32 v12, 0, v62
	v_lshlrev_b32_e32 v53, 16, v4
	v_and_b32_e32 v54, 0xffff0000, v4
	v_add_f32_e32 v14, 0, v60
	v_add_f32_e32 v15, 0, v59
	v_add_f32_e32 v42, 0, v58
	v_add_f32_e32 v43, 0, v57
	v_add_f32_e32 v44, 0, v56
	v_add_f32_e32 v45, 0, v55
	v_lshlrev_b32_e32 v52, 16, v5
	v_and_b32_e32 v51, 0xffff0000, v5
	v_lshlrev_b32_e32 v50, 16, v6
	v_and_b32_e32 v49, 0xffff0000, v6
	v_lshlrev_b32_e32 v48, 16, v7
	v_and_b32_e32 v47, 0xffff0000, v7
	v_add_f32_e32 v5, v13, v53
	v_add_f32_e32 v4, v12, v54
	v_lshlrev_b32_e32 v46, 16, v20
	v_and_b32_e32 v20, 0xffff0000, v20
	v_add_f32_e32 v6, v14, v52
	v_add_f32_e32 v7, v15, v51
	v_add_f32_e32 v12, v42, v50
	v_add_f32_e32 v13, v43, v49
	v_add_f32_e32 v14, v44, v48
	v_add_f32_e32 v15, v45, v47
	v_lshlrev_b32_e32 v45, 16, v21
	v_and_b32_e32 v44, 0xffff0000, v21
	v_lshlrev_b32_e32 v43, 16, v22
	v_and_b32_e32 v42, 0xffff0000, v22
	v_lshlrev_b32_e32 v22, 16, v23
	v_and_b32_e32 v21, 0xffff0000, v23
	v_add_f32_e32 v5, v5, v46
	v_add_f32_e32 v4, v4, v20
	v_lshlrev_b32_e32 v23, 16, v16
	v_and_b32_e32 v16, 0xffff0000, v16
	v_add_f32_e32 v5, v5, v23
	v_add_f32_e32 v4, v4, v16
	v_lshlrev_b32_e32 v16, 16, v32
	v_add_f32_e32 v12, v12, v43
	v_add_f32_e32 v15, v15, v21
	v_lshlrev_b32_e32 v68, 16, v18
	v_lshlrev_b32_e32 v69, 16, v19
	v_and_b32_e32 v19, 0xffff0000, v19
	v_add_f32_e32 v5, v5, v16
	v_and_b32_e32 v16, 0xffff0000, v32
	v_add_f32_e32 v12, v12, v68
	v_add_f32_e32 v15, v15, v19
	v_lshlrev_b32_e32 v19, 16, v34
	v_add_f32_e32 v4, v4, v16
	v_lshlrev_b32_e32 v16, 16, v28
	v_add_f32_e32 v12, v12, v19
	v_lshlrev_b32_e32 v19, 16, v30
	v_add_f32_e32 v5, v5, v16
	v_and_b32_e32 v16, 0xffff0000, v28
	v_add_f32_e32 v4, v4, v16
	v_add_f32_e32 v12, v12, v19
	v_lshlrev_b32_e32 v16, 16, v36
	v_lshlrev_b32_e32 v19, 16, v38
	v_add_f32_e32 v16, v5, v16
	v_add_f32_e32 v19, v12, v19
	v_add_f32_e32 v6, v6, v45
	v_add_f32_e32 v7, v7, v44
	s_waitcnt vmcnt(0) lgkmcnt(0)
	v_lshlrev_b32_e32 v12, 16, v64
	v_add_f32_e32 v32, v16, v12
	v_min_i32_e32 v16, 7, v101
	v_add_f32_e32 v13, v13, v42
	v_add_f32_e32 v14, v14, v22
	v_lshlrev_b32_e32 v63, 16, v17
	v_and_b32_e32 v17, 0xffff0000, v17
	v_and_b32_e32 v18, 0xffff0000, v18
	v_add_u32_e32 v16, 1, v16
	v_add_f32_e32 v6, v6, v63
	v_add_f32_e32 v7, v7, v17
	v_add_f32_e32 v13, v13, v18
	v_add_f32_e32 v14, v14, v69
	v_lshlrev_b32_e32 v17, 16, v33
	v_and_b32_e32 v18, 0xffff0000, v33
	v_lshlrev_b32_e32 v33, 16, v35
	v_cvt_f32_u32_e32 v16, v16
	v_and_b32_e32 v23, 0xffff0000, v34
	v_and_b32_e32 v34, 0xffff0000, v35
	v_add_f32_e32 v6, v6, v17
	v_add_f32_e32 v7, v7, v18
	v_add_f32_e32 v14, v14, v33
	v_lshlrev_b32_e32 v17, 16, v29
	v_and_b32_e32 v18, 0xffff0000, v29
	v_lshlrev_b32_e32 v29, 16, v31
	v_add_f32_e32 v13, v13, v23
	v_add_f32_e32 v15, v15, v34
	v_and_b32_e32 v23, 0xffff0000, v30
	v_and_b32_e32 v30, 0xffff0000, v31
	v_add_f32_e32 v6, v6, v17
	v_add_f32_e32 v14, v14, v29
	v_lshlrev_b32_e32 v17, 16, v37
	v_lshlrev_b32_e32 v28, 16, v39
	v_add_f32_e32 v7, v7, v18
	v_add_f32_e32 v15, v15, v30
	v_and_b32_e32 v18, 0xffff0000, v37
	v_and_b32_e32 v29, 0xffff0000, v39
	v_add_f32_e32 v17, v6, v17
	v_add_f32_e32 v28, v14, v28
	v_lshlrev_b32_e32 v14, 16, v65
	v_add_f32_e32 v18, v7, v18
	v_add_f32_e32 v35, v15, v29
	v_and_b32_e32 v15, 0xffff0000, v65
	v_add_f32_e32 v29, v17, v14
	v_div_scale_f32 v17, s[0:1], v16, v16, 1.0
	v_add_f32_e32 v34, v18, v15
	v_rcp_f32_e32 v18, v17
	v_and_b32_e32 v5, 0xffff0000, v36
	v_add_f32_e32 v30, v4, v5
	v_lshlrev_b32_e32 v4, 16, v66
	v_add_f32_e32 v13, v13, v23
	v_and_b32_e32 v23, 0xffff0000, v38
	v_add_f32_e32 v33, v19, v4
	v_fma_f32 v19, -v17, v18, 1.0
	v_add_f32_e32 v23, v13, v23
	v_and_b32_e32 v13, 0xffff0000, v64
	v_and_b32_e32 v5, 0xffff0000, v66
	v_and_b32_e32 v7, 0xffff0000, v67
	v_fmac_f32_e32 v18, v19, v18
	v_div_scale_f32 v19, vcc, 1.0, v16, 1.0
	v_add_f32_e32 v31, v30, v13
	v_add_f32_e32 v30, v23, v5
	v_add_f32_e32 v23, v35, v7
	v_mul_f32_e32 v35, v19, v18
	v_fma_f32 v36, -v17, v35, v19
	v_fmac_f32_e32 v35, v36, v18
	v_fma_f32 v17, -v17, v35, v19
	v_lshlrev_b32_e32 v6, 16, v67
	v_div_fmas_f32 v17, v17, v18, v35
	v_add_f32_e32 v28, v28, v6
	v_div_fixup_f32 v16, v17, v16, 1.0
	v_fma_f32 v17, v16, v32, -v12
	v_fma_f32 v18, v16, v31, -v13
	v_fma_f32 v19, v16, v29, -v14
	v_fma_f32 v35, v16, v34, -v15
	v_fma_f32 v38, v16, v33, -v4
	v_fma_f32 v39, v16, v30, -v5
	v_fma_f32 v63, v16, v28, -v6
	v_fma_f32 v16, v16, v23, -v7
	v_mov_b32_e32 v93, v97
	v_cvt_pk_bf16_f32 v36, v17, v18
	v_cvt_pk_bf16_f32 v37, v19, v35
	v_cvt_pk_bf16_f32 v38, v38, v39
	v_cvt_pk_bf16_f32 v39, v63, v16
	v_lshl_add_u64 v[16:17], s[86:87], 0, v[92:93]
	v_lshl_add_u64 v[18:19], v[16:17], 0, v[40:41]
	v_add_co_u32_e32 v64, vcc, 0x7900000, v18
	s_movk_i32 s0, 0x3ff0
	s_nop 0
	v_addc_co_u32_e32 v65, vcc, 0, v19, vcc
	v_cmp_lt_u32_e32 vcc, s0, v101
	global_store_dwordx4 v[64:65], v[36:39], off offset:1024 nt
	s_and_saveexec_b64 s[0:1], vcc
	s_cbranch_execz .LBB0_339
	v_add_u32_e32 v35, s7, v101
	v_add_u32_e32 v36, 0xffffc00f, v35
	v_mov_b32_e32 v37, v97
	v_lshlrev_b64 v[36:37], 11, v[36:37]
	v_lshl_add_u64 v[36:37], v[88:89], 0, v[36:37]
	global_store_dwordx4 v[36:37], v[12:15], off nt
	global_store_dwordx4 v[36:37], v[4:7], off offset:16 nt
; __device__ __forceinline__ void unpack8(const u32x4 w, float* f) { f[0] = bf_lo(w.x); f[1] = bf_hi(w.x); f[2] = bf_lo(w.y); f[3] = bf_hi(w.y); f[4] = bf_lo(w.z); f[5] = bf_hi(w.z); f[6] = bf_lo(w.w); f[7] = bf_hi(w.w); }
; __device__ __forceinline__ u32x4 pack8(const float* f) { u32x4 w; w.x = cvt_pk_bf16(f[0], f[1]); w.y = cvt_pk_bf16(f[2], f[3]); w.z = cvt_pk_bf16(f[4], f[5]); w.w = cvt_pk_bf16(f[6], f[7]); return w; }
; template <int W>
; __device__ __forceinline__ void pool_task_prompt(const Params& p, int l, int b, int c, int g, int rg, int ch, long row0) {
;     ...
;     for (int r = 1; r < 4; ++r) { float xin[8], xout[8]; unpack8(raw[W - 1 + r], xin); unpack8(raw[r - 1], xout);
; #pragma unroll
;         for (int k = 0; k < 8; ++k) { a[r][k] = a[r - 1][k] + (xin[k] - xout[k]); cur[r][k] = xin[k]; } }
; #pragma unroll
;     for (int r = 0; r < 4; ++r) {
;         const int t = t0 + r;
;         const float inv = 1.0f / (float)((t + 1) < W ? (t + 1) : W);
;         float d[8];
; #pragma unroll
;         for (int k = 0; k < 8; ++k) d[k] = a[r][k] * inv - cur[r][k];
;         *(u32x4*)(AD + (size_t)(row0 + tl0 + r) * DM + 512 + col) = pack8(d);
;         if (t >= SEQ - 15) { float* pd = p.out + O_PP + (((size_t)l * 2 + b) * 15 + (t - (SEQ - 15))) * 512 + col;
;             *(f32x4*)pd = (f32x4){cur[r][0], cur[r][1], cur[r][2], cur[r][3]}; *(f32x4*)(pd + 4) = (f32x4){cur[r][4], cur[r][5], cur[r][6], cur[r][7]}; }
.LBB0_339:
	s_or_b64 exec, exec, s[0:1]
	v_lshlrev_b32_e32 v12, 16, v24
	v_and_b32_e32 v13, 0xffff0000, v24
	v_sub_f32_e32 v24, v12, v61
	v_add_f32_e32 v24, v32, v24
	v_add_u32_e32 v32, 1, v101
	v_min_i32_e32 v32, 7, v32
	v_add_u32_e32 v32, 1, v32
	v_cvt_f32_u32_e32 v32, v32
	v_lshlrev_b32_e32 v14, 16, v25
	v_lshlrev_b32_e32 v4, 16, v26
	v_and_b32_e32 v5, 0xffff0000, v26
	v_sub_f32_e32 v26, v14, v60
	v_and_b32_e32 v15, 0xffff0000, v25
	v_add_f32_e32 v26, v29, v26
	v_sub_f32_e32 v29, v4, v58
	v_lshlrev_b32_e32 v6, 16, v27
	v_and_b32_e32 v7, 0xffff0000, v27
	v_sub_f32_e32 v27, v15, v59
	v_add_f32_e32 v29, v33, v29
	v_div_scale_f32 v33, s[0:1], v32, v32, 1.0
	v_sub_f32_e32 v25, v13, v62
	v_add_f32_e32 v27, v34, v27
	v_rcp_f32_e32 v34, v33
	v_add_f32_e32 v25, v31, v25
	v_sub_f32_e32 v31, v5, v57
	v_add_f32_e32 v30, v30, v31
	v_sub_f32_e32 v31, v6, v56
	v_add_f32_e32 v28, v28, v31
	v_sub_f32_e32 v31, v7, v55
	v_add_f32_e32 v23, v23, v31
	v_fma_f32 v31, -v33, v34, 1.0
	v_fmac_f32_e32 v34, v31, v34
	v_div_scale_f32 v31, vcc, 1.0, v32, 1.0
	v_mul_f32_e32 v35, v31, v34
	v_fma_f32 v36, -v33, v35, v31
	v_fmac_f32_e32 v35, v36, v34
	v_fma_f32 v31, -v33, v35, v31
	v_div_fmas_f32 v31, v31, v34, v35
	v_div_fixup_f32 v31, v31, v32, 1.0
	v_add_co_u32_e32 v18, vcc, 0x7900000, v18
	s_movk_i32 s0, 0x3fef
	v_fma_f32 v32, v31, v24, -v12
	v_fma_f32 v33, v31, v25, -v13
	v_fma_f32 v34, v31, v26, -v14
	v_fma_f32 v35, v31, v27, -v15
	v_addc_co_u32_e32 v19, vcc, 0, v19, vcc
	v_cmp_lt_u32_e64 s[0:1], s0, v101
	v_fma_f32 v36, v31, v29, -v4
	v_fma_f32 v37, v31, v30, -v5
	v_fma_f32 v38, v31, v28, -v6
	v_fma_f32 v31, v31, v23, -v7
	v_cvt_pk_bf16_f32 v32, v32, v33
	v_cvt_pk_bf16_f32 v33, v34, v35
	v_cvt_pk_bf16_f32 v34, v36, v37
	v_cvt_pk_bf16_f32 v35, v38, v31
	global_store_dwordx4 v[18:19], v[32:35], off offset:3072 nt
	s_and_saveexec_b64 s[14:15], s[0:1]
	s_cbranch_execz .LBB0_341
	v_add_u32_e32 v18, s7, v101
	v_add_u32_e32 v18, 0xffffc010, v18
	v_mov_b32_e32 v19, v97
	v_lshlrev_b64 v[18:19], 11, v[18:19]
	v_lshl_add_u64 v[18:19], v[88:89], 0, v[18:19]
	global_store_dwordx4 v[18:19], v[12:15], off nt
	global_store_dwordx4 v[18:19], v[4:7], off offset:16 nt
.LBB0_341:
	s_or_b64 exec, exec, s[14:15]
	v_lshlrev_b32_e32 v14, 16, v9
	v_and_b32_e32 v15, 0xffff0000, v9
	v_add_u32_e32 v9, 2, v101
	v_min_i32_e32 v9, 7, v9
	v_lshlrev_b32_e32 v12, 16, v8
	v_add_u32_e32 v9, 1, v9
	v_and_b32_e32 v13, 0xffff0000, v8
	v_sub_f32_e32 v8, v12, v53
	v_cvt_f32_u32_e32 v9, v9
	v_lshlrev_b32_e32 v4, 16, v10
	v_and_b32_e32 v5, 0xffff0000, v10
	v_add_f32_e32 v10, v8, v24
	v_sub_f32_e32 v8, v13, v54
	v_lshlrev_b32_e32 v6, 16, v11
	v_and_b32_e32 v7, 0xffff0000, v11
	v_add_f32_e32 v11, v8, v25
	v_sub_f32_e32 v8, v14, v52
	v_add_f32_e32 v18, v8, v26
	v_sub_f32_e32 v8, v15, v51
	v_add_f32_e32 v19, v8, v27
	v_sub_f32_e32 v8, v4, v50
	v_div_scale_f32 v27, s[14:15], v9, v9, 1.0
	v_add_f32_e32 v24, v8, v29
	v_rcp_f32_e32 v29, v27
	v_sub_f32_e32 v8, v5, v49
	v_add_f32_e32 v25, v8, v30
	v_sub_f32_e32 v8, v6, v48
	v_add_f32_e32 v26, v8, v28
	v_sub_f32_e32 v8, v7, v47
	v_add_f32_e32 v23, v8, v23
	v_fma_f32 v8, -v27, v29, 1.0
	v_fmac_f32_e32 v29, v8, v29
	v_div_scale_f32 v8, vcc, 1.0, v9, 1.0
	v_mul_f32_e32 v28, v8, v29
	v_fma_f32 v30, -v27, v28, v8
	v_fmac_f32_e32 v28, v30, v29
	v_fma_f32 v8, -v27, v28, v8
	v_div_fmas_f32 v8, v8, v29, v28
	v_div_fixup_f32 v8, v8, v9, 1.0
	v_fma_f32 v9, v8, v10, -v12
	v_fma_f32 v27, v8, v11, -v13
	v_fma_f32 v29, v8, v18, -v14
	v_fma_f32 v30, v8, v19, -v15
	v_fma_f32 v31, v8, v24, -v4
	v_fma_f32 v32, v8, v25, -v5
	v_fma_f32 v33, v8, v26, -v6
	v_fma_f32 v8, v8, v23, -v7
	v_mov_b32_e32 v41, v97
	v_cvt_pk_bf16_f32 v28, v9, v27
	v_cvt_pk_bf16_f32 v29, v29, v30
	v_cvt_pk_bf16_f32 v30, v31, v32
	v_cvt_pk_bf16_f32 v31, v33, v8
	v_lshl_add_u64 v[8:9], v[16:17], 0, v[40:41]
	v_add_co_u32_e32 v16, vcc, 0x7901000, v8
	s_nop 1
	v_addc_co_u32_e32 v17, vcc, 0, v9, vcc
	global_store_dwordx4 v[16:17], v[28:31], off offset:1024 nt
	s_and_saveexec_b64 s[14:15], s[0:1]
	s_cbranch_execz .LBB0_343
	v_add_u32_e32 v16, s7, v101
	v_add_u32_e32 v16, 0xffffc011, v16
	v_mov_b32_e32 v17, v97
	v_lshlrev_b64 v[16:17], 11, v[16:17]
	v_lshl_add_u64 v[16:17], v[88:89], 0, v[16:17]
	global_store_dwordx4 v[16:17], v[12:15], off nt
	global_store_dwordx4 v[16:17], v[4:7], off offset:16 nt
.LBB0_343:
	s_or_b64 exec, exec, s[14:15]
	v_add_u32_e32 v16, 3, v101
	v_min_i32_e32 v17, 7, v16
	v_add_u32_e32 v17, 1, v17
	v_cvt_f32_u32_e32 v17, v17
	v_and_b32_e32 v7, 0xffff0000, v1
	v_lshlrev_b32_e32 v4, 16, v0
	v_sub_f32_e32 v13, v7, v44
	v_and_b32_e32 v5, 0xffff0000, v0
	v_sub_f32_e32 v12, v4, v46
	v_add_f32_e32 v13, v13, v19
	v_div_scale_f32 v19, s[0:1], v17, v17, 1.0
	v_add_f32_e32 v10, v12, v10
	v_sub_f32_e32 v12, v5, v20
	v_rcp_f32_e32 v20, v19
	v_lshlrev_b32_e32 v6, 16, v1
	v_lshlrev_b32_e32 v0, 16, v2
	v_and_b32_e32 v1, 0xffff0000, v2
	v_lshlrev_b32_e32 v2, 16, v3
	v_add_f32_e32 v11, v12, v11
	v_sub_f32_e32 v12, v6, v45
	v_and_b32_e32 v3, 0xffff0000, v3
	v_add_f32_e32 v12, v12, v18
	v_sub_f32_e32 v18, v2, v22
	v_fma_f32 v22, -v19, v20, 1.0
	v_sub_f32_e32 v21, v3, v21
	v_fmac_f32_e32 v20, v22, v20
	v_div_scale_f32 v22, vcc, 1.0, v17, 1.0
	v_sub_f32_e32 v14, v0, v43
	v_add_f32_e32 v21, v21, v23
	v_mul_f32_e32 v23, v22, v20
	v_add_f32_e32 v14, v14, v24
	v_fma_f32 v24, -v19, v23, v22
	v_fmac_f32_e32 v23, v24, v20
	v_fma_f32 v19, -v19, v23, v22
	v_div_fmas_f32 v19, v19, v20, v23
	v_add_co_u32_e32 v8, vcc, 0x7901000, v8
	s_movk_i32 s0, 0x3ff0
	s_nop 0
	v_addc_co_u32_e32 v9, vcc, 0, v9, vcc
	v_sub_f32_e32 v15, v1, v42
	v_div_fixup_f32 v17, v19, v17, 1.0
	v_cmp_lt_u32_e32 vcc, s0, v16
	v_add_f32_e32 v15, v15, v25
	v_add_f32_e32 v18, v18, v26
	v_fma_f32 v10, v17, v10, -v4
	v_fma_f32 v11, v17, v11, -v5
	v_fma_f32 v12, v17, v12, -v6
	v_fma_f32 v13, v17, v13, -v7
	s_and_b64 s[14:15], vcc, exec
	s_xor_b64 s[0:1], exec, -1
	v_fma_f32 v14, v17, v14, -v0
	v_fma_f32 v15, v17, v15, -v1
	v_fma_f32 v18, v17, v18, -v2
	v_fma_f32 v17, v17, v21, -v3
	v_cvt_pk_bf16_f32 v10, v10, v11
	v_cvt_pk_bf16_f32 v11, v12, v13
	v_cvt_pk_bf16_f32 v12, v14, v15
	v_cvt_pk_bf16_f32 v13, v18, v17
	global_store_dwordx4 v[8:9], v[10:13], off offset:3072 nt

; __device__ __forceinline__ void unpack8(const u32x4 w, float* f) { f[0] = bf_lo(w.x); f[1] = bf_hi(w.x); f[2] = bf_lo(w.y); f[3] = bf_hi(w.y); f[4] = bf_lo(w.z); f[5] = bf_hi(w.z); f[6] = bf_lo(w.w); f[7] = bf_hi(w.w); }
; __device__ __forceinline__ u32x4 pack8(const float* f) { u32x4 w; w.x = cvt_pk_bf16(f[0], f[1]); w.y = cvt_pk_bf16(f[2], f[3]); w.z = cvt_pk_bf16(f[4], f[5]); w.w = cvt_pk_bf16(f[6], f[7]); return w; }
; template <int W>
; __device__ __forceinline__ void pool_task_prompt(const Params& p, int l, int b, int c, int g, int rg, int ch, long row0) {
;     ...
;     const int col = g * 128 + ch * 8, tl0 = 4 * rg, t0 = c * 64 + tl0;
;     u32x4 raw[W + 3];
; #pragma unroll
;     for (int i = 0; i < W + 3; ++i) { const int tt = t0 - (W - 1) + i; raw[i] = (u32x4){0u, 0u, 0u, 0u};
;         if (tt >= 0) raw[i] = *(const u32x4*)(P + (size_t)((long)b * SEQ + tt) * INW + 768 + col); }
;     float a[4][8], cur[4][8];
; #pragma unroll
;     for (int k = 0; k < 8; ++k) a[0][k] = 0.f;
; #pragma unroll
;     for (int i = 0; i < W; ++i) { float x[8]; unpack8(raw[i], x);
; #pragma unroll
;         for (int k = 0; k < 8; ++k) { a[0][k] += x[k]; if (i == W - 1) cur[0][k] = x[k]; } }
; #pragma unroll
;     for (int r = 1; r < 4; ++r) { float xin[8], xout[8]; unpack8(raw[W - 1 + r], xin); unpack8(raw[r - 1], xout);
; #pragma unroll
;         for (int k = 0; k < 8; ++k) { a[r][k] = a[r - 1][k] + (xin[k] - xout[k]); cur[r][k] = xin[k]; } }
; #pragma unroll
;     for (int r = 0; r < 4; ++r) {
;         const int t = t0 + r;
;         const float inv = 1.0f / (float)((t + 1) < W ? (t + 1) : W);
;         float d[8];
; #pragma unroll
;         for (int k = 0; k < 8; ++k) d[k] = a[r][k] * inv - cur[r][k];
;         *(u32x4*)(AD + (size_t)(row0 + tl0 + r) * DM + 512 + col) = pack8(d);
;         if (t >= SEQ - 15) { float* pd = p.out + O_PP + (((size_t)l * 2 + b) * 15 + (t - (SEQ - 15))) * 512 + col;
;             *(f32x4*)pd = (f32x4){cur[r][0], cur[r][1], cur[r][2], cur[r][3]}; *(f32x4*)(pd + 4) = (f32x4){cur[r][4], cur[r][5], cur[r][6], cur[r][7]}; }
.LBB0_352:
	s_or_b64 exec, exec, s[16:17]
	v_lshl_add_u64 v[12:13], s[86:87], 0, v[96:97]
	v_mov_b32_e32 v21, v97
	v_lshl_add_u64 v[16:17], v[12:13], 0, v[20:21]
	v_add_co_u32_e32 v12, vcc, 0xfb00000, v16
	s_waitcnt vmcnt(0) lgkmcnt(0)
	v_lshlrev_b32_e32 v40, 16, v0
	v_addc_co_u32_e32 v13, vcc, 0, v17, vcc
	global_load_dwordx4 v[12:15], v[12:13], off offset:1536
	v_and_b32_e32 v41, 0xffff0000, v0
	v_add_co_u32_e32 v0, vcc, 0xfb02000, v16
	v_lshlrev_b32_e32 v39, 16, v1
	v_and_b32_e32 v38, 0xffff0000, v1
	v_addc_co_u32_e32 v1, vcc, 0, v17, vcc
	v_lshlrev_b32_e32 v37, 16, v2
	v_and_b32_e32 v36, 0xffff0000, v2
	v_add_co_u32_e32 v2, vcc, 0xfb03000, v16
	v_lshlrev_b32_e32 v35, 16, v3
	v_and_b32_e32 v34, 0xffff0000, v3
	v_addc_co_u32_e32 v3, vcc, 0, v17, vcc
	v_lshlrev_b32_e32 v32, 16, v8
	v_lshlrev_b32_e32 v31, 16, v9
	v_and_b32_e32 v30, 0xffff0000, v9
	v_lshlrev_b32_e32 v29, 16, v10
	v_and_b32_e32 v28, 0xffff0000, v10
	v_lshlrev_b32_e32 v27, 16, v11
	v_and_b32_e32 v26, 0xffff0000, v11
	v_and_b32_e32 v33, 0xffff0000, v8
	global_load_dwordx4 v[8:11], v[0:1], off
	v_add_co_u32_e32 v0, vcc, 0xfb05000, v16
	v_lshlrev_b32_e32 v48, 16, v4
	s_nop 0
	v_addc_co_u32_e32 v1, vcc, 0, v17, vcc
	v_lshlrev_b32_e32 v47, 16, v5
	v_and_b32_e32 v46, 0xffff0000, v5
	v_lshlrev_b32_e32 v45, 16, v6
	v_and_b32_e32 v44, 0xffff0000, v6
	v_lshlrev_b32_e32 v43, 16, v7
	v_and_b32_e32 v42, 0xffff0000, v7
	v_and_b32_e32 v49, 0xffff0000, v4
	global_load_dwordx4 v[4:7], v[2:3], off offset:2560
	s_nop 0
	global_load_dwordx4 v[0:3], v[0:1], off offset:1024
	v_add_f32_e32 v16, 0, v48
	v_add_f32_e32 v18, 0, v47
	v_add_f32_e32 v16, v16, v40
	v_add_f32_e32 v18, v18, v39
	v_add_f32_e32 v50, v16, v32
	v_add_f32_e32 v53, v18, v31
	v_add_f32_e32 v17, 0, v49
	v_add_f32_e32 v22, 0, v45
	v_add_f32_e32 v17, v17, v41
	v_add_f32_e32 v22, v22, v37
	v_add_f32_e32 v51, v17, v33
	v_add_f32_e32 v22, v22, v29
	v_add_f32_e32 v19, 0, v46
	v_add_f32_e32 v23, 0, v44
	v_add_f32_e32 v19, v19, v38
	v_add_f32_e32 v23, v23, v36
	v_add_f32_e32 v24, 0, v43
	v_add_f32_e32 v54, v19, v30
	v_add_f32_e32 v23, v23, v28
	v_add_f32_e32 v25, 0, v42
	v_add_f32_e32 v24, v24, v35
	v_add_f32_e32 v25, v25, v34
	v_add_f32_e32 v24, v24, v27
	v_add_f32_e32 v25, v25, v26
	v_mov_b32_e32 v93, v97
	s_waitcnt vmcnt(0) lgkmcnt(0)
	v_lshlrev_b32_e32 v16, 16, v12
	v_lshlrev_b32_e32 v18, 16, v13
	v_add_f32_e32 v52, v50, v16
	v_add_f32_e32 v50, v53, v18
	v_min_i32_e32 v53, 3, v101
	v_add_u32_e32 v53, 1, v53
	v_cvt_f32_u32_e32 v58, v53
	v_and_b32_e32 v17, 0xffff0000, v12
	v_lshlrev_b32_e32 v12, 16, v14
	v_add_f32_e32 v56, v22, v12
	v_div_scale_f32 v22, s[0:1], v58, v58, 1.0
	v_rcp_f32_e32 v59, v22
	v_and_b32_e32 v19, 0xffff0000, v13
	v_and_b32_e32 v13, 0xffff0000, v14
	v_add_f32_e32 v55, v23, v13
	v_fma_f32 v23, -v22, v59, 1.0
	v_lshlrev_b32_e32 v14, 16, v15
	v_fmac_f32_e32 v59, v23, v59
	v_div_scale_f32 v23, vcc, 1.0, v58, 1.0
	v_and_b32_e32 v15, 0xffff0000, v15
	v_add_f32_e32 v57, v54, v19
	v_add_f32_e32 v54, v24, v14
	v_mul_f32_e32 v24, v23, v59
	v_add_f32_e32 v53, v25, v15
	v_fma_f32 v25, -v22, v24, v23
	v_fmac_f32_e32 v24, v25, v59
	v_fma_f32 v22, -v22, v24, v23
	v_div_fmas_f32 v22, v22, v59, v24
	v_add_f32_e32 v51, v51, v17
	v_div_fixup_f32 v22, v22, v58, 1.0
	v_fma_f32 v23, v22, v52, -v16
	v_fma_f32 v24, v22, v51, -v17
	v_fma_f32 v25, v22, v50, -v18
	v_fma_f32 v59, v22, v57, -v19
	v_fma_f32 v60, v22, v56, -v12
	v_fma_f32 v61, v22, v55, -v13
	v_fma_f32 v62, v22, v54, -v14
	v_fma_f32 v22, v22, v53, -v15
	v_cvt_pk_bf16_f32 v58, v23, v24
	v_cvt_pk_bf16_f32 v59, v25, v59
	v_cvt_pk_bf16_f32 v60, v60, v61
	v_cvt_pk_bf16_f32 v61, v62, v22
	v_lshl_add_u64 v[22:23], s[86:87], 0, v[92:93]
	v_lshl_add_u64 v[24:25], v[22:23], 0, v[20:21]
	v_add_co_u32_e32 v62, vcc, 0x7900000, v24
	s_movk_i32 s0, 0x3ff0
	s_nop 0
	v_addc_co_u32_e32 v63, vcc, 0, v25, vcc
	v_cmp_lt_u32_e32 vcc, s0, v101
	global_store_dwordx4 v[62:63], v[58:61], off offset:1024 nt
	s_and_saveexec_b64 s[0:1], vcc
	s_cbranch_execz .LBB0_354
	v_add_u32_e32 v21, s7, v101
	v_add_u32_e32 v58, 0xffffc00f, v21
	v_mov_b32_e32 v59, v97
	v_lshlrev_b64 v[58:59], 11, v[58:59]
	v_lshl_add_u64 v[58:59], v[90:91], 0, v[58:59]
	global_store_dwordx4 v[58:59], v[16:19], off nt
	global_store_dwordx4 v[58:59], v[12:15], off offset:16 nt
; __device__ __forceinline__ void unpack8(const u32x4 w, float* f) { f[0] = bf_lo(w.x); f[1] = bf_hi(w.x); f[2] = bf_lo(w.y); f[3] = bf_hi(w.y); f[4] = bf_lo(w.z); f[5] = bf_hi(w.z); f[6] = bf_lo(w.w); f[7] = bf_hi(w.w); }
; __device__ __forceinline__ u32x4 pack8(const float* f) { u32x4 w; w.x = cvt_pk_bf16(f[0], f[1]); w.y = cvt_pk_bf16(f[2], f[3]); w.z = cvt_pk_bf16(f[4], f[5]); w.w = cvt_pk_bf16(f[6], f[7]); return w; }
; template <int W>
; __device__ __forceinline__ void pool_task_prompt(const Params& p, int l, int b, int c, int g, int rg, int ch, long row0) {
;     ...
;     for (int r = 1; r < 4; ++r) { float xin[8], xout[8]; unpack8(raw[W - 1 + r], xin); unpack8(raw[r - 1], xout);
; #pragma unroll
;         for (int k = 0; k < 8; ++k) { a[r][k] = a[r - 1][k] + (xin[k] - xout[k]); cur[r][k] = xin[k]; } }
; #pragma unroll
;     for (int r = 0; r < 4; ++r) {
;         const int t = t0 + r;
;         const float inv = 1.0f / (float)((t + 1) < W ? (t + 1) : W);
;         float d[8];
; #pragma unroll
;         for (int k = 0; k < 8; ++k) d[k] = a[r][k] * inv - cur[r][k];
;         *(u32x4*)(AD + (size_t)(row0 + tl0 + r) * DM + 512 + col) = pack8(d);
;         if (t >= SEQ - 15) { float* pd = p.out + O_PP + (((size_t)l * 2 + b) * 15 + (t - (SEQ - 15))) * 512 + col;
;             *(f32x4*)pd = (f32x4){cur[r][0], cur[r][1], cur[r][2], cur[r][3]}; *(f32x4*)(pd + 4) = (f32x4){cur[r][4], cur[r][5], cur[r][6], cur[r][7]}; }
.LBB0_354:
	s_or_b64 exec, exec, s[0:1]
	s_nop 0
	v_lshlrev_b32_e32 v12, 16, v8
	v_and_b32_e32 v13, 0xffff0000, v8
	v_lshlrev_b32_e32 v8, 16, v10
	v_sub_f32_e32 v21, v8, v45
	v_add_u32_e32 v45, 1, v101
	v_min_i32_e32 v45, 3, v45
	v_add_u32_e32 v45, 1, v45
	v_cvt_f32_u32_e32 v45, v45
	v_and_b32_e32 v15, 0xffff0000, v9
	v_lshlrev_b32_e32 v14, 16, v9
	v_sub_f32_e32 v19, v15, v46
	v_div_scale_f32 v46, s[0:1], v45, v45, 1.0
	v_sub_f32_e32 v18, v14, v47
	v_rcp_f32_e32 v47, v46
	v_sub_f32_e32 v16, v12, v48
	v_sub_f32_e32 v17, v13, v49
	v_add_f32_e32 v18, v50, v18
	v_fma_f32 v48, -v46, v47, 1.0
	v_fmac_f32_e32 v47, v48, v47
	v_div_scale_f32 v48, vcc, 1.0, v45, 1.0
	v_mul_f32_e32 v49, v48, v47
	v_fma_f32 v50, -v46, v49, v48
	v_fmac_f32_e32 v49, v50, v47
	v_fma_f32 v46, -v46, v49, v48
	v_and_b32_e32 v9, 0xffff0000, v10
	v_lshlrev_b32_e32 v10, 16, v11
	v_and_b32_e32 v11, 0xffff0000, v11
	v_div_fmas_f32 v46, v46, v47, v49
	v_add_f32_e32 v16, v52, v16
	v_add_f32_e32 v17, v51, v17
	v_add_f32_e32 v19, v57, v19
	v_sub_f32_e32 v44, v9, v44
	v_sub_f32_e32 v43, v10, v43
	v_sub_f32_e32 v42, v11, v42
	v_div_fixup_f32 v45, v46, v45, 1.0
	v_add_co_u32_e32 v24, vcc, 0x7900000, v24
	s_movk_i32 s0, 0x3fef
	v_add_f32_e32 v21, v56, v21
	v_add_f32_e32 v44, v55, v44
	v_add_f32_e32 v43, v54, v43
	v_add_f32_e32 v42, v53, v42
	v_fma_f32 v46, v45, v16, -v12
	v_fma_f32 v47, v45, v17, -v13
	v_fma_f32 v48, v45, v18, -v14
	v_fma_f32 v49, v45, v19, -v15
	v_addc_co_u32_e32 v25, vcc, 0, v25, vcc
	v_cmp_lt_u32_e64 s[0:1], s0, v101
	v_fma_f32 v50, v45, v21, -v8
	v_fma_f32 v51, v45, v44, -v9
	v_fma_f32 v52, v45, v43, -v10
	v_fma_f32 v45, v45, v42, -v11
	v_cvt_pk_bf16_f32 v46, v46, v47
	v_cvt_pk_bf16_f32 v47, v48, v49
	v_cvt_pk_bf16_f32 v48, v50, v51
	v_cvt_pk_bf16_f32 v49, v52, v45
	global_store_dwordx4 v[24:25], v[46:49], off offset:3072 nt
	s_and_saveexec_b64 s[16:17], s[0:1]
	s_cbranch_execz .LBB0_356
	v_add_u32_e32 v24, s7, v101
	v_add_u32_e32 v24, 0xffffc010, v24
	v_mov_b32_e32 v25, v97
	v_lshlrev_b64 v[24:25], 11, v[24:25]
	v_lshl_add_u64 v[24:25], v[90:91], 0, v[24:25]
	global_store_dwordx4 v[24:25], v[12:15], off nt
	global_store_dwordx4 v[24:25], v[8:11], off offset:16 nt
.LBB0_356:
	s_or_b64 exec, exec, s[16:17]
	v_add_u32_e32 v13, 2, v101
	v_lshlrev_b32_e32 v8, 16, v4
	v_min_i32_e32 v13, 3, v13
	v_and_b32_e32 v9, 0xffff0000, v4
	v_sub_f32_e32 v12, v8, v40
	v_add_u32_e32 v13, 1, v13
	v_lshlrev_b32_e32 v10, 16, v5
	v_add_f32_e32 v14, v12, v16
	v_sub_f32_e32 v12, v9, v41
	v_cvt_f32_u32_e32 v13, v13
	v_and_b32_e32 v11, 0xffff0000, v5
	v_add_f32_e32 v15, v12, v17
	v_sub_f32_e32 v12, v10, v39
	v_lshlrev_b32_e32 v4, 16, v6
	v_add_f32_e32 v16, v12, v18
	v_sub_f32_e32 v12, v11, v38
	v_and_b32_e32 v5, 0xffff0000, v6
	v_add_f32_e32 v17, v12, v19
	v_sub_f32_e32 v12, v4, v37
	v_lshlrev_b32_e32 v6, 16, v7
	v_add_f32_e32 v18, v12, v21
	v_sub_f32_e32 v12, v5, v36
	v_div_scale_f32 v21, s[16:17], v13, v13, 1.0
	v_add_f32_e32 v19, v12, v44
	v_sub_f32_e32 v12, v6, v35
	v_rcp_f32_e32 v35, v21
	v_and_b32_e32 v7, 0xffff0000, v7
	v_add_f32_e32 v24, v12, v43
	v_sub_f32_e32 v12, v7, v34
	v_add_f32_e32 v25, v12, v42
	v_fma_f32 v12, -v21, v35, 1.0
	v_fmac_f32_e32 v35, v12, v35
	v_div_scale_f32 v12, vcc, 1.0, v13, 1.0
	v_mul_f32_e32 v34, v12, v35
	v_fma_f32 v36, -v21, v34, v12
	v_fmac_f32_e32 v34, v36, v35
	v_fma_f32 v12, -v21, v34, v12
	v_div_fmas_f32 v12, v12, v35, v34
	v_div_fixup_f32 v12, v12, v13, 1.0
	v_fma_f32 v21, v12, v15, -v9
	v_fma_f32 v13, v12, v14, -v8
	v_fma_f32 v35, v12, v16, -v10
	v_fma_f32 v36, v12, v17, -v11
	v_fma_f32 v37, v12, v18, -v4
	v_fma_f32 v38, v12, v19, -v5
	v_fma_f32 v39, v12, v24, -v6
	v_fma_f32 v12, v12, v25, -v7
	v_cvt_pk_bf16_f32 v34, v13, v21
	v_mov_b32_e32 v21, v97
	v_cvt_pk_bf16_f32 v35, v35, v36
	v_cvt_pk_bf16_f32 v36, v37, v38
	v_cvt_pk_bf16_f32 v37, v39, v12
	v_lshl_add_u64 v[12:13], v[22:23], 0, v[20:21]
	v_add_co_u32_e32 v20, vcc, 0x7901000, v12
	s_nop 1
	v_addc_co_u32_e32 v21, vcc, 0, v13, vcc
	global_store_dwordx4 v[20:21], v[34:37], off offset:1024 nt
	s_and_saveexec_b64 s[16:17], s[0:1]
	s_cbranch_execz .LBB0_358
	v_add_u32_e32 v20, s7, v101
	v_add_u32_e32 v20, 0xffffc011, v20
	v_mov_b32_e32 v21, v97
	v_lshlrev_b64 v[20:21], 11, v[20:21]
	v_lshl_add_u64 v[20:21], v[90:91], 0, v[20:21]
	global_store_dwordx4 v[20:21], v[8:11], off nt
	global_store_dwordx4 v[20:21], v[4:7], off offset:16 nt
.LBB0_358:
	s_or_b64 exec, exec, s[16:17]
	s_nop 0
	v_lshlrev_b32_e32 v4, 16, v0
	v_and_b32_e32 v5, 0xffff0000, v0
	v_lshlrev_b32_e32 v6, 16, v1
	v_and_b32_e32 v7, 0xffff0000, v1
	v_lshlrev_b32_e32 v0, 16, v2
	v_and_b32_e32 v1, 0xffff0000, v2
	v_lshlrev_b32_e32 v2, 16, v3
	v_and_b32_e32 v3, 0xffff0000, v3
	v_sub_f32_e32 v8, v4, v32
	v_sub_f32_e32 v9, v5, v33
	v_sub_f32_e32 v10, v6, v31
	v_sub_f32_e32 v11, v7, v30
	v_add_f32_e32 v8, v8, v14
	v_add_f32_e32 v9, v9, v15
	v_add_f32_e32 v10, v10, v16
	v_add_f32_e32 v11, v11, v17
	v_sub_f32_e32 v14, v0, v29
	v_sub_f32_e32 v15, v1, v28
	v_sub_f32_e32 v16, v2, v27
	v_sub_f32_e32 v17, v3, v26
	v_add_f32_e32 v14, v14, v18
	v_add_f32_e32 v15, v15, v19
	v_add_f32_e32 v16, v16, v24
	v_add_f32_e32 v17, v17, v25
	s_mov_b32 s0, 0x3e800000
	v_add_co_u32_e32 v12, vcc, 0x7901000, v12
	v_add_u32_e32 v18, 3, v101
	v_fma_f32 v8, v8, s0, -v4
	v_fma_f32 v9, v9, s0, -v5
	v_fma_f32 v10, v10, s0, -v6
	v_fma_f32 v11, v11, s0, -v7
	v_fma_f32 v14, v14, s0, -v0
	v_fma_f32 v15, v15, s0, -v1
	v_fma_f32 v16, v16, s0, -v2
	v_fma_f32 v17, v17, s0, -v3
	v_addc_co_u32_e32 v13, vcc, 0, v13, vcc
	s_movk_i32 s0, 0x3ff0
	v_cmp_lt_u32_e32 vcc, s0, v18
	v_cvt_pk_bf16_f32 v8, v8, v9
	v_cvt_pk_bf16_f32 v9, v10, v11
	s_andn2_b64 s[0:1], s[14:15], exec
	s_and_b64 s[14:15], vcc, exec
	v_cvt_pk_bf16_f32 v10, v14, v15
	v_cvt_pk_bf16_f32 v11, v16, v17
	global_store_dwordx4 v[12:13], v[8:11], off offset:3072 nt
	s_or_b64 s[14:15], s[0:1], s[14:15]
	s_nop 0
	v_mov_b64_e32 v[8:9], v[80:81]

; __device__ __forceinline__ void unpack8(const u32x4 w, float* f) { f[0] = bf_lo(w.x); f[1] = bf_hi(w.x); f[2] = bf_lo(w.y); f[3] = bf_hi(w.y); f[4] = bf_lo(w.z); f[5] = bf_hi(w.z); f[6] = bf_lo(w.w); f[7] = bf_hi(w.w); }
; template <int W>
; __device__ __forceinline__ void pool_task_prompt(const Params& p, int l, int b, int c, int g, int rg, int ch, long row0) {
;     ...
;     u32x4 raw[W + 3];
; #pragma unroll
;     for (int i = 0; i < W + 3; ++i) { const int tt = t0 - (W - 1) + i; raw[i] = (u32x4){0u, 0u, 0u, 0u};
;         if (tt >= 0) raw[i] = *(const u32x4*)(P + (size_t)((long)b * SEQ + tt) * INW + 768 + col); }
;     float a[4][8], cur[4][8];
; #pragma unroll
;     for (int k = 0; k < 8; ++k) a[0][k] = 0.f;
; #pragma unroll
;     for (int i = 0; i < W; ++i) { float x[8]; unpack8(raw[i], x);
; #pragma unroll
;         for (int k = 0; k < 8; ++k) { a[0][k] += x[k]; if (i == W - 1) cur[0][k] = x[k]; } }
; #pragma unroll
;     for (int r = 1; r < 4; ++r) { float xin[8], xout[8]; unpack8(raw[W - 1 + r], xin); unpack8(raw[r - 1], xout);
; #pragma unroll
;         for (int k = 0; k < 8; ++k) { a[r][k] = a[r - 1][k] + (xin[k] - xout[k]); cur[r][k] = xin[k]; } }
.LBB0_391:
	s_or_b64 exec, exec, s[12:13]
	v_lshl_add_u64 v[16:17], s[86:87], 0, v[96:97]
	v_lshlrev_b64 v[94:95], 1, v[82:83]
	v_lshl_add_u64 v[16:17], v[16:17], 0, v[94:95]
	v_add_co_u32_e32 v18, vcc, 0xfb00000, v16
	s_waitcnt vmcnt(0) lgkmcnt(0)
	v_lshlrev_b32_e32 v121, 16, v4
	v_addc_co_u32_e32 v19, vcc, 0, v17, vcc
	v_add_co_u32_e32 v36, vcc, 0xfb02000, v16
	v_and_b32_e32 v122, 0xffff0000, v4
	s_nop 0
	v_addc_co_u32_e32 v37, vcc, 0, v17, vcc
	global_load_dwordx4 v[72:75], v[18:19], off offset:1536
	global_load_dwordx4 v[56:59], v[36:37], off
	v_add_co_u32_e32 v18, vcc, 0xfb03000, v16
	v_lshlrev_b32_e32 v120, 16, v5
	s_nop 0
	v_addc_co_u32_e32 v19, vcc, 0, v17, vcc
	v_add_co_u32_e32 v16, vcc, 0xfb05000, v16
	v_and_b32_e32 v119, 0xffff0000, v5
	s_nop 0
	v_addc_co_u32_e32 v17, vcc, 0, v17, vcc
	global_load_dwordx4 v[36:39], v[18:19], off offset:2560
	s_nop 0
	global_load_dwordx4 v[16:19], v[16:17], off offset:1024
	v_and_b32_e32 v117, 0xffff0000, v6
	v_lshlrev_b32_e32 v116, 16, v7
	v_and_b32_e32 v115, 0xffff0000, v7
	v_add_f32_e32 v5, 0, v121
	v_add_f32_e32 v4, 0, v122
	v_lshlrev_b32_e32 v113, 16, v0
	v_and_b32_e32 v114, 0xffff0000, v0
	v_lshlrev_b32_e32 v118, 16, v6
	v_add_f32_e32 v6, 0, v120
	v_add_f32_e32 v7, 0, v119
	v_add_f32_e32 v102, 0, v117
	v_add_f32_e32 v103, 0, v116
	v_add_f32_e32 v104, 0, v115
	v_lshlrev_b32_e32 v112, 16, v1
	v_and_b32_e32 v111, 0xffff0000, v1
	v_and_b32_e32 v109, 0xffff0000, v2
	v_lshlrev_b32_e32 v108, 16, v3
	v_and_b32_e32 v107, 0xffff0000, v3
	v_add_f32_e32 v1, v5, v113
	v_add_f32_e32 v0, v4, v114
	v_lshlrev_b32_e32 v106, 16, v12
	v_and_b32_e32 v12, 0xffff0000, v12
	v_lshlrev_b32_e32 v110, 16, v2
	v_add_f32_e32 v2, v6, v112
	v_add_f32_e32 v3, v7, v111
	v_add_f32_e32 v5, v102, v109
	v_add_f32_e32 v6, v103, v108
	v_add_f32_e32 v7, v104, v107
	v_lshlrev_b32_e32 v105, 16, v13
	v_and_b32_e32 v104, 0xffff0000, v13
	v_lshlrev_b32_e32 v103, 16, v14
	v_and_b32_e32 v102, 0xffff0000, v14
	v_lshlrev_b32_e32 v14, 16, v15
	v_and_b32_e32 v13, 0xffff0000, v15
	v_add_f32_e32 v1, v1, v106
	v_add_f32_e32 v0, v0, v12
	v_lshlrev_b32_e32 v15, 16, v8
	v_and_b32_e32 v8, 0xffff0000, v8
	v_add_f32_e32 v1, v1, v15
	v_add_f32_e32 v0, v0, v8
	v_lshlrev_b32_e32 v8, 16, v24
	v_add_f32_e32 v1, v1, v8
	v_and_b32_e32 v8, 0xffff0000, v24
	v_add_f32_e32 v0, v0, v8
	v_lshlrev_b32_e32 v8, 16, v20
	v_add_f32_e32 v1, v1, v8
	v_and_b32_e32 v8, 0xffff0000, v20
	v_add_f32_e32 v0, v0, v8
	v_lshlrev_b32_e32 v8, 16, v32
	v_add_f32_e32 v1, v1, v8
	v_and_b32_e32 v8, 0xffff0000, v32
	v_add_f32_e32 v0, v0, v8
	v_lshlrev_b32_e32 v8, 16, v28
	v_add_f32_e32 v93, 0, v118
	v_add_f32_e32 v1, v1, v8
	v_and_b32_e32 v8, 0xffff0000, v28
	v_add_f32_e32 v4, v93, v110
	v_add_f32_e32 v0, v0, v8
	v_lshlrev_b32_e32 v8, 16, v44
	v_add_f32_e32 v4, v4, v103
	v_add_f32_e32 v7, v7, v13
	v_lshlrev_b32_e32 v123, 16, v10
	v_lshlrev_b32_e32 v124, 16, v11
	v_and_b32_e32 v11, 0xffff0000, v11
	v_add_f32_e32 v1, v1, v8
	v_and_b32_e32 v8, 0xffff0000, v44
	v_add_f32_e32 v5, v5, v102
	v_and_b32_e32 v10, 0xffff0000, v10
	v_add_f32_e32 v4, v4, v123
	v_add_f32_e32 v7, v7, v11
	v_lshlrev_b32_e32 v11, 16, v26
	v_add_f32_e32 v0, v0, v8
	v_lshlrev_b32_e32 v8, 16, v40
	v_add_f32_e32 v5, v5, v10
	v_and_b32_e32 v15, 0xffff0000, v26
	v_add_f32_e32 v4, v4, v11
	v_lshlrev_b32_e32 v11, 16, v22
	v_add_f32_e32 v1, v1, v8
	v_and_b32_e32 v8, 0xffff0000, v40
	v_add_f32_e32 v5, v5, v15
	v_and_b32_e32 v15, 0xffff0000, v22
	v_add_f32_e32 v4, v4, v11
	v_lshlrev_b32_e32 v11, 16, v34
	v_add_f32_e32 v0, v0, v8
	v_lshlrev_b32_e32 v8, 16, v52
	v_add_f32_e32 v5, v5, v15
	v_and_b32_e32 v15, 0xffff0000, v34
	v_add_f32_e32 v4, v4, v11
	v_lshlrev_b32_e32 v11, 16, v30
	v_add_f32_e32 v1, v1, v8
	v_and_b32_e32 v8, 0xffff0000, v52
	v_add_f32_e32 v5, v5, v15
	v_and_b32_e32 v15, 0xffff0000, v30
	v_add_f32_e32 v4, v4, v11
	v_lshlrev_b32_e32 v11, 16, v46
	v_add_f32_e32 v0, v0, v8
	v_lshlrev_b32_e32 v8, 16, v48
	v_add_f32_e32 v2, v2, v105
	v_add_f32_e32 v3, v3, v104
	v_add_f32_e32 v6, v6, v14
	v_lshlrev_b32_e32 v93, 16, v9
	v_and_b32_e32 v9, 0xffff0000, v9
	v_add_f32_e32 v5, v5, v15
	v_and_b32_e32 v15, 0xffff0000, v46
	v_add_f32_e32 v4, v4, v11
	v_lshlrev_b32_e32 v11, 16, v42
	v_add_f32_e32 v1, v1, v8
	v_and_b32_e32 v8, 0xffff0000, v48
	v_add_f32_e32 v2, v2, v93
	v_add_f32_e32 v3, v3, v9
	v_add_f32_e32 v6, v6, v124
	v_lshlrev_b32_e32 v9, 16, v25
	v_and_b32_e32 v10, 0xffff0000, v25
	v_lshlrev_b32_e32 v25, 16, v27
	v_add_f32_e32 v5, v5, v15
	v_and_b32_e32 v15, 0xffff0000, v42
	v_add_f32_e32 v4, v4, v11
	v_lshlrev_b32_e32 v11, 16, v54
	v_add_f32_e32 v0, v0, v8
	v_lshlrev_b32_e32 v8, 16, v64
	v_and_b32_e32 v26, 0xffff0000, v27
	v_add_f32_e32 v2, v2, v9
	v_add_f32_e32 v3, v3, v10
	v_add_f32_e32 v6, v6, v25
	v_lshlrev_b32_e32 v9, 16, v21
	v_and_b32_e32 v10, 0xffff0000, v21
	v_lshlrev_b32_e32 v21, 16, v23
	v_add_f32_e32 v5, v5, v15
	v_and_b32_e32 v15, 0xffff0000, v54
	v_add_f32_e32 v4, v4, v11
	v_lshlrev_b32_e32 v11, 16, v50
	v_add_f32_e32 v1, v1, v8
	v_and_b32_e32 v8, 0xffff0000, v64
	v_add_f32_e32 v7, v7, v26
	v_and_b32_e32 v22, 0xffff0000, v23
	v_add_f32_e32 v2, v2, v9
	v_add_f32_e32 v6, v6, v21
	v_lshlrev_b32_e32 v9, 16, v33
	v_lshlrev_b32_e32 v20, 16, v35
	v_add_f32_e32 v5, v5, v15
	v_and_b32_e32 v15, 0xffff0000, v50
	v_add_f32_e32 v4, v4, v11
	v_lshlrev_b32_e32 v11, 16, v66
	v_add_f32_e32 v0, v0, v8
	v_lshlrev_b32_e32 v8, 16, v60
	v_add_f32_e32 v7, v7, v22
	v_and_b32_e32 v21, 0xffff0000, v35
	v_add_f32_e32 v2, v2, v9
	v_add_f32_e32 v6, v6, v20
	v_lshlrev_b32_e32 v9, 16, v29
	v_lshlrev_b32_e32 v20, 16, v31
	v_add_f32_e32 v5, v5, v15
	v_and_b32_e32 v15, 0xffff0000, v66
	v_add_f32_e32 v4, v4, v11
	v_lshlrev_b32_e32 v11, 16, v62
	v_add_f32_e32 v1, v1, v8
	v_and_b32_e32 v8, 0xffff0000, v60
	v_add_f32_e32 v7, v7, v21
	v_and_b32_e32 v21, 0xffff0000, v31
	v_add_f32_e32 v2, v2, v9
	v_add_f32_e32 v6, v6, v20
	v_lshlrev_b32_e32 v9, 16, v45
	v_lshlrev_b32_e32 v20, 16, v47
	v_add_f32_e32 v5, v5, v15
	v_and_b32_e32 v15, 0xffff0000, v62
	v_add_f32_e32 v0, v0, v8
	v_add_f32_e32 v4, v4, v11
	v_lshlrev_b32_e32 v8, 16, v68
	v_lshlrev_b32_e32 v11, 16, v70
	v_add_f32_e32 v7, v7, v21
	v_and_b32_e32 v21, 0xffff0000, v47
	v_add_f32_e32 v2, v2, v9
	v_add_f32_e32 v6, v6, v20
	v_lshlrev_b32_e32 v9, 16, v41
	v_lshlrev_b32_e32 v20, 16, v43
	v_add_f32_e32 v5, v5, v15
	v_and_b32_e32 v15, 0xffff0000, v70
	v_add_f32_e32 v8, v1, v8
	v_add_f32_e32 v11, v4, v11
	s_waitcnt vmcnt(0) lgkmcnt(0)
; __device__ __forceinline__ void unpack8(const u32x4 w, float* f) { f[0] = bf_lo(w.x); f[1] = bf_hi(w.x); f[2] = bf_lo(w.y); f[3] = bf_hi(w.y); f[4] = bf_lo(w.z); f[5] = bf_hi(w.z); f[6] = bf_lo(w.w); f[7] = bf_hi(w.w); }
; __device__ __forceinline__ u32x4 pack8(const float* f) { u32x4 w; w.x = cvt_pk_bf16(f[0], f[1]); w.y = cvt_pk_bf16(f[2], f[3]); w.z = cvt_pk_bf16(f[4], f[5]); w.w = cvt_pk_bf16(f[6], f[7]); return w; }
; template <int W>
; __device__ __forceinline__ void pool_task_prompt(const Params& p, int l, int b, int c, int g, int rg, int ch, long row0) {
;     ...
;     for (int i = 0; i < W; ++i) { float x[8]; unpack8(raw[i], x);
; #pragma unroll
;         for (int k = 0; k < 8; ++k) { a[0][k] += x[k]; if (i == W - 1) cur[0][k] = x[k]; } }
; #pragma unroll
;     for (int r = 1; r < 4; ++r) { float xin[8], xout[8]; unpack8(raw[W - 1 + r], xin); unpack8(raw[r - 1], xout);
; #pragma unroll
;         for (int k = 0; k < 8; ++k) { a[r][k] = a[r - 1][k] + (xin[k] - xout[k]); cur[r][k] = xin[k]; } }
; #pragma unroll
;     for (int r = 0; r < 4; ++r) {
;         const int t = t0 + r;
;         const float inv = 1.0f / (float)((t + 1) < W ? (t + 1) : W);
;         float d[8];
; #pragma unroll
;         for (int k = 0; k < 8; ++k) d[k] = a[r][k] * inv - cur[r][k];
;         *(u32x4*)(AD + (size_t)(row0 + tl0 + r) * DM + 512 + col) = pack8(d);
;         if (t >= SEQ - 15) { float* pd = p.out + O_PP + (((size_t)l * 2 + b) * 15 + (t - (SEQ - 15))) * 512 + col;
;             *(f32x4*)pd = (f32x4){cur[r][0], cur[r][1], cur[r][2], cur[r][3]}; *(f32x4*)(pd + 4) = (f32x4){cur[r][4], cur[r][5], cur[r][6], cur[r][7]}; }
	v_lshlrev_b32_e32 v4, 16, v72
	v_add_f32_e32 v7, v7, v21
	v_and_b32_e32 v21, 0xffff0000, v43
	v_add_f32_e32 v2, v2, v9
	v_add_f32_e32 v6, v6, v20
	v_lshlrev_b32_e32 v9, 16, v53
	v_lshlrev_b32_e32 v20, 16, v55
	v_add_f32_e32 v24, v5, v15
	v_add_f32_e32 v15, v8, v4
	v_min_i32_e32 v8, 15, v101
	v_add_f32_e32 v7, v7, v21
	v_and_b32_e32 v21, 0xffff0000, v55
	v_add_f32_e32 v2, v2, v9
	v_add_f32_e32 v6, v6, v20
	v_lshlrev_b32_e32 v9, 16, v49
	v_lshlrev_b32_e32 v20, 16, v51
	v_add_u32_e32 v8, 1, v8
	v_add_f32_e32 v7, v7, v21
	v_and_b32_e32 v21, 0xffff0000, v51
	v_add_f32_e32 v2, v2, v9
	v_add_f32_e32 v6, v6, v20
	v_lshlrev_b32_e32 v9, 16, v65
	v_lshlrev_b32_e32 v20, 16, v67
	v_cvt_f32_u32_e32 v8, v8
	v_add_f32_e32 v3, v3, v10
	v_and_b32_e32 v10, 0xffff0000, v33
	v_add_f32_e32 v7, v7, v21
	v_and_b32_e32 v21, 0xffff0000, v67
	v_add_f32_e32 v2, v2, v9
	v_add_f32_e32 v6, v6, v20
	v_lshlrev_b32_e32 v9, 16, v61
	v_lshlrev_b32_e32 v20, 16, v63
	v_add_f32_e32 v3, v3, v10
	v_and_b32_e32 v10, 0xffff0000, v29
	v_add_f32_e32 v7, v7, v21
	v_and_b32_e32 v21, 0xffff0000, v63
	v_add_f32_e32 v2, v2, v9
	v_add_f32_e32 v6, v6, v20
	v_lshlrev_b32_e32 v9, 16, v69
	v_lshlrev_b32_e32 v20, 16, v71
	v_add_f32_e32 v3, v3, v10
	v_and_b32_e32 v10, 0xffff0000, v45
	v_add_f32_e32 v7, v7, v21
	v_and_b32_e32 v21, 0xffff0000, v71
	v_add_f32_e32 v9, v2, v9
	v_add_f32_e32 v25, v6, v20
	v_lshlrev_b32_e32 v6, 16, v73
	v_add_f32_e32 v3, v3, v10
	v_and_b32_e32 v10, 0xffff0000, v41
	v_add_f32_e32 v26, v7, v21
	v_add_f32_e32 v21, v9, v6
	v_div_scale_f32 v9, s[0:1], v8, v8, 1.0
	v_add_f32_e32 v3, v3, v10
	v_and_b32_e32 v10, 0xffff0000, v53
	v_rcp_f32_e32 v27, v9
	v_add_f32_e32 v3, v3, v10
	v_and_b32_e32 v10, 0xffff0000, v49
	v_add_f32_e32 v3, v3, v10
	v_and_b32_e32 v10, 0xffff0000, v65
	v_and_b32_e32 v1, 0xffff0000, v68
	v_add_f32_e32 v3, v3, v10
	v_and_b32_e32 v10, 0xffff0000, v61
	v_add_f32_e32 v22, v0, v1
	v_lshlrev_b32_e32 v0, 16, v74
	v_lshlrev_b32_e32 v2, 16, v75
	v_add_f32_e32 v3, v3, v10
	v_and_b32_e32 v10, 0xffff0000, v69
	v_add_f32_e32 v23, v11, v0
	v_add_f32_e32 v11, v25, v2
	v_fma_f32 v25, -v9, v27, 1.0
	v_add_f32_e32 v10, v3, v10
	v_and_b32_e32 v5, 0xffff0000, v72
	v_and_b32_e32 v7, 0xffff0000, v73
	v_and_b32_e32 v3, 0xffff0000, v75
	v_fmac_f32_e32 v27, v25, v27
	v_div_scale_f32 v25, vcc, 1.0, v8, 1.0
	v_add_f32_e32 v20, v22, v5
	v_add_f32_e32 v22, v10, v7
	v_add_f32_e32 v10, v26, v3
	v_mul_f32_e32 v26, v25, v27
	v_fma_f32 v28, -v9, v26, v25
	v_fmac_f32_e32 v26, v28, v27
	v_fma_f32 v9, -v9, v26, v25
	v_and_b32_e32 v1, 0xffff0000, v74
	v_div_fmas_f32 v9, v9, v27, v26
	v_add_f32_e32 v24, v24, v1
	v_div_fixup_f32 v8, v9, v8, 1.0
	v_fma_f32 v9, v8, v15, -v4
	v_fma_f32 v25, v8, v20, -v5
	v_fma_f32 v27, v8, v21, -v6
	v_fma_f32 v28, v8, v22, -v7
	v_fma_f32 v29, v8, v23, -v0
	v_fma_f32 v30, v8, v24, -v1
	v_fma_f32 v31, v8, v11, -v2
	v_fma_f32 v8, v8, v10, -v3
	v_mov_b32_e32 v93, v97
	v_cvt_pk_bf16_f32 v26, v9, v25
	v_cvt_pk_bf16_f32 v27, v27, v28
	v_cvt_pk_bf16_f32 v28, v29, v30
	v_cvt_pk_bf16_f32 v29, v31, v8
	v_lshl_add_u64 v[8:9], s[86:87], 0, v[92:93]
	v_lshl_add_u64 v[30:31], v[8:9], 0, v[94:95]
	v_add_co_u32_e32 v30, vcc, 0x7900000, v30
	s_movk_i32 s0, 0x3ff0
	s_nop 0
	v_addc_co_u32_e32 v31, vcc, 0, v31, vcc
	v_cmp_lt_u32_e32 vcc, s0, v101
	global_store_dwordx4 v[30:31], v[26:29], off offset:1024 nt
	s_and_saveexec_b64 s[0:1], vcc
	s_cbranch_execz .LBB0_393
	v_add_u32_e32 v25, s7, v101
	v_add_u32_e32 v26, 0xffffc00f, v25
	v_mov_b32_e32 v27, v97
	v_lshlrev_b64 v[26:27], 11, v[26:27]
	v_lshl_add_u64 v[26:27], v[86:87], 0, v[26:27]
	global_store_dwordx4 v[26:27], v[4:7], off nt
	global_store_dwordx4 v[26:27], v[0:3], off offset:16 nt
.LBB0_393:
	s_or_b64 exec, exec, s[0:1]
	v_add_u32_e32 v26, 1, v101
	v_min_i32_e32 v26, 15, v26
	v_add_u32_e32 v26, 1, v26
	v_lshlrev_b32_e32 v4, 16, v56
	v_cvt_f32_u32_e32 v26, v26
	v_and_b32_e32 v5, 0xffff0000, v56
	v_sub_f32_e32 v25, v4, v121
	v_lshlrev_b32_e32 v6, 16, v57
	v_add_f32_e32 v15, v15, v25
	v_sub_f32_e32 v25, v5, v122
	v_and_b32_e32 v7, 0xffff0000, v57
	v_add_f32_e32 v20, v20, v25
	v_sub_f32_e32 v25, v6, v120
	v_lshlrev_b32_e32 v0, 16, v58
	v_add_f32_e32 v21, v21, v25
	v_sub_f32_e32 v25, v7, v119
	v_div_scale_f32 v27, s[0:1], v26, v26, 1.0
	v_and_b32_e32 v1, 0xffff0000, v58
	v_add_f32_e32 v22, v22, v25
	v_sub_f32_e32 v25, v0, v118
	v_rcp_f32_e32 v28, v27
	v_lshlrev_b32_e32 v2, 16, v59
	v_add_f32_e32 v23, v23, v25
	v_sub_f32_e32 v25, v1, v117
	v_and_b32_e32 v3, 0xffff0000, v59
	v_add_f32_e32 v24, v24, v25
	v_sub_f32_e32 v25, v2, v116
	v_add_f32_e32 v11, v11, v25
	v_sub_f32_e32 v25, v3, v115
	v_add_f32_e32 v10, v10, v25
	v_fma_f32 v25, -v27, v28, 1.0
	v_fmac_f32_e32 v28, v25, v28
	v_div_scale_f32 v25, vcc, 1.0, v26, 1.0
	v_mul_f32_e32 v29, v25, v28
	v_fma_f32 v30, -v27, v29, v25
	v_fmac_f32_e32 v29, v30, v28
	v_fma_f32 v25, -v27, v29, v25
	v_div_fmas_f32 v25, v25, v28, v29
	v_div_fixup_f32 v25, v25, v26, 1.0
	v_fma_f32 v26, v25, v15, -v4
	v_fma_f32 v27, v25, v20, -v5
	v_fma_f32 v28, v25, v21, -v6
	v_fma_f32 v30, v25, v23, -v0
	v_lshl_add_u64 v[8:9], v[82:83], 1, v[8:9]
	v_fma_f32 v29, v25, v22, -v7
	v_fma_f32 v31, v25, v24, -v1
	v_cvt_pk_bf16_f32 v26, v26, v27
	v_cvt_pk_bf16_f32 v27, v28, v29
	v_cvt_pk_bf16_f32 v28, v30, v31
	v_add_co_u32_e32 v30, vcc, 0x7900000, v8
	s_movk_i32 s0, 0x3fef
	s_nop 0
	v_addc_co_u32_e32 v31, vcc, 0, v9, vcc
	v_cmp_lt_u32_e64 s[0:1], s0, v101
	v_fma_f32 v32, v25, v11, -v2
	v_fma_f32 v25, v25, v10, -v3
	v_cvt_pk_bf16_f32 v29, v32, v25
	global_store_dwordx4 v[30:31], v[26:29], off offset:3072 nt
	s_and_saveexec_b64 s[12:13], s[0:1]
	s_cbranch_execz .LBB0_395
	v_add_u32_e32 v25, s7, v101
	v_add_u32_e32 v26, 0xffffc010, v25
	v_mov_b32_e32 v27, v97
	v_lshlrev_b64 v[26:27], 11, v[26:27]
	v_lshl_add_u64 v[26:27], v[86:87], 0, v[26:27]
	global_store_dwordx4 v[26:27], v[4:7], off nt
	global_store_dwordx4 v[26:27], v[0:3], off offset:16 nt
; __device__ __forceinline__ void unpack8(const u32x4 w, float* f) { f[0] = bf_lo(w.x); f[1] = bf_hi(w.x); f[2] = bf_lo(w.y); f[3] = bf_hi(w.y); f[4] = bf_lo(w.z); f[5] = bf_hi(w.z); f[6] = bf_lo(w.w); f[7] = bf_hi(w.w); }
; __device__ __forceinline__ u32x4 pack8(const float* f) { u32x4 w; w.x = cvt_pk_bf16(f[0], f[1]); w.y = cvt_pk_bf16(f[2], f[3]); w.z = cvt_pk_bf16(f[4], f[5]); w.w = cvt_pk_bf16(f[6], f[7]); return w; }
; template <int W>
; __device__ __forceinline__ void pool_task_prompt(const Params& p, int l, int b, int c, int g, int rg, int ch, long row0) {
;     ...
;     for (int r = 1; r < 4; ++r) { float xin[8], xout[8]; unpack8(raw[W - 1 + r], xin); unpack8(raw[r - 1], xout);
; #pragma unroll
;         for (int k = 0; k < 8; ++k) { a[r][k] = a[r - 1][k] + (xin[k] - xout[k]); cur[r][k] = xin[k]; } }
; #pragma unroll
;     for (int r = 0; r < 4; ++r) {
;         const int t = t0 + r;
;         const float inv = 1.0f / (float)((t + 1) < W ? (t + 1) : W);
;         float d[8];
; #pragma unroll
;         for (int k = 0; k < 8; ++k) d[k] = a[r][k] * inv - cur[r][k];
;         *(u32x4*)(AD + (size_t)(row0 + tl0 + r) * DM + 512 + col) = pack8(d);
;         if (t >= SEQ - 15) { float* pd = p.out + O_PP + (((size_t)l * 2 + b) * 15 + (t - (SEQ - 15))) * 512 + col;
;             *(f32x4*)pd = (f32x4){cur[r][0], cur[r][1], cur[r][2], cur[r][3]}; *(f32x4*)(pd + 4) = (f32x4){cur[r][4], cur[r][5], cur[r][6], cur[r][7]}; }
.LBB0_395:
	s_or_b64 exec, exec, s[12:13]
	v_add_u32_e32 v26, 2, v101
	v_min_i32_e32 v26, 15, v26
	v_add_u32_e32 v26, 1, v26
	v_lshlrev_b32_e32 v4, 16, v36
	v_cvt_f32_u32_e32 v26, v26
	v_and_b32_e32 v5, 0xffff0000, v36
	v_sub_f32_e32 v25, v4, v113
	v_lshlrev_b32_e32 v6, 16, v37
	v_add_f32_e32 v15, v25, v15
	v_sub_f32_e32 v25, v5, v114
	v_and_b32_e32 v7, 0xffff0000, v37
	v_add_f32_e32 v20, v25, v20
	v_sub_f32_e32 v25, v6, v112
	v_lshlrev_b32_e32 v0, 16, v38
	v_add_f32_e32 v21, v25, v21
	v_sub_f32_e32 v25, v7, v111
	v_div_scale_f32 v27, s[12:13], v26, v26, 1.0
	v_and_b32_e32 v1, 0xffff0000, v38
	v_add_f32_e32 v22, v25, v22
	v_sub_f32_e32 v25, v0, v110
	v_rcp_f32_e32 v28, v27
	v_lshlrev_b32_e32 v2, 16, v39
	v_add_f32_e32 v23, v25, v23
	v_sub_f32_e32 v25, v1, v109
	v_and_b32_e32 v3, 0xffff0000, v39
	v_add_f32_e32 v24, v25, v24
	v_sub_f32_e32 v25, v2, v108
	v_add_f32_e32 v11, v25, v11
	v_sub_f32_e32 v25, v3, v107
	v_add_f32_e32 v10, v25, v10
	v_fma_f32 v25, -v27, v28, 1.0
	v_fmac_f32_e32 v28, v25, v28
	v_div_scale_f32 v25, vcc, 1.0, v26, 1.0
	v_mul_f32_e32 v29, v25, v28
	v_fma_f32 v30, -v27, v29, v25
	v_fmac_f32_e32 v29, v30, v28
	v_fma_f32 v25, -v27, v29, v25
	v_div_fmas_f32 v25, v25, v28, v29
	v_div_fixup_f32 v25, v25, v26, 1.0
	v_fma_f32 v26, v25, v15, -v4
	v_fma_f32 v27, v25, v20, -v5
	v_fma_f32 v28, v25, v21, -v6
	v_fma_f32 v30, v25, v23, -v0
	v_fma_f32 v29, v25, v22, -v7
	v_fma_f32 v31, v25, v24, -v1
	v_cvt_pk_bf16_f32 v26, v26, v27
	v_cvt_pk_bf16_f32 v27, v28, v29
	v_cvt_pk_bf16_f32 v28, v30, v31
	v_add_co_u32_e32 v30, vcc, 0x7901000, v8
	v_fma_f32 v32, v25, v11, -v2
	s_nop 0
	v_addc_co_u32_e32 v31, vcc, 0, v9, vcc
	v_fma_f32 v25, v25, v10, -v3
	v_cvt_pk_bf16_f32 v29, v32, v25
	global_store_dwordx4 v[30:31], v[26:29], off offset:1024 nt
	s_and_saveexec_b64 s[12:13], s[0:1]
	s_cbranch_execz .LBB0_397
	v_add_u32_e32 v25, s7, v101
	v_add_u32_e32 v26, 0xffffc011, v25
	v_mov_b32_e32 v27, v97
	v_lshlrev_b64 v[26:27], 11, v[26:27]
	v_lshl_add_u64 v[26:27], v[86:87], 0, v[26:27]
	global_store_dwordx4 v[26:27], v[4:7], off nt
	global_store_dwordx4 v[26:27], v[0:3], off offset:16 nt
.LBB0_397:
	s_or_b64 exec, exec, s[12:13]
	v_lshlrev_b32_e32 v4, 16, v16
	v_and_b32_e32 v5, 0xffff0000, v16
	v_lshlrev_b32_e32 v6, 16, v17
	v_sub_f32_e32 v16, v4, v106
	v_sub_f32_e32 v12, v5, v12
	v_add_f32_e32 v15, v16, v15
	v_add_f32_e32 v12, v12, v20
	v_sub_f32_e32 v16, v6, v105
	v_add_u32_e32 v20, 3, v101
	v_add_f32_e32 v16, v16, v21
	v_min_i32_e32 v21, 15, v20
	v_add_u32_e32 v21, 1, v21
	v_cvt_f32_u32_e32 v21, v21
	v_and_b32_e32 v7, 0xffff0000, v17
	v_lshlrev_b32_e32 v0, 16, v18
	v_sub_f32_e32 v17, v7, v104
	v_and_b32_e32 v1, 0xffff0000, v18
	v_add_f32_e32 v17, v17, v22
	v_sub_f32_e32 v18, v0, v103
	v_div_scale_f32 v22, s[0:1], v21, v21, 1.0
	v_add_f32_e32 v18, v18, v23
	v_rcp_f32_e32 v23, v22
	v_and_b32_e32 v3, 0xffff0000, v19
	v_sub_f32_e32 v13, v3, v13
	v_lshlrev_b32_e32 v2, 16, v19
	v_add_f32_e32 v10, v13, v10
	v_fma_f32 v13, -v22, v23, 1.0
	v_sub_f32_e32 v14, v2, v14
	v_fmac_f32_e32 v23, v13, v23
	v_div_scale_f32 v13, vcc, 1.0, v21, 1.0
	v_sub_f32_e32 v19, v1, v102
	v_add_f32_e32 v11, v14, v11
	v_mul_f32_e32 v14, v13, v23
	v_add_f32_e32 v19, v19, v24
	v_fma_f32 v24, -v22, v14, v13
	v_fmac_f32_e32 v14, v24, v23
	v_fma_f32 v13, -v22, v14, v13
	v_div_fmas_f32 v13, v13, v23, v14
	v_add_co_u32_e32 v8, vcc, 0x7901000, v8
	s_movk_i32 s0, 0x3ff0
	s_nop 0
	v_addc_co_u32_e32 v9, vcc, 0, v9, vcc
	v_div_fixup_f32 v13, v13, v21, 1.0
	v_cmp_lt_u32_e32 vcc, s0, v20
	v_fma_f32 v14, v13, v15, -v4
	v_fma_f32 v12, v13, v12, -v5
	v_fma_f32 v15, v13, v16, -v6
	v_fma_f32 v16, v13, v17, -v7
	v_fma_f32 v17, v13, v18, -v0
	v_fma_f32 v18, v13, v19, -v1
	v_fma_f32 v19, v13, v11, -v2
	v_fma_f32 v13, v13, v10, -v3
	s_andn2_b64 s[0:1], s[8:9], exec
	s_and_b64 s[8:9], vcc, exec
	v_cvt_pk_bf16_f32 v10, v14, v12
	v_cvt_pk_bf16_f32 v11, v15, v16
	v_cvt_pk_bf16_f32 v12, v17, v18
	v_cvt_pk_bf16_f32 v13, v19, v13
	global_store_dwordx4 v[8:9], v[10:13], off offset:3072 nt
	s_or_b64 s[8:9], s[0:1], s[8:9]
	s_andn2_b64 s[2:3], s[2:3], exec
	v_mov_b64_e32 v[8:9], v[82:83]
	s_or_b64 exec, exec, s[10:11]
	s_and_saveexec_b64 s[0:1], s[2:3]
	s_xor_b64 s[2:3], exec, s[0:1]
	s_cbranch_execnz .LBB0_402

; __device__ __forceinline__ void unpack8(const u32x4 w, float* f) { f[0] = bf_lo(w.x); f[1] = bf_hi(w.x); f[2] = bf_lo(w.y); f[3] = bf_hi(w.y); f[4] = bf_lo(w.z); f[5] = bf_hi(w.z); f[6] = bf_lo(w.w); f[7] = bf_hi(w.w); }
; __device__ __forceinline__ u32x4 pack8(const float* f) { u32x4 w; w.x = cvt_pk_bf16(f[0], f[1]); w.y = cvt_pk_bf16(f[2], f[3]); w.z = cvt_pk_bf16(f[4], f[5]); w.w = cvt_pk_bf16(f[6], f[7]); return w; }
; template <int W>
; __device__ __forceinline__ void pool_task_prompt(const Params& p, int l, int b, int c, int g, int rg, int ch, long row0) {
;     ...
;     const int col = g * 128 + ch * 8, tl0 = 4 * rg, t0 = c * 64 + tl0;
;     u32x4 raw[W + 3];
; #pragma unroll
;     for (int i = 0; i < W + 3; ++i) { const int tt = t0 - (W - 1) + i; raw[i] = (u32x4){0u, 0u, 0u, 0u};
;         if (tt >= 0) raw[i] = *(const u32x4*)(P + (size_t)((long)b * SEQ + tt) * INW + 768 + col); }
;     float a[4][8], cur[4][8];
; #pragma unroll
;     for (int k = 0; k < 8; ++k) a[0][k] = 0.f;
; #pragma unroll
;     for (int i = 0; i < W; ++i) { float x[8]; unpack8(raw[i], x);
; #pragma unroll
;         for (int k = 0; k < 8; ++k) { a[0][k] += x[k]; if (i == W - 1) cur[0][k] = x[k]; } }
; #pragma unroll
;     for (int r = 1; r < 4; ++r) { float xin[8], xout[8]; unpack8(raw[W - 1 + r], xin); unpack8(raw[r - 1], xout);
; #pragma unroll
;         for (int k = 0; k < 8; ++k) { a[r][k] = a[r - 1][k] + (xin[k] - xout[k]); cur[r][k] = xin[k]; } }
; #pragma unroll
;     for (int r = 0; r < 4; ++r) {
;         const int t = t0 + r;
;         const float inv = 1.0f / (float)((t + 1) < W ? (t + 1) : W);
;         float d[8];
; #pragma unroll
;         for (int k = 0; k < 8; ++k) d[k] = a[r][k] * inv - cur[r][k];
;         *(u32x4*)(AD + (size_t)(row0 + tl0 + r) * DM + 512 + col) = pack8(d);
;         if (t >= SEQ - 15) { float* pd = p.out + O_PP + (((size_t)l * 2 + b) * 15 + (t - (SEQ - 15))) * 512 + col;
;             *(f32x4*)pd = (f32x4){cur[r][0], cur[r][1], cur[r][2], cur[r][3]}; *(f32x4*)(pd + 4) = (f32x4){cur[r][4], cur[r][5], cur[r][6], cur[r][7]}; }
.LBB0_404:
	s_or_b64 exec, exec, s[0:1]
	v_lshl_add_u64 v[0:1], s[86:87], 0, v[96:97]
	v_mov_b32_e32 v29, v97
	v_lshl_add_u64 v[0:1], v[0:1], 0, v[28:29]
	v_add_co_u32_e32 v2, vcc, 0xfb00000, v0
	s_waitcnt vmcnt(0) lgkmcnt(0)
	v_lshlrev_b32_e32 v36, 16, v8
	v_addc_co_u32_e32 v3, vcc, 0, v1, vcc
	global_load_dwordx4 v[20:23], v[2:3], off offset:1536
	v_add_co_u32_e32 v2, vcc, 0xfb02000, v0
	v_and_b32_e32 v37, 0xffff0000, v8
	s_nop 0
	v_addc_co_u32_e32 v3, vcc, 0, v1, vcc
	v_add_co_u32_e32 v4, vcc, 0xfb03000, v0
	global_load_dwordx4 v[16:19], v[2:3], off
	s_nop 0
	v_addc_co_u32_e32 v5, vcc, 0, v1, vcc
	v_add_co_u32_e32 v0, vcc, 0xfb05000, v0
	v_min_i32_e32 v8, 1, v101
	s_nop 0
	v_addc_co_u32_e32 v1, vcc, 0, v1, vcc
	global_load_dwordx4 v[4:7], v[4:5], off offset:2560
	s_nop 0
	global_load_dwordx4 v[0:3], v[0:1], off offset:1024
	v_add_u32_e32 v8, 1, v8
	v_cvt_f32_u32_e32 v8, v8
	v_lshlrev_b32_e32 v35, 16, v9
	v_and_b32_e32 v34, 0xffff0000, v9
	v_lshlrev_b32_e32 v33, 16, v10
	v_div_scale_f32 v9, s[0:1], v8, v8, 1.0
	v_and_b32_e32 v32, 0xffff0000, v10
	v_rcp_f32_e32 v10, v9
	v_lshlrev_b32_e32 v27, 16, v11
	v_and_b32_e32 v26, 0xffff0000, v11
	v_div_scale_f32 v11, vcc, 1.0, v8, 1.0
	v_fma_f32 v12, -v9, v10, 1.0
	v_fmac_f32_e32 v10, v12, v10
	v_mul_f32_e32 v12, v11, v10
	v_fma_f32 v13, -v9, v12, v11
	v_fmac_f32_e32 v12, v13, v10
	v_fma_f32 v9, -v9, v12, v11
	v_div_fmas_f32 v9, v9, v10, v12
	v_add_f32_e32 v24, 0, v36
	v_add_f32_e32 v25, 0, v37
	v_add_f32_e32 v30, 0, v35
	v_add_f32_e32 v31, 0, v34
	v_add_f32_e32 v38, 0, v33
	v_add_f32_e32 v39, 0, v32
	v_add_f32_e32 v46, 0, v27
	v_add_f32_e32 v47, 0, v26
	v_div_fixup_f32 v48, v9, v8, 1.0
	v_mov_b32_e32 v93, v97
	s_movk_i32 s0, 0x3ff0
	s_waitcnt vmcnt(0) lgkmcnt(0)
	v_lshlrev_b32_e32 v12, 16, v20
	v_and_b32_e32 v13, 0xffff0000, v20
	v_lshlrev_b32_e32 v14, 16, v21
	v_and_b32_e32 v15, 0xffff0000, v21
	v_lshlrev_b32_e32 v8, 16, v22
	v_and_b32_e32 v9, 0xffff0000, v22
	v_lshlrev_b32_e32 v10, 16, v23
	v_and_b32_e32 v11, 0xffff0000, v23
	v_add_f32_e32 v45, v24, v12
	v_add_f32_e32 v44, v25, v13
	v_add_f32_e32 v43, v30, v14
	v_add_f32_e32 v42, v31, v15
	v_add_f32_e32 v41, v38, v8
	v_add_f32_e32 v40, v39, v9
	v_add_f32_e32 v39, v46, v10
	v_add_f32_e32 v38, v47, v11
	v_fma_f32 v20, v48, v45, -v12
	v_fma_f32 v21, v48, v44, -v13
	v_fma_f32 v22, v48, v43, -v14
	v_fma_f32 v23, v48, v42, -v15
	v_fma_f32 v30, v48, v39, -v10
	v_fma_f32 v31, v48, v38, -v11
	v_fma_f32 v24, v48, v41, -v8
	v_fma_f32 v25, v48, v40, -v9
	v_cvt_pk_bf16_f32 v20, v20, v21
	v_cvt_pk_bf16_f32 v21, v22, v23
	v_cvt_pk_bf16_f32 v22, v24, v25
	v_cvt_pk_bf16_f32 v23, v30, v31
	v_lshl_add_u64 v[30:31], s[86:87], 0, v[92:93]
	v_lshl_add_u64 v[24:25], v[30:31], 0, v[28:29]
	v_add_co_u32_e32 v46, vcc, 0x7900000, v24
	s_nop 1
	v_addc_co_u32_e32 v47, vcc, 0, v25, vcc
	v_cmp_lt_u32_e32 vcc, s0, v101
	global_store_dwordx4 v[46:47], v[20:23], off offset:1024 nt
	s_and_saveexec_b64 s[0:1], vcc
	s_cbranch_execz .LBB0_406
	v_add_u32_e32 v20, s7, v101
	v_add_u32_e32 v20, 0xffffc00f, v20
	v_mov_b32_e32 v21, v97
	v_lshlrev_b64 v[20:21], 11, v[20:21]
	v_lshl_add_u64 v[20:21], v[84:85], 0, v[20:21]
	global_store_dwordx4 v[20:21], v[12:15], off nt
	global_store_dwordx4 v[20:21], v[8:11], off offset:16 nt
.LBB0_406:
	s_or_b64 exec, exec, s[0:1]
	v_lshlrev_b32_e32 v20, 16, v16
	v_and_b32_e32 v21, 0xffff0000, v16
	v_lshlrev_b32_e32 v22, 16, v17
	v_and_b32_e32 v23, 0xffff0000, v17
	v_lshlrev_b32_e32 v16, 16, v18
	v_and_b32_e32 v17, 0xffff0000, v18
	v_lshlrev_b32_e32 v18, 16, v19
	v_and_b32_e32 v19, 0xffff0000, v19
	v_sub_f32_e32 v34, v23, v34
	v_sub_f32_e32 v33, v16, v33
	v_sub_f32_e32 v32, v17, v32
	v_sub_f32_e32 v29, v20, v36
	v_sub_f32_e32 v36, v21, v37
	v_sub_f32_e32 v35, v22, v35
	v_add_f32_e32 v34, v42, v34
	v_add_f32_e32 v33, v41, v33
	v_add_f32_e32 v32, v40, v32
	v_sub_f32_e32 v27, v18, v27
	v_sub_f32_e32 v26, v19, v26
	v_add_co_u32_e32 v24, vcc, 0x7900000, v24
	s_movk_i32 s0, 0x3fef
	v_add_f32_e32 v29, v45, v29
	v_add_f32_e32 v36, v44, v36
	v_add_f32_e32 v35, v43, v35
	v_add_f32_e32 v37, v39, v27
	v_add_f32_e32 v38, v38, v26
	v_fma_f32 v41, v34, 0.5, -v23
	v_fma_f32 v42, v33, 0.5, -v16
	v_fma_f32 v43, v32, 0.5, -v17
	v_addc_co_u32_e32 v25, vcc, 0, v25, vcc
	v_cmp_lt_u32_e64 s[0:1], s0, v101
	v_fma_f32 v26, v29, 0.5, -v20
	v_fma_f32 v27, v36, 0.5, -v21
	v_fma_f32 v39, v35, 0.5, -v22
	v_fma_f32 v44, v37, 0.5, -v18
	v_fma_f32 v45, v38, 0.5, -v19
	v_cvt_pk_bf16_f32 v40, v26, v27
	v_cvt_pk_bf16_f32 v41, v39, v41
	v_cvt_pk_bf16_f32 v42, v42, v43
	v_cvt_pk_bf16_f32 v43, v44, v45
	global_store_dwordx4 v[24:25], v[40:43], off offset:3072 nt
	s_and_saveexec_b64 s[10:11], s[0:1]
	s_cbranch_execz .LBB0_408
	v_add_u32_e32 v24, s7, v101
	v_add_u32_e32 v24, 0xffffc010, v24
	v_mov_b32_e32 v25, v97
	v_lshlrev_b64 v[24:25], 11, v[24:25]
	v_lshl_add_u64 v[24:25], v[84:85], 0, v[24:25]
	global_store_dwordx4 v[24:25], v[20:23], off nt
	global_store_dwordx4 v[24:25], v[16:19], off offset:16 nt
; __device__ __forceinline__ void unpack8(const u32x4 w, float* f) { f[0] = bf_lo(w.x); f[1] = bf_hi(w.x); f[2] = bf_lo(w.y); f[3] = bf_hi(w.y); f[4] = bf_lo(w.z); f[5] = bf_hi(w.z); f[6] = bf_lo(w.w); f[7] = bf_hi(w.w); }
; __device__ __forceinline__ u32x4 pack8(const float* f) { u32x4 w; w.x = cvt_pk_bf16(f[0], f[1]); w.y = cvt_pk_bf16(f[2], f[3]); w.z = cvt_pk_bf16(f[4], f[5]); w.w = cvt_pk_bf16(f[6], f[7]); return w; }
; template <int W>
; __device__ __forceinline__ void pool_task_prompt(const Params& p, int l, int b, int c, int g, int rg, int ch, long row0) {
;     ...
;     for (int r = 1; r < 4; ++r) { float xin[8], xout[8]; unpack8(raw[W - 1 + r], xin); unpack8(raw[r - 1], xout);
; #pragma unroll
;         for (int k = 0; k < 8; ++k) { a[r][k] = a[r - 1][k] + (xin[k] - xout[k]); cur[r][k] = xin[k]; } }
; #pragma unroll
;     for (int r = 0; r < 4; ++r) {
;         const int t = t0 + r;
;         const float inv = 1.0f / (float)((t + 1) < W ? (t + 1) : W);
;         float d[8];
; #pragma unroll
;         for (int k = 0; k < 8; ++k) d[k] = a[r][k] * inv - cur[r][k];
;         *(u32x4*)(AD + (size_t)(row0 + tl0 + r) * DM + 512 + col) = pack8(d);
;         if (t >= SEQ - 15) { float* pd = p.out + O_PP + (((size_t)l * 2 + b) * 15 + (t - (SEQ - 15))) * 512 + col;
;             *(f32x4*)pd = (f32x4){cur[r][0], cur[r][1], cur[r][2], cur[r][3]}; *(f32x4*)(pd + 4) = (f32x4){cur[r][4], cur[r][5], cur[r][6], cur[r][7]}; }
.LBB0_408:
	s_or_b64 exec, exec, s[10:11]
	v_lshlrev_b32_e32 v24, 16, v4
	v_and_b32_e32 v25, 0xffff0000, v4
	v_lshlrev_b32_e32 v4, 16, v6
	v_lshlrev_b32_e32 v26, 16, v5
	v_and_b32_e32 v27, 0xffff0000, v5
	v_and_b32_e32 v5, 0xffff0000, v6
	v_sub_f32_e32 v8, v4, v8
	v_lshlrev_b32_e32 v6, 16, v7
	v_sub_f32_e32 v14, v26, v14
	v_sub_f32_e32 v15, v27, v15
	v_add_f32_e32 v33, v8, v33
	v_sub_f32_e32 v8, v5, v9
	v_and_b32_e32 v7, 0xffff0000, v7
	v_sub_f32_e32 v12, v24, v12
	v_sub_f32_e32 v13, v25, v13
	v_add_f32_e32 v14, v14, v35
	v_add_f32_e32 v15, v15, v34
	v_add_f32_e32 v32, v8, v32
	v_sub_f32_e32 v8, v6, v10
	v_add_f32_e32 v12, v12, v29
	v_add_f32_e32 v13, v13, v36
	v_add_f32_e32 v10, v8, v37
	v_sub_f32_e32 v8, v7, v11
	v_fma_f32 v29, v14, 0.5, -v26
	v_fma_f32 v35, v15, 0.5, -v27
	v_add_f32_e32 v11, v8, v38
	v_fma_f32 v8, v12, 0.5, -v24
	v_fma_f32 v9, v13, 0.5, -v25
	v_cvt_pk_bf16_f32 v34, v8, v9
	v_cvt_pk_bf16_f32 v35, v29, v35
	v_mov_b32_e32 v29, v97
	v_lshl_add_u64 v[8:9], v[30:31], 0, v[28:29]
	v_add_co_u32_e32 v28, vcc, 0x7901000, v8
	v_fma_f32 v36, v33, 0.5, -v4
	v_fma_f32 v37, v32, 0.5, -v5
	v_addc_co_u32_e32 v29, vcc, 0, v9, vcc
	v_fma_f32 v38, v10, 0.5, -v6
	v_fma_f32 v39, v11, 0.5, -v7
	v_cvt_pk_bf16_f32 v36, v36, v37
	v_cvt_pk_bf16_f32 v37, v38, v39
	global_store_dwordx4 v[28:29], v[34:37], off offset:1024 nt
	s_and_saveexec_b64 s[10:11], s[0:1]
	s_cbranch_execz .LBB0_410
	v_add_u32_e32 v28, s7, v101
	v_add_u32_e32 v28, 0xffffc011, v28
	v_mov_b32_e32 v29, v97
	v_lshlrev_b64 v[28:29], 11, v[28:29]
	v_lshl_add_u64 v[28:29], v[84:85], 0, v[28:29]
	global_store_dwordx4 v[28:29], v[24:27], off nt
	global_store_dwordx4 v[28:29], v[4:7], off offset:16 nt
.LBB0_410:
	s_or_b64 exec, exec, s[10:11]
	s_nop 0
	v_lshlrev_b32_e32 v4, 16, v0
	v_and_b32_e32 v5, 0xffff0000, v0
	v_lshlrev_b32_e32 v6, 16, v1
	v_and_b32_e32 v7, 0xffff0000, v1
	v_lshlrev_b32_e32 v0, 16, v2
	v_and_b32_e32 v1, 0xffff0000, v2
	v_lshlrev_b32_e32 v2, 16, v3
	v_and_b32_e32 v3, 0xffff0000, v3
	v_sub_f32_e32 v20, v4, v20
	v_sub_f32_e32 v18, v2, v18
	v_add_f32_e32 v12, v20, v12
	v_sub_f32_e32 v20, v5, v21
	v_add_f32_e32 v10, v18, v10
	v_sub_f32_e32 v18, v3, v19
	v_add_co_u32_e32 v8, vcc, 0x7901000, v8
	v_add_f32_e32 v13, v20, v13
	v_sub_f32_e32 v20, v6, v22
	v_add_f32_e32 v11, v18, v11
	v_add_u32_e32 v18, 3, v101
	v_addc_co_u32_e32 v9, vcc, 0, v9, vcc
	s_movk_i32 s0, 0x3ff0
	v_add_f32_e32 v14, v20, v14
	v_sub_f32_e32 v20, v7, v23
	v_sub_f32_e32 v16, v0, v16
	v_sub_f32_e32 v17, v1, v17
	v_cmp_lt_u32_e32 vcc, s0, v18
	v_add_f32_e32 v15, v20, v15
	v_add_f32_e32 v16, v16, v33
	v_add_f32_e32 v17, v17, v32
	v_fma_f32 v12, v12, 0.5, -v4
	v_fma_f32 v13, v13, 0.5, -v5
	s_andn2_b64 s[0:1], s[8:9], exec
	s_and_b64 s[8:9], vcc, exec
	v_fma_f32 v14, v14, 0.5, -v6
	v_fma_f32 v15, v15, 0.5, -v7
	v_fma_f32 v16, v16, 0.5, -v0
	v_fma_f32 v17, v17, 0.5, -v1
	v_fma_f32 v19, v10, 0.5, -v2
	v_fma_f32 v20, v11, 0.5, -v3
	v_cvt_pk_bf16_f32 v10, v12, v13
	v_cvt_pk_bf16_f32 v11, v14, v15
	v_cvt_pk_bf16_f32 v12, v16, v17
	v_cvt_pk_bf16_f32 v13, v19, v20
	global_store_dwordx4 v[8:9], v[10:13], off offset:3072 nt
	s_or_b64 s[8:9], s[0:1], s[8:9]
	v_mov_b64_e32 v[8:9], v[76:77]
	s_or_b64 exec, exec, s[2:3]
	s_and_saveexec_b64 s[0:1], s[8:9]
	s_cbranch_execz .LBB0_319
.LBB0_411:
	v_add_u32_e32 v10, s7, v101
	v_add_u32_e32 v10, 0xffffc012, v10
	v_mov_b32_e32 v11, v97
	v_lshlrev_b64 v[10:11], 11, v[10:11]
	v_lshl_add_u64 v[10:11], s[60:61], 0, v[10:11]
	v_lshl_add_u64 v[8:9], v[8:9], 2, v[10:11]
	global_store_dwordx4 v[8:9], v[4:7], off nt
	global_store_dwordx4 v[8:9], v[0:3], off offset:16 nt
	s_branch .LBB0_319

; __device__ __forceinline__ void unpack8(const u32x4 w, float* f) { f[0] = bf_lo(w.x); f[1] = bf_hi(w.x); f[2] = bf_lo(w.y); f[3] = bf_hi(w.y); f[4] = bf_lo(w.z); f[5] = bf_hi(w.z); f[6] = bf_lo(w.w); f[7] = bf_hi(w.w); }
; __device__ __forceinline__ u32x4 pack8(const float* f) { u32x4 w; w.x = cvt_pk_bf16(f[0], f[1]); w.y = cvt_pk_bf16(f[2], f[3]); w.z = cvt_pk_bf16(f[4], f[5]); w.w = cvt_pk_bf16(f[6], f[7]); return w; }
; template <int W>
; __device__ __forceinline__ void pool_items(const Params& p, int l, bool sample, int b, int c, int g, long row0, int tid) {
;     ...
;         for (int i = 0; i < W; ++i) {
;             const int tt = t - i;
;             raw[i] = (u32x4){0u, 0u, 0u, 0u}; h0[i] = (f32x4){0.f, 0.f, 0.f, 0.f}; h1[i] = h0[i];
;             if (tt >= 0) raw[i] = *(const u32x4*)(P + (size_t)(prow - i) * INW + 768 + col);
;             else if (sample) { const float* sp = p.state_pool + (((size_t)l * 8 + b) * 15 + (15 + tt)) * 512 + col; h0[i] = *(const f32x4*)sp; h1[i] = *(const f32x4*)(sp + 4); }
;         }
;         float cur[8], a[8];
;         unpack8(raw[0], cur);
; #pragma unroll
;         for (int k = 0; k < 8; ++k) a[k] = cur[k];
; #pragma unroll
;         for (int i = 1; i < W; ++i) { float x[8]; unpack8(raw[i], x);
; #pragma unroll
;             for (int k = 0; k < 4; ++k) { a[k] += x[k] + h0[i][k]; a[4 + k] += x[4 + k] + h1[i][k]; } }
;         const float cnt = sample ? (float)W : (float)((t + 1) < W ? (t + 1) : W);
;         const float inv = 1.0f / cnt;
;         float d[8];
; #pragma unroll
;         for (int k = 0; k < 8; ++k) d[k] = a[k] * inv - cur[k];
;         *(u32x4*)(AD + (size_t)prow * DM + 512 + col) = pack8(d);
;         float* pd = nullptr;
;         if (!sample) { if (t >= SEQ - 15) pd = p.out + O_PP + (((size_t)l * 2 + b) * 15 + (t - (SEQ - 15))) * 512 + col; }
;         else if (tl >= 1) pd = p.out + O_PS + (((size_t)l * 8 + b) * 15 + (tl - 1)) * 512 + col;
;         if (pd) { *(f32x4*)pd = (f32x4){cur[0], cur[1], cur[2], cur[3]}; *(f32x4*)(pd + 4) = (f32x4){cur[4], cur[5], cur[6], cur[7]}; }
.LBB0_448:
	s_or_b64 exec, exec, s[14:15]
	s_waitcnt vmcnt(0) lgkmcnt(0)
	v_lshlrev_b32_e32 v69, 16, v4
	v_and_b32_e32 v4, 0xffff0000, v4
	v_and_b32_e32 v61, 0xffff0000, v0
	v_lshlrev_b32_e32 v102, 16, v6
	v_and_b32_e32 v6, 0xffff0000, v6
	v_add_f32_e32 v4, v9, v4
	v_lshlrev_b32_e32 v62, 16, v1
	v_and_b32_e32 v63, 0xffff0000, v1
	v_and_b32_e32 v1, 0xffff0000, v2
	v_lshlrev_b32_e32 v71, 16, v5
	v_add_f32_e32 v9, v4, v61
	v_add_f32_e32 v4, v13, v6
	v_lshlrev_b32_e32 v103, 16, v7
	v_add_f32_e32 v6, v4, v1
	v_add_f32_e32 v4, v10, v71
	v_lshlrev_b32_e32 v60, 16, v0
	v_lshlrev_b32_e32 v0, 16, v2
	v_lshlrev_b32_e32 v2, 16, v3
	v_and_b32_e32 v5, 0xffff0000, v5
	v_add_f32_e32 v10, v4, v62
	v_add_f32_e32 v4, v14, v103
	v_and_b32_e32 v7, 0xffff0000, v7
	v_add_f32_e32 v13, v4, v2
	v_add_f32_e32 v4, v11, v5
	v_and_b32_e32 v3, 0xffff0000, v3
	v_add_f32_e32 v11, v4, v63
	v_add_f32_e32 v4, v15, v7
	v_add_f32_e32 v8, v8, v69
	v_add_f32_e32 v7, v4, v3
	v_lshlrev_b32_e32 v5, 16, v28
	v_lshlrev_b32_e32 v4, 16, v24
	v_add_f32_e32 v8, v8, v60
	v_pk_add_f32 v[4:5], v[20:21], v[4:5]
	v_add_f32_e32 v12, v12, v102
	v_add_f32_e32 v4, v8, v4
	v_add_f32_e32 v8, v4, v5
	v_lshlrev_b32_e32 v5, 16, v30
	v_lshlrev_b32_e32 v4, 16, v26
	v_add_f32_e32 v12, v12, v0
	v_pk_add_f32 v[4:5], v[16:17], v[4:5]
	s_mov_b32 s7, 0x3e000000
	v_add_f32_e32 v4, v12, v4
	v_add_f32_e32 v12, v4, v5
	v_and_b32_e32 v5, 0xffff0000, v28
	v_and_b32_e32 v4, 0xffff0000, v24
	v_pk_add_f32 v[4:5], v[80:81], v[4:5]
	v_mov_b32_e32 v71, v97
	v_add_f32_e32 v4, v9, v4
	v_add_f32_e32 v9, v4, v5
	v_and_b32_e32 v5, 0xffff0000, v30
	v_and_b32_e32 v4, 0xffff0000, v26
	v_pk_add_f32 v[4:5], v[78:79], v[4:5]
	s_nop 0
	v_add_f32_e32 v4, v6, v4
	v_add_f32_e32 v6, v4, v5
	v_lshlrev_b32_e32 v4, 16, v25
	v_lshlrev_b32_e32 v5, 16, v29
	v_pk_add_f32 v[4:5], v[22:23], v[4:5]
	s_nop 0
	v_add_f32_e32 v4, v10, v4
	v_add_f32_e32 v10, v4, v5
	v_lshlrev_b32_e32 v4, 16, v27
	v_lshlrev_b32_e32 v5, 16, v31
	v_pk_add_f32 v[4:5], v[18:19], v[4:5]
	s_nop 0
	v_add_f32_e32 v4, v13, v4
	v_add_f32_e32 v13, v4, v5
	v_and_b32_e32 v5, 0xffff0000, v29
	v_and_b32_e32 v4, 0xffff0000, v25
	v_pk_add_f32 v[4:5], v[76:77], v[4:5]
	s_nop 0
	v_add_f32_e32 v4, v11, v4
	v_add_f32_e32 v11, v4, v5
	v_and_b32_e32 v5, 0xffff0000, v31
	v_and_b32_e32 v4, 0xffff0000, v27
	v_pk_add_f32 v[4:5], v[74:75], v[4:5]
	s_nop 0
	v_add_f32_e32 v4, v7, v4
	v_add_f32_e32 v7, v4, v5
	v_lshlrev_b32_e32 v5, 16, v44
	v_lshlrev_b32_e32 v4, 16, v40
	v_pk_add_f32 v[4:5], v[36:37], v[4:5]
	s_nop 0
	v_add_f32_e32 v4, v8, v4
	v_add_f32_e32 v8, v4, v5
	v_lshlrev_b32_e32 v5, 16, v46
	v_lshlrev_b32_e32 v4, 16, v42
	v_pk_add_f32 v[4:5], v[32:33], v[4:5]
	s_nop 0
	v_add_f32_e32 v4, v12, v4
	v_add_f32_e32 v12, v4, v5
	v_and_b32_e32 v5, 0xffff0000, v44
	v_and_b32_e32 v4, 0xffff0000, v40
	v_pk_add_f32 v[4:5], v[88:89], v[4:5]
	s_nop 0
	v_add_f32_e32 v4, v9, v4
	v_add_f32_e32 v9, v4, v5
	v_and_b32_e32 v5, 0xffff0000, v46
	v_and_b32_e32 v4, 0xffff0000, v42
	v_pk_add_f32 v[4:5], v[86:87], v[4:5]
	s_nop 0
	v_add_f32_e32 v4, v6, v4
	v_add_f32_e32 v6, v4, v5
	v_lshlrev_b32_e32 v4, 16, v41
	v_lshlrev_b32_e32 v5, 16, v45
	v_pk_add_f32 v[4:5], v[38:39], v[4:5]
	s_nop 0
	v_add_f32_e32 v4, v10, v4
	v_add_f32_e32 v10, v4, v5
	v_lshlrev_b32_e32 v4, 16, v43
	v_lshlrev_b32_e32 v5, 16, v47
	v_pk_add_f32 v[4:5], v[34:35], v[4:5]
	s_nop 0
	v_add_f32_e32 v4, v13, v4
	v_add_f32_e32 v13, v4, v5
	v_and_b32_e32 v5, 0xffff0000, v45
	v_and_b32_e32 v4, 0xffff0000, v41
	v_pk_add_f32 v[4:5], v[84:85], v[4:5]
	s_nop 0
	v_add_f32_e32 v4, v11, v4
	v_add_f32_e32 v11, v4, v5
	v_and_b32_e32 v5, 0xffff0000, v47
	v_and_b32_e32 v4, 0xffff0000, v43
	v_pk_add_f32 v[4:5], v[82:83], v[4:5]
	s_nop 0
	v_add_f32_e32 v4, v7, v4
	v_add_f32_e32 v7, v4, v5
	v_lshlrev_b32_e32 v5, 16, v64
	v_lshlrev_b32_e32 v4, 16, v56
	v_pk_add_f32 v[4:5], v[52:53], v[4:5]
	s_nop 0
	v_add_f32_e32 v4, v8, v4
	v_add_f32_e32 v8, v4, v5
	v_lshlrev_b32_e32 v5, 16, v66
	v_lshlrev_b32_e32 v4, 16, v58
	v_pk_add_f32 v[4:5], v[48:49], v[4:5]
	s_nop 0
	v_add_f32_e32 v4, v12, v4
	v_add_f32_e32 v12, v4, v5
	v_and_b32_e32 v5, 0xffff0000, v64
	v_and_b32_e32 v4, 0xffff0000, v56
	v_pk_add_f32 v[4:5], v[98:99], v[4:5]
	s_nop 0
	v_add_f32_e32 v4, v9, v4
	v_add_f32_e32 v9, v4, v5
	v_and_b32_e32 v5, 0xffff0000, v66
	v_and_b32_e32 v4, 0xffff0000, v58
	v_pk_add_f32 v[4:5], v[94:95], v[4:5]
	s_nop 0
	v_add_f32_e32 v4, v6, v4
	v_add_f32_e32 v6, v4, v5
	v_lshlrev_b32_e32 v4, 16, v57
	v_lshlrev_b32_e32 v5, 16, v65
	v_pk_add_f32 v[4:5], v[54:55], v[4:5]
	v_fma_f32 v6, v6, s7, -v1
	v_add_f32_e32 v4, v10, v4
	v_add_f32_e32 v10, v4, v5
	v_lshlrev_b32_e32 v4, 16, v59
	v_lshlrev_b32_e32 v5, 16, v67
	v_pk_add_f32 v[4:5], v[50:51], v[4:5]
	s_nop 0
	v_add_f32_e32 v4, v13, v4
	v_add_f32_e32 v13, v4, v5
	v_and_b32_e32 v5, 0xffff0000, v65
	v_and_b32_e32 v4, 0xffff0000, v57
	v_pk_add_f32 v[4:5], v[92:93], v[4:5]
	s_nop 0
	v_add_f32_e32 v4, v11, v4
	v_add_f32_e32 v11, v4, v5
	v_and_b32_e32 v5, 0xffff0000, v67
	v_and_b32_e32 v4, 0xffff0000, v59
	v_pk_add_f32 v[4:5], v[90:91], v[4:5]
	s_nop 0
	v_add_f32_e32 v4, v7, v4
	v_add_f32_e32 v4, v4, v5
	v_fma_f32 v5, v8, s7, -v60
	v_fma_f32 v7, v9, s7, -v61
	v_fma_f32 v8, v10, s7, -v62
	v_fma_f32 v9, v11, s7, -v63
	v_fma_f32 v10, v12, s7, -v0
	v_fma_f32 v12, v4, s7, -v3
	v_cvt_pk_bf16_f32 v4, v5, v7
	v_cvt_pk_bf16_f32 v5, v8, v9
	v_lshlrev_b64 v[8:9], 11, v[72:73]
	v_lshl_add_u64 v[8:9], s[86:87], 0, v[8:9]
	v_lshl_add_u64 v[8:9], v[8:9], 0, v[70:71]
	v_add_co_u32_e32 v8, vcc, 0x7900000, v8
	v_fma_f32 v11, v13, s7, -v2
	s_nop 0
	v_addc_co_u32_e32 v9, vcc, 0, v9, vcc
	v_cvt_pk_bf16_f32 v6, v10, v6
	v_cvt_pk_bf16_f32 v7, v11, v12
	global_store_dwordx4 v[8:9], v[4:7], off offset:1024 nt
	s_and_saveexec_b64 s[14:15], s[44:45]
	s_cbranch_execz .LBB0_417
	v_add_u32_e32 v4, -1, v68
	v_mov_b32_e32 v5, v97
	v_lshl_add_u64 v[4:5], s[2:3], 0, v[4:5]
	v_lshlrev_b64 v[4:5], 11, v[4:5]
	v_lshl_add_u64 v[4:5], s[62:63], 0, v[4:5]
	v_lshl_add_u64 v[4:5], v[4:5], 0, v[96:97]
	global_store_dwordx4 v[4:5], v[60:63], off offset:1024 nt
	global_store_dwordx4 v[4:5], v[0:3], off offset:1040 nt
	s_branch .LBB0_417

; __device__ __forceinline__ void unpack8(const u32x4 w, float* f) { f[0] = bf_lo(w.x); f[1] = bf_hi(w.x); f[2] = bf_lo(w.y); f[3] = bf_hi(w.y); f[4] = bf_lo(w.z); f[5] = bf_hi(w.z); f[6] = bf_lo(w.w); f[7] = bf_hi(w.w); }
; __device__ __forceinline__ u32x4 pack8(const float* f) { u32x4 w; w.x = cvt_pk_bf16(f[0], f[1]); w.y = cvt_pk_bf16(f[2], f[3]); w.z = cvt_pk_bf16(f[4], f[5]); w.w = cvt_pk_bf16(f[6], f[7]); return w; }
; template <int W>
; __device__ __forceinline__ void pool_items(const Params& p, int l, bool sample, int b, int c, int g, long row0, int tid) {
;     ...
;         unpack8(raw[0], cur);
; #pragma unroll
;         for (int k = 0; k < 8; ++k) a[k] = cur[k];
; #pragma unroll
;         for (int i = 1; i < W; ++i) { float x[8]; unpack8(raw[i], x);
; #pragma unroll
;             for (int k = 0; k < 4; ++k) { a[k] += x[k] + h0[i][k]; a[4 + k] += x[4 + k] + h1[i][k]; } }
;         const float cnt = sample ? (float)W : (float)((t + 1) < W ? (t + 1) : W);
;         const float inv = 1.0f / cnt;
;         float d[8];
; #pragma unroll
;         for (int k = 0; k < 8; ++k) d[k] = a[k] * inv - cur[k];
;         *(u32x4*)(AD + (size_t)prow * DM + 512 + col) = pack8(d);
;         float* pd = nullptr;
;         if (!sample) { if (t >= SEQ - 15) pd = p.out + O_PP + (((size_t)l * 2 + b) * 15 + (t - (SEQ - 15))) * 512 + col; }
;         else if (tl >= 1) pd = p.out + O_PS + (((size_t)l * 8 + b) * 15 + (tl - 1)) * 512 + col;
;         if (pd) { *(f32x4*)pd = (f32x4){cur[0], cur[1], cur[2], cur[3]}; *(f32x4*)(pd + 4) = (f32x4){cur[4], cur[5], cur[6], cur[7]}; }
.LBB0_460:
	s_or_b64 exec, exec, s[16:17]
	s_waitcnt vmcnt(0) lgkmcnt(0)
	v_lshlrev_b32_e32 v21, 16, v4
	v_and_b32_e32 v4, 0xffff0000, v4
	v_lshlrev_b32_e32 v25, 16, v5
	v_and_b32_e32 v5, 0xffff0000, v5
	v_lshlrev_b32_e32 v12, 16, v0
	v_and_b32_e32 v13, 0xffff0000, v0
	v_lshlrev_b32_e32 v14, 16, v1
	v_and_b32_e32 v15, 0xffff0000, v1
	v_add_f32_e32 v8, v8, v21
	v_add_f32_e32 v4, v9, v4
	v_add_f32_e32 v9, v10, v25
	v_add_f32_e32 v5, v11, v5
	v_add_f32_e32 v8, v8, v12
	v_add_f32_e32 v4, v4, v13
	v_add_f32_e32 v9, v9, v14
	v_add_f32_e32 v5, v5, v15
	v_fma_f32 v8, v8, 0.5, -v12
	v_fma_f32 v4, v4, 0.5, -v13
	v_fma_f32 v9, v9, 0.5, -v14
	v_fma_f32 v5, v5, 0.5, -v15
	v_cvt_pk_bf16_f32 v4, v8, v4
	v_cvt_pk_bf16_f32 v5, v9, v5
	v_lshlrev_b64 v[8:9], 11, v[22:23]
	v_lshlrev_b32_e32 v28, 16, v6
	v_and_b32_e32 v6, 0xffff0000, v6
	v_lshlrev_b32_e32 v29, 16, v7
	v_and_b32_e32 v7, 0xffff0000, v7
	v_lshl_add_u64 v[8:9], s[86:87], 0, v[8:9]
	v_lshlrev_b32_e32 v0, 16, v2
	v_and_b32_e32 v1, 0xffff0000, v2
	v_lshlrev_b32_e32 v2, 16, v3
	v_and_b32_e32 v3, 0xffff0000, v3
	v_add_f32_e32 v6, v17, v6
	v_add_f32_e32 v7, v19, v7
	v_lshl_add_u64 v[8:9], v[8:9], 0, v[96:97]
	v_add_f32_e32 v16, v16, v28
	v_add_f32_e32 v6, v6, v1
	v_add_f32_e32 v10, v18, v29
	v_add_f32_e32 v7, v7, v3
	v_add_co_u32_e32 v8, vcc, 0x7900000, v8
	v_add_f32_e32 v16, v16, v0
	v_add_f32_e32 v10, v10, v2
	v_fma_f32 v6, v6, 0.5, -v1
	v_fma_f32 v7, v7, 0.5, -v3
	v_addc_co_u32_e32 v9, vcc, 0, v9, vcc
	v_fma_f32 v11, v16, 0.5, -v0
	v_fma_f32 v10, v10, 0.5, -v2
	v_cvt_pk_bf16_f32 v6, v11, v6
	v_cvt_pk_bf16_f32 v7, v10, v7
	global_store_dwordx4 v[8:9], v[4:7], off offset:1024 nt
	s_and_saveexec_b64 s[16:17], s[0:1]
	s_cbranch_execz .LBB0_453
	v_add_u32_e32 v96, -1, v20
	v_lshl_add_u64 v[4:5], s[2:3], 0, v[96:97]
	v_lshlrev_b64 v[4:5], 11, v[4:5]
	v_lshl_add_u64 v[4:5], s[62:63], 0, v[4:5]
	v_mov_b32_e32 v25, v97
	v_lshl_add_u64 v[4:5], v[4:5], 0, v[24:25]
	global_store_dwordx4 v[4:5], v[12:15], off nt
	global_store_dwordx4 v[4:5], v[0:3], off offset:16 nt
	s_branch .LBB0_453

; __device__ __forceinline__ void unpack8(const u32x4 w, float* f) { f[0] = bf_lo(w.x); f[1] = bf_hi(w.x); f[2] = bf_lo(w.y); f[3] = bf_hi(w.y); f[4] = bf_lo(w.z); f[5] = bf_hi(w.z); f[6] = bf_lo(w.w); f[7] = bf_hi(w.w); }
; template <int W>
; __device__ __forceinline__ void pool_items(const Params& p, int l, bool sample, int b, int c, int g, long row0, int tid) {
;     ...
;         for (int i = 0; i < W; ++i) {
;             const int tt = t - i;
;             raw[i] = (u32x4){0u, 0u, 0u, 0u}; h0[i] = (f32x4){0.f, 0.f, 0.f, 0.f}; h1[i] = h0[i];
;             if (tt >= 0) raw[i] = *(const u32x4*)(P + (size_t)(prow - i) * INW + 768 + col);
;             else if (sample) { const float* sp = p.state_pool + (((size_t)l * 8 + b) * 15 + (15 + tt)) * 512 + col; h0[i] = *(const f32x4*)sp; h1[i] = *(const f32x4*)(sp + 4); }
;         }
;         float cur[8], a[8];
;         unpack8(raw[0], cur);
; #pragma unroll
;         for (int k = 0; k < 8; ++k) a[k] = cur[k];
; #pragma unroll
;         for (int i = 1; i < W; ++i) { float x[8]; unpack8(raw[i], x);
; #pragma unroll
;             for (int k = 0; k < 4; ++k) { a[k] += x[k] + h0[i][k]; a[4 + k] += x[4 + k] + h1[i][k]; } }
.LBB0_529:
	s_or_b64 exec, exec, s[12:13]
	s_waitcnt vmcnt(0) lgkmcnt(0)
	v_lshlrev_b32_e32 v159, 16, v4
	v_lshlrev_b32_e32 v161, 16, v5
	v_and_b32_e32 v5, 0xffff0000, v5
	v_lshlrev_b32_e32 v150, 16, v0
	v_lshlrev_b32_e32 v212, 16, v6
	v_and_b32_e32 v6, 0xffff0000, v6
	v_add_f32_e32 v8, v8, v159
	v_add_f32_e32 v5, v11, v5
	v_lshlrev_b32_e32 v11, 16, v24
	v_and_b32_e32 v151, 0xffff0000, v0
	v_lshlrev_b32_e32 v0, 16, v2
	v_and_b32_e32 v4, 0xffff0000, v4
	v_add_f32_e32 v8, v8, v150
	v_add_f32_e32 v12, v12, v212
	v_add_f32_e32 v6, v13, v6
	v_and_b32_e32 v13, 0xffff0000, v24
	v_lshlrev_b32_e32 v24, 16, v26
	v_add_f32_e32 v11, v16, v11
	v_lshlrev_b32_e32 v213, 16, v7
	v_and_b32_e32 v7, 0xffff0000, v7
	v_add_f32_e32 v12, v12, v0
	v_add_f32_e32 v4, v9, v4
	v_add_f32_e32 v8, v8, v11
	v_add_f32_e32 v11, v20, v24
	v_lshlrev_b32_e32 v152, 16, v1
	v_and_b32_e32 v153, 0xffff0000, v1
	v_and_b32_e32 v1, 0xffff0000, v2
	v_add_f32_e32 v4, v4, v151
	v_add_f32_e32 v9, v10, v161
	v_add_f32_e32 v10, v14, v213
	v_add_f32_e32 v7, v15, v7
	v_lshlrev_b32_e32 v14, 16, v25
	v_and_b32_e32 v15, 0xffff0000, v25
	v_and_b32_e32 v25, 0xffff0000, v26
	v_add_f32_e32 v11, v12, v11
	v_add_f32_e32 v12, v17, v13
	v_add_f32_e32 v6, v6, v1
	v_add_f32_e32 v4, v4, v12
	v_add_f32_e32 v12, v21, v25
	v_lshlrev_b32_e32 v2, 16, v3
	v_add_f32_e32 v9, v9, v152
	v_lshlrev_b32_e32 v26, 16, v27
	v_add_f32_e32 v6, v6, v12
	v_add_f32_e32 v12, v18, v14
	v_add_f32_e32 v10, v10, v2
	v_add_f32_e32 v9, v9, v12
	v_add_f32_e32 v12, v22, v26
	v_and_b32_e32 v3, 0xffff0000, v3
	v_add_f32_e32 v5, v5, v153
	v_and_b32_e32 v27, 0xffff0000, v27
	v_add_f32_e32 v10, v10, v12
	v_add_f32_e32 v12, v19, v15
	v_add_f32_e32 v7, v7, v3
	v_add_f32_e32 v5, v5, v12
	v_add_f32_e32 v12, v23, v27
	v_add_f32_e32 v7, v7, v12
	v_lshlrev_b32_e32 v12, 16, v36
	v_lshlrev_b32_e32 v16, 16, v38
	v_add_f32_e32 v12, v28, v12
	v_and_b32_e32 v13, 0xffff0000, v36
	v_add_f32_e32 v8, v8, v12
	v_add_f32_e32 v12, v32, v16
	v_and_b32_e32 v17, 0xffff0000, v38
	v_add_f32_e32 v11, v11, v12
	v_add_f32_e32 v12, v29, v13
	v_lshlrev_b32_e32 v14, 16, v37
	v_add_f32_e32 v4, v4, v12
	v_add_f32_e32 v12, v33, v17
	v_lshlrev_b32_e32 v18, 16, v39
	v_add_f32_e32 v6, v6, v12
	v_add_f32_e32 v12, v30, v14
	v_and_b32_e32 v15, 0xffff0000, v37
	v_add_f32_e32 v9, v9, v12
	v_add_f32_e32 v12, v34, v18
	v_and_b32_e32 v19, 0xffff0000, v39
	v_add_f32_e32 v10, v10, v12
	v_add_f32_e32 v12, v31, v15
	v_add_f32_e32 v5, v5, v12
	v_add_f32_e32 v12, v35, v19
	v_add_f32_e32 v7, v7, v12
	v_lshlrev_b32_e32 v12, 16, v48
	v_lshlrev_b32_e32 v16, 16, v50
	v_add_f32_e32 v12, v40, v12
	v_and_b32_e32 v13, 0xffff0000, v48
	v_add_f32_e32 v8, v8, v12
	v_add_f32_e32 v12, v44, v16
	v_and_b32_e32 v17, 0xffff0000, v50
	v_add_f32_e32 v11, v11, v12
	v_add_f32_e32 v12, v41, v13
	v_lshlrev_b32_e32 v14, 16, v49
	v_add_f32_e32 v4, v4, v12
	v_add_f32_e32 v12, v45, v17
	v_lshlrev_b32_e32 v18, 16, v51
	v_add_f32_e32 v6, v6, v12
	v_add_f32_e32 v12, v42, v14
	v_and_b32_e32 v15, 0xffff0000, v49
	v_add_f32_e32 v9, v9, v12
	v_add_f32_e32 v12, v46, v18
	v_and_b32_e32 v19, 0xffff0000, v51
	v_add_f32_e32 v10, v10, v12
	v_add_f32_e32 v12, v43, v15
	v_add_f32_e32 v5, v5, v12
	v_add_f32_e32 v12, v47, v19
	v_add_f32_e32 v7, v7, v12
	v_lshlrev_b32_e32 v12, 16, v60
	v_lshlrev_b32_e32 v16, 16, v62
	v_add_f32_e32 v12, v52, v12
	v_and_b32_e32 v13, 0xffff0000, v60
	v_add_f32_e32 v8, v8, v12
	v_add_f32_e32 v12, v56, v16
	v_and_b32_e32 v17, 0xffff0000, v62
	v_add_f32_e32 v11, v11, v12
	v_add_f32_e32 v12, v53, v13
	v_lshlrev_b32_e32 v14, 16, v61
	v_add_f32_e32 v4, v4, v12
	v_add_f32_e32 v12, v57, v17
	v_lshlrev_b32_e32 v18, 16, v63
	v_add_f32_e32 v6, v6, v12
	v_add_f32_e32 v12, v54, v14
	v_and_b32_e32 v15, 0xffff0000, v61
	v_add_f32_e32 v9, v9, v12
	v_add_f32_e32 v12, v58, v18
	v_and_b32_e32 v19, 0xffff0000, v63
	v_add_f32_e32 v10, v10, v12
	v_add_f32_e32 v12, v55, v15
	v_add_f32_e32 v5, v5, v12
	v_add_f32_e32 v12, v59, v19
	v_add_f32_e32 v7, v7, v12
	v_lshlrev_b32_e32 v12, 16, v72
	v_lshlrev_b32_e32 v16, 16, v74
	v_add_f32_e32 v12, v64, v12
	v_and_b32_e32 v13, 0xffff0000, v72
	v_add_f32_e32 v8, v8, v12
	v_add_f32_e32 v12, v68, v16
	v_and_b32_e32 v17, 0xffff0000, v74
	v_add_f32_e32 v11, v11, v12
	v_add_f32_e32 v12, v65, v13
	v_lshlrev_b32_e32 v14, 16, v73
	v_add_f32_e32 v4, v4, v12
	v_add_f32_e32 v12, v69, v17
	v_lshlrev_b32_e32 v18, 16, v75
	v_add_f32_e32 v6, v6, v12
	v_add_f32_e32 v12, v66, v14
	v_and_b32_e32 v15, 0xffff0000, v73
	v_add_f32_e32 v9, v9, v12
	v_add_f32_e32 v12, v70, v18
	v_and_b32_e32 v19, 0xffff0000, v75
	v_add_f32_e32 v10, v10, v12
	v_add_f32_e32 v12, v67, v15
	v_add_f32_e32 v5, v5, v12
	v_add_f32_e32 v12, v71, v19
	v_add_f32_e32 v7, v7, v12
	v_lshlrev_b32_e32 v12, 16, v84
	v_lshlrev_b32_e32 v16, 16, v86
	v_add_f32_e32 v12, v76, v12
	v_and_b32_e32 v13, 0xffff0000, v84
	v_add_f32_e32 v8, v8, v12
	v_add_f32_e32 v12, v80, v16
	v_and_b32_e32 v17, 0xffff0000, v86
	v_add_f32_e32 v11, v11, v12
	v_add_f32_e32 v12, v77, v13
	v_lshlrev_b32_e32 v14, 16, v85
	v_add_f32_e32 v12, v4, v12
	v_add_f32_e32 v4, v81, v17
	v_lshlrev_b32_e32 v18, 16, v87
	v_add_f32_e32 v6, v6, v4
	v_add_f32_e32 v4, v78, v14
	v_and_b32_e32 v15, 0xffff0000, v85
	v_add_f32_e32 v9, v9, v4
	v_add_f32_e32 v4, v82, v18
	v_and_b32_e32 v19, 0xffff0000, v87
	v_add_f32_e32 v10, v10, v4
	v_add_f32_e32 v4, v79, v15
	v_add_f32_e32 v13, v5, v4
	v_add_f32_e32 v4, v83, v19
	v_add_f32_e32 v7, v7, v4
	v_lshlrev_b32_e32 v5, 16, v102
	v_lshlrev_b32_e32 v4, 16, v98
	v_pk_add_f32 v[4:5], v[92:93], v[4:5]
	s_mov_b32 s7, 0x3d800000
	v_add_f32_e32 v4, v8, v4
	v_add_f32_e32 v8, v4, v5
	v_lshlrev_b32_e32 v5, 16, v104
	v_lshlrev_b32_e32 v4, 16, v100
; __device__ __forceinline__ void unpack8(const u32x4 w, float* f) { f[0] = bf_lo(w.x); f[1] = bf_hi(w.x); f[2] = bf_lo(w.y); f[3] = bf_hi(w.y); f[4] = bf_lo(w.z); f[5] = bf_hi(w.z); f[6] = bf_lo(w.w); f[7] = bf_hi(w.w); }
; __device__ __forceinline__ u32x4 pack8(const float* f) { u32x4 w; w.x = cvt_pk_bf16(f[0], f[1]); w.y = cvt_pk_bf16(f[2], f[3]); w.z = cvt_pk_bf16(f[4], f[5]); w.w = cvt_pk_bf16(f[6], f[7]); return w; }
; template <int W>
; __device__ __forceinline__ void pool_items(const Params& p, int l, bool sample, int b, int c, int g, long row0, int tid) {
;     ...
;         unpack8(raw[0], cur);
; #pragma unroll
;         for (int k = 0; k < 8; ++k) a[k] = cur[k];
; #pragma unroll
;         for (int i = 1; i < W; ++i) { float x[8]; unpack8(raw[i], x);
; #pragma unroll
;             for (int k = 0; k < 4; ++k) { a[k] += x[k] + h0[i][k]; a[4 + k] += x[4 + k] + h1[i][k]; } }
;         const float cnt = sample ? (float)W : (float)((t + 1) < W ? (t + 1) : W);
;         const float inv = 1.0f / cnt;
;         float d[8];
; #pragma unroll
;         for (int k = 0; k < 8; ++k) d[k] = a[k] * inv - cur[k];
;         *(u32x4*)(AD + (size_t)prow * DM + 512 + col) = pack8(d);
;         float* pd = nullptr;
;         if (!sample) { if (t >= SEQ - 15) pd = p.out + O_PP + (((size_t)l * 2 + b) * 15 + (t - (SEQ - 15))) * 512 + col; }
;         else if (tl >= 1) pd = p.out + O_PS + (((size_t)l * 8 + b) * 15 + (tl - 1)) * 512 + col;
;         if (pd) { *(f32x4*)pd = (f32x4){cur[0], cur[1], cur[2], cur[3]}; *(f32x4*)(pd + 4) = (f32x4){cur[4], cur[5], cur[6], cur[7]}; }
	v_pk_add_f32 v[4:5], v[88:89], v[4:5]
	v_mov_b32_e32 v161, v97
	v_add_f32_e32 v4, v11, v4
	v_add_f32_e32 v11, v4, v5
	v_and_b32_e32 v5, 0xffff0000, v102
	v_and_b32_e32 v4, 0xffff0000, v98
	v_pk_add_f32 v[4:5], v[170:171], v[4:5]
	s_nop 0
	v_add_f32_e32 v4, v12, v4
	v_add_f32_e32 v12, v4, v5
	v_and_b32_e32 v5, 0xffff0000, v104
	v_and_b32_e32 v4, 0xffff0000, v100
	v_pk_add_f32 v[4:5], v[168:169], v[4:5]
	s_nop 0
	v_add_f32_e32 v4, v6, v4
	v_add_f32_e32 v6, v4, v5
	v_lshlrev_b32_e32 v4, 16, v99
	v_lshlrev_b32_e32 v5, 16, v103
	v_pk_add_f32 v[4:5], v[94:95], v[4:5]
	s_nop 0
	v_add_f32_e32 v4, v9, v4
	v_add_f32_e32 v9, v4, v5
	v_lshlrev_b32_e32 v4, 16, v101
	v_lshlrev_b32_e32 v5, 16, v105
	v_pk_add_f32 v[4:5], v[90:91], v[4:5]
	s_nop 0
	v_add_f32_e32 v4, v10, v4
	v_add_f32_e32 v10, v4, v5
	v_and_b32_e32 v5, 0xffff0000, v103
	v_and_b32_e32 v4, 0xffff0000, v99
	v_pk_add_f32 v[4:5], v[166:167], v[4:5]
	s_nop 0
	v_add_f32_e32 v4, v13, v4
	v_add_f32_e32 v13, v4, v5
	v_and_b32_e32 v5, 0xffff0000, v105
	v_and_b32_e32 v4, 0xffff0000, v101
	v_pk_add_f32 v[4:5], v[164:165], v[4:5]
	s_nop 0
	v_add_f32_e32 v4, v7, v4
	v_add_f32_e32 v7, v4, v5
	v_lshlrev_b32_e32 v5, 16, v118
	v_lshlrev_b32_e32 v4, 16, v114
	v_pk_add_f32 v[4:5], v[110:111], v[4:5]
	s_nop 0
	v_add_f32_e32 v4, v8, v4
	v_add_f32_e32 v8, v4, v5
	v_lshlrev_b32_e32 v5, 16, v120
	v_lshlrev_b32_e32 v4, 16, v116
	v_pk_add_f32 v[4:5], v[106:107], v[4:5]
	s_nop 0
	v_add_f32_e32 v4, v11, v4
	v_add_f32_e32 v11, v4, v5
	v_and_b32_e32 v5, 0xffff0000, v118
	v_and_b32_e32 v4, 0xffff0000, v114
	v_pk_add_f32 v[4:5], v[178:179], v[4:5]
	s_nop 0
	v_add_f32_e32 v4, v12, v4
	v_add_f32_e32 v12, v4, v5
	v_and_b32_e32 v5, 0xffff0000, v120
	v_and_b32_e32 v4, 0xffff0000, v116
	v_pk_add_f32 v[4:5], v[176:177], v[4:5]
	s_nop 0
	v_add_f32_e32 v4, v6, v4
	v_add_f32_e32 v6, v4, v5
	v_lshlrev_b32_e32 v4, 16, v115
	v_lshlrev_b32_e32 v5, 16, v119
	v_pk_add_f32 v[4:5], v[112:113], v[4:5]
	s_nop 0
	v_add_f32_e32 v4, v9, v4
	v_add_f32_e32 v9, v4, v5
	v_lshlrev_b32_e32 v4, 16, v117
	v_lshlrev_b32_e32 v5, 16, v121
	v_pk_add_f32 v[4:5], v[108:109], v[4:5]
	s_nop 0
	v_add_f32_e32 v4, v10, v4
	v_add_f32_e32 v10, v4, v5
	v_and_b32_e32 v5, 0xffff0000, v119
	v_and_b32_e32 v4, 0xffff0000, v115
	v_pk_add_f32 v[4:5], v[174:175], v[4:5]
	s_nop 0
	v_add_f32_e32 v4, v13, v4
	v_add_f32_e32 v13, v4, v5
	v_and_b32_e32 v5, 0xffff0000, v121
	v_and_b32_e32 v4, 0xffff0000, v117
	v_pk_add_f32 v[4:5], v[172:173], v[4:5]
	s_nop 0
	v_add_f32_e32 v4, v7, v4
	v_add_f32_e32 v7, v4, v5
	v_lshlrev_b32_e32 v5, 16, v134
	v_lshlrev_b32_e32 v4, 16, v130
	v_pk_add_f32 v[4:5], v[126:127], v[4:5]
	s_nop 0
	v_add_f32_e32 v4, v8, v4
	v_add_f32_e32 v8, v4, v5
	v_lshlrev_b32_e32 v5, 16, v136
	v_lshlrev_b32_e32 v4, 16, v132
	v_pk_add_f32 v[4:5], v[122:123], v[4:5]
	s_nop 0
	v_add_f32_e32 v4, v11, v4
	v_add_f32_e32 v11, v4, v5
	v_and_b32_e32 v5, 0xffff0000, v134
	v_and_b32_e32 v4, 0xffff0000, v130
	v_pk_add_f32 v[4:5], v[186:187], v[4:5]
	s_nop 0
	v_add_f32_e32 v4, v12, v4
	v_add_f32_e32 v12, v4, v5
	v_and_b32_e32 v5, 0xffff0000, v136
	v_and_b32_e32 v4, 0xffff0000, v132
	v_pk_add_f32 v[4:5], v[184:185], v[4:5]
	s_nop 0
	v_add_f32_e32 v4, v6, v4
	v_add_f32_e32 v6, v4, v5
	v_lshlrev_b32_e32 v4, 16, v131
	v_lshlrev_b32_e32 v5, 16, v135
	v_pk_add_f32 v[4:5], v[128:129], v[4:5]
	s_nop 0
	v_add_f32_e32 v4, v9, v4
	v_add_f32_e32 v9, v4, v5
	v_lshlrev_b32_e32 v4, 16, v133
	v_lshlrev_b32_e32 v5, 16, v137
	v_pk_add_f32 v[4:5], v[124:125], v[4:5]
	s_nop 0
	v_add_f32_e32 v4, v10, v4
	v_add_f32_e32 v10, v4, v5
	v_and_b32_e32 v5, 0xffff0000, v135
	v_and_b32_e32 v4, 0xffff0000, v131
	v_pk_add_f32 v[4:5], v[182:183], v[4:5]
	s_nop 0
	v_add_f32_e32 v4, v13, v4
	v_add_f32_e32 v13, v4, v5
	v_and_b32_e32 v5, 0xffff0000, v137
	v_and_b32_e32 v4, 0xffff0000, v133
	v_pk_add_f32 v[4:5], v[180:181], v[4:5]
	s_nop 0
	v_add_f32_e32 v4, v7, v4
	v_add_f32_e32 v7, v4, v5
	v_lshlrev_b32_e32 v5, 16, v154
	v_lshlrev_b32_e32 v4, 16, v146
	v_pk_add_f32 v[4:5], v[142:143], v[4:5]
	s_nop 0
	v_add_f32_e32 v4, v8, v4
	v_add_f32_e32 v8, v4, v5
	v_lshlrev_b32_e32 v5, 16, v156
	v_lshlrev_b32_e32 v4, 16, v148
	v_pk_add_f32 v[4:5], v[138:139], v[4:5]
	s_nop 0
	v_add_f32_e32 v4, v11, v4
	v_add_f32_e32 v11, v4, v5
	v_and_b32_e32 v5, 0xffff0000, v154
	v_and_b32_e32 v4, 0xffff0000, v146
	v_pk_add_f32 v[4:5], v[206:207], v[4:5]
	v_fma_f32 v11, v11, s7, -v0
	v_add_f32_e32 v4, v12, v4
	v_add_f32_e32 v12, v4, v5
	v_and_b32_e32 v5, 0xffff0000, v156
	v_and_b32_e32 v4, 0xffff0000, v148
	v_pk_add_f32 v[4:5], v[192:193], v[4:5]
	s_nop 0
	v_add_f32_e32 v4, v6, v4
	v_add_f32_e32 v6, v4, v5
	v_lshlrev_b32_e32 v4, 16, v147
	v_lshlrev_b32_e32 v5, 16, v155
	v_pk_add_f32 v[4:5], v[144:145], v[4:5]
	v_fma_f32 v6, v6, s7, -v1
	v_add_f32_e32 v4, v9, v4
	v_add_f32_e32 v9, v4, v5
	v_lshlrev_b32_e32 v4, 16, v149
	v_lshlrev_b32_e32 v5, 16, v157
	v_pk_add_f32 v[4:5], v[140:141], v[4:5]
	s_nop 0
	v_add_f32_e32 v4, v10, v4
	v_add_f32_e32 v10, v4, v5
	v_and_b32_e32 v5, 0xffff0000, v155
	v_and_b32_e32 v4, 0xffff0000, v147
	v_pk_add_f32 v[4:5], v[190:191], v[4:5]
	v_fma_f32 v10, v10, s7, -v2
	v_add_f32_e32 v4, v13, v4
	v_add_f32_e32 v13, v4, v5
	v_and_b32_e32 v5, 0xffff0000, v157
	v_and_b32_e32 v4, 0xffff0000, v149
	v_pk_add_f32 v[4:5], v[188:189], v[4:5]
	s_nop 0
	v_add_f32_e32 v4, v7, v4
	v_add_f32_e32 v4, v4, v5
	v_fma_f32 v5, v8, s7, -v150
	v_fma_f32 v8, v9, s7, -v152
	v_fma_f32 v9, v13, s7, -v153
	v_fma_f32 v7, v12, s7, -v151
	v_fma_f32 v12, v4, s7, -v3
	v_cvt_pk_bf16_f32 v4, v5, v7
	v_cvt_pk_bf16_f32 v5, v8, v9
	v_lshlrev_b64 v[8:9], 11, v[162:163]
	v_lshl_add_u64 v[8:9], s[86:87], 0, v[8:9]
	v_lshl_add_u64 v[8:9], v[8:9], 0, v[160:161]
	v_add_co_u32_e32 v8, vcc, 0x7900000, v8
	v_cvt_pk_bf16_f32 v6, v11, v6
	v_cvt_pk_bf16_f32 v7, v10, v12
	s_nop 1
	v_addc_co_u32_e32 v9, vcc, 0, v9, vcc
	global_store_dwordx4 v[8:9], v[4:7], off offset:1024 nt
	s_and_saveexec_b64 s[12:13], s[44:45]
	s_cbranch_execz .LBB0_466
	v_add_u32_e32 v4, -1, v158
	v_mov_b32_e32 v5, v97
	v_lshl_add_u64 v[4:5], s[2:3], 0, v[4:5]
	v_lshlrev_b64 v[4:5], 11, v[4:5]
	v_lshl_add_u64 v[4:5], s[62:63], 0, v[4:5]
	v_lshl_add_u64 v[4:5], v[4:5], 0, v[96:97]
	global_store_dwordx4 v[4:5], v[150:153], off offset:1536 nt
	global_store_dwordx4 v[4:5], v[0:3], off offset:1552 nt
	s_branch .LBB0_466

; __device__ __forceinline__ void unpack8(const u32x4 w, float* f) { f[0] = bf_lo(w.x); f[1] = bf_hi(w.x); f[2] = bf_lo(w.y); f[3] = bf_hi(w.y); f[4] = bf_lo(w.z); f[5] = bf_hi(w.z); f[6] = bf_lo(w.w); f[7] = bf_hi(w.w); }
; __device__ __forceinline__ u32x4 pack8(const float* f) { u32x4 w; w.x = cvt_pk_bf16(f[0], f[1]); w.y = cvt_pk_bf16(f[2], f[3]); w.z = cvt_pk_bf16(f[4], f[5]); w.w = cvt_pk_bf16(f[6], f[7]); return w; }
; template <int W>
; __device__ __forceinline__ void pool_items(const Params& p, int l, bool sample, int b, int c, int g, long row0, int tid) {
;     ...
;         for (int i = 0; i < W; ++i) {
;             const int tt = t - i;
;             raw[i] = (u32x4){0u, 0u, 0u, 0u}; h0[i] = (f32x4){0.f, 0.f, 0.f, 0.f}; h1[i] = h0[i];
;             if (tt >= 0) raw[i] = *(const u32x4*)(P + (size_t)(prow - i) * INW + 768 + col);
;             else if (sample) { const float* sp = p.state_pool + (((size_t)l * 8 + b) * 15 + (15 + tt)) * 512 + col; h0[i] = *(const f32x4*)sp; h1[i] = *(const f32x4*)(sp + 4); }
;         }
;         float cur[8], a[8];
;         unpack8(raw[0], cur);
; #pragma unroll
;         for (int k = 0; k < 8; ++k) a[k] = cur[k];
; #pragma unroll
;         for (int i = 1; i < W; ++i) { float x[8]; unpack8(raw[i], x);
; #pragma unroll
;             for (int k = 0; k < 4; ++k) { a[k] += x[k] + h0[i][k]; a[4 + k] += x[4 + k] + h1[i][k]; } }
;         const float cnt = sample ? (float)W : (float)((t + 1) < W ? (t + 1) : W);
;         const float inv = 1.0f / cnt;
;         float d[8];
; #pragma unroll
;         for (int k = 0; k < 8; ++k) d[k] = a[k] * inv - cur[k];
;         *(u32x4*)(AD + (size_t)prow * DM + 512 + col) = pack8(d);
;         float* pd = nullptr;
;         if (!sample) { if (t >= SEQ - 15) pd = p.out + O_PP + (((size_t)l * 2 + b) * 15 + (t - (SEQ - 15))) * 512 + col; }
;         else if (tl >= 1) pd = p.out + O_PS + (((size_t)l * 8 + b) * 15 + (tl - 1)) * 512 + col;
;         if (pd) { *(f32x4*)pd = (f32x4){cur[0], cur[1], cur[2], cur[3]}; *(f32x4*)(pd + 4) = (f32x4){cur[4], cur[5], cur[6], cur[7]}; }
.LBB0_551:
	s_or_b64 exec, exec, s[14:15]
	s_waitcnt vmcnt(0) lgkmcnt(0)
	v_lshlrev_b32_e32 v37, 16, v4
	v_and_b32_e32 v4, 0xffff0000, v4
	v_and_b32_e32 v29, 0xffff0000, v0
	v_lshlrev_b32_e32 v52, 16, v6
	v_and_b32_e32 v6, 0xffff0000, v6
	v_add_f32_e32 v4, v9, v4
	v_lshlrev_b32_e32 v30, 16, v1
	v_and_b32_e32 v31, 0xffff0000, v1
	v_and_b32_e32 v1, 0xffff0000, v2
	v_lshlrev_b32_e32 v39, 16, v5
	v_add_f32_e32 v9, v4, v29
	v_add_f32_e32 v4, v13, v6
	v_lshlrev_b32_e32 v53, 16, v7
	v_add_f32_e32 v6, v4, v1
	v_add_f32_e32 v4, v10, v39
	v_lshlrev_b32_e32 v28, 16, v0
	v_lshlrev_b32_e32 v0, 16, v2
	v_lshlrev_b32_e32 v2, 16, v3
	v_and_b32_e32 v5, 0xffff0000, v5
	v_add_f32_e32 v10, v4, v30
	v_add_f32_e32 v4, v14, v53
	v_and_b32_e32 v7, 0xffff0000, v7
	v_add_f32_e32 v13, v4, v2
	v_add_f32_e32 v4, v11, v5
	v_and_b32_e32 v3, 0xffff0000, v3
	v_add_f32_e32 v11, v4, v31
	v_add_f32_e32 v4, v15, v7
	v_add_f32_e32 v8, v8, v37
	v_add_f32_e32 v7, v4, v3
	v_lshlrev_b32_e32 v5, 16, v32
	v_lshlrev_b32_e32 v4, 16, v24
	v_add_f32_e32 v8, v8, v28
	v_pk_add_f32 v[4:5], v[20:21], v[4:5]
	v_add_f32_e32 v12, v12, v52
	v_add_f32_e32 v4, v8, v4
	v_add_f32_e32 v8, v4, v5
	v_lshlrev_b32_e32 v5, 16, v34
	v_lshlrev_b32_e32 v4, 16, v26
	v_add_f32_e32 v12, v12, v0
	v_pk_add_f32 v[4:5], v[16:17], v[4:5]
	s_mov_b32 s7, 0x3e800000
	v_add_f32_e32 v4, v12, v4
	v_add_f32_e32 v12, v4, v5
	v_and_b32_e32 v5, 0xffff0000, v32
	v_and_b32_e32 v4, 0xffff0000, v24
	v_pk_add_f32 v[4:5], v[48:49], v[4:5]
	v_mov_b32_e32 v39, v97
	v_add_f32_e32 v4, v9, v4
	v_add_f32_e32 v9, v4, v5
	v_and_b32_e32 v5, 0xffff0000, v34
	v_and_b32_e32 v4, 0xffff0000, v26
	v_pk_add_f32 v[4:5], v[46:47], v[4:5]
	s_nop 0
	v_add_f32_e32 v4, v6, v4
	v_add_f32_e32 v6, v4, v5
	v_lshlrev_b32_e32 v4, 16, v25
	v_lshlrev_b32_e32 v5, 16, v33
	v_pk_add_f32 v[4:5], v[22:23], v[4:5]
	v_fma_f32 v6, v6, s7, -v1
	v_add_f32_e32 v4, v10, v4
	v_add_f32_e32 v10, v4, v5
	v_lshlrev_b32_e32 v4, 16, v27
	v_lshlrev_b32_e32 v5, 16, v35
	v_pk_add_f32 v[4:5], v[18:19], v[4:5]
	s_nop 0
	v_add_f32_e32 v4, v13, v4
	v_add_f32_e32 v13, v4, v5
	v_and_b32_e32 v5, 0xffff0000, v33
	v_and_b32_e32 v4, 0xffff0000, v25
	v_pk_add_f32 v[4:5], v[44:45], v[4:5]
	s_nop 0
	v_add_f32_e32 v4, v11, v4
	v_add_f32_e32 v11, v4, v5
	v_and_b32_e32 v5, 0xffff0000, v35
	v_and_b32_e32 v4, 0xffff0000, v27
	v_pk_add_f32 v[4:5], v[42:43], v[4:5]
	s_nop 0
	v_add_f32_e32 v4, v7, v4
	v_add_f32_e32 v4, v4, v5
	v_fma_f32 v5, v8, s7, -v28
	v_fma_f32 v7, v9, s7, -v29
	v_fma_f32 v8, v10, s7, -v30
	v_fma_f32 v9, v11, s7, -v31
	v_fma_f32 v10, v12, s7, -v0
	v_fma_f32 v12, v4, s7, -v3
	v_cvt_pk_bf16_f32 v4, v5, v7
	v_cvt_pk_bf16_f32 v5, v8, v9
	v_lshlrev_b64 v[8:9], 11, v[40:41]
	v_lshl_add_u64 v[8:9], s[86:87], 0, v[8:9]
	v_lshl_add_u64 v[8:9], v[8:9], 0, v[38:39]
	v_add_co_u32_e32 v8, vcc, 0x7900000, v8
	v_fma_f32 v11, v13, s7, -v2
	s_nop 0
	v_addc_co_u32_e32 v9, vcc, 0, v9, vcc
	v_cvt_pk_bf16_f32 v6, v10, v6
	v_cvt_pk_bf16_f32 v7, v11, v12
	global_store_dwordx4 v[8:9], v[4:7], off offset:1024 nt
	s_and_saveexec_b64 s[14:15], s[0:1]
	s_cbranch_execz .LBB0_536
	v_add_u32_e32 v4, -1, v36
	v_mov_b32_e32 v5, v97
	v_lshl_add_u64 v[4:5], s[2:3], 0, v[4:5]
	v_lshlrev_b64 v[4:5], 11, v[4:5]
	v_lshl_add_u64 v[4:5], s[62:63], 0, v[4:5]
	v_lshl_add_u64 v[4:5], v[4:5], 0, v[96:97]
	global_store_dwordx4 v[4:5], v[28:31], off offset:512 nt
	global_store_dwordx4 v[4:5], v[0:3], off offset:528 nt
	s_branch .LBB0_536

; #define LAS __attribute__((address_space(3)))
; __device__ __forceinline__ unsigned cvt_pk_bf16(float lo, float hi) { unsigned r; asm volatile("v_cvt_pk_bf16_f32 %0, %1, %2" : "=v"(r) : "v"(lo), "v"(hi)); return r; }
; __device__ __forceinline__ u32x4 pack8(const float* f) { u32x4 w; w.x = cvt_pk_bf16(f[0], f[1]); w.y = cvt_pk_bf16(f[2], f[3]); w.z = cvt_pk_bf16(f[4], f[5]); w.w = cvt_pk_bf16(f[6], f[7]); return w; }
; __device__ __forceinline__ void attn_unit(const Params& p, int l, LAS unsigned char* lds, bool sample, int b, int c, int kvh) {
;     ...
;         *(LAS u32x4*)(Ks + j * KS_LD + ch * 8) = pack8(kf);
; #pragma unroll
;         for (int i = 0; i < 8; i += 2) { const unsigned w = cvt_pk_bf16(vf[i], vf[i + 1]); const int js = j ^ (ch << 3);
;             Vt[(ch * 8 + i) * VT_LD + js] = (bf16_t)(w & 0xffffu); Vt[(ch * 8 + i + 1) * VT_LD + js] = (bf16_t)(w >> 16); }
;         float* kd = nullptr; float* vd = nullptr;
;         if (!sample) { if (c >= 254 && j >= 128) { const size_t o = ((((size_t)l * 2 + b) * 128 + (c - 254) * 64 + (j - 128)) * 2 + kvh) * 64 + ch * 8; kd = p.out + O_KP + o; vd = p.out + O_VP + o; } }
;         else if (j >= 16 && j < 144) { const size_t o = ((((size_t)l * 8 + b) * 128 + (j - 16)) * 2 + kvh) * 64 + ch * 8; kd = p.out + O_KS + o; vd = p.out + O_VS + o; }
;         if (kd) { *(f32x4*)kd = (f32x4){kf[0], kf[1], kf[2], kf[3]}; *(f32x4*)(kd + 4) = (f32x4){kf[4], kf[5], kf[6], kf[7]};
;                   *(f32x4*)vd = (f32x4){vf[0], vf[1], vf[2], vf[3]}; *(f32x4*)(vd + 4) = (f32x4){vf[4], vf[5], vf[6], vf[7]}; }
.LBB0_580:
	s_or_b64 exec, exec, s[0:1]
	v_lshl_add_u32 v84, v98, 1, 0
	v_mad_u64_u32 v[86:87], s[0:1], v94, s83, v[84:85]
	v_cvt_pk_bf16_f32 v100, v64, v65
	v_xor_b32_e32 v81, v98, v94
	s_movk_i32 s0, 0x18e
	v_cvt_pk_bf16_f32 v101, v66, v67
	v_cvt_pk_bf16_f32 v102, v56, v57
	v_cvt_pk_bf16_f32 v103, v58, v59
	ds_write_b128 v86, v[100:103]
	v_mad_u32_u24 v100, v98, s0, v84
	v_lshlrev_b32_e32 v81, 1, v81
	s_movk_i32 s0, 0x190
	s_waitcnt lgkmcnt(1)
	v_cvt_pk_bf16_f32 v83, v68, v69
	v_add_u32_e32 v86, v100, v81
	v_mad_i32_i24 v101, v96, s0, 0
	ds_write_b16 v86, v83 offset:27648
	ds_write_b16_d16_hi v86, v83 offset:28048
	v_cvt_pk_bf16_f32 v83, v70, v71
	v_add_u32_e32 v86, v101, v81
	v_mad_i32_i24 v102, v82, s0, 0
	ds_write_b16 v86, v83 offset:27648
	ds_write_b16_d16_hi v86, v83 offset:28048
	v_cvt_pk_bf16_f32 v83, v60, v61
	v_add_u32_e32 v86, v102, v81
	v_mad_i32_i24 v103, v80, s0, 0
	ds_write_b16 v86, v83 offset:27648
	ds_write_b16_d16_hi v86, v83 offset:28048
	v_cvt_pk_bf16_f32 v83, v62, v63
	v_add_u32_e32 v81, v103, v81
	s_lshl_b64 s[8:9], s[8:9], 8
	ds_write_b16 v81, v83 offset:27648
	ds_write_b16_d16_hi v81, v83 offset:28048
	v_add_u32_e32 v81, -16, v94
	s_or_b32 s8, s8, s12
	s_movk_i32 s14, 0x190
	v_cmp_gt_u32_e32 vcc, s31, v81
	v_mov_b64_e32 v[86:87], 0
	v_mov_b64_e32 v[94:95], 0
	s_and_saveexec_b64 s[0:1], vcc
	v_lshl_or_b32 v86, v81, 1, s8
	v_mov_b32_e32 v87, s9
	v_lshlrev_b64 v[86:87], 8, v[86:87]
	v_lshl_or_b32 v86, v98, 2, v86
	v_lshl_add_u64 v[94:95], s[46:47], 0, v[86:87]
	v_lshl_add_u64 v[86:87], s[52:53], 0, v[86:87]
	s_or_b64 exec, exec, s[0:1]
	v_cmp_ne_u64_e32 vcc, 0, v[94:95]
	s_and_saveexec_b64 s[0:1], vcc
	s_cbranch_execz .LBB0_584
	global_store_dwordx4 v[94:95], v[64:67], off nt
	global_store_dwordx4 v[94:95], v[56:59], off offset:16 nt
	global_store_dwordx4 v[86:87], v[68:71], off nt
	global_store_dwordx4 v[86:87], v[60:63], off offset:16 nt

; #define LAS __attribute__((address_space(3)))
; __device__ __forceinline__ unsigned cvt_pk_bf16(float lo, float hi) { unsigned r; asm volatile("v_cvt_pk_bf16_f32 %0, %1, %2" : "=v"(r) : "v"(lo), "v"(hi)); return r; }
; __device__ __forceinline__ u32x4 pack8(const float* f) { u32x4 w; w.x = cvt_pk_bf16(f[0], f[1]); w.y = cvt_pk_bf16(f[2], f[3]); w.z = cvt_pk_bf16(f[4], f[5]); w.w = cvt_pk_bf16(f[6], f[7]); return w; }
; __device__ __forceinline__ void attn_unit(const Params& p, int l, LAS unsigned char* lds, bool sample, int b, int c, int kvh) {
;     ...
;         *(LAS u32x4*)(Ks + j * KS_LD + ch * 8) = pack8(kf);
; #pragma unroll
;         for (int i = 0; i < 8; i += 2) { const unsigned w = cvt_pk_bf16(vf[i], vf[i + 1]); const int js = j ^ (ch << 3);
;             Vt[(ch * 8 + i) * VT_LD + js] = (bf16_t)(w & 0xffffu); Vt[(ch * 8 + i + 1) * VT_LD + js] = (bf16_t)(w >> 16); }
;         float* kd = nullptr; float* vd = nullptr;
;         if (!sample) { if (c >= 254 && j >= 128) { const size_t o = ((((size_t)l * 2 + b) * 128 + (c - 254) * 64 + (j - 128)) * 2 + kvh) * 64 + ch * 8; kd = p.out + O_KP + o; vd = p.out + O_VP + o; } }
;         else if (j >= 16 && j < 144) { const size_t o = ((((size_t)l * 8 + b) * 128 + (j - 16)) * 2 + kvh) * 64 + ch * 8; kd = p.out + O_KS + o; vd = p.out + O_VS + o; }
;         if (kd) { *(f32x4*)kd = (f32x4){kf[0], kf[1], kf[2], kf[3]}; *(f32x4*)(kd + 4) = (f32x4){kf[4], kf[5], kf[6], kf[7]};
;                   *(f32x4*)vd = (f32x4){vf[0], vf[1], vf[2], vf[3]}; *(f32x4*)(vd + 4) = (f32x4){vf[4], vf[5], vf[6], vf[7]}; }
.LBB0_590:
	s_or_b64 exec, exec, s[0:1]
	v_cvt_pk_bf16_f32 v56, v36, v37
	v_mad_u64_u32 v[60:61], s[0:1], v92, s83, v[84:85]
	s_waitcnt lgkmcnt(0)
	v_cvt_pk_bf16_f32 v57, v38, v39
	v_cvt_pk_bf16_f32 v58, v32, v33
	v_cvt_pk_bf16_f32 v59, v34, v35
	ds_write_b128 v60, v[56:59]
	v_xor_b32_e32 v56, v92, v98
	v_lshlrev_b32_e32 v56, 1, v56
	v_cvt_pk_bf16_f32 v57, v44, v45
	v_add_u32_e32 v58, v100, v56
	ds_write_b16 v58, v57 offset:27648
	ds_write_b16_d16_hi v58, v57 offset:28048
	v_cvt_pk_bf16_f32 v57, v46, v47
	v_add_u32_e32 v58, v101, v56
	ds_write_b16 v58, v57 offset:27648
	ds_write_b16_d16_hi v58, v57 offset:28048
	v_cvt_pk_bf16_f32 v57, v40, v41
	v_add_u32_e32 v58, v102, v56
	ds_write_b16 v58, v57 offset:27648
	ds_write_b16_d16_hi v58, v57 offset:28048
	v_cvt_pk_bf16_f32 v57, v42, v43
	v_add_u32_e32 v56, v103, v56
	v_add_u32_e32 v60, -16, v92
	ds_write_b16 v56, v57 offset:27648
	ds_write_b16_d16_hi v56, v57 offset:28048
	v_cmp_gt_u32_e32 vcc, s31, v60
	v_mov_b64_e32 v[56:57], 0
	v_mov_b64_e32 v[58:59], 0
	s_and_saveexec_b64 s[0:1], vcc
	v_lshl_or_b32 v56, v60, 1, s8
	v_mov_b32_e32 v57, s9
	v_lshlrev_b64 v[56:57], 8, v[56:57]
	v_lshl_or_b32 v56, v98, 2, v56
	v_lshl_add_u64 v[58:59], s[46:47], 0, v[56:57]
	v_lshl_add_u64 v[56:57], s[52:53], 0, v[56:57]
	s_or_b64 exec, exec, s[0:1]
	v_cmp_ne_u64_e32 vcc, 0, v[58:59]
	s_and_saveexec_b64 s[0:1], vcc
	s_cbranch_execz .LBB0_594
	global_store_dwordx4 v[58:59], v[36:39], off nt
	global_store_dwordx4 v[58:59], v[32:35], off offset:16 nt
	global_store_dwordx4 v[56:57], v[44:47], off nt
	global_store_dwordx4 v[56:57], v[40:43], off offset:16 nt

; #define LAS __attribute__((address_space(3)))
; __device__ __forceinline__ unsigned cvt_pk_bf16(float lo, float hi) { unsigned r; asm volatile("v_cvt_pk_bf16_f32 %0, %1, %2" : "=v"(r) : "v"(lo), "v"(hi)); return r; }
; __device__ __forceinline__ u32x4 pack8(const float* f) { u32x4 w; w.x = cvt_pk_bf16(f[0], f[1]); w.y = cvt_pk_bf16(f[2], f[3]); w.z = cvt_pk_bf16(f[4], f[5]); w.w = cvt_pk_bf16(f[6], f[7]); return w; }
; __device__ __forceinline__ void attn_unit(const Params& p, int l, LAS unsigned char* lds, bool sample, int b, int c, int kvh) {
;     ...
;         *(LAS u32x4*)(Ks + j * KS_LD + ch * 8) = pack8(kf);
; #pragma unroll
;         for (int i = 0; i < 8; i += 2) { const unsigned w = cvt_pk_bf16(vf[i], vf[i + 1]); const int js = j ^ (ch << 3);
;             Vt[(ch * 8 + i) * VT_LD + js] = (bf16_t)(w & 0xffffu); Vt[(ch * 8 + i + 1) * VT_LD + js] = (bf16_t)(w >> 16); }
;         float* kd = nullptr; float* vd = nullptr;
;         if (!sample) { if (c >= 254 && j >= 128) { const size_t o = ((((size_t)l * 2 + b) * 128 + (c - 254) * 64 + (j - 128)) * 2 + kvh) * 64 + ch * 8; kd = p.out + O_KP + o; vd = p.out + O_VP + o; } }
;         else if (j >= 16 && j < 144) { const size_t o = ((((size_t)l * 8 + b) * 128 + (j - 16)) * 2 + kvh) * 64 + ch * 8; kd = p.out + O_KS + o; vd = p.out + O_VS + o; }
;         if (kd) { *(f32x4*)kd = (f32x4){kf[0], kf[1], kf[2], kf[3]}; *(f32x4*)(kd + 4) = (f32x4){kf[4], kf[5], kf[6], kf[7]};
;                   *(f32x4*)vd = (f32x4){vf[0], vf[1], vf[2], vf[3]}; *(f32x4*)(vd + 4) = (f32x4){vf[4], vf[5], vf[6], vf[7]}; }
.LBB0_600:
	s_or_b64 exec, exec, s[0:1]
	v_cvt_pk_bf16_f32 v32, v20, v21
	v_mad_u64_u32 v[36:37], s[0:1], v90, s83, v[84:85]
	s_waitcnt lgkmcnt(0)
	v_cvt_pk_bf16_f32 v33, v22, v23
	v_cvt_pk_bf16_f32 v34, v16, v17
	v_cvt_pk_bf16_f32 v35, v18, v19
	ds_write_b128 v36, v[32:35]
	v_xor_b32_e32 v32, v90, v98
	v_lshlrev_b32_e32 v32, 1, v32
	v_cvt_pk_bf16_f32 v33, v28, v29
	v_add_u32_e32 v34, v100, v32
	ds_write_b16 v34, v33 offset:27648
	ds_write_b16_d16_hi v34, v33 offset:28048
	v_cvt_pk_bf16_f32 v33, v30, v31
	v_add_u32_e32 v34, v101, v32
	ds_write_b16 v34, v33 offset:27648
	ds_write_b16_d16_hi v34, v33 offset:28048
	v_cvt_pk_bf16_f32 v33, v24, v25
	v_add_u32_e32 v34, v102, v32
	ds_write_b16 v34, v33 offset:27648
	ds_write_b16_d16_hi v34, v33 offset:28048
	v_cvt_pk_bf16_f32 v33, v26, v27
	v_add_u32_e32 v32, v103, v32
	v_add_u32_e32 v36, -16, v90
	ds_write_b16 v32, v33 offset:27648
	ds_write_b16_d16_hi v32, v33 offset:28048
	v_cmp_gt_u32_e32 vcc, s31, v36
	v_mov_b64_e32 v[32:33], 0
	v_mov_b64_e32 v[34:35], 0
	s_and_saveexec_b64 s[0:1], vcc
	v_lshl_or_b32 v32, v36, 1, s8
	v_mov_b32_e32 v33, s9
	v_lshlrev_b64 v[32:33], 8, v[32:33]
	v_lshl_or_b32 v32, v98, 2, v32
	v_lshl_add_u64 v[34:35], s[46:47], 0, v[32:33]
	v_lshl_add_u64 v[32:33], s[52:53], 0, v[32:33]
	s_or_b64 exec, exec, s[0:1]
	v_cmp_ne_u64_e32 vcc, 0, v[34:35]
	s_and_saveexec_b64 s[0:1], vcc
	s_cbranch_execz .LBB0_604
	global_store_dwordx4 v[34:35], v[20:23], off nt
	global_store_dwordx4 v[34:35], v[16:19], off offset:16 nt
	global_store_dwordx4 v[32:33], v[28:31], off nt
	global_store_dwordx4 v[32:33], v[24:27], off offset:16 nt

; #define LAS __attribute__((address_space(3)))
; __device__ __forceinline__ unsigned cvt_pk_bf16(float lo, float hi) { unsigned r; asm volatile("v_cvt_pk_bf16_f32 %0, %1, %2" : "=v"(r) : "v"(lo), "v"(hi)); return r; }
; __device__ __forceinline__ void attn_unit(const Params& p, int l, LAS unsigned char* lds, bool sample, int b, int c, int kvh) {
;     ...
;         f32x16 o[2]; o[0] = (f32x16){}; o[1] = (f32x16){};
; #pragma unroll
;         for (int kt = 0; kt < 6; ++kt)
; #pragma unroll
;             for (int jj = 0; jj < 2; ++jj) {
;                 u32x4 pw;
;                 pw.x = cvt_pk_bf16(s[kt][8 * jj + 0], s[kt][8 * jj + 1]); pw.y = cvt_pk_bf16(s[kt][8 * jj + 2], s[kt][8 * jj + 3]);
;                 pw.z = cvt_pk_bf16(s[kt][8 * jj + 4], s[kt][8 * jj + 5]); pw.w = cvt_pk_bf16(s[kt][8 * jj + 6], s[kt][8 * jj + 7]);
;                 const bf16x8 pa = __builtin_bit_cast(bf16x8, pw);
;                 const int e0 = 32 * kt + 16 * jj + 4 * hi;
; #pragma unroll
;                 for (int db = 0; db < 2; ++db) {
;                     const int sw = (((db * 32 + q32) >> 3) & 7) << 3;
;                     const u32x2 lo = *(const LAS u32x2*)(Vt + (db * 32 + q32) * VT_LD + (e0 ^ sw)), hi2 = *(const LAS u32x2*)(Vt + (db * 32 + q32) * VT_LD + ((e0 + 8) ^ sw));
;                     const bf16x8 vb = __builtin_bit_cast(bf16x8, (u32x4){lo.x, lo.y, hi2.x, hi2.y});
;                     o[db] = __builtin_amdgcn_mfma_f32_32x32x16_bf16(pa, vb, o[db], 0, 0, 0);
;                 }
;                 __builtin_amdgcn_sched_barrier(0);
;             }
.LBB0_607:
	s_or_b64 exec, exec, s[0:1]
	v_mad_u32_u24 v148, v111, s14, 0
	v_bitop3_b32 v0, v98, v208, 24 bitop3:0x78
	s_waitcnt lgkmcnt(0)
	v_bitop3_b32 v1, v83, v208, 24 bitop3:0x78
	v_lshl_add_u32 v0, v0, 1, v148
	v_lshl_add_u32 v2, v1, 1, v148
	v_cvt_pk_bf16_f32 v16, v8, v9
	v_cvt_pk_bf16_f32 v17, v10, v11
	v_cvt_pk_bf16_f32 v18, v14, v15
	v_cvt_pk_bf16_f32 v19, v28, v29
	ds_read_b64 v[0:1], v0 offset:27648
	ds_read_b64 v[2:3], v2 offset:27648
	v_or_b32_e32 v96, 32, v111
	v_add_u32_e32 v149, 0x3200, v148
	v_bitop3_b32 v4, v96, v98, 56 bitop3:0x6c
	v_bitop3_b32 v5, v96, v83, 56 bitop3:0x6c
	v_lshl_add_u32 v4, v4, 1, v149
	v_lshl_add_u32 v5, v5, 1, v149
	ds_read_b64 v[20:21], v4 offset:27648
	ds_read_b64 v[22:23], v5 offset:27648
	s_waitcnt lgkmcnt(2)
	v_mfma_f32_32x32x16_bf16 v[0:15], v[16:19], v[0:3], 0
	s_waitcnt lgkmcnt(0)
	v_mfma_f32_32x32x16_bf16 v[16:31], v[16:19], v[20:23], 0
	v_bitop3_b32 v83, v81, v208, 24 bitop3:0x78
	v_lshl_add_u32 v83, v83, 1, v148
	v_cvt_pk_bf16_f32 v150, v126, v127
	v_cvt_pk_bf16_f32 v151, v124, v125
	v_cvt_pk_bf16_f32 v152, v123, v121
	v_cvt_pk_bf16_f32 v153, v122, v120
	ds_read_b64 v[120:121], v83 offset:27648
	v_bitop3_b32 v83, v82, v208, 24 bitop3:0x78
	v_lshl_add_u32 v83, v83, 1, v148
	ds_read_b64 v[122:123], v83 offset:27648
	v_bitop3_b32 v81, v96, v81, 56 bitop3:0x6c
	s_waitcnt lgkmcnt(0)
	v_mfma_f32_32x32x16_bf16 v[0:15], v[150:153], v[120:123], v[0:15]
	v_lshl_add_u32 v81, v81, 1, v149
	ds_read_b64 v[120:121], v81 offset:27648
	v_bitop3_b32 v81, v96, v82, 56 bitop3:0x6c
	v_lshl_add_u32 v81, v81, 1, v149
	ds_read_b64 v[122:123], v81 offset:27648
	s_waitcnt lgkmcnt(0)
	v_mfma_f32_32x32x16_bf16 v[16:31], v[150:153], v[120:123], v[16:31]
	v_bitop3_b32 v81, v80, v208, 24 bitop3:0x78
	v_lshl_add_u32 v81, v81, 1, v148
	v_cvt_pk_bf16_f32 v120, v119, v117
	v_cvt_pk_bf16_f32 v121, v118, v116
	v_cvt_pk_bf16_f32 v122, v115, v114
	v_cvt_pk_bf16_f32 v123, v113, v112
	ds_read_b64 v[112:113], v81 offset:27648
	v_bitop3_b32 v81, v67, v208, 24 bitop3:0x78
	v_lshl_add_u32 v81, v81, 1, v148
	ds_read_b64 v[114:115], v81 offset:27648
	s_waitcnt lgkmcnt(0)
	v_mfma_f32_32x32x16_bf16 v[0:15], v[120:123], v[112:115], v[0:15]
	v_bitop3_b32 v80, v96, v80, 56 bitop3:0x6c
	v_bitop3_b32 v67, v96, v67, 56 bitop3:0x6c
	v_lshl_add_u32 v80, v80, 1, v149
	v_lshl_add_u32 v67, v67, 1, v149
	ds_read_b64 v[80:81], v80 offset:27648
	ds_read_b64 v[82:83], v67 offset:27648
	s_waitcnt lgkmcnt(0)
	v_mfma_f32_32x32x16_bf16 v[16:31], v[120:123], v[80:83], v[16:31]
	v_bitop3_b32 v67, v65, v208, 24 bitop3:0x78
	v_lshl_add_u32 v67, v67, 1, v148
	v_cvt_pk_bf16_f32 v80, v108, v109
	v_cvt_pk_bf16_f32 v81, v106, v107
	v_cvt_pk_bf16_f32 v82, v105, v103
	v_cvt_pk_bf16_f32 v83, v104, v102
	ds_read_b64 v[102:103], v67 offset:27648
	v_bitop3_b32 v67, v66, v208, 24 bitop3:0x78
	v_lshl_add_u32 v67, v67, 1, v148
	ds_read_b64 v[104:105], v67 offset:27648
	v_bitop3_b32 v65, v96, v65, 56 bitop3:0x6c
	s_waitcnt lgkmcnt(0)
	v_mfma_f32_32x32x16_bf16 v[0:15], v[80:83], v[102:105], v[0:15]
	v_lshl_add_u32 v65, v65, 1, v149
	ds_read_b64 v[102:103], v65 offset:27648
	v_bitop3_b32 v65, v96, v66, 56 bitop3:0x6c
	v_lshl_add_u32 v65, v65, 1, v149
	ds_read_b64 v[104:105], v65 offset:27648
	s_waitcnt lgkmcnt(0)
	v_mfma_f32_32x32x16_bf16 v[16:31], v[80:83], v[102:105], v[16:31]
	v_bitop3_b32 v65, v64, v208, 24 bitop3:0x78
	v_lshl_add_u32 v65, v65, 1, v148
	v_cvt_pk_bf16_f32 v80, v101, v100
	v_cvt_pk_bf16_f32 v81, v99, v95
	v_cvt_pk_bf16_f32 v82, v94, v93
	v_cvt_pk_bf16_f32 v83, v92, v91
	ds_read_b64 v[92:93], v65 offset:27648
	v_bitop3_b32 v65, v52, v208, 24 bitop3:0x78
	v_lshl_add_u32 v65, v65, 1, v148
	ds_read_b64 v[94:95], v65 offset:27648
	s_waitcnt lgkmcnt(0)
	v_mfma_f32_32x32x16_bf16 v[0:15], v[80:83], v[92:95], v[0:15]
	v_bitop3_b32 v64, v96, v64, 56 bitop3:0x6c
	v_bitop3_b32 v52, v96, v52, 56 bitop3:0x6c
	v_lshl_add_u32 v64, v64, 1, v149
	v_lshl_add_u32 v52, v52, 1, v149
	ds_read_b64 v[64:65], v64 offset:27648
	ds_read_b64 v[66:67], v52 offset:27648
	s_waitcnt lgkmcnt(0)
	v_mfma_f32_32x32x16_bf16 v[16:31], v[80:83], v[64:67], v[16:31]
	v_bitop3_b32 v52, v50, v208, 24 bitop3:0x78
	v_lshl_add_u32 v52, v52, 1, v148
	v_cvt_pk_bf16_f32 v64, v90, v89
	v_cvt_pk_bf16_f32 v65, v88, v87
	v_cvt_pk_bf16_f32 v66, v86, v85
	v_cvt_pk_bf16_f32 v67, v84, v79
	ds_read_b64 v[80:81], v52 offset:27648
	v_bitop3_b32 v52, v51, v208, 24 bitop3:0x78
	v_lshl_add_u32 v52, v52, 1, v148
	ds_read_b64 v[82:83], v52 offset:27648
	v_bitop3_b32 v50, v96, v50, 56 bitop3:0x6c
	s_waitcnt lgkmcnt(0)
	v_mfma_f32_32x32x16_bf16 v[0:15], v[64:67], v[80:83], v[0:15]
	v_lshl_add_u32 v50, v50, 1, v149
	ds_read_b64 v[80:81], v50 offset:27648
	v_bitop3_b32 v50, v96, v51, 56 bitop3:0x6c
	v_lshl_add_u32 v50, v50, 1, v149
	ds_read_b64 v[82:83], v50 offset:27648
	s_waitcnt lgkmcnt(0)
	v_mfma_f32_32x32x16_bf16 v[16:31], v[64:67], v[80:83], v[16:31]
	v_bitop3_b32 v50, v48, v208, 24 bitop3:0x78
	v_lshl_add_u32 v50, v50, 1, v148
	v_cvt_pk_bf16_f32 v64, v78, v77
	v_cvt_pk_bf16_f32 v65, v76, v75
	v_cvt_pk_bf16_f32 v66, v74, v73
	v_cvt_pk_bf16_f32 v67, v72, v71
	ds_read_b64 v[72:73], v50 offset:27648
	v_bitop3_b32 v50, v49, v208, 24 bitop3:0x78
	v_lshl_add_u32 v50, v50, 1, v148
	ds_read_b64 v[74:75], v50 offset:27648
	v_bitop3_b32 v48, v96, v48, 56 bitop3:0x6c
	s_waitcnt lgkmcnt(0)
	v_mfma_f32_32x32x16_bf16 v[0:15], v[64:67], v[72:75], v[0:15]
	v_lshl_add_u32 v48, v48, 1, v149
	ds_read_b64 v[72:73], v48 offset:27648
	v_bitop3_b32 v48, v96, v49, 56 bitop3:0x6c
	v_lshl_add_u32 v48, v48, 1, v149
	ds_read_b64 v[74:75], v48 offset:27648
	s_waitcnt lgkmcnt(0)
; #define LAS __attribute__((address_space(3)))
; __device__ __forceinline__ unsigned cvt_pk_bf16(float lo, float hi) { unsigned r; asm volatile("v_cvt_pk_bf16_f32 %0, %1, %2" : "=v"(r) : "v"(lo), "v"(hi)); return r; }
; __device__ __forceinline__ int crow(int r, int hi) { return (r & 3) + 8 * (r >> 2) + 4 * hi; }
; __device__ __forceinline__ void attn_unit(const Params& p, int l, LAS unsigned char* lds, bool sample, int b, int c, int kvh) {
;     ...
;         for (int kt = 0; kt < 6; ++kt)
; #pragma unroll
;             for (int jj = 0; jj < 2; ++jj) {
;                 u32x4 pw;
;                 pw.x = cvt_pk_bf16(s[kt][8 * jj + 0], s[kt][8 * jj + 1]); pw.y = cvt_pk_bf16(s[kt][8 * jj + 2], s[kt][8 * jj + 3]);
;                 pw.z = cvt_pk_bf16(s[kt][8 * jj + 4], s[kt][8 * jj + 5]); pw.w = cvt_pk_bf16(s[kt][8 * jj + 6], s[kt][8 * jj + 7]);
;                 const bf16x8 pa = __builtin_bit_cast(bf16x8, pw);
;                 const int e0 = 32 * kt + 16 * jj + 4 * hi;
; #pragma unroll
;                 for (int db = 0; db < 2; ++db) {
;                     const int sw = (((db * 32 + q32) >> 3) & 7) << 3;
;                     const u32x2 lo = *(const LAS u32x2*)(Vt + (db * 32 + q32) * VT_LD + (e0 ^ sw)), hi2 = *(const LAS u32x2*)(Vt + (db * 32 + q32) * VT_LD + ((e0 + 8) ^ sw));
;                     const bf16x8 vb = __builtin_bit_cast(bf16x8, (u32x4){lo.x, lo.y, hi2.x, hi2.y});
;                     o[db] = __builtin_amdgcn_mfma_f32_32x32x16_bf16(pa, vb, o[db], 0, 0, 0);
;                 }
;                 __builtin_amdgcn_sched_barrier(0);
;             }
;         asm volatile("s_waitcnt lgkmcnt(0)" ::: "memory");
;         LAS bf16_t* ost = (LAS bf16_t*)(lds + LDS_OST) + wid * (32 * 72);
; #pragma unroll
;         for (int r = 0; r < 16; ++r) {
;             const int qq = crow(r, hi);
;             const float inv = wsc[qq];
; #pragma unroll
;             for (int db = 0; db < 2; ++db) ost[qq * 72 + db * 32 + q32] = (bf16_t)(cvt_pk_bf16(o[db][r] * inv, 0.f) & 0xffffu);
	v_mfma_f32_32x32x16_bf16 v[16:31], v[64:67], v[72:75], v[16:31]
	v_bitop3_b32 v52, v40, v208, 24 bitop3:0x78
	v_lshl_add_u32 v52, v52, 1, v148
	v_cvt_pk_bf16_f32 v48, v70, v69
	v_cvt_pk_bf16_f32 v49, v68, v63
	v_cvt_pk_bf16_f32 v50, v62, v61
	v_cvt_pk_bf16_f32 v51, v60, v59
	ds_read_b64 v[60:61], v52 offset:27648
	v_bitop3_b32 v52, v41, v208, 24 bitop3:0x78
	v_lshl_add_u32 v52, v52, 1, v148
	ds_read_b64 v[62:63], v52 offset:27648
	v_bitop3_b32 v40, v96, v40, 56 bitop3:0x6c
	s_waitcnt lgkmcnt(0)
	v_mfma_f32_32x32x16_bf16 v[0:15], v[48:51], v[60:63], v[0:15]
	v_lshl_add_u32 v40, v40, 1, v149
	ds_read_b64 v[60:61], v40 offset:27648
	v_bitop3_b32 v40, v96, v41, 56 bitop3:0x6c
	v_lshl_add_u32 v40, v40, 1, v149
	ds_read_b64 v[62:63], v40 offset:27648
	s_waitcnt lgkmcnt(0)
	v_mfma_f32_32x32x16_bf16 v[16:31], v[48:51], v[60:63], v[16:31]
	v_bitop3_b32 v40, v38, v208, 24 bitop3:0x78
	v_lshl_add_u32 v40, v40, 1, v148
	v_cvt_pk_bf16_f32 v48, v58, v57
	v_cvt_pk_bf16_f32 v49, v56, v55
	v_cvt_pk_bf16_f32 v50, v54, v53
	v_cvt_pk_bf16_f32 v51, v130, v134
	ds_read_b64 v[52:53], v40 offset:27648
	v_bitop3_b32 v40, v39, v208, 24 bitop3:0x78
	v_lshl_add_u32 v40, v40, 1, v148
	ds_read_b64 v[54:55], v40 offset:27648
	v_bitop3_b32 v38, v96, v38, 56 bitop3:0x6c
	s_waitcnt lgkmcnt(0)
	v_mfma_f32_32x32x16_bf16 v[0:15], v[48:51], v[52:55], v[0:15]
	v_lshl_add_u32 v38, v38, 1, v149
	ds_read_b64 v[52:53], v38 offset:27648
	v_bitop3_b32 v38, v96, v39, 56 bitop3:0x6c
	v_lshl_add_u32 v38, v38, 1, v149
	ds_read_b64 v[54:55], v38 offset:27648
	s_waitcnt lgkmcnt(0)
	v_mfma_f32_32x32x16_bf16 v[16:31], v[48:51], v[52:55], v[16:31]
	v_cvt_pk_bf16_f32 v38, v45, v44
	v_cvt_pk_bf16_f32 v39, v43, v46
	v_bitop3_b32 v43, v36, v208, 24 bitop3:0x78
	v_lshl_add_u32 v43, v43, 1, v148
	v_cvt_pk_bf16_f32 v40, v131, v135
	v_cvt_pk_bf16_f32 v41, v137, v140
	ds_read_b64 v[48:49], v43 offset:27648
	v_bitop3_b32 v43, v37, v208, 24 bitop3:0x78
	v_lshl_add_u32 v43, v43, 1, v148
	ds_read_b64 v[50:51], v43 offset:27648
	v_bitop3_b32 v36, v96, v36, 56 bitop3:0x6c
	s_waitcnt lgkmcnt(0)
	v_mfma_f32_32x32x16_bf16 v[0:15], v[38:41], v[48:51], v[0:15]
	v_lshl_add_u32 v36, v36, 1, v149
	ds_read_b64 v[48:49], v36 offset:27648
	v_bitop3_b32 v36, v96, v37, 56 bitop3:0x6c
	v_lshl_add_u32 v36, v36, 1, v149
	ds_read_b64 v[50:51], v36 offset:27648
	s_waitcnt lgkmcnt(0)
	v_mfma_f32_32x32x16_bf16 v[16:31], v[38:41], v[48:51], v[16:31]
	v_cvt_pk_bf16_f32 v36, v42, v47
	v_bitop3_b32 v40, v34, v208, 24 bitop3:0x78
	v_bitop3_b32 v42, v35, v208, 24 bitop3:0x78
	v_lshl_add_u32 v40, v40, 1, v148
	v_lshl_add_u32 v42, v42, 1, v148
	v_cvt_pk_bf16_f32 v37, v128, v132
	v_cvt_pk_bf16_f32 v38, v138, v141
	v_cvt_pk_bf16_f32 v39, v142, v144
	ds_read_b64 v[40:41], v40 offset:27648
	ds_read_b64 v[42:43], v42 offset:27648
	v_bitop3_b32 v34, v96, v34, 56 bitop3:0x6c
	s_waitcnt lgkmcnt(0)
	v_mfma_f32_32x32x16_bf16 v[0:15], v[36:39], v[40:43], v[0:15]
	v_lshl_add_u32 v34, v34, 1, v149
	ds_read_b64 v[40:41], v34 offset:27648
	v_bitop3_b32 v34, v96, v35, 56 bitop3:0x6c
	v_lshl_add_u32 v34, v34, 1, v149
	ds_read_b64 v[42:43], v34 offset:27648
	s_waitcnt lgkmcnt(0)
	v_mfma_f32_32x32x16_bf16 v[16:31], v[36:39], v[40:43], v[16:31]
	v_bitop3_b32 v38, v32, v208, 24 bitop3:0x78
	v_bitop3_b32 v40, v33, v208, 24 bitop3:0x78
	v_lshl_add_u32 v38, v38, 1, v148
	v_lshl_add_u32 v40, v40, 1, v148
	v_cvt_pk_bf16_f32 v34, v129, v133
	v_cvt_pk_bf16_f32 v35, v136, v139
	v_cvt_pk_bf16_f32 v36, v143, v145
	v_cvt_pk_bf16_f32 v37, v146, v147
	ds_read_b64 v[38:39], v38 offset:27648
	ds_read_b64 v[40:41], v40 offset:27648
	v_bitop3_b32 v32, v96, v32, 56 bitop3:0x6c
	s_waitcnt lgkmcnt(0)
	v_mfma_f32_32x32x16_bf16 v[0:15], v[34:37], v[38:41], v[0:15]
	v_lshl_add_u32 v32, v32, 1, v149
	ds_read_b64 v[38:39], v32 offset:27648
	v_bitop3_b32 v32, v96, v33, 56 bitop3:0x6c
	v_lshl_add_u32 v32, v32, 1, v149
	ds_read_b64 v[40:41], v32 offset:27648
	s_waitcnt lgkmcnt(0)
	v_mfma_f32_32x32x16_bf16 v[16:31], v[34:37], v[38:41], v[16:31]
	s_waitcnt lgkmcnt(0)
	v_lshl_add_u32 v36, v98, 2, s8
	ds_read_b32 v33, v36 offset:53248
	s_mulk_i32 s9, 0x1200
	s_add_i32 s7, s9, 0
	v_lshl_add_u32 v32, v111, 1, s7
	s_movk_i32 s0, 0x240
	s_waitcnt lgkmcnt(0)
	v_mul_f32_e32 v0, v0, v33
	v_mad_u64_u32 v[34:35], s[0:1], v110, s0, v[32:33]
	v_cvt_pk_bf16_f32 v0, v0, v97
	ds_write_b16 v34, v0 offset:54272
	s_nop 1
	v_mul_f32_e32 v0, v16, v33
	v_cvt_pk_bf16_f32 v0, v0, v97
	ds_read_b32 v16, v36 offset:53252
	ds_write_b16 v34, v0 offset:54336
	v_or_b32_e32 v0, 1, v98
	v_mad_u64_u32 v[32:33], s[0:1], v0, s83, v[32:33]
	s_waitcnt lgkmcnt(1)
; #define LAS __attribute__((address_space(3)))
; __device__ __forceinline__ unsigned cvt_pk_bf16(float lo, float hi) { unsigned r; asm volatile("v_cvt_pk_bf16_f32 %0, %1, %2" : "=v"(r) : "v"(lo), "v"(hi)); return r; }
; __device__ __forceinline__ int crow(int r, int hi) { return (r & 3) + 8 * (r >> 2) + 4 * hi; }
; __device__ __forceinline__ void attn_unit(const Params& p, int l, LAS unsigned char* lds, bool sample, int b, int c, int kvh) {
;     ...
;         for (int r = 0; r < 16; ++r) {
;             const int qq = crow(r, hi);
;             const float inv = wsc[qq];
; #pragma unroll
;             for (int db = 0; db < 2; ++db) ost[qq * 72 + db * 32 + q32] = (bf16_t)(cvt_pk_bf16(o[db][r] * inv, 0.f) & 0xffffu);
;         }
;         asm volatile("s_waitcnt lgkmcnt(0)" ::: "memory");
; #pragma unroll
;         for (int i = 0; i < 4; ++i) {
;             const int row = i * 8 + (lane >> 3), chn = lane & 7;
;             const u32x4 v = *(const LAS u32x4*)(ost + row * 72 + chn * 8);
;             if (!sample || row < 16) { const long orow = sample ? row0 + row : row0 + half * 32 + row; *(u32x4*)(AD + (size_t)orow * DM + h * 64 + chn * 8) = v; }
;         }
	v_mul_f32_e32 v0, v1, v16
	v_cvt_pk_bf16_f32 v0, v0, v97
	ds_write_b16 v32, v0 offset:54272
	v_mul_f32_e32 v0, v17, v16
	v_cvt_pk_bf16_f32 v0, v0, v97
	ds_read_b32 v1, v36 offset:53256
	ds_write_b16 v32, v0 offset:54336
	s_lshl_b64 s[0:1], s[2:3], 1
	s_add_u32 s0, s48, s0
	s_addc_u32 s1, s49, s1
	s_waitcnt lgkmcnt(1)
	v_mul_f32_e32 v0, v2, v1
	v_cvt_pk_bf16_f32 v0, v0, v97
	ds_write_b16 v32, v0 offset:54416
	v_mul_f32_e32 v0, v18, v1
	v_cvt_pk_bf16_f32 v0, v0, v97
	ds_read_b32 v1, v36 offset:53260
	ds_write_b16 v32, v0 offset:54480
	s_waitcnt lgkmcnt(1)
	v_mul_f32_e32 v0, v3, v1
	v_cvt_pk_bf16_f32 v0, v0, v97
	ds_write_b16 v32, v0 offset:54560
	v_mul_f32_e32 v0, v19, v1
	v_cvt_pk_bf16_f32 v0, v0, v97
	ds_read_b32 v1, v36 offset:53280
	ds_write_b16 v32, v0 offset:54624
	s_waitcnt lgkmcnt(1)
	v_mul_f32_e32 v0, v4, v1
	v_cvt_pk_bf16_f32 v0, v0, v97
	ds_write_b16 v32, v0 offset:55280
	v_mul_f32_e32 v0, v20, v1
	v_cvt_pk_bf16_f32 v0, v0, v97
	ds_read_b32 v1, v36 offset:53284
	ds_write_b16 v32, v0 offset:55344
	s_waitcnt lgkmcnt(1)
	v_mul_f32_e32 v0, v5, v1
	v_cvt_pk_bf16_f32 v0, v0, v97
	ds_write_b16 v32, v0 offset:55424
	v_mul_f32_e32 v0, v21, v1
	v_cvt_pk_bf16_f32 v0, v0, v97
	ds_read_b32 v1, v36 offset:53288
	ds_write_b16 v32, v0 offset:55488
	s_waitcnt lgkmcnt(1)
	v_mul_f32_e32 v0, v6, v1
	v_cvt_pk_bf16_f32 v0, v0, v97
	ds_write_b16 v32, v0 offset:55568
	v_mul_f32_e32 v0, v22, v1
	v_cvt_pk_bf16_f32 v0, v0, v97
	ds_read_b32 v1, v36 offset:53292
	ds_write_b16 v32, v0 offset:55632
	s_waitcnt lgkmcnt(1)
	v_mul_f32_e32 v0, v7, v1
	v_cvt_pk_bf16_f32 v0, v0, v97
	ds_write_b16 v32, v0 offset:55712
	v_mul_f32_e32 v0, v23, v1
	v_cvt_pk_bf16_f32 v0, v0, v97
	ds_read_b32 v1, v36 offset:53312
	ds_write_b16 v32, v0 offset:55776
	s_waitcnt lgkmcnt(1)
	v_mul_f32_e32 v0, v8, v1
	v_cvt_pk_bf16_f32 v0, v0, v97
	ds_write_b16 v32, v0 offset:56432
	v_mul_f32_e32 v0, v24, v1
	v_cvt_pk_bf16_f32 v0, v0, v97
	ds_read_b32 v1, v36 offset:53316
	ds_write_b16 v32, v0 offset:56496
	s_waitcnt lgkmcnt(1)
	v_mul_f32_e32 v0, v9, v1
	v_cvt_pk_bf16_f32 v0, v0, v97
	ds_write_b16 v32, v0 offset:56576
	v_mul_f32_e32 v0, v25, v1
	v_cvt_pk_bf16_f32 v0, v0, v97
	ds_read_b32 v1, v36 offset:53320
	ds_write_b16 v32, v0 offset:56640
	s_waitcnt lgkmcnt(1)
	v_mul_f32_e32 v0, v10, v1
	v_cvt_pk_bf16_f32 v0, v0, v97
	ds_write_b16 v32, v0 offset:56720
	v_mul_f32_e32 v0, v26, v1
	v_cvt_pk_bf16_f32 v0, v0, v97
	ds_read_b32 v1, v36 offset:53324
	ds_write_b16 v32, v0 offset:56784
	s_waitcnt lgkmcnt(1)
	v_mul_f32_e32 v0, v11, v1
	v_cvt_pk_bf16_f32 v0, v0, v97
	ds_write_b16 v32, v0 offset:56864
	v_mul_f32_e32 v0, v27, v1
	v_cvt_pk_bf16_f32 v0, v0, v97
	ds_read_b32 v1, v36 offset:53344
	ds_write_b16 v32, v0 offset:56928
	s_waitcnt lgkmcnt(1)
	v_mul_f32_e32 v0, v12, v1
	v_cvt_pk_bf16_f32 v0, v0, v97
	ds_write_b16 v32, v0 offset:57584
	v_mul_f32_e32 v0, v28, v1
	v_cvt_pk_bf16_f32 v0, v0, v97
	ds_read_b32 v1, v36 offset:53348
	ds_write_b16 v32, v0 offset:57648
	s_waitcnt lgkmcnt(1)
	v_mul_f32_e32 v0, v13, v1
	v_cvt_pk_bf16_f32 v0, v0, v97
	ds_write_b16 v32, v0 offset:57728
	v_mul_f32_e32 v0, v29, v1
	v_cvt_pk_bf16_f32 v0, v0, v97
	ds_read_b32 v1, v36 offset:53352
	ds_write_b16 v32, v0 offset:57792
	s_waitcnt lgkmcnt(1)
	v_mul_f32_e32 v0, v14, v1
	v_cvt_pk_bf16_f32 v0, v0, v97
	ds_write_b16 v32, v0 offset:57872
	v_mul_f32_e32 v0, v30, v1
	v_cvt_pk_bf16_f32 v0, v0, v97
	ds_read_b32 v1, v36 offset:53356
	ds_write_b16 v32, v0 offset:57936
	s_waitcnt lgkmcnt(1)
	v_mul_f32_e32 v0, v15, v1
	v_cvt_pk_bf16_f32 v0, v0, v97
	ds_write_b16 v32, v0 offset:58016
	v_mul_f32_e32 v0, v31, v1
	v_cvt_pk_bf16_f32 v0, v0, v97
	ds_write_b16 v32, v0 offset:58080
	s_waitcnt lgkmcnt(0)
	v_lshlrev_b32_e32 v1, 4, v208
	v_ashrrev_i32_e32 v0, 3, v208
	v_and_b32_e32 v96, 0x70, v1
	v_add_u32_e32 v2, s7, v96
	v_lshl_add_u64 v[4:5], s[0:1], 0, v[96:97]
	v_cmp_gt_i32_e32 vcc, 16, v0
	s_and_saveexec_b64 s[0:1], vcc
	s_cbranch_execz .LBB0_611
	v_mad_u64_u32 v[6:7], s[2:3], v0, s83, v[2:3]
	ds_read_b128 v[6:9], v6 offset:54272
	v_ashrrev_i32_e32 v1, 31, v0
	v_lshl_add_u64 v[10:11], s[40:41], 0, v[0:1]
	v_lshlrev_b64 v[10:11], 11, v[10:11]
	v_lshl_add_u64 v[10:11], v[4:5], 0, v[10:11]
	s_waitcnt lgkmcnt(0)
	global_store_dwordx4 v[10:11], v[6:9], off nt
	s_or_b64 exec, exec, s[0:1]
	v_cmp_gt_i32_e32 vcc, 8, v0
	s_and_saveexec_b64 s[0:1], vcc
	s_cbranch_execnz .LBB0_612

; #define LAS __attribute__((address_space(3)))
; __device__ __forceinline__ void attn_unit(const Params& p, int l, LAS unsigned char* lds, bool sample, int b, int c, int kvh) {
;     ...
; #pragma unroll
;         for (int i = 0; i < 4; ++i) {
;             const int row = i * 8 + (lane >> 3), chn = lane & 7;
;             const u32x4 v = *(const LAS u32x4*)(ost + row * 72 + chn * 8);
;             if (!sample || row < 16) { const long orow = sample ? row0 + row : row0 + half * 32 + row; *(u32x4*)(AD + (size_t)orow * DM + h * 64 + chn * 8) = v; }
;         }
.LBB0_610:
	v_mad_u64_u32 v[6:7], s[2:3], v0, s83, v[2:3]
	v_add_u32_e32 v10, 16, v0
	ds_read_b128 v[6:9], v6 offset:56576
	v_ashrrev_i32_e32 v11, 31, v10
	v_lshl_add_u64 v[10:11], s[40:41], 0, v[10:11]
	v_lshlrev_b64 v[10:11], 11, v[10:11]
	v_lshl_add_u64 v[10:11], v[4:5], 0, v[10:11]
	s_waitcnt lgkmcnt(0)
	global_store_dwordx4 v[10:11], v[6:9], off nt
	s_or_b64 exec, exec, s[0:1]
	v_cmp_gt_i32_e32 vcc, -8, v0
	s_and_saveexec_b64 s[0:1], vcc
	s_cbranch_execz .LBB0_284
	s_branch .LBB0_614

; #define LAS __attribute__((address_space(3)))
; __device__ __forceinline__ void attn_unit(const Params& p, int l, LAS unsigned char* lds, bool sample, int b, int c, int kvh) {
;     ...
; #pragma unroll
;         for (int i = 0; i < 4; ++i) {
;             const int row = i * 8 + (lane >> 3), chn = lane & 7;
;             const u32x4 v = *(const LAS u32x4*)(ost + row * 72 + chn * 8);
;             if (!sample || row < 16) { const long orow = sample ? row0 + row : row0 + half * 32 + row; *(u32x4*)(AD + (size_t)orow * DM + h * 64 + chn * 8) = v; }
;         }
.LBB0_612:
	v_mad_u64_u32 v[6:7], s[2:3], v0, s83, v[2:3]
	v_add_u32_e32 v10, 8, v0
	ds_read_b128 v[6:9], v6 offset:55424
	v_ashrrev_i32_e32 v11, 31, v10
	v_lshl_add_u64 v[10:11], s[40:41], 0, v[10:11]
	v_lshlrev_b64 v[10:11], 11, v[10:11]
	v_lshl_add_u64 v[10:11], v[4:5], 0, v[10:11]
	s_waitcnt lgkmcnt(0)
	global_store_dwordx4 v[10:11], v[6:9], off nt
	s_or_b64 exec, exec, s[0:1]
	v_cmp_gt_i32_e32 vcc, 0, v0
	s_and_saveexec_b64 s[0:1], vcc
	s_cbranch_execnz .LBB0_610

; #define LAS __attribute__((address_space(3)))
; __device__ __forceinline__ void attn_unit(const Params& p, int l, LAS unsigned char* lds, bool sample, int b, int c, int kvh) {
;     ...
; #pragma unroll
;         for (int i = 0; i < 4; ++i) {
;             const int row = i * 8 + (lane >> 3), chn = lane & 7;
;             const u32x4 v = *(const LAS u32x4*)(ost + row * 72 + chn * 8);
;             if (!sample || row < 16) { const long orow = sample ? row0 + row : row0 + half * 32 + row; *(u32x4*)(AD + (size_t)orow * DM + h * 64 + chn * 8) = v; }
;         }
.LBB0_614:
	v_add_u32_e32 v6, 24, v0
	v_mad_u64_u32 v[0:1], s[2:3], v0, s83, v[2:3]
	ds_read_b128 v[0:3], v0 offset:57728
	v_ashrrev_i32_e32 v7, 31, v6
	v_lshl_add_u64 v[6:7], s[40:41], 0, v[6:7]
	v_lshlrev_b64 v[6:7], 11, v[6:7]
	v_lshl_add_u64 v[4:5], v[4:5], 0, v[6:7]
	s_waitcnt lgkmcnt(0)
	global_store_dwordx4 v[4:5], v[0:3], off nt
	s_branch .LBB0_284

; #define LAS __attribute__((address_space(3)))
; __device__ __forceinline__ void transpose_item(const float* W, int N, const float* ks, bf16_t* WT, int ldo, int orow0, int k0, int n0, LAS float* scr, int lane) {
;     f32x4 v[8];
; #pragma unroll
;     for (int i = 0; i < 8; ++i) v[i] = *(const f32x4*)(W + (size_t)(k0 + i * 4 + (lane >> 4)) * N + n0 + 4 * (lane & 15));
; #pragma unroll
;     for (int i = 0; i < 8; ++i) { const int kk = i * 4 + (lane >> 4); const float sc = ks ? ks[k0 + kk] : 1.0f; LAS float* d = scr + kk * 65 + 4 * (lane & 15);
;         d[0] = v[i][0] * sc; d[1] = v[i][1] * sc; d[2] = v[i][2] * sc; d[3] = v[i][3] * sc; }
;     asm volatile("s_waitcnt lgkmcnt(0)" ::: "memory");
;     const int kc = lane & 3;
; #pragma unroll
;     for (int j = 0; j < 4; ++j) { const int n = (lane >> 2) + 16 * j; const LAS float* s = scr + (8 * kc) * 65 + n;
;         u32x4 o; o.x = cvt_pk_bf16(s[0 * 65], s[1 * 65]); o.y = cvt_pk_bf16(s[2 * 65], s[3 * 65]); o.z = cvt_pk_bf16(s[4 * 65], s[5 * 65]); o.w = cvt_pk_bf16(s[6 * 65], s[7 * 65]);
;         *(u32x4*)(WT + (size_t)(orow0 + n) * ldo + k0 + 8 * kc) = o; }
;     asm volatile("s_waitcnt lgkmcnt(0)" ::: "memory");
; }
; __device__ __forceinline__ void convert_weights(const Params& p, LAS unsigned char* lds, int first, int last, int worker, int nworkers) {
;     ...
;     for (int it = first + worker; it < last; it += nworkers) {
;         const int l = it / WI_L; int r = it % WI_L;
;         unsigned char* wb = p.ws + WS_W + (size_t)l * W_LAYER;
;         if (r < WI_IN) { const int kb = r / 52, nb = r % 52; transpose_item(p.w_in + (size_t)l * DM * INW, INW, p.norm_mix + l * DM, (bf16_t*)(wb + WO_IN), DM, nb * 64, kb * 32, nb * 64, scr, lane); continue; } r -= WI_IN;
;         if (r < WI_BA) { const int kb = r / 16, nb = r % 16; transpose_item(p.w_br_attn + (size_t)l * 512 * DM, DM, nullptr, (bf16_t*)(wb + WO_MIX), 512, nb * 64, kb * 32, nb * 64, scr, lane); continue; } r -= WI_BA;
;         if (r < WI_OUT) { const int kb = r / 16, nb = r % 16; transpose_item(p.w_out + (size_t)l * DM * DM, DM, nullptr, (bf16_t*)(wb + WO_OUT), DM, nb * 64, kb * 32, nb * 64, scr, lane); continue; } r -= WI_OUT;
;         if (r < WI_UP) { const int kb = r / 88, nb = r % 88; const int n0 = nb * 64; const int nn = n0 < FF ? n0 : n0 - FF; const int orow = (nn >> 7) * 256 + (n0 < FF ? 0 : 128) + (nn & 127);
.LBB0_621:
	s_mul_hi_i32 s0, s7, 0x4ec4ec4f
	s_lshr_b32 s1, s0, 31
	s_ashr_i32 s0, s0, 11
	s_add_i32 s2, s0, s1
	s_mul_i32 s0, s2, 0xffffe600
	s_add_i32 s16, s7, s0
	s_ashr_i32 s3, s2, 31
	s_mul_i32 s1, s2, 0x1b00000
	s_mul_hi_i32 s0, s2, 0x1b00000
	s_add_u32 s14, s80, s1
	s_addc_u32 s15, s82, s0
	s_cmpk_gt_i32 s16, 0x67f
	s_mov_b64 s[0:1], -1
	s_cbranch_scc0 .LBB0_643
	s_cmpk_gt_u32 s16, 0x77f
	s_cbranch_scc0 .LBB0_640
	s_cmpk_gt_u32 s16, 0x97f
	s_cbranch_scc0 .LBB0_637
	s_cmpk_gt_u32 s16, 0x147f
	s_cbranch_scc0 .LBB0_626
	v_readlane_b32 s52, v248, 54
	s_mul_i32 s1, s2, 0xb00000
	v_readlane_b32 s62, v247, 0
	s_mul_hi_i32 s0, s2, 0xb00000
	v_readlane_b32 s63, v247, 1
	s_add_u32 s1, s62, s1
	s_mul_i32 s8, s2, 0xffffcc00
	s_addc_u32 s9, s63, s0
	s_add_i32 s8, s10, s8
	s_and_b32 s0, s12, 0x3c0
	s_and_b32 s8, s8, 0x7fffffe0
	s_add_i32 s96, s8, 0xffffd700
	s_lshl_b32 s8, s0, 2
	s_add_u32 s8, s1, s8
	v_or_b32_e32 v28, s96, v32
	s_addc_u32 s9, s9, 0
	v_lshlrev_b32_e32 v96, 2, v34
	v_mov_b32_e32 v29, v97
	v_lshl_add_u64 v[30:31], s[8:9], 0, v[96:97]
	v_lshlrev_b64 v[0:1], 12, v[28:29]
	v_or_b32_e32 v96, 4, v28
	v_lshl_add_u64 v[0:1], v[30:31], 0, v[0:1]
	v_lshlrev_b64 v[4:5], 12, v[96:97]
	global_load_dwordx4 v[0:3], v[0:1], off
	v_lshl_add_u64 v[4:5], v[30:31], 0, v[4:5]
	v_or_b32_e32 v96, 8, v28
	global_load_dwordx4 v[4:7], v[4:5], off
	v_lshlrev_b64 v[8:9], 12, v[96:97]
	v_lshl_add_u64 v[8:9], v[30:31], 0, v[8:9]
	v_or_b32_e32 v96, 12, v28
	global_load_dwordx4 v[8:11], v[8:9], off
	v_lshlrev_b64 v[12:13], 12, v[96:97]
	v_lshl_add_u64 v[12:13], v[30:31], 0, v[12:13]
	v_or_b32_e32 v96, 16, v28
	global_load_dwordx4 v[12:15], v[12:13], off
	v_lshlrev_b64 v[16:17], 12, v[96:97]
	v_lshl_add_u64 v[16:17], v[30:31], 0, v[16:17]
	v_or_b32_e32 v96, 20, v28
	global_load_dwordx4 v[16:19], v[16:17], off
	v_lshlrev_b64 v[20:21], 12, v[96:97]
	v_lshl_add_u64 v[20:21], v[30:31], 0, v[20:21]
	v_or_b32_e32 v96, 24, v28
	global_load_dwordx4 v[20:23], v[20:21], off
	v_lshlrev_b64 v[24:25], 12, v[96:97]
	v_lshl_add_u64 v[24:25], v[30:31], 0, v[24:25]
	v_or_b32_e32 v96, 28, v28
	global_load_dwordx4 v[24:27], v[24:25], off
	v_lshlrev_b64 v[28:29], 12, v[96:97]
	v_lshl_add_u64 v[28:29], v[30:31], 0, v[28:29]
	global_load_dwordx4 v[28:31], v[28:29], off
	v_add_u32_e32 v38, v35, v37
	s_lshl_b64 s[8:9], s[96:97], 1
	s_add_u32 s8, s14, s8
	s_addc_u32 s9, s15, s9
	v_lshlrev_b32_e32 v96, 1, v36
	v_readlane_b32 s53, v248, 55
	v_readlane_b32 s54, v248, 56
	v_readlane_b32 s55, v248, 57
	v_readlane_b32 s56, v248, 58
	v_readlane_b32 s57, v248, 59
	v_readlane_b32 s58, v248, 60
	v_readlane_b32 s59, v248, 61
	v_readlane_b32 s60, v248, 62
	v_readlane_b32 s61, v248, 63
	v_readlane_b32 s64, v247, 2
	v_readlane_b32 s65, v247, 3
	v_readlane_b32 s66, v247, 4
	v_readlane_b32 s67, v247, 5
	s_waitcnt vmcnt(0)
	ds_write2_b32 v38, v0, v1 offset1:1
	ds_write2_b32 v38, v2, v3 offset0:2 offset1:3
	v_add_u32_e32 v0, 0x410, v38
	ds_write2_b32 v0, v4, v5 offset1:1
	v_add_u32_e32 v0, 0x418, v38
	ds_write2_b32 v0, v6, v7 offset1:1
	v_add_u32_e32 v0, 0x820, v38
	ds_write2_b32 v0, v8, v9 offset1:1
	v_add_u32_e32 v0, 0x828, v38
	ds_write2_b32 v0, v10, v11 offset1:1
	v_add_u32_e32 v0, 0xc30, v38
	ds_write2_b32 v0, v12, v13 offset1:1
	v_add_u32_e32 v0, 0xc38, v38
	ds_write2_b32 v0, v14, v15 offset1:1
	v_add_u32_e32 v0, 0x1040, v38
	ds_write2_b32 v0, v16, v17 offset1:1
	v_add_u32_e32 v0, 0x1048, v38
	ds_write2_b32 v0, v18, v19 offset1:1
	v_add_u32_e32 v0, 0x1450, v38
	ds_write2_b32 v0, v20, v21 offset1:1
	v_add_u32_e32 v0, 0x1458, v38
	ds_write2_b32 v0, v22, v23 offset1:1
	v_add_u32_e32 v0, 0x1860, v38
	ds_write2_b32 v0, v24, v25 offset1:1
	v_add_u32_e32 v0, 0x1868, v38
	ds_write2_b32 v0, v26, v27 offset1:1
	v_add_u32_e32 v0, 0x1c70, v38
	ds_write2_b32 v0, v28, v29 offset1:1
	v_add_u32_e32 v0, 0x1c78, v38
	ds_write2_b32 v0, v30, v31 offset1:1
	s_waitcnt lgkmcnt(0)
	v_lshl_add_u64 v[0:1], s[8:9], 0, v[96:97]
	s_mov_b64 s[8:9], 0x1580000
	v_lshl_add_u64 v[4:5], v[0:1], 0, s[8:9]
	ds_read2_b32 v[0:1], v43 offset1:65
	s_waitcnt lgkmcnt(0)
	v_cvt_pk_bf16_f32 v0, v0, v1
	ds_read2_b32 v[2:3], v43 offset0:130 offset1:195
	v_add_u32_e32 v8, 0x400, v43
	s_waitcnt lgkmcnt(0)
	v_cvt_pk_bf16_f32 v1, v2, v3
	ds_read2_b32 v[2:3], v8 offset0:4 offset1:69
	s_waitcnt lgkmcnt(0)
	v_cvt_pk_bf16_f32 v2, v2, v3
	ds_read2_b32 v[6:7], v8 offset0:134 offset1:199
	s_waitcnt lgkmcnt(0)
	v_cvt_pk_bf16_f32 v3, v6, v7
	v_or_b32_e32 v6, s0, v39
	v_mul_u32_u24_e32 v6, 0xb00, v6
	v_lshlrev_b32_e32 v96, 1, v6
	v_lshl_add_u64 v[6:7], v[4:5], 0, v[96:97]
	global_store_dwordx4 v[6:7], v[0:3], off nt
	ds_read2_b32 v[0:1], v43 offset0:16 offset1:81
	s_waitcnt lgkmcnt(0)
	v_cvt_pk_bf16_f32 v0, v0, v1
	ds_read2_b32 v[2:3], v43 offset0:146 offset1:211
	s_waitcnt lgkmcnt(0)
	v_cvt_pk_bf16_f32 v1, v2, v3
	ds_read2_b32 v[2:3], v8 offset0:20 offset1:85
	s_waitcnt lgkmcnt(0)
	v_cvt_pk_bf16_f32 v2, v2, v3
	ds_read2_b32 v[6:7], v8 offset0:150 offset1:215
	s_waitcnt lgkmcnt(0)
	v_cvt_pk_bf16_f32 v3, v6, v7
	v_or_b32_e32 v6, s0, v44
	v_mul_u32_u24_e32 v6, 0xb00, v6
	v_lshlrev_b32_e32 v96, 1, v6
	v_lshl_add_u64 v[6:7], v[4:5], 0, v[96:97]
	global_store_dwordx4 v[6:7], v[0:3], off nt
	ds_read2_b32 v[0:1], v43 offset0:32 offset1:97
	s_waitcnt lgkmcnt(0)
	v_cvt_pk_bf16_f32 v0, v0, v1
	ds_read2_b32 v[2:3], v43 offset0:162 offset1:227
	s_waitcnt lgkmcnt(0)
	v_cvt_pk_bf16_f32 v1, v2, v3
	ds_read2_b32 v[2:3], v8 offset0:36 offset1:101
	s_waitcnt lgkmcnt(0)
	v_cvt_pk_bf16_f32 v2, v2, v3
	ds_read2_b32 v[6:7], v8 offset0:166 offset1:231
	s_waitcnt lgkmcnt(0)
	v_cvt_pk_bf16_f32 v3, v6, v7
	v_or_b32_e32 v6, s0, v45
	v_mul_u32_u24_e32 v6, 0xb00, v6
	v_lshlrev_b32_e32 v96, 1, v6
	v_lshl_add_u64 v[6:7], v[4:5], 0, v[96:97]
	global_store_dwordx4 v[6:7], v[0:3], off nt
	ds_read2_b32 v[0:1], v43 offset0:48 offset1:113
	s_waitcnt lgkmcnt(0)
	v_cvt_pk_bf16_f32 v0, v0, v1
	ds_read2_b32 v[2:3], v43 offset0:178 offset1:243
	s_waitcnt lgkmcnt(0)
	v_cvt_pk_bf16_f32 v1, v2, v3
	ds_read2_b32 v[2:3], v8 offset0:52 offset1:117
	s_waitcnt lgkmcnt(0)
	v_cvt_pk_bf16_f32 v2, v2, v3
	ds_read2_b32 v[6:7], v8 offset0:182 offset1:247
	s_waitcnt lgkmcnt(0)
	v_cvt_pk_bf16_f32 v3, v6, v7
	v_or_b32_e32 v6, s0, v46
	v_mul_u32_u24_e32 v6, 0xb00, v6
	v_lshlrev_b32_e32 v96, 1, v6
	v_lshl_add_u64 v[4:5], v[4:5], 0, v[96:97]
	global_store_dwordx4 v[4:5], v[0:3], off nt
	s_waitcnt lgkmcnt(0)
	s_mov_b64 s[0:1], 0

; #define LAS __attribute__((address_space(3)))
; __device__ __forceinline__ unsigned cvt_pk_bf16(float lo, float hi) { unsigned r; asm volatile("v_cvt_pk_bf16_f32 %0, %1, %2" : "=v"(r) : "v"(lo), "v"(hi)); return r; }
; __device__ __forceinline__ void transpose_item(const float* W, int N, const float* ks, bf16_t* WT, int ldo, int orow0, int k0, int n0, LAS float* scr, int lane) {
;     f32x4 v[8];
; #pragma unroll
;     for (int i = 0; i < 8; ++i) v[i] = *(const f32x4*)(W + (size_t)(k0 + i * 4 + (lane >> 4)) * N + n0 + 4 * (lane & 15));
; #pragma unroll
;     for (int i = 0; i < 8; ++i) { const int kk = i * 4 + (lane >> 4); const float sc = ks ? ks[k0 + kk] : 1.0f; LAS float* d = scr + kk * 65 + 4 * (lane & 15);
;         d[0] = v[i][0] * sc; d[1] = v[i][1] * sc; d[2] = v[i][2] * sc; d[3] = v[i][3] * sc; }
;     asm volatile("s_waitcnt lgkmcnt(0)" ::: "memory");
;     const int kc = lane & 3;
; #pragma unroll
;     for (int j = 0; j < 4; ++j) { const int n = (lane >> 2) + 16 * j; const LAS float* s = scr + (8 * kc) * 65 + n;
;         u32x4 o; o.x = cvt_pk_bf16(s[0 * 65], s[1 * 65]); o.y = cvt_pk_bf16(s[2 * 65], s[3 * 65]); o.z = cvt_pk_bf16(s[4 * 65], s[5 * 65]); o.w = cvt_pk_bf16(s[6 * 65], s[7 * 65]);
;         *(u32x4*)(WT + (size_t)(orow0 + n) * ldo + k0 + 8 * kc) = o; }
;     asm volatile("s_waitcnt lgkmcnt(0)" ::: "memory");
; }
; __device__ __forceinline__ void convert_weights(const Params& p, LAS unsigned char* lds, int first, int last, int worker, int nworkers) {
;     ...
;     for (int it = first + worker; it < last; it += nworkers) {
;         const int l = it / WI_L; int r = it % WI_L;
;         unsigned char* wb = p.ws + WS_W + (size_t)l * W_LAYER;
;         if (r < WI_IN) { const int kb = r / 52, nb = r % 52; transpose_item(p.w_in + (size_t)l * DM * INW, INW, p.norm_mix + l * DM, (bf16_t*)(wb + WO_IN), DM, nb * 64, kb * 32, nb * 64, scr, lane); continue; } r -= WI_IN;
;         if (r < WI_BA) { const int kb = r / 16, nb = r % 16; transpose_item(p.w_br_attn + (size_t)l * 512 * DM, DM, nullptr, (bf16_t*)(wb + WO_MIX), 512, nb * 64, kb * 32, nb * 64, scr, lane); continue; } r -= WI_BA;
;         if (r < WI_OUT) { const int kb = r / 16, nb = r % 16; transpose_item(p.w_out + (size_t)l * DM * DM, DM, nullptr, (bf16_t*)(wb + WO_OUT), DM, nb * 64, kb * 32, nb * 64, scr, lane); continue; } r -= WI_OUT;
.LBB0_637:
	s_andn2_b64 vcc, exec, s[0:1]
	s_cbranch_vccnz .LBB0_639
	s_lshl_b64 s[0:1], s[2:3], 22
	v_readlane_b32 s52, v248, 54
	v_readlane_b32 s53, v248, 55
	s_add_u32 s8, s52, s0
	s_mul_i32 s9, s2, 0xffffcc00
	s_addc_u32 s1, s53, s1
	s_add_i32 s9, s10, s9
	s_and_b32 s0, s12, 0x3c0
	s_and_b32 s9, s9, 0x1fe0
	s_add_i32 s96, s9, 0xfffff100
	s_lshl_b32 s9, s0, 2
	s_add_u32 s8, s8, s9
	v_or_b32_e32 v28, s96, v32
	s_addc_u32 s9, s1, 0
	v_lshlrev_b32_e32 v96, 2, v34
	v_mov_b32_e32 v29, v97
	v_lshl_add_u64 v[30:31], s[8:9], 0, v[96:97]
	v_lshlrev_b64 v[0:1], 12, v[28:29]
	v_or_b32_e32 v96, 4, v28
	v_lshl_add_u64 v[0:1], v[30:31], 0, v[0:1]
	v_lshlrev_b64 v[4:5], 12, v[96:97]
	global_load_dwordx4 v[0:3], v[0:1], off
	v_lshl_add_u64 v[4:5], v[30:31], 0, v[4:5]
	v_or_b32_e32 v96, 8, v28
	global_load_dwordx4 v[4:7], v[4:5], off
	v_lshlrev_b64 v[8:9], 12, v[96:97]
	v_lshl_add_u64 v[8:9], v[30:31], 0, v[8:9]
	v_or_b32_e32 v96, 12, v28
	global_load_dwordx4 v[8:11], v[8:9], off
	v_lshlrev_b64 v[12:13], 12, v[96:97]
	v_lshl_add_u64 v[12:13], v[30:31], 0, v[12:13]
	v_or_b32_e32 v96, 16, v28
	global_load_dwordx4 v[12:15], v[12:13], off
	v_lshlrev_b64 v[16:17], 12, v[96:97]
	v_lshl_add_u64 v[16:17], v[30:31], 0, v[16:17]
	v_or_b32_e32 v96, 20, v28
	global_load_dwordx4 v[16:19], v[16:17], off
	v_lshlrev_b64 v[20:21], 12, v[96:97]
	v_lshl_add_u64 v[20:21], v[30:31], 0, v[20:21]
	v_or_b32_e32 v96, 24, v28
	global_load_dwordx4 v[20:23], v[20:21], off
	v_lshlrev_b64 v[24:25], 12, v[96:97]
	v_lshl_add_u64 v[24:25], v[30:31], 0, v[24:25]
	v_or_b32_e32 v96, 28, v28
	global_load_dwordx4 v[24:27], v[24:25], off
	v_lshlrev_b64 v[28:29], 12, v[96:97]
	v_lshl_add_u64 v[28:29], v[30:31], 0, v[28:29]
	global_load_dwordx4 v[28:31], v[28:29], off
	v_add_u32_e32 v38, v35, v37
	s_lshl_b64 s[8:9], s[96:97], 1
	s_add_u32 s8, s14, s8
	s_addc_u32 s9, s15, s9
	v_lshlrev_b32_e32 v96, 1, v36
	v_readlane_b32 s54, v248, 56
	v_readlane_b32 s55, v248, 57
	v_readlane_b32 s56, v248, 58
	v_readlane_b32 s57, v248, 59
	v_readlane_b32 s58, v248, 60
	v_readlane_b32 s59, v248, 61
	v_readlane_b32 s60, v248, 62
	v_readlane_b32 s61, v248, 63
	v_readlane_b32 s62, v247, 0
	v_readlane_b32 s63, v247, 1
	v_readlane_b32 s64, v247, 2
	v_readlane_b32 s65, v247, 3
	v_readlane_b32 s66, v247, 4
	v_readlane_b32 s67, v247, 5
	s_waitcnt vmcnt(0)
	ds_write2_b32 v38, v0, v1 offset1:1
	ds_write2_b32 v38, v2, v3 offset0:2 offset1:3
	v_add_u32_e32 v0, 0x410, v38
	ds_write2_b32 v0, v4, v5 offset1:1
	v_add_u32_e32 v0, 0x418, v38
	ds_write2_b32 v0, v6, v7 offset1:1
	v_add_u32_e32 v0, 0x820, v38
	ds_write2_b32 v0, v8, v9 offset1:1
	v_add_u32_e32 v0, 0x828, v38
	ds_write2_b32 v0, v10, v11 offset1:1
	v_add_u32_e32 v0, 0xc30, v38
	ds_write2_b32 v0, v12, v13 offset1:1
	v_add_u32_e32 v0, 0xc38, v38
	ds_write2_b32 v0, v14, v15 offset1:1
	v_add_u32_e32 v0, 0x1040, v38
	ds_write2_b32 v0, v16, v17 offset1:1
	v_add_u32_e32 v0, 0x1048, v38
	ds_write2_b32 v0, v18, v19 offset1:1
	v_add_u32_e32 v0, 0x1450, v38
	ds_write2_b32 v0, v20, v21 offset1:1
	v_add_u32_e32 v0, 0x1458, v38
	ds_write2_b32 v0, v22, v23 offset1:1
	v_add_u32_e32 v0, 0x1860, v38
	ds_write2_b32 v0, v24, v25 offset1:1
	v_add_u32_e32 v0, 0x1868, v38
	ds_write2_b32 v0, v26, v27 offset1:1
	v_add_u32_e32 v0, 0x1c70, v38
	ds_write2_b32 v0, v28, v29 offset1:1
	v_add_u32_e32 v0, 0x1c78, v38
	ds_write2_b32 v0, v30, v31 offset1:1
	s_waitcnt lgkmcnt(0)
	v_lshl_add_u64 v[0:1], s[8:9], 0, v[96:97]
	s_mov_b64 s[8:9], 0x880000
	v_lshl_add_u64 v[4:5], v[0:1], 0, s[8:9]
	ds_read2_b32 v[0:1], v43 offset1:65
	s_waitcnt lgkmcnt(0)
	v_cvt_pk_bf16_f32 v0, v0, v1
	ds_read2_b32 v[2:3], v43 offset0:130 offset1:195
	v_add_u32_e32 v8, 0x400, v43
	s_waitcnt lgkmcnt(0)
	v_cvt_pk_bf16_f32 v1, v2, v3
	ds_read2_b32 v[2:3], v8 offset0:4 offset1:69
	s_waitcnt lgkmcnt(0)
	v_cvt_pk_bf16_f32 v2, v2, v3
	ds_read2_b32 v[6:7], v8 offset0:134 offset1:199
	s_waitcnt lgkmcnt(0)
	v_cvt_pk_bf16_f32 v3, v6, v7
	v_or_b32_e32 v6, s0, v39
	v_lshlrev_b32_e32 v96, 11, v6
	v_lshl_add_u64 v[6:7], v[4:5], 0, v[96:97]
	global_store_dwordx4 v[6:7], v[0:3], off nt
	ds_read2_b32 v[0:1], v43 offset0:16 offset1:81
	s_waitcnt lgkmcnt(0)
	v_cvt_pk_bf16_f32 v0, v0, v1
	ds_read2_b32 v[2:3], v43 offset0:146 offset1:211
	s_waitcnt lgkmcnt(0)
	v_cvt_pk_bf16_f32 v1, v2, v3
	ds_read2_b32 v[2:3], v8 offset0:20 offset1:85
	s_waitcnt lgkmcnt(0)
	v_cvt_pk_bf16_f32 v2, v2, v3
	ds_read2_b32 v[6:7], v8 offset0:150 offset1:215
	s_waitcnt lgkmcnt(0)
	v_cvt_pk_bf16_f32 v3, v6, v7
	v_or_b32_e32 v6, s0, v44
	v_lshlrev_b32_e32 v96, 11, v6
	v_lshl_add_u64 v[6:7], v[4:5], 0, v[96:97]
	global_store_dwordx4 v[6:7], v[0:3], off nt
	ds_read2_b32 v[0:1], v43 offset0:32 offset1:97
	s_waitcnt lgkmcnt(0)
	v_cvt_pk_bf16_f32 v0, v0, v1
	ds_read2_b32 v[2:3], v43 offset0:162 offset1:227
	s_waitcnt lgkmcnt(0)
	v_cvt_pk_bf16_f32 v1, v2, v3
	ds_read2_b32 v[2:3], v8 offset0:36 offset1:101
	s_waitcnt lgkmcnt(0)
	v_cvt_pk_bf16_f32 v2, v2, v3
	ds_read2_b32 v[6:7], v8 offset0:166 offset1:231
	s_waitcnt lgkmcnt(0)
	v_cvt_pk_bf16_f32 v3, v6, v7
	v_or_b32_e32 v6, s0, v45
	v_lshlrev_b32_e32 v96, 11, v6
	v_lshl_add_u64 v[6:7], v[4:5], 0, v[96:97]
	global_store_dwordx4 v[6:7], v[0:3], off nt
	ds_read2_b32 v[0:1], v43 offset0:48 offset1:113
	s_waitcnt lgkmcnt(0)
	v_cvt_pk_bf16_f32 v0, v0, v1
	ds_read2_b32 v[2:3], v43 offset0:178 offset1:243
	s_waitcnt lgkmcnt(0)
	v_cvt_pk_bf16_f32 v1, v2, v3
	ds_read2_b32 v[2:3], v8 offset0:52 offset1:117
	s_waitcnt lgkmcnt(0)
	v_cvt_pk_bf16_f32 v2, v2, v3
	ds_read2_b32 v[6:7], v8 offset0:182 offset1:247
	s_waitcnt lgkmcnt(0)
	v_cvt_pk_bf16_f32 v3, v6, v7
	v_or_b32_e32 v6, s0, v46
	v_lshlrev_b32_e32 v96, 11, v6
	v_lshl_add_u64 v[4:5], v[4:5], 0, v[96:97]
	global_store_dwordx4 v[4:5], v[0:3], off nt
	s_waitcnt lgkmcnt(0)

; #define LAS __attribute__((address_space(3)))
; __device__ __forceinline__ unsigned cvt_pk_bf16(float lo, float hi) { unsigned r; asm volatile("v_cvt_pk_bf16_f32 %0, %1, %2" : "=v"(r) : "v"(lo), "v"(hi)); return r; }
; __device__ __forceinline__ void transpose_item(const float* W, int N, const float* ks, bf16_t* WT, int ldo, int orow0, int k0, int n0, LAS float* scr, int lane) {
;     f32x4 v[8];
; #pragma unroll
;     for (int i = 0; i < 8; ++i) v[i] = *(const f32x4*)(W + (size_t)(k0 + i * 4 + (lane >> 4)) * N + n0 + 4 * (lane & 15));
; #pragma unroll
;     for (int i = 0; i < 8; ++i) { const int kk = i * 4 + (lane >> 4); const float sc = ks ? ks[k0 + kk] : 1.0f; LAS float* d = scr + kk * 65 + 4 * (lane & 15);
;         d[0] = v[i][0] * sc; d[1] = v[i][1] * sc; d[2] = v[i][2] * sc; d[3] = v[i][3] * sc; }
;     asm volatile("s_waitcnt lgkmcnt(0)" ::: "memory");
;     const int kc = lane & 3;
; #pragma unroll
;     for (int j = 0; j < 4; ++j) { const int n = (lane >> 2) + 16 * j; const LAS float* s = scr + (8 * kc) * 65 + n;
;         u32x4 o; o.x = cvt_pk_bf16(s[0 * 65], s[1 * 65]); o.y = cvt_pk_bf16(s[2 * 65], s[3 * 65]); o.z = cvt_pk_bf16(s[4 * 65], s[5 * 65]); o.w = cvt_pk_bf16(s[6 * 65], s[7 * 65]);
;         *(u32x4*)(WT + (size_t)(orow0 + n) * ldo + k0 + 8 * kc) = o; }
;     asm volatile("s_waitcnt lgkmcnt(0)" ::: "memory");
; }
; __device__ __forceinline__ void convert_weights(const Params& p, LAS unsigned char* lds, int first, int last, int worker, int nworkers) {
;     ...
;     for (int it = first + worker; it < last; it += nworkers) {
;         const int l = it / WI_L; int r = it % WI_L;
;         unsigned char* wb = p.ws + WS_W + (size_t)l * W_LAYER;
;         if (r < WI_IN) { const int kb = r / 52, nb = r % 52; transpose_item(p.w_in + (size_t)l * DM * INW, INW, p.norm_mix + l * DM, (bf16_t*)(wb + WO_IN), DM, nb * 64, kb * 32, nb * 64, scr, lane); continue; } r -= WI_IN;
;         if (r < WI_BA) { const int kb = r / 16, nb = r % 16; transpose_item(p.w_br_attn + (size_t)l * 512 * DM, DM, nullptr, (bf16_t*)(wb + WO_MIX), 512, nb * 64, kb * 32, nb * 64, scr, lane); continue; } r -= WI_BA;
.LBB0_640:
	s_andn2_b64 vcc, exec, s[0:1]
	s_cbranch_vccnz .LBB0_642
	v_readlane_b32 s52, v249, 20
	v_readlane_b32 s62, v249, 30
	v_readlane_b32 s63, v249, 31
	s_lshl_b64 s[0:1], s[2:3], 21
	s_mov_b64 s[50:51], s[62:63]
	s_add_u32 s3, s50, s0
	s_addc_u32 s1, s51, s1
	s_lshl_b32 s8, s2, 10
	s_sub_i32 s8, s10, s8
	s_and_b32 s0, s12, 0x3c0
	s_and_b32 s8, s8, 0xfe0
	s_add_i32 s96, s8, 0xfffff300
	s_lshl_b32 s8, s0, 2
	s_add_u32 s8, s3, s8
	v_or_b32_e32 v28, s96, v32
	s_addc_u32 s9, s1, 0
	v_lshlrev_b32_e32 v96, 2, v34
	v_mov_b32_e32 v29, v97
	v_lshl_add_u64 v[30:31], s[8:9], 0, v[96:97]
	v_lshlrev_b64 v[0:1], 12, v[28:29]
	v_or_b32_e32 v96, 4, v28
	v_lshl_add_u64 v[0:1], v[30:31], 0, v[0:1]
	v_lshlrev_b64 v[4:5], 12, v[96:97]
	global_load_dwordx4 v[0:3], v[0:1], off
	v_lshl_add_u64 v[4:5], v[30:31], 0, v[4:5]
	v_or_b32_e32 v96, 8, v28
	global_load_dwordx4 v[4:7], v[4:5], off
	v_lshlrev_b64 v[8:9], 12, v[96:97]
	v_lshl_add_u64 v[8:9], v[30:31], 0, v[8:9]
	v_or_b32_e32 v96, 12, v28
	global_load_dwordx4 v[8:11], v[8:9], off
	v_lshlrev_b64 v[12:13], 12, v[96:97]
	v_lshl_add_u64 v[12:13], v[30:31], 0, v[12:13]
	v_or_b32_e32 v96, 16, v28
	global_load_dwordx4 v[12:15], v[12:13], off
	v_lshlrev_b64 v[16:17], 12, v[96:97]
	v_lshl_add_u64 v[16:17], v[30:31], 0, v[16:17]
	v_or_b32_e32 v96, 20, v28
	global_load_dwordx4 v[16:19], v[16:17], off
	v_lshlrev_b64 v[20:21], 12, v[96:97]
	v_lshl_add_u64 v[20:21], v[30:31], 0, v[20:21]
	v_or_b32_e32 v96, 24, v28
	global_load_dwordx4 v[20:23], v[20:21], off
	v_lshlrev_b64 v[24:25], 12, v[96:97]
	v_lshl_add_u64 v[24:25], v[30:31], 0, v[24:25]
	v_or_b32_e32 v96, 28, v28
	global_load_dwordx4 v[24:27], v[24:25], off
	v_lshlrev_b64 v[28:29], 12, v[96:97]
	v_lshl_add_u64 v[28:29], v[30:31], 0, v[28:29]
	global_load_dwordx4 v[28:31], v[28:29], off
	v_add_u32_e32 v38, v35, v37
	s_lshl_b64 s[8:9], s[96:97], 1
	s_add_u32 s8, s14, s8
	s_addc_u32 s9, s15, s9
	v_lshlrev_b32_e32 v96, 1, v36
	v_readlane_b32 s53, v249, 21
	v_readlane_b32 s54, v249, 22
	v_readlane_b32 s55, v249, 23
	v_readlane_b32 s56, v249, 24
	v_readlane_b32 s57, v249, 25
	v_readlane_b32 s58, v249, 26
	v_readlane_b32 s59, v249, 27
	v_readlane_b32 s60, v249, 28
	v_readlane_b32 s61, v249, 29
	v_readlane_b32 s64, v249, 32
	v_readlane_b32 s65, v249, 33
	v_readlane_b32 s66, v249, 34
	v_readlane_b32 s67, v249, 35
	s_waitcnt vmcnt(0)
	ds_write2_b32 v38, v0, v1 offset1:1
	ds_write2_b32 v38, v2, v3 offset0:2 offset1:3
	v_add_u32_e32 v0, 0x410, v38
	ds_write2_b32 v0, v4, v5 offset1:1
	v_add_u32_e32 v0, 0x418, v38
	ds_write2_b32 v0, v6, v7 offset1:1
	v_add_u32_e32 v0, 0x820, v38
	ds_write2_b32 v0, v8, v9 offset1:1
	v_add_u32_e32 v0, 0x828, v38
	ds_write2_b32 v0, v10, v11 offset1:1
	v_add_u32_e32 v0, 0xc30, v38
	ds_write2_b32 v0, v12, v13 offset1:1
	v_add_u32_e32 v0, 0xc38, v38
	ds_write2_b32 v0, v14, v15 offset1:1
	v_add_u32_e32 v0, 0x1040, v38
	ds_write2_b32 v0, v16, v17 offset1:1
	v_add_u32_e32 v0, 0x1048, v38
	ds_write2_b32 v0, v18, v19 offset1:1
	v_add_u32_e32 v0, 0x1450, v38
	ds_write2_b32 v0, v20, v21 offset1:1
	v_add_u32_e32 v0, 0x1458, v38
	ds_write2_b32 v0, v22, v23 offset1:1
	v_add_u32_e32 v0, 0x1860, v38
	ds_write2_b32 v0, v24, v25 offset1:1
	v_add_u32_e32 v0, 0x1868, v38
	ds_write2_b32 v0, v26, v27 offset1:1
	v_add_u32_e32 v0, 0x1c70, v38
	ds_write2_b32 v0, v28, v29 offset1:1
	v_add_u32_e32 v0, 0x1c78, v38
	ds_write2_b32 v0, v30, v31 offset1:1
	s_waitcnt lgkmcnt(0)
	v_lshl_add_u64 v[0:1], s[8:9], 0, v[96:97]
	s_mov_b64 s[8:9], 0x680000
	v_lshl_add_u64 v[4:5], v[0:1], 0, s[8:9]
	ds_read2_b32 v[0:1], v43 offset1:65
	s_waitcnt lgkmcnt(0)
	v_cvt_pk_bf16_f32 v0, v0, v1
	ds_read2_b32 v[2:3], v43 offset0:130 offset1:195
	v_add_u32_e32 v8, 0x400, v43
	s_waitcnt lgkmcnt(0)
	v_cvt_pk_bf16_f32 v1, v2, v3
	ds_read2_b32 v[2:3], v8 offset0:4 offset1:69
	s_waitcnt lgkmcnt(0)
	v_cvt_pk_bf16_f32 v2, v2, v3
	ds_read2_b32 v[6:7], v8 offset0:134 offset1:199
	s_waitcnt lgkmcnt(0)
	v_cvt_pk_bf16_f32 v3, v6, v7
	v_or_b32_e32 v6, s0, v39
	v_lshlrev_b32_e32 v96, 10, v6
	v_lshl_add_u64 v[6:7], v[4:5], 0, v[96:97]
	global_store_dwordx4 v[6:7], v[0:3], off nt
	ds_read2_b32 v[0:1], v43 offset0:16 offset1:81
	s_waitcnt lgkmcnt(0)
	v_cvt_pk_bf16_f32 v0, v0, v1
	ds_read2_b32 v[2:3], v43 offset0:146 offset1:211
	s_waitcnt lgkmcnt(0)
	v_cvt_pk_bf16_f32 v1, v2, v3
	ds_read2_b32 v[2:3], v8 offset0:20 offset1:85
	s_waitcnt lgkmcnt(0)
	v_cvt_pk_bf16_f32 v2, v2, v3
	ds_read2_b32 v[6:7], v8 offset0:150 offset1:215
	s_waitcnt lgkmcnt(0)
	v_cvt_pk_bf16_f32 v3, v6, v7
	v_or_b32_e32 v6, s0, v44
	v_lshlrev_b32_e32 v96, 10, v6
	v_lshl_add_u64 v[6:7], v[4:5], 0, v[96:97]
	global_store_dwordx4 v[6:7], v[0:3], off nt
	ds_read2_b32 v[0:1], v43 offset0:32 offset1:97
	s_waitcnt lgkmcnt(0)
	v_cvt_pk_bf16_f32 v0, v0, v1
	ds_read2_b32 v[2:3], v43 offset0:162 offset1:227
	s_waitcnt lgkmcnt(0)
	v_cvt_pk_bf16_f32 v1, v2, v3
	ds_read2_b32 v[2:3], v8 offset0:36 offset1:101
	s_waitcnt lgkmcnt(0)
	v_cvt_pk_bf16_f32 v2, v2, v3
	ds_read2_b32 v[6:7], v8 offset0:166 offset1:231
	s_waitcnt lgkmcnt(0)
	v_cvt_pk_bf16_f32 v3, v6, v7
	v_or_b32_e32 v6, s0, v45
	v_lshlrev_b32_e32 v96, 10, v6
	v_lshl_add_u64 v[6:7], v[4:5], 0, v[96:97]
	global_store_dwordx4 v[6:7], v[0:3], off nt
	ds_read2_b32 v[0:1], v43 offset0:48 offset1:113
	s_waitcnt lgkmcnt(0)
	v_cvt_pk_bf16_f32 v0, v0, v1
	ds_read2_b32 v[2:3], v43 offset0:178 offset1:243
	s_waitcnt lgkmcnt(0)
	v_cvt_pk_bf16_f32 v1, v2, v3
	ds_read2_b32 v[2:3], v8 offset0:52 offset1:117
	s_waitcnt lgkmcnt(0)
	v_cvt_pk_bf16_f32 v2, v2, v3
	ds_read2_b32 v[6:7], v8 offset0:182 offset1:247
	s_waitcnt lgkmcnt(0)
	v_cvt_pk_bf16_f32 v3, v6, v7
	v_or_b32_e32 v6, s0, v46
	v_lshlrev_b32_e32 v96, 10, v6
	v_lshl_add_u64 v[4:5], v[4:5], 0, v[96:97]
	global_store_dwordx4 v[4:5], v[0:3], off nt
	s_waitcnt lgkmcnt(0)

; __device__ __forceinline__ void unpack8(const u32x4 w, float* f) { f[0] = bf_lo(w.x); f[1] = bf_hi(w.x); f[2] = bf_lo(w.y); f[3] = bf_hi(w.y); f[4] = bf_lo(w.z); f[5] = bf_hi(w.z); f[6] = bf_lo(w.w); f[7] = bf_hi(w.w); }
; __device__ __forceinline__ u32x4 pack8(const float* f) { u32x4 w; w.x = cvt_pk_bf16(f[0], f[1]); w.y = cvt_pk_bf16(f[2], f[3]); w.z = cvt_pk_bf16(f[4], f[5]); w.w = cvt_pk_bf16(f[6], f[7]); return w; }
;     __device__ __forceinline__ void operator()(AccT& acc, const Unit& u, int wr, int wc, int fr, int fq) const {
;     ...
; #pragma unroll
;         for (int ai = 0; ai < 2; ++ai)
; #pragma unroll
;             for (int m = 0; m < 4; ++m)
; #pragma unroll
;                 for (int bj = 0; bj < 2; ++bj) gw[ai][m][bj] = __builtin_nontemporal_load((const u32x4*)(Pb + (unsigned)(((u.pm * 256 + ai * 128 + wr * 64 + m * 16 + fr) * INW + col0 + bj * 128 + 2304) * 2)));
; #pragma unroll
;         for (int ai = 0; ai < 2; ++ai)
; #pragma unroll
;             for (int m = 0; m < 4; ++m)
; #pragma unroll
;                 for (int bj = 0; bj < 2; ++bj) {
;                     const int row = u.pm * 256 + ai * 128 + wr * 64 + m * 16 + fr, col = col0 + bj * 128;
;                     float g1[8]; unpack8(gw[ai][m][bj], g1);
;                     if (u.z == 0) {
; #pragma unroll
;                         for (int n = 0; n < 2; ++n)
; #pragma unroll
;                             for (int j = 0; j < 4; ++j) acc[ai][bj][m][n][j] *= __builtin_amdgcn_rcpf(__builtin_fmaxf(g1[n * 4 + j], 1.0e-30f));
;                     } else {
;                         float v[8];
; #pragma unroll
;                         for (int n = 0; n < 2; ++n)
; #pragma unroll
;                             for (int j = 0; j < 4; ++j) v[n * 4 + j] = acc[ai][bj][m][n][j] * g1[n * 4 + j];
;                         *(u32x4*)((char*)MIX + (unsigned)((row * DM + col) * 2)) = pack8(v);
.LBB0_735:
	v_add_u32_e32 v96, 0x1200, v234
	v_lshl_add_u64 v[132:133], s[84:85], 0, v[96:97]
	v_add_u32_e32 v96, 0x1300, v234
	v_lshl_add_u64 v[134:135], s[84:85], 0, v[96:97]
	v_add_u32_e32 v96, 0x1200, v233
	global_load_dwordx4 v[236:239], v[132:133], off nt
	global_load_dwordx4 v[188:191], v[134:135], off nt
	v_lshl_add_u64 v[132:133], s[84:85], 0, v[96:97]
	v_add_u32_e32 v96, 0x1300, v233
	v_lshl_add_u64 v[134:135], s[84:85], 0, v[96:97]
	v_add_u32_e32 v96, 0x1200, v232
	global_load_dwordx4 v[184:187], v[132:133], off nt
	global_load_dwordx4 v[180:183], v[134:135], off nt
	v_lshl_add_u64 v[132:133], s[84:85], 0, v[96:97]
	v_add_u32_e32 v96, 0x1300, v232
	v_lshl_add_u64 v[134:135], s[84:85], 0, v[96:97]
	v_add_u32_e32 v96, 0x1200, v231
	global_load_dwordx4 v[176:179], v[132:133], off nt
	global_load_dwordx4 v[172:175], v[134:135], off nt
	v_lshl_add_u64 v[132:133], s[84:85], 0, v[96:97]
	v_add_u32_e32 v96, 0x1300, v231
	v_lshl_add_u64 v[134:135], s[84:85], 0, v[96:97]
	v_add_u32_e32 v96, 0x1200, v230
	global_load_dwordx4 v[168:171], v[132:133], off nt
	global_load_dwordx4 v[164:167], v[134:135], off nt
	v_lshl_add_u64 v[132:133], s[84:85], 0, v[96:97]
	v_add_u32_e32 v96, 0x1300, v230
	v_lshl_add_u64 v[134:135], s[84:85], 0, v[96:97]
	v_add_u32_e32 v96, 0x1200, v229
	global_load_dwordx4 v[160:163], v[132:133], off nt
	global_load_dwordx4 v[156:159], v[134:135], off nt
	v_lshl_add_u64 v[132:133], s[84:85], 0, v[96:97]
	v_add_u32_e32 v96, 0x1300, v229
	v_lshl_add_u64 v[134:135], s[84:85], 0, v[96:97]
	v_add_u32_e32 v96, 0x1200, v221
	global_load_dwordx4 v[152:155], v[132:133], off nt
	global_load_dwordx4 v[148:151], v[134:135], off nt
	v_lshl_add_u64 v[132:133], s[84:85], 0, v[96:97]
	v_add_u32_e32 v96, 0x1300, v221
	v_lshl_add_u64 v[134:135], s[84:85], 0, v[96:97]
	v_add_u32_e32 v96, 0x1200, v220
	global_load_dwordx4 v[144:147], v[132:133], off nt
	global_load_dwordx4 v[140:143], v[134:135], off nt
	v_lshl_add_u64 v[132:133], s[84:85], 0, v[96:97]
	v_add_u32_e32 v96, 0x1300, v220
	v_lshl_add_u64 v[134:135], s[84:85], 0, v[96:97]
	global_load_dwordx4 v[136:139], v[132:133], off nt
	s_nop 0
	global_load_dwordx4 v[132:135], v[134:135], off nt
	v_cndmask_b32_e64 v96, 0, 1, s[16:17]
	v_lshlrev_b32_e32 v98, 1, v98
	v_cmp_ne_u32_e64 s[46:47], 1, v96
	s_andn2_b64 vcc, exec, s[16:17]
	v_lshlrev_b32_e32 v99, 11, v99
	s_waitcnt vmcnt(0) lgkmcnt(0)
	v_lshlrev_b32_e32 v234, 16, v236
	v_and_b32_e32 v233, 0xffff0000, v236
	v_lshlrev_b32_e32 v232, 16, v237
	v_and_b32_e32 v231, 0xffff0000, v237
	v_lshlrev_b32_e32 v230, 16, v238
	v_and_b32_e32 v229, 0xffff0000, v238
	v_lshlrev_b32_e32 v221, 16, v239
	v_and_b32_e32 v220, 0xffff0000, v239
	s_cbranch_vccnz .LBB0_788
	s_lshl_b32 s9, s71, 19
	v_mul_f32_e32 v96, v128, v234
	s_add_i32 s9, s9, s42
	v_mul_f32_e32 v235, v129, v233
	v_mul_f32_e32 v237, v130, v232
	v_mul_f32_e32 v238, v131, v231
	v_mul_f32_e32 v239, v124, v230
	v_mul_f32_e32 v240, v125, v229
	v_mul_f32_e32 v241, v126, v221
	v_cvt_pk_bf16_f32 v236, v96, v235
	v_add3_u32 v96, s9, v99, v98
	v_mul_f32_e32 v242, v127, v220
	v_cvt_pk_bf16_f32 v237, v237, v238
	v_cvt_pk_bf16_f32 v238, v239, v240
	v_cvt_pk_bf16_f32 v239, v241, v242
	v_lshl_add_u64 v[240:241], s[54:55], 0, v[96:97]
	global_store_dwordx4 v[240:241], v[236:239], off nt
	s_cbranch_execnz .LBB0_738

; __device__ __forceinline__ void unpack8(const u32x4 w, float* f) { f[0] = bf_lo(w.x); f[1] = bf_hi(w.x); f[2] = bf_lo(w.y); f[3] = bf_hi(w.y); f[4] = bf_lo(w.z); f[5] = bf_hi(w.z); f[6] = bf_lo(w.w); f[7] = bf_hi(w.w); }
; __device__ __forceinline__ u32x4 pack8(const float* f) { u32x4 w; w.x = cvt_pk_bf16(f[0], f[1]); w.y = cvt_pk_bf16(f[2], f[3]); w.z = cvt_pk_bf16(f[4], f[5]); w.w = cvt_pk_bf16(f[6], f[7]); return w; }
;     __device__ __forceinline__ void operator()(AccT& acc, const Unit& u, int wr, int wc, int fr, int fq) const {
;     ...
;                 for (int bj = 0; bj < 2; ++bj) {
;                     const int row = u.pm * 256 + ai * 128 + wr * 64 + m * 16 + fr, col = col0 + bj * 128;
;                     float g1[8]; unpack8(gw[ai][m][bj], g1);
;                     if (u.z == 0) {
; #pragma unroll
;                         for (int n = 0; n < 2; ++n)
; #pragma unroll
;                             for (int j = 0; j < 4; ++j) acc[ai][bj][m][n][j] *= __builtin_amdgcn_rcpf(__builtin_fmaxf(g1[n * 4 + j], 1.0e-30f));
;                     } else {
;                         float v[8];
; #pragma unroll
;                         for (int n = 0; n < 2; ++n)
; #pragma unroll
;                             for (int j = 0; j < 4; ++j) v[n * 4 + j] = acc[ai][bj][m][n][j] * g1[n * 4 + j];
;                         *(u32x4*)((char*)MIX + (unsigned)((row * DM + col) * 2)) = pack8(v);
.LBB0_738:
	v_lshlrev_b32_e32 v231, 16, v188
	v_and_b32_e32 v230, 0xffff0000, v188
	v_lshlrev_b32_e32 v229, 16, v189
	v_and_b32_e32 v221, 0xffff0000, v189
	v_lshlrev_b32_e32 v220, 16, v190
	v_and_b32_e32 v190, 0xffff0000, v190
	v_lshlrev_b32_e32 v188, 16, v191
	s_and_b64 vcc, exec, s[46:47]
	v_and_b32_e32 v189, 0xffff0000, v191
	s_cbranch_vccnz .LBB0_789
	s_lshl_b32 s9, s71, 19
	v_mul_f32_e32 v96, v92, v231
	s_add_i32 s9, s43, s9
	v_mul_f32_e32 v191, v93, v230
	v_mul_f32_e32 v233, v94, v229
	v_mul_f32_e32 v234, v95, v221
	v_mul_f32_e32 v235, v88, v220
	v_mul_f32_e32 v236, v89, v190
	v_mul_f32_e32 v237, v90, v188
	v_cvt_pk_bf16_f32 v232, v96, v191
	v_add3_u32 v96, s9, v99, v98
	v_mul_f32_e32 v238, v91, v189
	v_cvt_pk_bf16_f32 v233, v233, v234
	v_cvt_pk_bf16_f32 v234, v235, v236
	v_cvt_pk_bf16_f32 v235, v237, v238
	v_lshl_add_u64 v[236:237], s[54:55], 0, v[96:97]
	global_store_dwordx4 v[236:237], v[232:235], off nt
	s_cbranch_execnz .LBB0_741

; __device__ __forceinline__ void unpack8(const u32x4 w, float* f) { f[0] = bf_lo(w.x); f[1] = bf_hi(w.x); f[2] = bf_lo(w.y); f[3] = bf_hi(w.y); f[4] = bf_lo(w.z); f[5] = bf_hi(w.z); f[6] = bf_lo(w.w); f[7] = bf_hi(w.w); }
; __device__ __forceinline__ u32x4 pack8(const float* f) { u32x4 w; w.x = cvt_pk_bf16(f[0], f[1]); w.y = cvt_pk_bf16(f[2], f[3]); w.z = cvt_pk_bf16(f[4], f[5]); w.w = cvt_pk_bf16(f[6], f[7]); return w; }
;     __device__ __forceinline__ void operator()(AccT& acc, const Unit& u, int wr, int wc, int fr, int fq) const {
;     ...
;                 for (int bj = 0; bj < 2; ++bj) {
;                     const int row = u.pm * 256 + ai * 128 + wr * 64 + m * 16 + fr, col = col0 + bj * 128;
;                     float g1[8]; unpack8(gw[ai][m][bj], g1);
;                     if (u.z == 0) {
; #pragma unroll
;                         for (int n = 0; n < 2; ++n)
; #pragma unroll
;                             for (int j = 0; j < 4; ++j) acc[ai][bj][m][n][j] *= __builtin_amdgcn_rcpf(__builtin_fmaxf(g1[n * 4 + j], 1.0e-30f));
;                     } else {
;                         float v[8];
; #pragma unroll
;                         for (int n = 0; n < 2; ++n)
; #pragma unroll
;                             for (int j = 0; j < 4; ++j) v[n * 4 + j] = acc[ai][bj][m][n][j] * g1[n * 4 + j];
;                         *(u32x4*)((char*)MIX + (unsigned)((row * DM + col) * 2)) = pack8(v);
.LBB0_741:
	v_lshlrev_b32_e32 v220, 16, v184
	v_and_b32_e32 v191, 0xffff0000, v184
	v_lshlrev_b32_e32 v190, 16, v185
	v_and_b32_e32 v189, 0xffff0000, v185
	v_lshlrev_b32_e32 v188, 16, v186
	v_and_b32_e32 v186, 0xffff0000, v186
	v_lshlrev_b32_e32 v184, 16, v187
	s_and_b64 vcc, exec, s[46:47]
	v_and_b32_e32 v185, 0xffff0000, v187
	s_cbranch_vccnz .LBB0_790
	s_lshl_b32 s9, s71, 19
	v_mul_f32_e32 v96, v120, v220
	s_add_i32 s9, s50, s9
	v_mul_f32_e32 v187, v121, v191
	v_mul_f32_e32 v232, v116, v188
	v_mul_f32_e32 v233, v117, v186
	v_mul_f32_e32 v234, v118, v184
	v_mul_f32_e32 v235, v119, v185
	v_cvt_pk_bf16_f32 v230, v96, v187
	v_add3_u32 v96, s9, v99, v98
	v_mul_f32_e32 v221, v122, v190
	v_mul_f32_e32 v229, v123, v189
	v_cvt_pk_bf16_f32 v231, v221, v229
	v_cvt_pk_bf16_f32 v232, v232, v233
	v_cvt_pk_bf16_f32 v233, v234, v235
	v_lshl_add_u64 v[234:235], s[54:55], 0, v[96:97]
	global_store_dwordx4 v[234:235], v[230:233], off nt
	s_cbranch_execnz .LBB0_744

; __device__ __forceinline__ void unpack8(const u32x4 w, float* f) { f[0] = bf_lo(w.x); f[1] = bf_hi(w.x); f[2] = bf_lo(w.y); f[3] = bf_hi(w.y); f[4] = bf_lo(w.z); f[5] = bf_hi(w.z); f[6] = bf_lo(w.w); f[7] = bf_hi(w.w); }
; __device__ __forceinline__ u32x4 pack8(const float* f) { u32x4 w; w.x = cvt_pk_bf16(f[0], f[1]); w.y = cvt_pk_bf16(f[2], f[3]); w.z = cvt_pk_bf16(f[4], f[5]); w.w = cvt_pk_bf16(f[6], f[7]); return w; }
;     __device__ __forceinline__ void operator()(AccT& acc, const Unit& u, int wr, int wc, int fr, int fq) const {
;     ...
;                 for (int bj = 0; bj < 2; ++bj) {
;                     const int row = u.pm * 256 + ai * 128 + wr * 64 + m * 16 + fr, col = col0 + bj * 128;
;                     float g1[8]; unpack8(gw[ai][m][bj], g1);
;                     if (u.z == 0) {
; #pragma unroll
;                         for (int n = 0; n < 2; ++n)
; #pragma unroll
;                             for (int j = 0; j < 4; ++j) acc[ai][bj][m][n][j] *= __builtin_amdgcn_rcpf(__builtin_fmaxf(g1[n * 4 + j], 1.0e-30f));
;                     } else {
;                         float v[8];
; #pragma unroll
;                         for (int n = 0; n < 2; ++n)
; #pragma unroll
;                             for (int j = 0; j < 4; ++j) v[n * 4 + j] = acc[ai][bj][m][n][j] * g1[n * 4 + j];
;                         *(u32x4*)((char*)MIX + (unsigned)((row * DM + col) * 2)) = pack8(v);
.LBB0_744:
	v_lshlrev_b32_e32 v188, 16, v180
	v_and_b32_e32 v187, 0xffff0000, v180
	v_lshlrev_b32_e32 v186, 16, v181
	v_and_b32_e32 v185, 0xffff0000, v181
	v_lshlrev_b32_e32 v184, 16, v182
	v_and_b32_e32 v182, 0xffff0000, v182
	v_lshlrev_b32_e32 v180, 16, v183
	s_and_b64 vcc, exec, s[46:47]
	v_and_b32_e32 v181, 0xffff0000, v183
	s_cbranch_vccnz .LBB0_791
	s_lshl_b32 s9, s71, 19
	v_mul_f32_e32 v96, v84, v188
	s_add_i32 s9, s51, s9
	v_mul_f32_e32 v183, v85, v187
	v_mul_f32_e32 v190, v87, v185
	v_mul_f32_e32 v191, v80, v184
	v_cvt_pk_bf16_f32 v230, v96, v183
	v_add3_u32 v96, s9, v99, v98
	v_mul_f32_e32 v189, v86, v186
	v_mul_f32_e32 v220, v81, v182
	v_cvt_pk_bf16_f32 v231, v189, v190
	v_cvt_pk_bf16_f32 v232, v191, v220
	v_lshl_add_u64 v[190:191], s[54:55], 0, v[96:97]
	v_mul_f32_e32 v221, v82, v180
	v_mul_f32_e32 v229, v83, v181
	v_cvt_pk_bf16_f32 v233, v221, v229
	global_store_dwordx4 v[190:191], v[230:233], off nt
	s_cbranch_execnz .LBB0_747

; __device__ __forceinline__ void unpack8(const u32x4 w, float* f) { f[0] = bf_lo(w.x); f[1] = bf_hi(w.x); f[2] = bf_lo(w.y); f[3] = bf_hi(w.y); f[4] = bf_lo(w.z); f[5] = bf_hi(w.z); f[6] = bf_lo(w.w); f[7] = bf_hi(w.w); }
; __device__ __forceinline__ u32x4 pack8(const float* f) { u32x4 w; w.x = cvt_pk_bf16(f[0], f[1]); w.y = cvt_pk_bf16(f[2], f[3]); w.z = cvt_pk_bf16(f[4], f[5]); w.w = cvt_pk_bf16(f[6], f[7]); return w; }
;     __device__ __forceinline__ void operator()(AccT& acc, const Unit& u, int wr, int wc, int fr, int fq) const {
;     ...
;                 for (int bj = 0; bj < 2; ++bj) {
;                     const int row = u.pm * 256 + ai * 128 + wr * 64 + m * 16 + fr, col = col0 + bj * 128;
;                     float g1[8]; unpack8(gw[ai][m][bj], g1);
;                     if (u.z == 0) {
; #pragma unroll
;                         for (int n = 0; n < 2; ++n)
; #pragma unroll
;                             for (int j = 0; j < 4; ++j) acc[ai][bj][m][n][j] *= __builtin_amdgcn_rcpf(__builtin_fmaxf(g1[n * 4 + j], 1.0e-30f));
;                     } else {
;                         float v[8];
; #pragma unroll
;                         for (int n = 0; n < 2; ++n)
; #pragma unroll
;                             for (int j = 0; j < 4; ++j) v[n * 4 + j] = acc[ai][bj][m][n][j] * g1[n * 4 + j];
;                         *(u32x4*)((char*)MIX + (unsigned)((row * DM + col) * 2)) = pack8(v);
.LBB0_747:
	v_lshlrev_b32_e32 v184, 16, v176
	v_and_b32_e32 v183, 0xffff0000, v176
	v_lshlrev_b32_e32 v182, 16, v177
	v_and_b32_e32 v181, 0xffff0000, v177
	v_lshlrev_b32_e32 v180, 16, v178
	v_and_b32_e32 v178, 0xffff0000, v178
	v_lshlrev_b32_e32 v176, 16, v179
	s_and_b64 vcc, exec, s[46:47]
	v_and_b32_e32 v177, 0xffff0000, v179
	s_cbranch_vccnz .LBB0_792
	s_lshl_b32 s9, s71, 19
	v_mul_f32_e32 v96, v112, v184
	s_add_i32 s9, s56, s9
	v_mul_f32_e32 v179, v113, v183
	v_mul_f32_e32 v187, v115, v181
	v_mul_f32_e32 v188, v108, v180
	v_mul_f32_e32 v189, v109, v178
	v_mul_f32_e32 v190, v110, v176
	v_mul_f32_e32 v191, v111, v177
	v_cvt_pk_bf16_f32 v186, v96, v179
	v_add3_u32 v96, s9, v99, v98
	v_mul_f32_e32 v185, v114, v182
	v_cvt_pk_bf16_f32 v187, v185, v187
	v_cvt_pk_bf16_f32 v188, v188, v189
	v_cvt_pk_bf16_f32 v189, v190, v191
	v_lshl_add_u64 v[190:191], s[54:55], 0, v[96:97]
	global_store_dwordx4 v[190:191], v[186:189], off nt
	s_cbranch_execnz .LBB0_750

; __device__ __forceinline__ void unpack8(const u32x4 w, float* f) { f[0] = bf_lo(w.x); f[1] = bf_hi(w.x); f[2] = bf_lo(w.y); f[3] = bf_hi(w.y); f[4] = bf_lo(w.z); f[5] = bf_hi(w.z); f[6] = bf_lo(w.w); f[7] = bf_hi(w.w); }
; __device__ __forceinline__ u32x4 pack8(const float* f) { u32x4 w; w.x = cvt_pk_bf16(f[0], f[1]); w.y = cvt_pk_bf16(f[2], f[3]); w.z = cvt_pk_bf16(f[4], f[5]); w.w = cvt_pk_bf16(f[6], f[7]); return w; }
;     __device__ __forceinline__ void operator()(AccT& acc, const Unit& u, int wr, int wc, int fr, int fq) const {
;     ...
;                 for (int bj = 0; bj < 2; ++bj) {
;                     const int row = u.pm * 256 + ai * 128 + wr * 64 + m * 16 + fr, col = col0 + bj * 128;
;                     float g1[8]; unpack8(gw[ai][m][bj], g1);
;                     if (u.z == 0) {
; #pragma unroll
;                         for (int n = 0; n < 2; ++n)
; #pragma unroll
;                             for (int j = 0; j < 4; ++j) acc[ai][bj][m][n][j] *= __builtin_amdgcn_rcpf(__builtin_fmaxf(g1[n * 4 + j], 1.0e-30f));
;                     } else {
;                         float v[8];
; #pragma unroll
;                         for (int n = 0; n < 2; ++n)
; #pragma unroll
;                             for (int j = 0; j < 4; ++j) v[n * 4 + j] = acc[ai][bj][m][n][j] * g1[n * 4 + j];
;                         *(u32x4*)((char*)MIX + (unsigned)((row * DM + col) * 2)) = pack8(v);
.LBB0_750:
	v_lshlrev_b32_e32 v180, 16, v172
	v_and_b32_e32 v179, 0xffff0000, v172
	v_lshlrev_b32_e32 v178, 16, v173
	v_and_b32_e32 v177, 0xffff0000, v173
	v_lshlrev_b32_e32 v176, 16, v174
	v_and_b32_e32 v174, 0xffff0000, v174
	v_lshlrev_b32_e32 v172, 16, v175
	s_and_b64 vcc, exec, s[46:47]
	v_and_b32_e32 v173, 0xffff0000, v175
	s_cbranch_vccnz .LBB0_793
	s_lshl_b32 s9, s71, 19
	v_mul_f32_e32 v96, v76, v180
	s_add_i32 s9, s57, s9
	v_mul_f32_e32 v175, v77, v179
	v_mul_f32_e32 v183, v79, v177
	v_mul_f32_e32 v184, v72, v176
	v_mul_f32_e32 v185, v73, v174
	v_mul_f32_e32 v186, v74, v172
	v_mul_f32_e32 v187, v75, v173
	v_cvt_pk_bf16_f32 v182, v96, v175
	v_add3_u32 v96, s9, v99, v98
	v_mul_f32_e32 v181, v78, v178
	v_cvt_pk_bf16_f32 v183, v181, v183
	v_cvt_pk_bf16_f32 v184, v184, v185
	v_cvt_pk_bf16_f32 v185, v186, v187
	v_lshl_add_u64 v[186:187], s[54:55], 0, v[96:97]
	global_store_dwordx4 v[186:187], v[182:185], off nt
	s_cbranch_execnz .LBB0_753

; __device__ __forceinline__ void unpack8(const u32x4 w, float* f) { f[0] = bf_lo(w.x); f[1] = bf_hi(w.x); f[2] = bf_lo(w.y); f[3] = bf_hi(w.y); f[4] = bf_lo(w.z); f[5] = bf_hi(w.z); f[6] = bf_lo(w.w); f[7] = bf_hi(w.w); }
; __device__ __forceinline__ u32x4 pack8(const float* f) { u32x4 w; w.x = cvt_pk_bf16(f[0], f[1]); w.y = cvt_pk_bf16(f[2], f[3]); w.z = cvt_pk_bf16(f[4], f[5]); w.w = cvt_pk_bf16(f[6], f[7]); return w; }
;     __device__ __forceinline__ void operator()(AccT& acc, const Unit& u, int wr, int wc, int fr, int fq) const {
;     ...
;                 for (int bj = 0; bj < 2; ++bj) {
;                     const int row = u.pm * 256 + ai * 128 + wr * 64 + m * 16 + fr, col = col0 + bj * 128;
;                     float g1[8]; unpack8(gw[ai][m][bj], g1);
;                     if (u.z == 0) {
; #pragma unroll
;                         for (int n = 0; n < 2; ++n)
; #pragma unroll
;                             for (int j = 0; j < 4; ++j) acc[ai][bj][m][n][j] *= __builtin_amdgcn_rcpf(__builtin_fmaxf(g1[n * 4 + j], 1.0e-30f));
;                     } else {
;                         float v[8];
; #pragma unroll
;                         for (int n = 0; n < 2; ++n)
; #pragma unroll
;                             for (int j = 0; j < 4; ++j) v[n * 4 + j] = acc[ai][bj][m][n][j] * g1[n * 4 + j];
;                         *(u32x4*)((char*)MIX + (unsigned)((row * DM + col) * 2)) = pack8(v);
.LBB0_753:
	v_lshlrev_b32_e32 v176, 16, v168
	v_and_b32_e32 v175, 0xffff0000, v168
	v_lshlrev_b32_e32 v174, 16, v169
	v_and_b32_e32 v173, 0xffff0000, v169
	v_lshlrev_b32_e32 v172, 16, v170
	v_and_b32_e32 v170, 0xffff0000, v170
	v_lshlrev_b32_e32 v168, 16, v171
	s_and_b64 vcc, exec, s[46:47]
	v_and_b32_e32 v169, 0xffff0000, v171
	s_cbranch_vccnz .LBB0_794
	s_lshl_b32 s9, s71, 19
	v_mul_f32_e32 v96, v104, v176
	s_add_i32 s9, s58, s9
	v_mul_f32_e32 v171, v105, v175
	v_mul_f32_e32 v179, v107, v173
	v_mul_f32_e32 v180, v100, v172
	v_mul_f32_e32 v181, v101, v170
	v_mul_f32_e32 v182, v102, v168
	v_mul_f32_e32 v183, v103, v169
	v_cvt_pk_bf16_f32 v178, v96, v171
	v_add3_u32 v96, s9, v99, v98
	v_mul_f32_e32 v177, v106, v174
	v_cvt_pk_bf16_f32 v179, v177, v179
	v_cvt_pk_bf16_f32 v180, v180, v181
	v_cvt_pk_bf16_f32 v181, v182, v183
	v_lshl_add_u64 v[182:183], s[54:55], 0, v[96:97]
	global_store_dwordx4 v[182:183], v[178:181], off nt
	s_cbranch_execnz .LBB0_756

; __device__ __forceinline__ void unpack8(const u32x4 w, float* f) { f[0] = bf_lo(w.x); f[1] = bf_hi(w.x); f[2] = bf_lo(w.y); f[3] = bf_hi(w.y); f[4] = bf_lo(w.z); f[5] = bf_hi(w.z); f[6] = bf_lo(w.w); f[7] = bf_hi(w.w); }
; __device__ __forceinline__ u32x4 pack8(const float* f) { u32x4 w; w.x = cvt_pk_bf16(f[0], f[1]); w.y = cvt_pk_bf16(f[2], f[3]); w.z = cvt_pk_bf16(f[4], f[5]); w.w = cvt_pk_bf16(f[6], f[7]); return w; }
;     __device__ __forceinline__ void operator()(AccT& acc, const Unit& u, int wr, int wc, int fr, int fq) const {
;     ...
;                 for (int bj = 0; bj < 2; ++bj) {
;                     const int row = u.pm * 256 + ai * 128 + wr * 64 + m * 16 + fr, col = col0 + bj * 128;
;                     float g1[8]; unpack8(gw[ai][m][bj], g1);
;                     if (u.z == 0) {
; #pragma unroll
;                         for (int n = 0; n < 2; ++n)
; #pragma unroll
;                             for (int j = 0; j < 4; ++j) acc[ai][bj][m][n][j] *= __builtin_amdgcn_rcpf(__builtin_fmaxf(g1[n * 4 + j], 1.0e-30f));
;                     } else {
;                         float v[8];
; #pragma unroll
;                         for (int n = 0; n < 2; ++n)
; #pragma unroll
;                             for (int j = 0; j < 4; ++j) v[n * 4 + j] = acc[ai][bj][m][n][j] * g1[n * 4 + j];
;                         *(u32x4*)((char*)MIX + (unsigned)((row * DM + col) * 2)) = pack8(v);
.LBB0_756:
	v_lshlrev_b32_e32 v172, 16, v164
	v_and_b32_e32 v171, 0xffff0000, v164
	v_lshlrev_b32_e32 v170, 16, v165
	v_and_b32_e32 v169, 0xffff0000, v165
	v_lshlrev_b32_e32 v168, 16, v166
	v_and_b32_e32 v166, 0xffff0000, v166
	v_lshlrev_b32_e32 v164, 16, v167
	s_and_b64 vcc, exec, s[46:47]
	v_and_b32_e32 v165, 0xffff0000, v167
	s_cbranch_vccnz .LBB0_795
	s_lshl_b32 s9, s71, 19
	v_mul_f32_e32 v96, v68, v172
	s_add_i32 s9, s59, s9
	v_mul_f32_e32 v167, v69, v171
	v_mul_f32_e32 v175, v71, v169
	v_mul_f32_e32 v176, v64, v168
	v_mul_f32_e32 v177, v65, v166
	v_mul_f32_e32 v178, v66, v164
	v_mul_f32_e32 v179, v67, v165
	v_cvt_pk_bf16_f32 v174, v96, v167
	v_add3_u32 v96, s9, v99, v98
	v_mul_f32_e32 v173, v70, v170
	v_cvt_pk_bf16_f32 v175, v173, v175
	v_cvt_pk_bf16_f32 v176, v176, v177
	v_cvt_pk_bf16_f32 v177, v178, v179
	v_lshl_add_u64 v[178:179], s[54:55], 0, v[96:97]
	global_store_dwordx4 v[178:179], v[174:177], off nt
	s_cbranch_execnz .LBB0_759

; __device__ __forceinline__ void unpack8(const u32x4 w, float* f) { f[0] = bf_lo(w.x); f[1] = bf_hi(w.x); f[2] = bf_lo(w.y); f[3] = bf_hi(w.y); f[4] = bf_lo(w.z); f[5] = bf_hi(w.z); f[6] = bf_lo(w.w); f[7] = bf_hi(w.w); }
; __device__ __forceinline__ u32x4 pack8(const float* f) { u32x4 w; w.x = cvt_pk_bf16(f[0], f[1]); w.y = cvt_pk_bf16(f[2], f[3]); w.z = cvt_pk_bf16(f[4], f[5]); w.w = cvt_pk_bf16(f[6], f[7]); return w; }
;     __device__ __forceinline__ void operator()(AccT& acc, const Unit& u, int wr, int wc, int fr, int fq) const {
;     ...
;                 for (int bj = 0; bj < 2; ++bj) {
;                     const int row = u.pm * 256 + ai * 128 + wr * 64 + m * 16 + fr, col = col0 + bj * 128;
;                     float g1[8]; unpack8(gw[ai][m][bj], g1);
;                     if (u.z == 0) {
; #pragma unroll
;                         for (int n = 0; n < 2; ++n)
; #pragma unroll
;                             for (int j = 0; j < 4; ++j) acc[ai][bj][m][n][j] *= __builtin_amdgcn_rcpf(__builtin_fmaxf(g1[n * 4 + j], 1.0e-30f));
;                     } else {
;                         float v[8];
; #pragma unroll
;                         for (int n = 0; n < 2; ++n)
; #pragma unroll
;                             for (int j = 0; j < 4; ++j) v[n * 4 + j] = acc[ai][bj][m][n][j] * g1[n * 4 + j];
;                         *(u32x4*)((char*)MIX + (unsigned)((row * DM + col) * 2)) = pack8(v);
.LBB0_759:
	v_lshlrev_b32_e32 v168, 16, v160
	v_and_b32_e32 v167, 0xffff0000, v160
	v_lshlrev_b32_e32 v166, 16, v161
	v_and_b32_e32 v165, 0xffff0000, v161
	v_lshlrev_b32_e32 v164, 16, v162
	v_and_b32_e32 v162, 0xffff0000, v162
	v_lshlrev_b32_e32 v160, 16, v163
	s_and_b64 vcc, exec, s[46:47]
	v_and_b32_e32 v161, 0xffff0000, v163
	s_cbranch_vccnz .LBB0_796
	s_lshl_b32 s9, s71, 19
	v_mul_f32_e32 v96, v60, v168
	s_add_i32 s9, s60, s9
	v_mul_f32_e32 v163, v61, v167
	v_mul_f32_e32 v171, v63, v165
	v_mul_f32_e32 v172, v56, v164
	v_mul_f32_e32 v173, v57, v162
	v_mul_f32_e32 v174, v58, v160
	v_mul_f32_e32 v175, v59, v161
	v_cvt_pk_bf16_f32 v170, v96, v163
	v_add3_u32 v96, s9, v99, v98
	v_mul_f32_e32 v169, v62, v166
	v_cvt_pk_bf16_f32 v171, v169, v171
	v_cvt_pk_bf16_f32 v172, v172, v173
	v_cvt_pk_bf16_f32 v173, v174, v175
	v_lshl_add_u64 v[174:175], s[54:55], 0, v[96:97]
	global_store_dwordx4 v[174:175], v[170:173], off nt
	s_cbranch_execnz .LBB0_762

; __device__ __forceinline__ void unpack8(const u32x4 w, float* f) { f[0] = bf_lo(w.x); f[1] = bf_hi(w.x); f[2] = bf_lo(w.y); f[3] = bf_hi(w.y); f[4] = bf_lo(w.z); f[5] = bf_hi(w.z); f[6] = bf_lo(w.w); f[7] = bf_hi(w.w); }
; __device__ __forceinline__ u32x4 pack8(const float* f) { u32x4 w; w.x = cvt_pk_bf16(f[0], f[1]); w.y = cvt_pk_bf16(f[2], f[3]); w.z = cvt_pk_bf16(f[4], f[5]); w.w = cvt_pk_bf16(f[6], f[7]); return w; }
;     __device__ __forceinline__ void operator()(AccT& acc, const Unit& u, int wr, int wc, int fr, int fq) const {
;     ...
;                 for (int bj = 0; bj < 2; ++bj) {
;                     const int row = u.pm * 256 + ai * 128 + wr * 64 + m * 16 + fr, col = col0 + bj * 128;
;                     float g1[8]; unpack8(gw[ai][m][bj], g1);
;                     if (u.z == 0) {
; #pragma unroll
;                         for (int n = 0; n < 2; ++n)
; #pragma unroll
;                             for (int j = 0; j < 4; ++j) acc[ai][bj][m][n][j] *= __builtin_amdgcn_rcpf(__builtin_fmaxf(g1[n * 4 + j], 1.0e-30f));
;                     } else {
;                         float v[8];
; #pragma unroll
;                         for (int n = 0; n < 2; ++n)
; #pragma unroll
;                             for (int j = 0; j < 4; ++j) v[n * 4 + j] = acc[ai][bj][m][n][j] * g1[n * 4 + j];
;                         *(u32x4*)((char*)MIX + (unsigned)((row * DM + col) * 2)) = pack8(v);
.LBB0_762:
	v_lshlrev_b32_e32 v164, 16, v156
	v_and_b32_e32 v163, 0xffff0000, v156
	v_lshlrev_b32_e32 v162, 16, v157
	v_and_b32_e32 v161, 0xffff0000, v157
	v_lshlrev_b32_e32 v160, 16, v158
	v_and_b32_e32 v158, 0xffff0000, v158
	v_lshlrev_b32_e32 v156, 16, v159
	s_and_b64 vcc, exec, s[46:47]
	v_and_b32_e32 v157, 0xffff0000, v159
	s_cbranch_vccnz .LBB0_797
	s_lshl_b32 s9, s71, 19
	v_mul_f32_e32 v96, v28, v164
	s_add_i32 s9, s61, s9
	v_mul_f32_e32 v159, v29, v163
	v_mul_f32_e32 v167, v31, v161
	v_mul_f32_e32 v168, v24, v160
	v_mul_f32_e32 v169, v25, v158
	v_mul_f32_e32 v170, v26, v156
	v_mul_f32_e32 v171, v27, v157
	v_cvt_pk_bf16_f32 v166, v96, v159
	v_add3_u32 v96, s9, v99, v98
	v_mul_f32_e32 v165, v30, v162
	v_cvt_pk_bf16_f32 v167, v165, v167
	v_cvt_pk_bf16_f32 v168, v168, v169
	v_cvt_pk_bf16_f32 v169, v170, v171
	v_lshl_add_u64 v[170:171], s[54:55], 0, v[96:97]
	global_store_dwordx4 v[170:171], v[166:169], off nt
	s_cbranch_execnz .LBB0_765

; __device__ __forceinline__ void unpack8(const u32x4 w, float* f) { f[0] = bf_lo(w.x); f[1] = bf_hi(w.x); f[2] = bf_lo(w.y); f[3] = bf_hi(w.y); f[4] = bf_lo(w.z); f[5] = bf_hi(w.z); f[6] = bf_lo(w.w); f[7] = bf_hi(w.w); }
; __device__ __forceinline__ u32x4 pack8(const float* f) { u32x4 w; w.x = cvt_pk_bf16(f[0], f[1]); w.y = cvt_pk_bf16(f[2], f[3]); w.z = cvt_pk_bf16(f[4], f[5]); w.w = cvt_pk_bf16(f[6], f[7]); return w; }
;     __device__ __forceinline__ void operator()(AccT& acc, const Unit& u, int wr, int wc, int fr, int fq) const {
;     ...
;                 for (int bj = 0; bj < 2; ++bj) {
;                     const int row = u.pm * 256 + ai * 128 + wr * 64 + m * 16 + fr, col = col0 + bj * 128;
;                     float g1[8]; unpack8(gw[ai][m][bj], g1);
;                     if (u.z == 0) {
; #pragma unroll
;                         for (int n = 0; n < 2; ++n)
; #pragma unroll
;                             for (int j = 0; j < 4; ++j) acc[ai][bj][m][n][j] *= __builtin_amdgcn_rcpf(__builtin_fmaxf(g1[n * 4 + j], 1.0e-30f));
;                     } else {
;                         float v[8];
; #pragma unroll
;                         for (int n = 0; n < 2; ++n)
; #pragma unroll
;                             for (int j = 0; j < 4; ++j) v[n * 4 + j] = acc[ai][bj][m][n][j] * g1[n * 4 + j];
;                         *(u32x4*)((char*)MIX + (unsigned)((row * DM + col) * 2)) = pack8(v);
.LBB0_765:
	v_lshlrev_b32_e32 v160, 16, v152
	v_and_b32_e32 v159, 0xffff0000, v152
	v_lshlrev_b32_e32 v158, 16, v153
	v_and_b32_e32 v157, 0xffff0000, v153
	v_lshlrev_b32_e32 v156, 16, v154
	v_and_b32_e32 v154, 0xffff0000, v154
	v_lshlrev_b32_e32 v152, 16, v155
	s_and_b64 vcc, exec, s[46:47]
	v_and_b32_e32 v153, 0xffff0000, v155
	s_cbranch_vccnz .LBB0_798
	s_lshl_b32 s9, s71, 19
	v_mul_f32_e32 v96, v52, v160
	s_add_i32 s9, s62, s9
	v_mul_f32_e32 v155, v53, v159
	v_mul_f32_e32 v163, v55, v157
	v_mul_f32_e32 v164, v48, v156
	v_mul_f32_e32 v165, v49, v154
	v_mul_f32_e32 v166, v50, v152
	v_mul_f32_e32 v167, v51, v153
	v_cvt_pk_bf16_f32 v162, v96, v155
	v_add3_u32 v96, s9, v99, v98
	v_mul_f32_e32 v161, v54, v158
	v_cvt_pk_bf16_f32 v163, v161, v163
	v_cvt_pk_bf16_f32 v164, v164, v165
	v_cvt_pk_bf16_f32 v165, v166, v167
	v_lshl_add_u64 v[166:167], s[54:55], 0, v[96:97]
	global_store_dwordx4 v[166:167], v[162:165], off nt
	s_cbranch_execnz .LBB0_768

; __device__ __forceinline__ void unpack8(const u32x4 w, float* f) { f[0] = bf_lo(w.x); f[1] = bf_hi(w.x); f[2] = bf_lo(w.y); f[3] = bf_hi(w.y); f[4] = bf_lo(w.z); f[5] = bf_hi(w.z); f[6] = bf_lo(w.w); f[7] = bf_hi(w.w); }
; __device__ __forceinline__ u32x4 pack8(const float* f) { u32x4 w; w.x = cvt_pk_bf16(f[0], f[1]); w.y = cvt_pk_bf16(f[2], f[3]); w.z = cvt_pk_bf16(f[4], f[5]); w.w = cvt_pk_bf16(f[6], f[7]); return w; }
;     __device__ __forceinline__ void operator()(AccT& acc, const Unit& u, int wr, int wc, int fr, int fq) const {
;     ...
;                 for (int bj = 0; bj < 2; ++bj) {
;                     const int row = u.pm * 256 + ai * 128 + wr * 64 + m * 16 + fr, col = col0 + bj * 128;
;                     float g1[8]; unpack8(gw[ai][m][bj], g1);
;                     if (u.z == 0) {
; #pragma unroll
;                         for (int n = 0; n < 2; ++n)
; #pragma unroll
;                             for (int j = 0; j < 4; ++j) acc[ai][bj][m][n][j] *= __builtin_amdgcn_rcpf(__builtin_fmaxf(g1[n * 4 + j], 1.0e-30f));
;                     } else {
;                         float v[8];
; #pragma unroll
;                         for (int n = 0; n < 2; ++n)
; #pragma unroll
;                             for (int j = 0; j < 4; ++j) v[n * 4 + j] = acc[ai][bj][m][n][j] * g1[n * 4 + j];
;                         *(u32x4*)((char*)MIX + (unsigned)((row * DM + col) * 2)) = pack8(v);
.LBB0_768:
	v_lshlrev_b32_e32 v156, 16, v148
	v_and_b32_e32 v155, 0xffff0000, v148
	v_lshlrev_b32_e32 v154, 16, v149
	v_and_b32_e32 v153, 0xffff0000, v149
	v_lshlrev_b32_e32 v152, 16, v150
	v_and_b32_e32 v150, 0xffff0000, v150
	v_lshlrev_b32_e32 v148, 16, v151
	s_and_b64 vcc, exec, s[46:47]
	v_and_b32_e32 v149, 0xffff0000, v151
	s_cbranch_vccnz .LBB0_799
	s_lshl_b32 s9, s71, 19
	v_mul_f32_e32 v96, v20, v156
	s_add_i32 s9, s63, s9
	v_mul_f32_e32 v151, v21, v155
	v_mul_f32_e32 v159, v23, v153
	v_mul_f32_e32 v160, v16, v152
	v_mul_f32_e32 v161, v17, v150
	v_mul_f32_e32 v162, v18, v148
	v_mul_f32_e32 v163, v19, v149
	v_cvt_pk_bf16_f32 v158, v96, v151
	v_add3_u32 v96, s9, v99, v98
	v_mul_f32_e32 v157, v22, v154
	v_cvt_pk_bf16_f32 v159, v157, v159
	v_cvt_pk_bf16_f32 v160, v160, v161
	v_cvt_pk_bf16_f32 v161, v162, v163
	v_lshl_add_u64 v[162:163], s[54:55], 0, v[96:97]
	global_store_dwordx4 v[162:163], v[158:161], off nt
	s_cbranch_execnz .LBB0_771

; __device__ __forceinline__ void unpack8(const u32x4 w, float* f) { f[0] = bf_lo(w.x); f[1] = bf_hi(w.x); f[2] = bf_lo(w.y); f[3] = bf_hi(w.y); f[4] = bf_lo(w.z); f[5] = bf_hi(w.z); f[6] = bf_lo(w.w); f[7] = bf_hi(w.w); }
; __device__ __forceinline__ u32x4 pack8(const float* f) { u32x4 w; w.x = cvt_pk_bf16(f[0], f[1]); w.y = cvt_pk_bf16(f[2], f[3]); w.z = cvt_pk_bf16(f[4], f[5]); w.w = cvt_pk_bf16(f[6], f[7]); return w; }
;     __device__ __forceinline__ void operator()(AccT& acc, const Unit& u, int wr, int wc, int fr, int fq) const {
;     ...
;                 for (int bj = 0; bj < 2; ++bj) {
;                     const int row = u.pm * 256 + ai * 128 + wr * 64 + m * 16 + fr, col = col0 + bj * 128;
;                     float g1[8]; unpack8(gw[ai][m][bj], g1);
;                     if (u.z == 0) {
; #pragma unroll
;                         for (int n = 0; n < 2; ++n)
; #pragma unroll
;                             for (int j = 0; j < 4; ++j) acc[ai][bj][m][n][j] *= __builtin_amdgcn_rcpf(__builtin_fmaxf(g1[n * 4 + j], 1.0e-30f));
;                     } else {
;                         float v[8];
; #pragma unroll
;                         for (int n = 0; n < 2; ++n)
; #pragma unroll
;                             for (int j = 0; j < 4; ++j) v[n * 4 + j] = acc[ai][bj][m][n][j] * g1[n * 4 + j];
;                         *(u32x4*)((char*)MIX + (unsigned)((row * DM + col) * 2)) = pack8(v);
.LBB0_771:
	v_lshlrev_b32_e32 v152, 16, v144
	v_and_b32_e32 v151, 0xffff0000, v144
	v_lshlrev_b32_e32 v150, 16, v145
	v_and_b32_e32 v149, 0xffff0000, v145
	v_lshlrev_b32_e32 v148, 16, v146
	v_and_b32_e32 v146, 0xffff0000, v146
	v_lshlrev_b32_e32 v144, 16, v147
	s_and_b64 vcc, exec, s[46:47]
	v_and_b32_e32 v145, 0xffff0000, v147
	s_cbranch_vccnz .LBB0_800
	s_lshl_b32 s9, s71, 19
	v_mul_f32_e32 v96, v44, v152
	s_add_i32 s9, s64, s9
	v_mul_f32_e32 v147, v45, v151
	v_mul_f32_e32 v155, v47, v149
	v_mul_f32_e32 v156, v40, v148
	v_mul_f32_e32 v157, v41, v146
	v_mul_f32_e32 v158, v42, v144
	v_mul_f32_e32 v159, v43, v145
	v_cvt_pk_bf16_f32 v154, v96, v147
	v_add3_u32 v96, s9, v99, v98
	v_mul_f32_e32 v153, v46, v150
	v_cvt_pk_bf16_f32 v155, v153, v155
	v_cvt_pk_bf16_f32 v156, v156, v157
	v_cvt_pk_bf16_f32 v157, v158, v159
	v_lshl_add_u64 v[158:159], s[54:55], 0, v[96:97]
	global_store_dwordx4 v[158:159], v[154:157], off nt
	s_cbranch_execnz .LBB0_774

; __device__ __forceinline__ void unpack8(const u32x4 w, float* f) { f[0] = bf_lo(w.x); f[1] = bf_hi(w.x); f[2] = bf_lo(w.y); f[3] = bf_hi(w.y); f[4] = bf_lo(w.z); f[5] = bf_hi(w.z); f[6] = bf_lo(w.w); f[7] = bf_hi(w.w); }
; __device__ __forceinline__ u32x4 pack8(const float* f) { u32x4 w; w.x = cvt_pk_bf16(f[0], f[1]); w.y = cvt_pk_bf16(f[2], f[3]); w.z = cvt_pk_bf16(f[4], f[5]); w.w = cvt_pk_bf16(f[6], f[7]); return w; }
;     __device__ __forceinline__ void operator()(AccT& acc, const Unit& u, int wr, int wc, int fr, int fq) const {
;     ...
;                 for (int bj = 0; bj < 2; ++bj) {
;                     const int row = u.pm * 256 + ai * 128 + wr * 64 + m * 16 + fr, col = col0 + bj * 128;
;                     float g1[8]; unpack8(gw[ai][m][bj], g1);
;                     if (u.z == 0) {
; #pragma unroll
;                         for (int n = 0; n < 2; ++n)
; #pragma unroll
;                             for (int j = 0; j < 4; ++j) acc[ai][bj][m][n][j] *= __builtin_amdgcn_rcpf(__builtin_fmaxf(g1[n * 4 + j], 1.0e-30f));
;                     } else {
;                         float v[8];
; #pragma unroll
;                         for (int n = 0; n < 2; ++n)
; #pragma unroll
;                             for (int j = 0; j < 4; ++j) v[n * 4 + j] = acc[ai][bj][m][n][j] * g1[n * 4 + j];
;                         *(u32x4*)((char*)MIX + (unsigned)((row * DM + col) * 2)) = pack8(v);
.LBB0_774:
	v_lshlrev_b32_e32 v148, 16, v140
	v_and_b32_e32 v147, 0xffff0000, v140
	v_lshlrev_b32_e32 v146, 16, v141
	v_and_b32_e32 v145, 0xffff0000, v141
	v_lshlrev_b32_e32 v144, 16, v142
	v_and_b32_e32 v142, 0xffff0000, v142
	v_lshlrev_b32_e32 v140, 16, v143
	s_and_b64 vcc, exec, s[46:47]
	v_and_b32_e32 v141, 0xffff0000, v143
	s_cbranch_vccnz .LBB0_801
	s_lshl_b32 s9, s71, 19
	v_mul_f32_e32 v96, v12, v148
	s_add_i32 s9, s65, s9
	v_mul_f32_e32 v143, v13, v147
	v_mul_f32_e32 v151, v15, v145
	v_mul_f32_e32 v152, v8, v144
	v_mul_f32_e32 v153, v9, v142
	v_mul_f32_e32 v154, v10, v140
	v_mul_f32_e32 v155, v11, v141
	v_cvt_pk_bf16_f32 v150, v96, v143
	v_add3_u32 v96, s9, v99, v98
	v_mul_f32_e32 v149, v14, v146
	v_cvt_pk_bf16_f32 v151, v149, v151
	v_cvt_pk_bf16_f32 v152, v152, v153
	v_cvt_pk_bf16_f32 v153, v154, v155
	v_lshl_add_u64 v[154:155], s[54:55], 0, v[96:97]
	global_store_dwordx4 v[154:155], v[150:153], off nt
	s_cbranch_execnz .LBB0_777

; __device__ __forceinline__ void unpack8(const u32x4 w, float* f) { f[0] = bf_lo(w.x); f[1] = bf_hi(w.x); f[2] = bf_lo(w.y); f[3] = bf_hi(w.y); f[4] = bf_lo(w.z); f[5] = bf_hi(w.z); f[6] = bf_lo(w.w); f[7] = bf_hi(w.w); }
; __device__ __forceinline__ u32x4 pack8(const float* f) { u32x4 w; w.x = cvt_pk_bf16(f[0], f[1]); w.y = cvt_pk_bf16(f[2], f[3]); w.z = cvt_pk_bf16(f[4], f[5]); w.w = cvt_pk_bf16(f[6], f[7]); return w; }
;     __device__ __forceinline__ void operator()(AccT& acc, const Unit& u, int wr, int wc, int fr, int fq) const {
;     ...
;                 for (int bj = 0; bj < 2; ++bj) {
;                     const int row = u.pm * 256 + ai * 128 + wr * 64 + m * 16 + fr, col = col0 + bj * 128;
;                     float g1[8]; unpack8(gw[ai][m][bj], g1);
;                     if (u.z == 0) {
; #pragma unroll
;                         for (int n = 0; n < 2; ++n)
; #pragma unroll
;                             for (int j = 0; j < 4; ++j) acc[ai][bj][m][n][j] *= __builtin_amdgcn_rcpf(__builtin_fmaxf(g1[n * 4 + j], 1.0e-30f));
;                     } else {
;                         float v[8];
; #pragma unroll
;                         for (int n = 0; n < 2; ++n)
; #pragma unroll
;                             for (int j = 0; j < 4; ++j) v[n * 4 + j] = acc[ai][bj][m][n][j] * g1[n * 4 + j];
;                         *(u32x4*)((char*)MIX + (unsigned)((row * DM + col) * 2)) = pack8(v);
.LBB0_777:
	v_lshlrev_b32_e32 v144, 16, v136
	v_and_b32_e32 v143, 0xffff0000, v136
	v_lshlrev_b32_e32 v142, 16, v137
	v_and_b32_e32 v141, 0xffff0000, v137
	v_lshlrev_b32_e32 v140, 16, v138
	v_and_b32_e32 v138, 0xffff0000, v138
	v_lshlrev_b32_e32 v136, 16, v139
	s_and_b64 vcc, exec, s[46:47]
	v_and_b32_e32 v137, 0xffff0000, v139
	s_cbranch_vccnz .LBB0_802
	s_lshl_b32 s9, s71, 19
	v_mul_f32_e32 v96, v36, v144
	s_add_i32 s9, s66, s9
	v_mul_f32_e32 v139, v37, v143
	v_mul_f32_e32 v147, v39, v141
	v_mul_f32_e32 v148, v32, v140
	v_mul_f32_e32 v149, v33, v138
	v_mul_f32_e32 v150, v34, v136
	v_mul_f32_e32 v151, v35, v137
	v_cvt_pk_bf16_f32 v146, v96, v139
	v_add3_u32 v96, s9, v99, v98
	v_mul_f32_e32 v145, v38, v142
	v_cvt_pk_bf16_f32 v147, v145, v147
	v_cvt_pk_bf16_f32 v148, v148, v149
	v_cvt_pk_bf16_f32 v149, v150, v151
	v_lshl_add_u64 v[150:151], s[54:55], 0, v[96:97]
	global_store_dwordx4 v[150:151], v[146:149], off nt
	s_cbranch_execnz .LBB0_780

; __device__ __forceinline__ void unpack8(const u32x4 w, float* f) { f[0] = bf_lo(w.x); f[1] = bf_hi(w.x); f[2] = bf_lo(w.y); f[3] = bf_hi(w.y); f[4] = bf_lo(w.z); f[5] = bf_hi(w.z); f[6] = bf_lo(w.w); f[7] = bf_hi(w.w); }
; __device__ __forceinline__ u32x4 pack8(const float* f) { u32x4 w; w.x = cvt_pk_bf16(f[0], f[1]); w.y = cvt_pk_bf16(f[2], f[3]); w.z = cvt_pk_bf16(f[4], f[5]); w.w = cvt_pk_bf16(f[6], f[7]); return w; }
;     __device__ __forceinline__ void operator()(AccT& acc, const Unit& u, int wr, int wc, int fr, int fq) const {
;     ...
;                 for (int bj = 0; bj < 2; ++bj) {
;                     const int row = u.pm * 256 + ai * 128 + wr * 64 + m * 16 + fr, col = col0 + bj * 128;
;                     float g1[8]; unpack8(gw[ai][m][bj], g1);
;                     if (u.z == 0) {
; #pragma unroll
;                         for (int n = 0; n < 2; ++n)
; #pragma unroll
;                             for (int j = 0; j < 4; ++j) acc[ai][bj][m][n][j] *= __builtin_amdgcn_rcpf(__builtin_fmaxf(g1[n * 4 + j], 1.0e-30f));
;                     } else {
;                         float v[8];
; #pragma unroll
;                         for (int n = 0; n < 2; ++n)
; #pragma unroll
;                             for (int j = 0; j < 4; ++j) v[n * 4 + j] = acc[ai][bj][m][n][j] * g1[n * 4 + j];
;                         *(u32x4*)((char*)MIX + (unsigned)((row * DM + col) * 2)) = pack8(v);
.LBB0_780:
	v_lshlrev_b32_e32 v140, 16, v132
	v_and_b32_e32 v139, 0xffff0000, v132
	v_lshlrev_b32_e32 v138, 16, v133
	v_and_b32_e32 v137, 0xffff0000, v133
	v_lshlrev_b32_e32 v136, 16, v134
	v_and_b32_e32 v134, 0xffff0000, v134
	v_lshlrev_b32_e32 v132, 16, v135
	s_and_b64 vcc, exec, s[46:47]
	v_and_b32_e32 v133, 0xffff0000, v135
	s_cbranch_vccnz .LBB0_803
	s_lshl_b32 s9, s71, 19
	v_mul_f32_e32 v96, v4, v140
	s_add_i32 s9, s67, s9
	v_mul_f32_e32 v135, v5, v139
	v_cvt_pk_bf16_f32 v142, v96, v135
	v_add3_u32 v96, s9, v99, v98
	v_mul_f32_e32 v143, v7, v137
	v_mul_f32_e32 v144, v0, v136
	v_mul_f32_e32 v145, v1, v134
	v_lshl_add_u64 v[98:99], s[54:55], 0, v[96:97]
	v_mul_f32_e32 v141, v6, v138
	v_mul_f32_e32 v146, v2, v132
	v_mul_f32_e32 v147, v3, v133
	v_cvt_pk_bf16_f32 v143, v141, v143
	v_cvt_pk_bf16_f32 v144, v144, v145
	v_cvt_pk_bf16_f32 v145, v146, v147
	global_store_dwordx4 v[98:99], v[142:145], off nt
	s_cbranch_execnz .LBB0_783

; __device__ __forceinline__ unsigned cvt_pk_bf16(float lo, float hi) { unsigned r; asm volatile("v_cvt_pk_bf16_f32 %0, %1, %2" : "=v"(r) : "v"(lo), "v"(hi)); return r; }
;     __device__ __forceinline__ void finish(const f32x4 x0, const f32x4 x1, int row, int col, float& s) const {
;         if (OUT_F32) { *(f32x4*)(out + (size_t)row * DM + col) = x0; *(f32x4*)(out + (size_t)row * DM + col + 4) = x1; }
;         else { u32x4 w; w.x = cvt_pk_bf16(x0[0], x0[1]); w.y = cvt_pk_bf16(x0[2], x0[3]); w.z = cvt_pk_bf16(x1[0], x1[1]); w.w = cvt_pk_bf16(x1[2], x1[3]); *(u32x4*)(XB + (size_t)row * DM + col) = w; }
;         s += (x0[0] * x0[0] + x0[1] * x0[1]) + (x0[2] * x0[2] + x0[3] * x0[3]) + (x1[0] * x1[0] + x1[1] * x1[1]) + (x1[2] * x1[2] + x1[3] * x1[3]);
;     __device__ __forceinline__ void operator()(AccT& acc, const Unit& u, int wr, int wc, int fr, int fq) const {
;     ...
;             u32x4 rb[2][4][2];
; #pragma unroll
;             for (int ai = 0; ai < 2; ++ai)
; #pragma unroll
;                 for (int m = 0; m < 4; ++m)
; #pragma unroll
;                     for (int bj = 0; bj < 2; ++bj) rb[ai][m][bj] = __builtin_nontemporal_load((const u32x4*)((const char*)XB + (unsigned)(((u.pm * 256 + ai * 128 + wr * 64 + m * 16 + fr) * DM + col0 + bj * 128) * 2)));
; #pragma unroll
;             for (int ai = 0; ai < 2; ++ai)
; #pragma unroll
;                 for (int m = 0; m < 4; ++m) {
;                     const int row = u.pm * 256 + ai * 128 + wr * 64 + m * 16 + fr; float s = 0.f;
; #pragma unroll
;                     for (int bj = 0; bj < 2; ++bj) { const u32x4 w = rb[ai][m][bj];
;                         finish((f32x4){bf_lo(w.x), bf_hi(w.x), bf_lo(w.y), bf_hi(w.y)} + acc[ai][bj][m][0], (f32x4){bf_lo(w.z), bf_hi(w.z), bf_lo(w.w), bf_hi(w.w)} + acc[ai][bj][m][1], row, col0 + bj * 128, s); }
;                     if (!OUT_F32) { s += __shfl_xor(s, 16); s += __shfl_xor(s, 32); if (fq == 0) atomicAdd(ssq_next + row, s); }
.LBB0_882:
	s_lshl_b32 s0, s48, 8
	v_mov_b32_e32 v96, v230
	v_mov_b32_e32 v219, v229
	s_or_b32 s0, s0, s37
	s_nop 0
	v_lshl_add_u32 v218, v219, 3, s0
	s_lshl_b32 s0, s45, 8
	s_add_i32 s0, s0, s33
	v_add_u32_e32 v220, s0, v96
	v_lshlrev_b32_e32 v96, 11, v220
	v_lshl_add_u32 v96, v218, 1, v96
	v_lshl_add_u64 v[118:119], s[90:91], 0, v[96:97]
	global_load_dwordx4 v[190:193], v[118:119], off nt
	v_add_u32_e32 v118, 0x100, v96
	v_mov_b32_e32 v119, v97
	v_lshl_add_u64 v[118:119], s[90:91], 0, v[118:119]
	global_load_dwordx4 v[186:189], v[118:119], off nt
	v_add_u32_e32 v118, 0x8000, v96
	v_mov_b32_e32 v119, v97
	v_lshl_add_u64 v[118:119], s[90:91], 0, v[118:119]
	global_load_dwordx4 v[182:185], v[118:119], off nt
	v_add_u32_e32 v118, 0x8100, v96
	v_mov_b32_e32 v119, v97
	v_lshl_add_u64 v[118:119], s[90:91], 0, v[118:119]
	global_load_dwordx4 v[178:181], v[118:119], off nt
	v_add_u32_e32 v118, 0x10000, v96
	v_mov_b32_e32 v119, v97
	v_lshl_add_u64 v[118:119], s[90:91], 0, v[118:119]
	global_load_dwordx4 v[174:177], v[118:119], off nt
	v_add_u32_e32 v118, 0x10100, v96
	v_mov_b32_e32 v119, v97
	v_lshl_add_u64 v[118:119], s[90:91], 0, v[118:119]
	global_load_dwordx4 v[170:173], v[118:119], off nt
	v_add_u32_e32 v118, 0x18000, v96
	v_mov_b32_e32 v119, v97
	v_lshl_add_u64 v[118:119], s[90:91], 0, v[118:119]
	global_load_dwordx4 v[166:169], v[118:119], off nt
	v_add_u32_e32 v118, 0x18100, v96
	v_mov_b32_e32 v119, v97
	v_lshl_add_u64 v[118:119], s[90:91], 0, v[118:119]
	global_load_dwordx4 v[162:165], v[118:119], off nt
	v_add_u32_e32 v118, 0x40000, v96
	v_mov_b32_e32 v119, v97
	v_lshl_add_u64 v[118:119], s[90:91], 0, v[118:119]
	global_load_dwordx4 v[158:161], v[118:119], off nt
	v_add_u32_e32 v118, 0x40100, v96
	v_mov_b32_e32 v119, v97
	v_lshl_add_u64 v[118:119], s[90:91], 0, v[118:119]
	global_load_dwordx4 v[154:157], v[118:119], off nt
	v_add_u32_e32 v118, 0x48000, v96
	v_mov_b32_e32 v119, v97
	v_lshl_add_u64 v[118:119], s[90:91], 0, v[118:119]
	global_load_dwordx4 v[150:153], v[118:119], off nt
	v_add_u32_e32 v118, 0x48100, v96
	v_mov_b32_e32 v119, v97
	v_lshl_add_u64 v[118:119], s[90:91], 0, v[118:119]
	global_load_dwordx4 v[146:149], v[118:119], off nt
	v_add_u32_e32 v118, 0x50000, v96
	v_mov_b32_e32 v119, v97
	v_lshl_add_u64 v[118:119], s[90:91], 0, v[118:119]
	global_load_dwordx4 v[134:137], v[118:119], off nt
	v_add_u32_e32 v118, 0x50100, v96
	v_mov_b32_e32 v119, v97
	v_lshl_add_u64 v[118:119], s[90:91], 0, v[118:119]
	global_load_dwordx4 v[126:129], v[118:119], off nt
	v_add_u32_e32 v118, 0x58000, v96
	v_mov_b32_e32 v119, v97
	v_add_u32_e32 v96, 0x58100, v96
	v_lshl_add_u64 v[118:119], s[90:91], 0, v[118:119]
	v_lshl_add_u64 v[138:139], s[90:91], 0, v[96:97]
	global_load_dwordx4 v[118:121], v[118:119], off nt
	v_ashrrev_i32_e32 v221, 31, v220
	global_load_dwordx4 v[138:141], v[138:139], off nt
	v_lshlrev_b64 v[234:235], 11, v[220:221]
	v_cmp_eq_u32_e32 vcc, 0, v219
	v_lshl_add_u64 v[234:235], s[90:91], 0, v[234:235]
	v_ashrrev_i32_e32 v219, 31, v218
	v_lshl_add_u64 v[234:235], v[218:219], 1, v[234:235]
	s_waitcnt vmcnt(0) lgkmcnt(0)
	v_lshlrev_b32_e32 v236, 16, v190
	v_and_b32_e32 v237, 0xffff0000, v190
	v_lshlrev_b32_e32 v190, 16, v191
	v_and_b32_e32 v191, 0xffff0000, v191
	v_pk_add_f32 v[144:145], v[144:145], v[190:191]
	v_lshlrev_b32_e32 v190, 16, v192
	v_and_b32_e32 v191, 0xffff0000, v192
	v_pk_add_f32 v[142:143], v[142:143], v[236:237]
	v_lshlrev_b32_e32 v192, 16, v193
	v_and_b32_e32 v193, 0xffff0000, v193
	v_pk_add_f32 v[190:191], v[130:131], v[190:191]
	v_cvt_pk_bf16_f32 v130, v142, v143
	v_pk_add_f32 v[192:193], v[132:133], v[192:193]
	v_cvt_pk_bf16_f32 v131, v144, v145
	v_cvt_pk_bf16_f32 v132, v190, v191
	v_mul_f32_e32 v96, v143, v143
	v_cvt_pk_bf16_f32 v133, v192, v193
	global_store_dwordx4 v[234:235], v[130:133], off nt
	v_fmac_f32_e32 v96, v142, v142
	s_nop 0
	v_mul_f32_e32 v130, v145, v145
	v_fmac_f32_e32 v130, v144, v144
	v_add_f32_e32 v96, v96, v130
	v_mul_f32_e32 v130, v191, v191
	v_fmac_f32_e32 v130, v190, v190
	v_add_f32_e32 v96, v130, v96
	v_mul_f32_e32 v130, v193, v193
	v_fmac_f32_e32 v130, v192, v192
	v_add_f32_e32 v96, v130, v96
	v_lshlrev_b32_e32 v130, 16, v186
	v_and_b32_e32 v131, 0xffff0000, v186
	v_lshlrev_b32_e32 v132, 16, v187
	v_and_b32_e32 v133, 0xffff0000, v187
	v_pk_add_f32 v[122:123], v[122:123], v[130:131]
	v_lshlrev_b32_e32 v130, 16, v188
	v_and_b32_e32 v131, 0xffff0000, v188
	v_pk_add_f32 v[124:125], v[124:125], v[132:133]
	v_lshlrev_b32_e32 v132, 16, v189
	v_and_b32_e32 v133, 0xffff0000, v189
	v_pk_add_f32 v[130:131], v[114:115], v[130:131]
	v_cvt_pk_bf16_f32 v114, v122, v123
	v_cvt_pk_bf16_f32 v115, v124, v125
	v_pk_add_f32 v[132:133], v[116:117], v[132:133]
	v_cvt_pk_bf16_f32 v116, v130, v131
	s_nop 0
	v_cvt_pk_bf16_f32 v117, v132, v133
	global_store_dwordx4 v[234:235], v[114:117], off offset:256 nt
	s_nop 1
	v_mul_f32_e32 v114, v123, v123
	v_mul_f32_e32 v115, v125, v125
	v_fmac_f32_e32 v114, v122, v122
	v_fmac_f32_e32 v115, v124, v124
	v_add_f32_e32 v114, v114, v115
	v_mul_f32_e32 v115, v131, v131
	v_fmac_f32_e32 v115, v130, v130
	v_add_f32_e32 v114, v115, v114
	v_mul_f32_e32 v115, v133, v133
	v_fmac_f32_e32 v115, v132, v132
	v_add_f32_e32 v114, v115, v114
	v_and_b32_e32 v115, 64, v225
	v_add_f32_e32 v114, v96, v114
	v_xor_b32_e32 v96, 16, v225
	v_add_u32_e32 v115, 64, v115
	v_cmp_lt_i32_e64 s[0:1], v96, v115
	s_nop 1
	v_cndmask_b32_e64 v96, v225, v96, s[0:1]
	v_lshlrev_b32_e32 v96, 2, v96
	ds_bpermute_b32 v116, v96, v114
	s_waitcnt lgkmcnt(0)
	v_add_f32_e32 v114, v114, v116
	v_xor_b32_e32 v116, 32, v225
	v_cmp_lt_i32_e64 s[0:1], v116, v115
	s_nop 1
	v_cndmask_b32_e64 v115, v225, v116, s[0:1]
	v_lshlrev_b32_e32 v116, 2, v115
	ds_bpermute_b32 v115, v116, v114
	s_and_saveexec_b64 s[0:1], vcc
	s_cbranch_execz .LBB0_884
	v_lshl_add_u64 v[122:123], v[220:221], 2, s[2:3]
	s_waitcnt lgkmcnt(0)
	v_add_f32_e32 v114, v114, v115
	global_atomic_add_f32 v[122:123], v114, off
; __device__ __forceinline__ unsigned cvt_pk_bf16(float lo, float hi) { unsigned r; asm volatile("v_cvt_pk_bf16_f32 %0, %1, %2" : "=v"(r) : "v"(lo), "v"(hi)); return r; }
;     __device__ __forceinline__ void finish(const f32x4 x0, const f32x4 x1, int row, int col, float& s) const {
;         if (OUT_F32) { *(f32x4*)(out + (size_t)row * DM + col) = x0; *(f32x4*)(out + (size_t)row * DM + col + 4) = x1; }
;         else { u32x4 w; w.x = cvt_pk_bf16(x0[0], x0[1]); w.y = cvt_pk_bf16(x0[2], x0[3]); w.z = cvt_pk_bf16(x1[0], x1[1]); w.w = cvt_pk_bf16(x1[2], x1[3]); *(u32x4*)(XB + (size_t)row * DM + col) = w; }
;         s += (x0[0] * x0[0] + x0[1] * x0[1]) + (x0[2] * x0[2] + x0[3] * x0[3]) + (x1[0] * x1[0] + x1[1] * x1[1]) + (x1[2] * x1[2] + x1[3] * x1[3]);
;     __device__ __forceinline__ void operator()(AccT& acc, const Unit& u, int wr, int wc, int fr, int fq) const {
;     ...
;             for (int ai = 0; ai < 2; ++ai)
; #pragma unroll
;                 for (int m = 0; m < 4; ++m) {
;                     const int row = u.pm * 256 + ai * 128 + wr * 64 + m * 16 + fr; float s = 0.f;
; #pragma unroll
;                     for (int bj = 0; bj < 2; ++bj) { const u32x4 w = rb[ai][m][bj];
;                         finish((f32x4){bf_lo(w.x), bf_hi(w.x), bf_lo(w.y), bf_hi(w.y)} + acc[ai][bj][m][0], (f32x4){bf_lo(w.z), bf_hi(w.z), bf_lo(w.w), bf_hi(w.w)} + acc[ai][bj][m][1], row, col0 + bj * 128, s); }
;                     if (!OUT_F32) { s += __shfl_xor(s, 16); s += __shfl_xor(s, 32); if (fq == 0) atomicAdd(ssq_next + row, s); }
.LBB0_884:
	s_or_b64 exec, exec, s[0:1]
	v_lshlrev_b32_e32 v124, 16, v182
	v_and_b32_e32 v125, 0xffff0000, v182
	v_lshlrev_b32_e32 v130, 16, v183
	v_and_b32_e32 v131, 0xffff0000, v183
	v_pk_add_f32 v[110:111], v[110:111], v[124:125]
	v_lshlrev_b32_e32 v124, 16, v184
	v_and_b32_e32 v125, 0xffff0000, v184
	v_pk_add_f32 v[112:113], v[112:113], v[130:131]
	v_pk_add_f32 v[124:125], v[106:107], v[124:125]
	v_cvt_pk_bf16_f32 v106, v110, v111
	v_mul_f32_e32 v111, v111, v111
	v_fmac_f32_e32 v111, v110, v110
	v_mul_f32_e32 v110, v113, v113
	v_fmac_f32_e32 v110, v112, v112
	v_lshlrev_b32_e32 v130, 16, v185
	v_and_b32_e32 v131, 0xffff0000, v185
	v_add_f32_e32 v110, v111, v110
	v_mul_f32_e32 v111, v125, v125
	v_pk_add_f32 v[130:131], v[108:109], v[130:131]
	v_fmac_f32_e32 v111, v124, v124
	v_add_f32_e32 v110, v111, v110
	v_mul_f32_e32 v111, v131, v131
	v_fmac_f32_e32 v111, v130, v130
	v_cvt_pk_bf16_f32 v107, v112, v113
	v_add_f32_e32 v117, v111, v110
	v_lshlrev_b32_e32 v110, 16, v178
	v_and_b32_e32 v111, 0xffff0000, v178
	v_lshlrev_b32_e32 v112, 16, v179
	v_and_b32_e32 v113, 0xffff0000, v179
	v_pk_add_f32 v[104:105], v[104:105], v[112:113]
	v_pk_add_f32 v[102:103], v[102:103], v[110:111]
	v_lshlrev_b32_e32 v110, 16, v180
	v_and_b32_e32 v111, 0xffff0000, v180
	v_pk_add_f32 v[110:111], v[98:99], v[110:111]
	v_mul_f32_e32 v98, v103, v103
	v_mul_f32_e32 v99, v105, v105
	v_fmac_f32_e32 v98, v102, v102
	v_fmac_f32_e32 v99, v104, v104
	v_lshlrev_b32_e32 v112, 16, v181
	v_and_b32_e32 v113, 0xffff0000, v181
	v_add_f32_e32 v98, v98, v99
	v_mul_f32_e32 v99, v111, v111
	v_pk_add_f32 v[112:113], v[100:101], v[112:113]
	v_fmac_f32_e32 v99, v110, v110
	v_add_f32_e32 v98, v99, v98
	v_mul_f32_e32 v99, v113, v113
	v_fmac_f32_e32 v99, v112, v112
	v_add_f32_e32 v98, v99, v98
	v_add_f32_e32 v101, v117, v98
	ds_bpermute_b32 v117, v96, v101
	v_add_u32_e32 v114, 16, v220
	s_waitcnt lgkmcnt(0)
	v_ashrrev_i32_e32 v115, 31, v114
	v_lshlrev_b64 v[122:123], 11, v[114:115]
	v_lshl_add_u64 v[98:99], s[90:91], 0, v[122:123]
	v_lshl_add_u64 v[122:123], v[218:219], 1, v[98:99]
	v_add_f32_e32 v98, v101, v117
	ds_bpermute_b32 v99, v116, v98
	v_cvt_pk_bf16_f32 v108, v124, v125
	v_cvt_pk_bf16_f32 v109, v130, v131
	global_store_dwordx4 v[122:123], v[106:109], off nt
	v_cvt_pk_bf16_f32 v100, v102, v103
	v_cvt_pk_bf16_f32 v101, v104, v105
	v_cvt_pk_bf16_f32 v102, v110, v111
	v_cvt_pk_bf16_f32 v103, v112, v113
	global_store_dwordx4 v[122:123], v[100:103], off offset:256 nt
	s_and_saveexec_b64 s[0:1], vcc
	s_cbranch_execz .LBB0_886
	v_lshl_add_u64 v[100:101], v[114:115], 2, s[2:3]
	s_waitcnt lgkmcnt(0)
	v_add_f32_e32 v98, v98, v99
	global_atomic_add_f32 v[100:101], v98, off
.LBB0_886:
	s_or_b64 exec, exec, s[0:1]
	v_lshlrev_b32_e32 v102, 16, v174
	v_and_b32_e32 v103, 0xffff0000, v174
	v_lshlrev_b32_e32 v104, 16, v175
	v_and_b32_e32 v105, 0xffff0000, v175
	v_pk_add_f32 v[92:93], v[92:93], v[102:103]
	v_lshlrev_b32_e32 v102, 16, v176
	v_and_b32_e32 v103, 0xffff0000, v176
	v_pk_add_f32 v[94:95], v[94:95], v[104:105]
	v_pk_add_f32 v[102:103], v[88:89], v[102:103]
	v_cvt_pk_bf16_f32 v88, v92, v93
	v_mul_f32_e32 v93, v93, v93
	v_fmac_f32_e32 v93, v92, v92
	v_mul_f32_e32 v92, v95, v95
	v_fmac_f32_e32 v92, v94, v94
	v_lshlrev_b32_e32 v104, 16, v177
	v_and_b32_e32 v105, 0xffff0000, v177
	v_add_f32_e32 v92, v93, v92
	v_mul_f32_e32 v93, v103, v103
	v_pk_add_f32 v[104:105], v[90:91], v[104:105]
	v_fmac_f32_e32 v93, v102, v102
	v_add_f32_e32 v92, v93, v92
	v_mul_f32_e32 v93, v105, v105
	v_fmac_f32_e32 v93, v104, v104
	v_cvt_pk_bf16_f32 v89, v94, v95
	v_cvt_pk_bf16_f32 v90, v102, v103
	v_add_f32_e32 v102, v93, v92
	v_lshlrev_b32_e32 v92, 16, v170
	v_and_b32_e32 v93, 0xffff0000, v170
	v_lshlrev_b32_e32 v94, 16, v171
	v_and_b32_e32 v95, 0xffff0000, v171
	v_pk_add_f32 v[86:87], v[86:87], v[94:95]
	v_pk_add_f32 v[84:85], v[84:85], v[92:93]
	v_lshlrev_b32_e32 v92, 16, v172
	v_and_b32_e32 v93, 0xffff0000, v172
	v_pk_add_f32 v[92:93], v[80:81], v[92:93]
	v_mul_f32_e32 v80, v85, v85
	v_mul_f32_e32 v81, v87, v87
	v_fmac_f32_e32 v80, v84, v84
	v_fmac_f32_e32 v81, v86, v86
	v_lshlrev_b32_e32 v94, 16, v173
	v_and_b32_e32 v95, 0xffff0000, v173
	v_add_f32_e32 v80, v80, v81
	v_mul_f32_e32 v81, v93, v93
	v_pk_add_f32 v[94:95], v[82:83], v[94:95]
	v_fmac_f32_e32 v81, v92, v92
	v_add_f32_e32 v80, v81, v80
	v_mul_f32_e32 v81, v95, v95
	v_fmac_f32_e32 v81, v94, v94
	v_add_f32_e32 v80, v81, v80
	v_add_f32_e32 v83, v102, v80
	ds_bpermute_b32 v102, v96, v83
	v_add_u32_e32 v98, 32, v220
	s_waitcnt lgkmcnt(0)
	v_ashrrev_i32_e32 v99, 31, v98
	v_lshlrev_b64 v[100:101], 11, v[98:99]
	v_lshl_add_u64 v[80:81], s[90:91], 0, v[100:101]
	v_lshl_add_u64 v[100:101], v[218:219], 1, v[80:81]
	v_add_f32_e32 v80, v83, v102
	ds_bpermute_b32 v81, v116, v80
	v_cvt_pk_bf16_f32 v91, v104, v105
	global_store_dwordx4 v[100:101], v[88:91], off nt
	v_cvt_pk_bf16_f32 v82, v84, v85
	v_cvt_pk_bf16_f32 v83, v86, v87
	v_cvt_pk_bf16_f32 v84, v92, v93
	v_cvt_pk_bf16_f32 v85, v94, v95
	global_store_dwordx4 v[100:101], v[82:85], off offset:256 nt
	s_and_saveexec_b64 s[0:1], vcc
	s_cbranch_execz .LBB0_888
	v_lshl_add_u64 v[82:83], v[98:99], 2, s[2:3]
	s_waitcnt lgkmcnt(0)
	v_add_f32_e32 v80, v80, v81
	global_atomic_add_f32 v[82:83], v80, off
; __device__ __forceinline__ unsigned cvt_pk_bf16(float lo, float hi) { unsigned r; asm volatile("v_cvt_pk_bf16_f32 %0, %1, %2" : "=v"(r) : "v"(lo), "v"(hi)); return r; }
;     __device__ __forceinline__ void finish(const f32x4 x0, const f32x4 x1, int row, int col, float& s) const {
;         if (OUT_F32) { *(f32x4*)(out + (size_t)row * DM + col) = x0; *(f32x4*)(out + (size_t)row * DM + col + 4) = x1; }
;         else { u32x4 w; w.x = cvt_pk_bf16(x0[0], x0[1]); w.y = cvt_pk_bf16(x0[2], x0[3]); w.z = cvt_pk_bf16(x1[0], x1[1]); w.w = cvt_pk_bf16(x1[2], x1[3]); *(u32x4*)(XB + (size_t)row * DM + col) = w; }
;         s += (x0[0] * x0[0] + x0[1] * x0[1]) + (x0[2] * x0[2] + x0[3] * x0[3]) + (x1[0] * x1[0] + x1[1] * x1[1]) + (x1[2] * x1[2] + x1[3] * x1[3]);
;     __device__ __forceinline__ void operator()(AccT& acc, const Unit& u, int wr, int wc, int fr, int fq) const {
;     ...
;             for (int ai = 0; ai < 2; ++ai)
; #pragma unroll
;                 for (int m = 0; m < 4; ++m) {
;                     const int row = u.pm * 256 + ai * 128 + wr * 64 + m * 16 + fr; float s = 0.f;
; #pragma unroll
;                     for (int bj = 0; bj < 2; ++bj) { const u32x4 w = rb[ai][m][bj];
;                         finish((f32x4){bf_lo(w.x), bf_hi(w.x), bf_lo(w.y), bf_hi(w.y)} + acc[ai][bj][m][0], (f32x4){bf_lo(w.z), bf_hi(w.z), bf_lo(w.w), bf_hi(w.w)} + acc[ai][bj][m][1], row, col0 + bj * 128, s); }
;                     if (!OUT_F32) { s += __shfl_xor(s, 16); s += __shfl_xor(s, 32); if (fq == 0) atomicAdd(ssq_next + row, s); }
.LBB0_888:
	s_or_b64 exec, exec, s[0:1]
	v_lshlrev_b32_e32 v84, 16, v166
	v_and_b32_e32 v85, 0xffff0000, v166
	v_lshlrev_b32_e32 v86, 16, v167
	v_and_b32_e32 v87, 0xffff0000, v167
	v_pk_add_f32 v[76:77], v[76:77], v[84:85]
	v_lshlrev_b32_e32 v84, 16, v168
	v_and_b32_e32 v85, 0xffff0000, v168
	v_pk_add_f32 v[78:79], v[78:79], v[86:87]
	v_pk_add_f32 v[84:85], v[72:73], v[84:85]
	v_cvt_pk_bf16_f32 v72, v76, v77
	v_mul_f32_e32 v77, v77, v77
	v_fmac_f32_e32 v77, v76, v76
	v_mul_f32_e32 v76, v79, v79
	v_fmac_f32_e32 v76, v78, v78
	v_lshlrev_b32_e32 v86, 16, v169
	v_and_b32_e32 v87, 0xffff0000, v169
	v_add_f32_e32 v76, v77, v76
	v_mul_f32_e32 v77, v85, v85
	v_pk_add_f32 v[86:87], v[74:75], v[86:87]
	v_fmac_f32_e32 v77, v84, v84
	v_add_f32_e32 v76, v77, v76
	v_mul_f32_e32 v77, v87, v87
	v_fmac_f32_e32 v77, v86, v86
	v_cvt_pk_bf16_f32 v73, v78, v79
	v_cvt_pk_bf16_f32 v74, v84, v85
	v_add_f32_e32 v84, v77, v76
	v_lshlrev_b32_e32 v76, 16, v162
	v_and_b32_e32 v77, 0xffff0000, v162
	v_lshlrev_b32_e32 v78, 16, v163
	v_and_b32_e32 v79, 0xffff0000, v163
	v_pk_add_f32 v[70:71], v[70:71], v[78:79]
	v_pk_add_f32 v[68:69], v[68:69], v[76:77]
	v_lshlrev_b32_e32 v76, 16, v164
	v_and_b32_e32 v77, 0xffff0000, v164
	v_pk_add_f32 v[76:77], v[64:65], v[76:77]
	v_mul_f32_e32 v64, v69, v69
	v_mul_f32_e32 v65, v71, v71
	v_fmac_f32_e32 v64, v68, v68
	v_fmac_f32_e32 v65, v70, v70
	v_lshlrev_b32_e32 v78, 16, v165
	v_and_b32_e32 v79, 0xffff0000, v165
	v_add_f32_e32 v64, v64, v65
	v_mul_f32_e32 v65, v77, v77
	v_pk_add_f32 v[78:79], v[66:67], v[78:79]
	v_fmac_f32_e32 v65, v76, v76
	v_add_f32_e32 v64, v65, v64
	v_mul_f32_e32 v65, v79, v79
	v_fmac_f32_e32 v65, v78, v78
	v_add_f32_e32 v64, v65, v64
	v_add_f32_e32 v67, v84, v64
	ds_bpermute_b32 v84, v96, v67
	v_add_u32_e32 v80, 48, v220
	s_waitcnt lgkmcnt(0)
	v_ashrrev_i32_e32 v81, 31, v80
	v_lshlrev_b64 v[82:83], 11, v[80:81]
	v_lshl_add_u64 v[64:65], s[90:91], 0, v[82:83]
	v_lshl_add_u64 v[82:83], v[218:219], 1, v[64:65]
	v_add_f32_e32 v64, v67, v84
	ds_bpermute_b32 v65, v116, v64
	v_cvt_pk_bf16_f32 v75, v86, v87
	global_store_dwordx4 v[82:83], v[72:75], off nt
	v_cvt_pk_bf16_f32 v66, v68, v69
	v_cvt_pk_bf16_f32 v67, v70, v71
	v_cvt_pk_bf16_f32 v68, v76, v77
	v_cvt_pk_bf16_f32 v69, v78, v79
	global_store_dwordx4 v[82:83], v[66:69], off offset:256 nt
	s_and_saveexec_b64 s[0:1], vcc
	s_cbranch_execz .LBB0_890
	v_lshl_add_u64 v[66:67], v[80:81], 2, s[2:3]
	s_waitcnt lgkmcnt(0)
	v_add_f32_e32 v64, v64, v65
	global_atomic_add_f32 v[66:67], v64, off
.LBB0_890:
	s_or_b64 exec, exec, s[0:1]
	v_lshlrev_b32_e32 v68, 16, v158
	v_and_b32_e32 v69, 0xffff0000, v158
	v_lshlrev_b32_e32 v70, 16, v159
	v_and_b32_e32 v71, 0xffff0000, v159
	v_pk_add_f32 v[60:61], v[60:61], v[68:69]
	v_lshlrev_b32_e32 v68, 16, v160
	v_and_b32_e32 v69, 0xffff0000, v160
	v_pk_add_f32 v[62:63], v[62:63], v[70:71]
	v_pk_add_f32 v[68:69], v[56:57], v[68:69]
	v_cvt_pk_bf16_f32 v56, v60, v61
	v_mul_f32_e32 v61, v61, v61
	v_fmac_f32_e32 v61, v60, v60
	v_mul_f32_e32 v60, v63, v63
	v_fmac_f32_e32 v60, v62, v62
	v_lshlrev_b32_e32 v70, 16, v161
	v_and_b32_e32 v71, 0xffff0000, v161
	v_add_f32_e32 v60, v61, v60
	v_mul_f32_e32 v61, v69, v69
	v_pk_add_f32 v[70:71], v[58:59], v[70:71]
	v_fmac_f32_e32 v61, v68, v68
	v_add_f32_e32 v60, v61, v60
	v_mul_f32_e32 v61, v71, v71
	v_fmac_f32_e32 v61, v70, v70
	v_cvt_pk_bf16_f32 v57, v62, v63
	v_cvt_pk_bf16_f32 v58, v68, v69
	v_add_f32_e32 v68, v61, v60
	v_lshlrev_b32_e32 v60, 16, v154
	v_and_b32_e32 v61, 0xffff0000, v154
	v_lshlrev_b32_e32 v62, 16, v155
	v_and_b32_e32 v63, 0xffff0000, v155
	v_pk_add_f32 v[54:55], v[54:55], v[62:63]
	v_pk_add_f32 v[52:53], v[52:53], v[60:61]
	v_lshlrev_b32_e32 v60, 16, v156
	v_and_b32_e32 v61, 0xffff0000, v156
	v_pk_add_f32 v[60:61], v[48:49], v[60:61]
	v_mul_f32_e32 v48, v53, v53
	v_mul_f32_e32 v49, v55, v55
	v_fmac_f32_e32 v48, v52, v52
	v_fmac_f32_e32 v49, v54, v54
	v_lshlrev_b32_e32 v62, 16, v157
	v_and_b32_e32 v63, 0xffff0000, v157
	v_add_f32_e32 v48, v48, v49
	v_mul_f32_e32 v49, v61, v61
	v_pk_add_f32 v[62:63], v[50:51], v[62:63]
	v_fmac_f32_e32 v49, v60, v60
	v_add_f32_e32 v48, v49, v48
	v_mul_f32_e32 v49, v63, v63
	v_fmac_f32_e32 v49, v62, v62
	v_add_f32_e32 v48, v49, v48
	v_add_f32_e32 v51, v68, v48
	ds_bpermute_b32 v68, v96, v51
	v_add_u32_e32 v64, 0x80, v220
	s_waitcnt lgkmcnt(0)
	v_ashrrev_i32_e32 v65, 31, v64
	v_lshlrev_b64 v[66:67], 11, v[64:65]
	v_lshl_add_u64 v[48:49], s[90:91], 0, v[66:67]
	v_lshl_add_u64 v[66:67], v[218:219], 1, v[48:49]
	v_add_f32_e32 v48, v51, v68
	ds_bpermute_b32 v49, v116, v48
	v_cvt_pk_bf16_f32 v59, v70, v71
	global_store_dwordx4 v[66:67], v[56:59], off nt
	v_cvt_pk_bf16_f32 v50, v52, v53
	v_cvt_pk_bf16_f32 v51, v54, v55
	v_cvt_pk_bf16_f32 v52, v60, v61
	v_cvt_pk_bf16_f32 v53, v62, v63
	global_store_dwordx4 v[66:67], v[50:53], off offset:256 nt
	s_and_saveexec_b64 s[0:1], vcc
	s_cbranch_execz .LBB0_892
	v_lshl_add_u64 v[50:51], v[64:65], 2, s[2:3]
	s_waitcnt lgkmcnt(0)
	v_add_f32_e32 v48, v48, v49
	global_atomic_add_f32 v[50:51], v48, off
; __device__ __forceinline__ unsigned cvt_pk_bf16(float lo, float hi) { unsigned r; asm volatile("v_cvt_pk_bf16_f32 %0, %1, %2" : "=v"(r) : "v"(lo), "v"(hi)); return r; }
;     __device__ __forceinline__ void finish(const f32x4 x0, const f32x4 x1, int row, int col, float& s) const {
;         if (OUT_F32) { *(f32x4*)(out + (size_t)row * DM + col) = x0; *(f32x4*)(out + (size_t)row * DM + col + 4) = x1; }
;         else { u32x4 w; w.x = cvt_pk_bf16(x0[0], x0[1]); w.y = cvt_pk_bf16(x0[2], x0[3]); w.z = cvt_pk_bf16(x1[0], x1[1]); w.w = cvt_pk_bf16(x1[2], x1[3]); *(u32x4*)(XB + (size_t)row * DM + col) = w; }
;         s += (x0[0] * x0[0] + x0[1] * x0[1]) + (x0[2] * x0[2] + x0[3] * x0[3]) + (x1[0] * x1[0] + x1[1] * x1[1]) + (x1[2] * x1[2] + x1[3] * x1[3]);
;     __device__ __forceinline__ void operator()(AccT& acc, const Unit& u, int wr, int wc, int fr, int fq) const {
;     ...
;             for (int ai = 0; ai < 2; ++ai)
; #pragma unroll
;                 for (int m = 0; m < 4; ++m) {
;                     const int row = u.pm * 256 + ai * 128 + wr * 64 + m * 16 + fr; float s = 0.f;
; #pragma unroll
;                     for (int bj = 0; bj < 2; ++bj) { const u32x4 w = rb[ai][m][bj];
;                         finish((f32x4){bf_lo(w.x), bf_hi(w.x), bf_lo(w.y), bf_hi(w.y)} + acc[ai][bj][m][0], (f32x4){bf_lo(w.z), bf_hi(w.z), bf_lo(w.w), bf_hi(w.w)} + acc[ai][bj][m][1], row, col0 + bj * 128, s); }
;                     if (!OUT_F32) { s += __shfl_xor(s, 16); s += __shfl_xor(s, 32); if (fq == 0) atomicAdd(ssq_next + row, s); }
.LBB0_892:
	s_or_b64 exec, exec, s[0:1]
	v_lshlrev_b32_e32 v52, 16, v150
	v_and_b32_e32 v53, 0xffff0000, v150
	v_lshlrev_b32_e32 v54, 16, v151
	v_and_b32_e32 v55, 0xffff0000, v151
	v_pk_add_f32 v[44:45], v[44:45], v[52:53]
	v_lshlrev_b32_e32 v52, 16, v152
	v_and_b32_e32 v53, 0xffff0000, v152
	v_pk_add_f32 v[46:47], v[46:47], v[54:55]
	v_pk_add_f32 v[52:53], v[40:41], v[52:53]
	v_cvt_pk_bf16_f32 v40, v44, v45
	v_mul_f32_e32 v45, v45, v45
	v_fmac_f32_e32 v45, v44, v44
	v_mul_f32_e32 v44, v47, v47
	v_fmac_f32_e32 v44, v46, v46
	v_lshlrev_b32_e32 v54, 16, v153
	v_and_b32_e32 v55, 0xffff0000, v153
	v_add_f32_e32 v44, v45, v44
	v_mul_f32_e32 v45, v53, v53
	v_pk_add_f32 v[54:55], v[42:43], v[54:55]
	v_fmac_f32_e32 v45, v52, v52
	v_add_f32_e32 v44, v45, v44
	v_mul_f32_e32 v45, v55, v55
	v_fmac_f32_e32 v45, v54, v54
	v_cvt_pk_bf16_f32 v41, v46, v47
	v_cvt_pk_bf16_f32 v42, v52, v53
	v_add_f32_e32 v52, v45, v44
	v_lshlrev_b32_e32 v44, 16, v146
	v_and_b32_e32 v45, 0xffff0000, v146
	v_lshlrev_b32_e32 v46, 16, v147
	v_and_b32_e32 v47, 0xffff0000, v147
	v_pk_add_f32 v[38:39], v[38:39], v[46:47]
	v_pk_add_f32 v[36:37], v[36:37], v[44:45]
	v_lshlrev_b32_e32 v44, 16, v148
	v_and_b32_e32 v45, 0xffff0000, v148
	v_pk_add_f32 v[44:45], v[32:33], v[44:45]
	v_mul_f32_e32 v32, v37, v37
	v_mul_f32_e32 v33, v39, v39
	v_fmac_f32_e32 v32, v36, v36
	v_fmac_f32_e32 v33, v38, v38
	v_lshlrev_b32_e32 v46, 16, v149
	v_and_b32_e32 v47, 0xffff0000, v149
	v_add_f32_e32 v32, v32, v33
	v_mul_f32_e32 v33, v45, v45
	v_pk_add_f32 v[46:47], v[34:35], v[46:47]
	v_fmac_f32_e32 v33, v44, v44
	v_add_f32_e32 v32, v33, v32
	v_mul_f32_e32 v33, v47, v47
	v_fmac_f32_e32 v33, v46, v46
	v_add_f32_e32 v32, v33, v32
	v_add_f32_e32 v35, v52, v32
	ds_bpermute_b32 v52, v96, v35
	v_add_u32_e32 v48, 0x90, v220
	s_waitcnt lgkmcnt(0)
	v_ashrrev_i32_e32 v49, 31, v48
	v_lshlrev_b64 v[50:51], 11, v[48:49]
	v_lshl_add_u64 v[32:33], s[90:91], 0, v[50:51]
	v_lshl_add_u64 v[50:51], v[218:219], 1, v[32:33]
	v_add_f32_e32 v32, v35, v52
	ds_bpermute_b32 v33, v116, v32
	v_cvt_pk_bf16_f32 v43, v54, v55
	global_store_dwordx4 v[50:51], v[40:43], off nt
	v_cvt_pk_bf16_f32 v34, v36, v37
	v_cvt_pk_bf16_f32 v35, v38, v39
	v_cvt_pk_bf16_f32 v36, v44, v45
	v_cvt_pk_bf16_f32 v37, v46, v47
	global_store_dwordx4 v[50:51], v[34:37], off offset:256 nt
	s_and_saveexec_b64 s[0:1], vcc
	s_cbranch_execz .LBB0_894
	v_lshl_add_u64 v[34:35], v[48:49], 2, s[2:3]
	s_waitcnt lgkmcnt(0)
	v_add_f32_e32 v32, v32, v33
	global_atomic_add_f32 v[34:35], v32, off
; __device__ __forceinline__ unsigned cvt_pk_bf16(float lo, float hi) { unsigned r; asm volatile("v_cvt_pk_bf16_f32 %0, %1, %2" : "=v"(r) : "v"(lo), "v"(hi)); return r; }
;     __device__ __forceinline__ void finish(const f32x4 x0, const f32x4 x1, int row, int col, float& s) const {
;         if (OUT_F32) { *(f32x4*)(out + (size_t)row * DM + col) = x0; *(f32x4*)(out + (size_t)row * DM + col + 4) = x1; }
;         else { u32x4 w; w.x = cvt_pk_bf16(x0[0], x0[1]); w.y = cvt_pk_bf16(x0[2], x0[3]); w.z = cvt_pk_bf16(x1[0], x1[1]); w.w = cvt_pk_bf16(x1[2], x1[3]); *(u32x4*)(XB + (size_t)row * DM + col) = w; }
;         s += (x0[0] * x0[0] + x0[1] * x0[1]) + (x0[2] * x0[2] + x0[3] * x0[3]) + (x1[0] * x1[0] + x1[1] * x1[1]) + (x1[2] * x1[2] + x1[3] * x1[3]);
;     __device__ __forceinline__ void operator()(AccT& acc, const Unit& u, int wr, int wc, int fr, int fq) const {
;     ...
;             for (int ai = 0; ai < 2; ++ai)
; #pragma unroll
;                 for (int m = 0; m < 4; ++m) {
;                     const int row = u.pm * 256 + ai * 128 + wr * 64 + m * 16 + fr; float s = 0.f;
; #pragma unroll
;                     for (int bj = 0; bj < 2; ++bj) { const u32x4 w = rb[ai][m][bj];
;                         finish((f32x4){bf_lo(w.x), bf_hi(w.x), bf_lo(w.y), bf_hi(w.y)} + acc[ai][bj][m][0], (f32x4){bf_lo(w.z), bf_hi(w.z), bf_lo(w.w), bf_hi(w.w)} + acc[ai][bj][m][1], row, col0 + bj * 128, s); }
;                     if (!OUT_F32) { s += __shfl_xor(s, 16); s += __shfl_xor(s, 32); if (fq == 0) atomicAdd(ssq_next + row, s); }
.LBB0_894:
	s_or_b64 exec, exec, s[0:1]
	v_lshlrev_b32_e32 v36, 16, v134
	v_and_b32_e32 v37, 0xffff0000, v134
	v_lshlrev_b32_e32 v38, 16, v135
	v_and_b32_e32 v39, 0xffff0000, v135
	v_pk_add_f32 v[28:29], v[28:29], v[36:37]
	v_lshlrev_b32_e32 v36, 16, v136
	v_and_b32_e32 v37, 0xffff0000, v136
	v_pk_add_f32 v[30:31], v[30:31], v[38:39]
	v_pk_add_f32 v[36:37], v[24:25], v[36:37]
	v_cvt_pk_bf16_f32 v24, v28, v29
	v_mul_f32_e32 v29, v29, v29
	v_fmac_f32_e32 v29, v28, v28
	v_mul_f32_e32 v28, v31, v31
	v_fmac_f32_e32 v28, v30, v30
	v_lshlrev_b32_e32 v38, 16, v137
	v_and_b32_e32 v39, 0xffff0000, v137
	v_add_f32_e32 v28, v29, v28
	v_mul_f32_e32 v29, v37, v37
	v_pk_add_f32 v[38:39], v[26:27], v[38:39]
	v_fmac_f32_e32 v29, v36, v36
	v_add_f32_e32 v28, v29, v28
	v_mul_f32_e32 v29, v39, v39
	v_fmac_f32_e32 v29, v38, v38
	v_cvt_pk_bf16_f32 v25, v30, v31
	v_cvt_pk_bf16_f32 v26, v36, v37
	v_add_f32_e32 v36, v29, v28
	v_lshlrev_b32_e32 v28, 16, v126
	v_and_b32_e32 v29, 0xffff0000, v126
	v_lshlrev_b32_e32 v30, 16, v127
	v_and_b32_e32 v31, 0xffff0000, v127
	v_pk_add_f32 v[22:23], v[22:23], v[30:31]
	v_pk_add_f32 v[20:21], v[20:21], v[28:29]
	v_lshlrev_b32_e32 v28, 16, v128
	v_and_b32_e32 v29, 0xffff0000, v128
	v_pk_add_f32 v[28:29], v[16:17], v[28:29]
	v_mul_f32_e32 v16, v21, v21
	v_mul_f32_e32 v17, v23, v23
	v_fmac_f32_e32 v16, v20, v20
	v_fmac_f32_e32 v17, v22, v22
	v_lshlrev_b32_e32 v30, 16, v129
	v_and_b32_e32 v31, 0xffff0000, v129
	v_add_f32_e32 v16, v16, v17
	v_mul_f32_e32 v17, v29, v29
	v_pk_add_f32 v[30:31], v[18:19], v[30:31]
	v_fmac_f32_e32 v17, v28, v28
	v_add_f32_e32 v16, v17, v16
	v_mul_f32_e32 v17, v31, v31
	v_fmac_f32_e32 v17, v30, v30
	v_add_f32_e32 v16, v17, v16
	v_add_f32_e32 v19, v36, v16
	ds_bpermute_b32 v36, v96, v19
	v_add_u32_e32 v32, 0xa0, v220
	s_waitcnt lgkmcnt(0)
	v_ashrrev_i32_e32 v33, 31, v32
	v_lshlrev_b64 v[34:35], 11, v[32:33]
	v_lshl_add_u64 v[16:17], s[90:91], 0, v[34:35]
	v_lshl_add_u64 v[34:35], v[218:219], 1, v[16:17]
	v_add_f32_e32 v16, v19, v36
	ds_bpermute_b32 v17, v116, v16
	v_cvt_pk_bf16_f32 v27, v38, v39
	global_store_dwordx4 v[34:35], v[24:27], off nt
	v_cvt_pk_bf16_f32 v18, v20, v21
	v_cvt_pk_bf16_f32 v19, v22, v23
	v_cvt_pk_bf16_f32 v20, v28, v29
	v_cvt_pk_bf16_f32 v21, v30, v31
	global_store_dwordx4 v[34:35], v[18:21], off offset:256 nt
	s_and_saveexec_b64 s[0:1], vcc
	s_cbranch_execz .LBB0_896
	v_lshl_add_u64 v[18:19], v[32:33], 2, s[2:3]
	s_waitcnt lgkmcnt(0)
	v_add_f32_e32 v16, v16, v17
	global_atomic_add_f32 v[18:19], v16, off
.LBB0_896:
	s_or_b64 exec, exec, s[0:1]
	v_lshlrev_b32_e32 v20, 16, v118
	v_and_b32_e32 v21, 0xffff0000, v118
	v_lshlrev_b32_e32 v22, 16, v119
	v_and_b32_e32 v23, 0xffff0000, v119
	v_pk_add_f32 v[12:13], v[12:13], v[20:21]
	v_lshlrev_b32_e32 v20, 16, v120
	v_and_b32_e32 v21, 0xffff0000, v120
	v_pk_add_f32 v[14:15], v[14:15], v[22:23]
	v_pk_add_f32 v[20:21], v[8:9], v[20:21]
	v_cvt_pk_bf16_f32 v8, v12, v13
	v_mul_f32_e32 v13, v13, v13
	v_fmac_f32_e32 v13, v12, v12
	v_mul_f32_e32 v12, v15, v15
	v_fmac_f32_e32 v12, v14, v14
	v_lshlrev_b32_e32 v22, 16, v121
	v_and_b32_e32 v23, 0xffff0000, v121
	v_add_f32_e32 v12, v13, v12
	v_mul_f32_e32 v13, v21, v21
	v_pk_add_f32 v[22:23], v[10:11], v[22:23]
	v_fmac_f32_e32 v13, v20, v20
	v_add_f32_e32 v12, v13, v12
	v_mul_f32_e32 v13, v23, v23
	v_fmac_f32_e32 v13, v22, v22
	v_cvt_pk_bf16_f32 v9, v14, v15
	v_cvt_pk_bf16_f32 v10, v20, v21
	v_add_f32_e32 v20, v13, v12
	v_lshlrev_b32_e32 v12, 16, v138
	v_and_b32_e32 v13, 0xffff0000, v138
	v_lshlrev_b32_e32 v14, 16, v139
	v_and_b32_e32 v15, 0xffff0000, v139
	v_pk_add_f32 v[6:7], v[6:7], v[14:15]
	v_pk_add_f32 v[4:5], v[4:5], v[12:13]
	v_lshlrev_b32_e32 v12, 16, v140
	v_and_b32_e32 v13, 0xffff0000, v140
	v_pk_add_f32 v[12:13], v[0:1], v[12:13]
	v_mul_f32_e32 v0, v5, v5
	v_mul_f32_e32 v1, v7, v7
	v_fmac_f32_e32 v0, v4, v4
	v_fmac_f32_e32 v1, v6, v6
	v_lshlrev_b32_e32 v14, 16, v141
	v_and_b32_e32 v15, 0xffff0000, v141
	v_add_f32_e32 v0, v0, v1
	v_mul_f32_e32 v1, v13, v13
	v_pk_add_f32 v[14:15], v[2:3], v[14:15]
	v_fmac_f32_e32 v1, v12, v12
	v_add_f32_e32 v0, v1, v0
	v_mul_f32_e32 v1, v15, v15
	v_fmac_f32_e32 v1, v14, v14
	v_add_f32_e32 v0, v1, v0
	v_add_f32_e32 v3, v20, v0
	ds_bpermute_b32 v20, v96, v3
	v_add_u32_e32 v16, 0xb0, v220
	s_waitcnt lgkmcnt(0)
	v_ashrrev_i32_e32 v17, 31, v16
	v_lshlrev_b64 v[18:19], 11, v[16:17]
	v_lshl_add_u64 v[0:1], s[90:91], 0, v[18:19]
	v_lshl_add_u64 v[18:19], v[218:219], 1, v[0:1]
	v_add_f32_e32 v0, v3, v20
	ds_bpermute_b32 v1, v116, v0
	v_cvt_pk_bf16_f32 v11, v22, v23
	global_store_dwordx4 v[18:19], v[8:11], off nt
	v_cvt_pk_bf16_f32 v2, v4, v5
	v_cvt_pk_bf16_f32 v3, v6, v7
	v_cvt_pk_bf16_f32 v4, v12, v13
	v_cvt_pk_bf16_f32 v5, v14, v15
	global_store_dwordx4 v[18:19], v[2:5], off offset:256 nt
	s_and_saveexec_b64 s[0:1], vcc
	s_cbranch_execz .LBB0_898
	v_lshl_add_u64 v[2:3], v[16:17], 2, s[2:3]
	s_waitcnt lgkmcnt(0)
	v_add_f32_e32 v0, v0, v1
	global_atomic_add_f32 v[2:3], v0, off

; __device__ __forceinline__ unsigned cvt_pk_bf16(float lo, float hi) { unsigned r; asm volatile("v_cvt_pk_bf16_f32 %0, %1, %2" : "=v"(r) : "v"(lo), "v"(hi)); return r; }
;     __device__ __forceinline__ void finish(const f32x4 x0, const f32x4 x1, int row, int col, float& s) const {
;         if (OUT_F32) { *(f32x4*)(out + (size_t)row * DM + col) = x0; *(f32x4*)(out + (size_t)row * DM + col + 4) = x1; }
;         else { u32x4 w; w.x = cvt_pk_bf16(x0[0], x0[1]); w.y = cvt_pk_bf16(x0[2], x0[3]); w.z = cvt_pk_bf16(x1[0], x1[1]); w.w = cvt_pk_bf16(x1[2], x1[3]); *(u32x4*)(XB + (size_t)row * DM + col) = w; }
;         s += (x0[0] * x0[0] + x0[1] * x0[1]) + (x0[2] * x0[2] + x0[3] * x0[3]) + (x1[0] * x1[0] + x1[1] * x1[1]) + (x1[2] * x1[2] + x1[3] * x1[3]);
;     __device__ __forceinline__ void operator()(AccT& acc, const Unit& u, int wr, int wc, int fr, int fq) const {
;     ...
; #pragma unroll
;             for (int ai = 0; ai < 2; ++ai) {
;                 f32x4 rv[4][2][2];
; #pragma unroll
;                 for (int m = 0; m < 4; ++m)
; #pragma unroll
;                     for (int bj = 0; bj < 2; ++bj) { const size_t o = (size_t)(u.pm * 256 + ai * 128 + wr * 64 + m * 16 + fr) * DM + col0 + bj * 128; rv[m][bj][0] = *(const f32x4*)(res + o); rv[m][bj][1] = *(const f32x4*)(res + o + 4); }
; #pragma unroll
;                 for (int m = 0; m < 4; ++m) {
;                     const int row = u.pm * 256 + ai * 128 + wr * 64 + m * 16 + fr; float s = 0.f;
; #pragma unroll
;                     for (int bj = 0; bj < 2; ++bj) finish(rv[m][bj][0] + acc[ai][bj][m][0], rv[m][bj][1] + acc[ai][bj][m][1], row, col0 + bj * 128, s);
;                     if (!OUT_F32) { s += __shfl_xor(s, 16); s += __shfl_xor(s, 32); if (fq == 0) atomicAdd(ssq_next + row, s); }
.LBB0_927:
	s_lshl_b32 s0, s48, 8
	v_mov_b32_e32 v130, v212
	v_mov_b32_e32 v131, v213
	s_or_b32 s0, s0, s37
	v_readlane_b32 s56, v249, 4
	v_lshl_add_u32 v188, v131, 3, s0
	s_lshl_b32 s0, s45, 8
	s_add_i32 s0, s0, s33
	v_add_u32_e32 v190, s0, v130
	v_ashrrev_i32_e32 v189, 31, v188
	v_readlane_b32 s57, v249, 5
	v_ashrrev_i32_e32 v191, 31, v190
	v_cmp_eq_u32_e32 vcc, 0, v131
	v_lshl_add_u64 v[192:193], v[188:189], 2, s[56:57]
	v_lshlrev_b64 v[130:131], 12, v[190:191]
	v_lshl_add_u64 v[130:131], v[192:193], 0, v[130:131]
	global_load_dwordx4 v[216:219], v[130:131], off offset:16
	global_load_dwordx4 v[230:233], v[130:131], off
	global_load_dwordx4 v[234:237], v[130:131], off offset:528
	global_load_dwordx4 v[238:241], v[130:131], off offset:512
	v_add_u32_e32 v210, 16, v190
	v_ashrrev_i32_e32 v211, 31, v210
	v_lshlrev_b64 v[130:131], 12, v[210:211]
	v_add_u32_e32 v208, 32, v190
	v_lshl_add_u64 v[130:131], v[192:193], 0, v[130:131]
	v_ashrrev_i32_e32 v209, 31, v208
	global_load_dwordx4 v[170:173], v[130:131], off offset:16
	global_load_dwordx4 v[174:177], v[130:131], off
	global_load_dwordx4 v[162:165], v[130:131], off offset:528
	global_load_dwordx4 v[166:169], v[130:131], off offset:512
	v_lshlrev_b64 v[130:131], 12, v[208:209]
	v_add_u32_e32 v206, 48, v190
	v_lshl_add_u64 v[130:131], v[192:193], 0, v[130:131]
	v_ashrrev_i32_e32 v207, 31, v206
	global_load_dwordx4 v[154:157], v[130:131], off offset:16
	global_load_dwordx4 v[158:161], v[130:131], off
	global_load_dwordx4 v[138:141], v[130:131], off offset:528
	global_load_dwordx4 v[142:145], v[130:131], off offset:512
	v_lshlrev_b64 v[130:131], 12, v[206:207]
	v_lshl_add_u64 v[134:135], v[192:193], 0, v[130:131]
	global_load_dwordx4 v[146:149], v[134:135], off offset:16
	global_load_dwordx4 v[150:153], v[134:135], off
	global_load_dwordx4 v[130:133], v[134:135], off offset:528
	s_nop 0
	global_load_dwordx4 v[134:137], v[134:135], off offset:512
	v_lshlrev_b64 v[220:221], 11, v[190:191]
	v_lshl_add_u64 v[220:221], s[90:91], 0, v[220:221]
	v_lshl_add_u64 v[220:221], v[188:189], 1, v[220:221]
	v_readlane_b32 s58, v249, 6
	v_readlane_b32 s59, v249, 7
	v_readlane_b32 s60, v249, 8
	v_readlane_b32 s61, v249, 9
	v_readlane_b32 s62, v249, 10
	v_readlane_b32 s63, v249, 11
	v_readlane_b32 s64, v249, 12
	v_readlane_b32 s65, v249, 13
	v_readlane_b32 s66, v249, 14
	v_readlane_b32 s67, v249, 15
	v_readlane_b32 s68, v249, 16
	v_readlane_b32 s69, v249, 17
	v_readlane_b32 s70, v249, 18
	v_readlane_b32 s71, v249, 19
	s_waitcnt vmcnt(0)
	v_pk_add_f32 v[216:217], v[122:123], v[216:217]
	v_pk_add_f32 v[128:129], v[128:129], v[232:233]
	v_pk_add_f32 v[126:127], v[126:127], v[230:231]
	v_pk_add_f32 v[218:219], v[124:125], v[218:219]
	v_cvt_pk_bf16_f32 v122, v126, v127
	v_cvt_pk_bf16_f32 v123, v128, v129
	v_cvt_pk_bf16_f32 v124, v216, v217
	v_pk_add_f32 v[120:121], v[120:121], v[240:241]
	v_cvt_pk_bf16_f32 v125, v218, v219
	global_store_dwordx4 v[220:221], v[122:125], off nt
	v_pk_add_f32 v[118:119], v[118:119], v[238:239]
	s_nop 0
	v_mul_f32_e32 v122, v127, v127
	v_mul_f32_e32 v123, v129, v129
	v_fmac_f32_e32 v122, v126, v126
	v_fmac_f32_e32 v123, v128, v128
	v_add_f32_e32 v122, v122, v123
	v_mul_f32_e32 v123, v217, v217
	v_fmac_f32_e32 v123, v216, v216
	v_add_f32_e32 v122, v122, v123
	v_mul_f32_e32 v123, v219, v219
	v_fmac_f32_e32 v123, v218, v218
	v_pk_add_f32 v[124:125], v[114:115], v[234:235]
	v_cvt_pk_bf16_f32 v114, v118, v119
	v_cvt_pk_bf16_f32 v115, v120, v121
	v_add_f32_e32 v126, v123, v122
	v_pk_add_f32 v[122:123], v[116:117], v[236:237]
	v_cvt_pk_bf16_f32 v116, v124, v125
	s_nop 0
	v_cvt_pk_bf16_f32 v117, v122, v123
	global_store_dwordx4 v[220:221], v[114:117], off offset:256 nt
	s_nop 1
	v_mul_f32_e32 v114, v119, v119
	v_mul_f32_e32 v115, v121, v121
	v_fmac_f32_e32 v114, v118, v118
	v_fmac_f32_e32 v115, v120, v120
	v_add_f32_e32 v114, v114, v115
	v_mul_f32_e32 v115, v125, v125
	v_fmac_f32_e32 v115, v124, v124
	v_add_f32_e32 v114, v114, v115
	v_mul_f32_e32 v115, v123, v123
	v_fmac_f32_e32 v115, v122, v122
	v_and_b32_e32 v116, 64, v225
	v_add_f32_e32 v114, v115, v114
	v_xor_b32_e32 v115, 16, v225
	v_add_u32_e32 v116, 64, v116
	v_cmp_lt_i32_e64 s[0:1], v115, v116
	v_add_f32_e32 v114, v126, v114
	s_nop 0
	v_cndmask_b32_e64 v115, v225, v115, s[0:1]
	v_lshlrev_b32_e32 v122, 2, v115
	ds_bpermute_b32 v115, v122, v114
	s_waitcnt lgkmcnt(0)
	v_add_f32_e32 v114, v114, v115
	v_xor_b32_e32 v115, 32, v225
	v_cmp_lt_i32_e64 s[0:1], v115, v116
	s_nop 1
	v_cndmask_b32_e64 v115, v225, v115, s[0:1]
	v_lshlrev_b32_e32 v123, 2, v115
	ds_bpermute_b32 v115, v123, v114
	s_and_saveexec_b64 s[0:1], vcc
	s_cbranch_execz .LBB0_929
	v_lshl_add_u64 v[116:117], v[190:191], 2, s[2:3]
	s_waitcnt lgkmcnt(0)
	v_add_f32_e32 v114, v114, v115
	global_atomic_add_f32 v[116:117], v114, off
; __device__ __forceinline__ unsigned cvt_pk_bf16(float lo, float hi) { unsigned r; asm volatile("v_cvt_pk_bf16_f32 %0, %1, %2" : "=v"(r) : "v"(lo), "v"(hi)); return r; }
;     __device__ __forceinline__ void finish(const f32x4 x0, const f32x4 x1, int row, int col, float& s) const {
;         if (OUT_F32) { *(f32x4*)(out + (size_t)row * DM + col) = x0; *(f32x4*)(out + (size_t)row * DM + col + 4) = x1; }
;         else { u32x4 w; w.x = cvt_pk_bf16(x0[0], x0[1]); w.y = cvt_pk_bf16(x0[2], x0[3]); w.z = cvt_pk_bf16(x1[0], x1[1]); w.w = cvt_pk_bf16(x1[2], x1[3]); *(u32x4*)(XB + (size_t)row * DM + col) = w; }
;         s += (x0[0] * x0[0] + x0[1] * x0[1]) + (x0[2] * x0[2] + x0[3] * x0[3]) + (x1[0] * x1[0] + x1[1] * x1[1]) + (x1[2] * x1[2] + x1[3] * x1[3]);
;     __device__ __forceinline__ void operator()(AccT& acc, const Unit& u, int wr, int wc, int fr, int fq) const {
;     ...
;                 for (int m = 0; m < 4; ++m) {
;                     const int row = u.pm * 256 + ai * 128 + wr * 64 + m * 16 + fr; float s = 0.f;
; #pragma unroll
;                     for (int bj = 0; bj < 2; ++bj) finish(rv[m][bj][0] + acc[ai][bj][m][0], rv[m][bj][1] + acc[ai][bj][m][1], row, col0 + bj * 128, s);
;                     if (!OUT_F32) { s += __shfl_xor(s, 16); s += __shfl_xor(s, 32); if (fq == 0) atomicAdd(ssq_next + row, s); }
.LBB0_929:
	s_or_b64 exec, exec, s[0:1]
	v_pk_add_f32 v[110:111], v[110:111], v[174:175]
	v_pk_add_f32 v[112:113], v[112:113], v[176:177]
	v_pk_add_f32 v[118:119], v[106:107], v[170:171]
	v_cvt_pk_bf16_f32 v106, v110, v111
	v_mul_f32_e32 v111, v111, v111
	v_fmac_f32_e32 v111, v110, v110
	v_mul_f32_e32 v110, v113, v113
	v_fmac_f32_e32 v110, v112, v112
	v_add_f32_e32 v110, v111, v110
	v_mul_f32_e32 v111, v119, v119
	v_pk_add_f32 v[104:105], v[104:105], v[168:169]
	v_pk_add_f32 v[102:103], v[102:103], v[166:167]
	v_pk_add_f32 v[116:117], v[108:109], v[172:173]
	v_cvt_pk_bf16_f32 v107, v112, v113
	v_fmac_f32_e32 v111, v118, v118
	v_pk_add_f32 v[112:113], v[98:99], v[162:163]
	v_mul_f32_e32 v98, v103, v103
	v_mul_f32_e32 v99, v105, v105
	v_add_f32_e32 v110, v110, v111
	v_mul_f32_e32 v111, v117, v117
	v_fmac_f32_e32 v98, v102, v102
	v_fmac_f32_e32 v99, v104, v104
	v_fmac_f32_e32 v111, v116, v116
	v_add_f32_e32 v98, v98, v99
	v_mul_f32_e32 v99, v113, v113
	v_cvt_pk_bf16_f32 v108, v118, v119
	v_cvt_pk_bf16_f32 v109, v116, v117
	v_add_f32_e32 v116, v111, v110
	v_pk_add_f32 v[110:111], v[100:101], v[164:165]
	v_fmac_f32_e32 v99, v112, v112
	v_add_f32_e32 v98, v98, v99
	v_mul_f32_e32 v99, v111, v111
	v_fmac_f32_e32 v99, v110, v110
	v_add_f32_e32 v98, v99, v98
	v_add_f32_e32 v101, v116, v98
	ds_bpermute_b32 v116, v122, v101
	s_waitcnt lgkmcnt(0)
	v_lshlrev_b64 v[114:115], 11, v[210:211]
	v_lshl_add_u64 v[98:99], s[90:91], 0, v[114:115]
	v_lshl_add_u64 v[114:115], v[188:189], 1, v[98:99]
	global_store_dwordx4 v[114:115], v[106:109], off nt
	v_add_f32_e32 v98, v101, v116
	ds_bpermute_b32 v99, v123, v98
	v_cvt_pk_bf16_f32 v100, v102, v103
	v_cvt_pk_bf16_f32 v101, v104, v105
	v_cvt_pk_bf16_f32 v102, v112, v113
	v_cvt_pk_bf16_f32 v103, v110, v111
	global_store_dwordx4 v[114:115], v[100:103], off offset:256 nt
	s_and_saveexec_b64 s[0:1], vcc
	s_cbranch_execz .LBB0_931
	v_lshl_add_u64 v[100:101], v[210:211], 2, s[2:3]
	s_waitcnt lgkmcnt(0)
	v_add_f32_e32 v98, v98, v99
	global_atomic_add_f32 v[100:101], v98, off
.LBB0_931:
	s_or_b64 exec, exec, s[0:1]
	v_pk_add_f32 v[92:93], v[92:93], v[158:159]
	v_pk_add_f32 v[94:95], v[94:95], v[160:161]
	v_pk_add_f32 v[102:103], v[88:89], v[154:155]
	v_cvt_pk_bf16_f32 v88, v92, v93
	v_mul_f32_e32 v93, v93, v93
	v_fmac_f32_e32 v93, v92, v92
	v_mul_f32_e32 v92, v95, v95
	v_fmac_f32_e32 v92, v94, v94
	v_add_f32_e32 v92, v93, v92
	v_mul_f32_e32 v93, v103, v103
	v_pk_add_f32 v[86:87], v[86:87], v[144:145]
	v_pk_add_f32 v[84:85], v[84:85], v[142:143]
	v_pk_add_f32 v[100:101], v[90:91], v[156:157]
	v_cvt_pk_bf16_f32 v89, v94, v95
	v_fmac_f32_e32 v93, v102, v102
	v_pk_add_f32 v[94:95], v[80:81], v[138:139]
	v_mul_f32_e32 v80, v85, v85
	v_mul_f32_e32 v81, v87, v87
	v_add_f32_e32 v92, v92, v93
	v_mul_f32_e32 v93, v101, v101
	v_fmac_f32_e32 v80, v84, v84
	v_fmac_f32_e32 v81, v86, v86
	v_fmac_f32_e32 v93, v100, v100
	v_add_f32_e32 v80, v80, v81
	v_mul_f32_e32 v81, v95, v95
	v_cvt_pk_bf16_f32 v90, v102, v103
	v_cvt_pk_bf16_f32 v91, v100, v101
	v_add_f32_e32 v100, v93, v92
	v_pk_add_f32 v[92:93], v[82:83], v[140:141]
	v_fmac_f32_e32 v81, v94, v94
	v_add_f32_e32 v80, v80, v81
	v_mul_f32_e32 v81, v93, v93
	v_fmac_f32_e32 v81, v92, v92
	v_add_f32_e32 v80, v81, v80
	v_add_f32_e32 v83, v100, v80
	ds_bpermute_b32 v100, v122, v83
	s_waitcnt lgkmcnt(0)
	v_lshlrev_b64 v[98:99], 11, v[208:209]
	v_lshl_add_u64 v[80:81], s[90:91], 0, v[98:99]
	v_lshl_add_u64 v[98:99], v[188:189], 1, v[80:81]
	global_store_dwordx4 v[98:99], v[88:91], off nt
	v_add_f32_e32 v80, v83, v100
	ds_bpermute_b32 v81, v123, v80
	v_cvt_pk_bf16_f32 v82, v84, v85
	v_cvt_pk_bf16_f32 v83, v86, v87
	v_cvt_pk_bf16_f32 v84, v94, v95
	v_cvt_pk_bf16_f32 v85, v92, v93
	global_store_dwordx4 v[98:99], v[82:85], off offset:256 nt
	s_and_saveexec_b64 s[0:1], vcc
	s_cbranch_execz .LBB0_933
	v_lshl_add_u64 v[82:83], v[208:209], 2, s[2:3]
	s_waitcnt lgkmcnt(0)
	v_add_f32_e32 v80, v80, v81
	global_atomic_add_f32 v[82:83], v80, off
.LBB0_933:
	s_or_b64 exec, exec, s[0:1]
	v_pk_add_f32 v[76:77], v[76:77], v[150:151]
	v_pk_add_f32 v[78:79], v[78:79], v[152:153]
	v_pk_add_f32 v[84:85], v[72:73], v[146:147]
	v_cvt_pk_bf16_f32 v72, v76, v77
	v_mul_f32_e32 v77, v77, v77
	v_fmac_f32_e32 v77, v76, v76
	v_mul_f32_e32 v76, v79, v79
	v_fmac_f32_e32 v76, v78, v78
	v_add_f32_e32 v76, v77, v76
	v_mul_f32_e32 v77, v85, v85
	v_pk_add_f32 v[70:71], v[70:71], v[136:137]
	v_pk_add_f32 v[68:69], v[68:69], v[134:135]
	v_pk_add_f32 v[82:83], v[74:75], v[148:149]
	v_cvt_pk_bf16_f32 v73, v78, v79
	v_fmac_f32_e32 v77, v84, v84
	v_pk_add_f32 v[78:79], v[64:65], v[130:131]
	v_mul_f32_e32 v64, v69, v69
	v_mul_f32_e32 v65, v71, v71
	v_add_f32_e32 v76, v76, v77
	v_mul_f32_e32 v77, v83, v83
	v_fmac_f32_e32 v64, v68, v68
	v_fmac_f32_e32 v65, v70, v70
	v_fmac_f32_e32 v77, v82, v82
	v_add_f32_e32 v64, v64, v65
	v_mul_f32_e32 v65, v79, v79
	v_cvt_pk_bf16_f32 v74, v84, v85
	v_cvt_pk_bf16_f32 v75, v82, v83
	v_add_f32_e32 v82, v77, v76
	v_pk_add_f32 v[76:77], v[66:67], v[132:133]
	v_fmac_f32_e32 v65, v78, v78
	v_add_f32_e32 v64, v64, v65
	v_mul_f32_e32 v65, v77, v77
	v_fmac_f32_e32 v65, v76, v76
	v_add_f32_e32 v64, v65, v64
	v_add_f32_e32 v67, v82, v64
	ds_bpermute_b32 v82, v122, v67
	s_waitcnt lgkmcnt(0)
	v_lshlrev_b64 v[80:81], 11, v[206:207]
	v_lshl_add_u64 v[64:65], s[90:91], 0, v[80:81]
	v_lshl_add_u64 v[80:81], v[188:189], 1, v[64:65]
	global_store_dwordx4 v[80:81], v[72:75], off nt
	v_add_f32_e32 v64, v67, v82
	ds_bpermute_b32 v65, v123, v64
	v_cvt_pk_bf16_f32 v66, v68, v69
	v_cvt_pk_bf16_f32 v67, v70, v71
	v_cvt_pk_bf16_f32 v68, v78, v79
	v_cvt_pk_bf16_f32 v69, v76, v77
	global_store_dwordx4 v[80:81], v[66:69], off offset:256 nt
	s_and_saveexec_b64 s[0:1], vcc
	s_cbranch_execz .LBB0_935
	v_lshl_add_u64 v[66:67], v[206:207], 2, s[2:3]
	s_waitcnt lgkmcnt(0)
	v_add_f32_e32 v64, v64, v65
	global_atomic_add_f32 v[66:67], v64, off
; __device__ __forceinline__ unsigned cvt_pk_bf16(float lo, float hi) { unsigned r; asm volatile("v_cvt_pk_bf16_f32 %0, %1, %2" : "=v"(r) : "v"(lo), "v"(hi)); return r; }
;     __device__ __forceinline__ void finish(const f32x4 x0, const f32x4 x1, int row, int col, float& s) const {
;         if (OUT_F32) { *(f32x4*)(out + (size_t)row * DM + col) = x0; *(f32x4*)(out + (size_t)row * DM + col + 4) = x1; }
;         else { u32x4 w; w.x = cvt_pk_bf16(x0[0], x0[1]); w.y = cvt_pk_bf16(x0[2], x0[3]); w.z = cvt_pk_bf16(x1[0], x1[1]); w.w = cvt_pk_bf16(x1[2], x1[3]); *(u32x4*)(XB + (size_t)row * DM + col) = w; }
;         s += (x0[0] * x0[0] + x0[1] * x0[1]) + (x0[2] * x0[2] + x0[3] * x0[3]) + (x1[0] * x1[0] + x1[1] * x1[1]) + (x1[2] * x1[2] + x1[3] * x1[3]);
;     __device__ __forceinline__ void operator()(AccT& acc, const Unit& u, int wr, int wc, int fr, int fq) const {
;     ...
; #pragma unroll
;             for (int ai = 0; ai < 2; ++ai) {
;                 f32x4 rv[4][2][2];
; #pragma unroll
;                 for (int m = 0; m < 4; ++m)
; #pragma unroll
;                     for (int bj = 0; bj < 2; ++bj) { const size_t o = (size_t)(u.pm * 256 + ai * 128 + wr * 64 + m * 16 + fr) * DM + col0 + bj * 128; rv[m][bj][0] = *(const f32x4*)(res + o); rv[m][bj][1] = *(const f32x4*)(res + o + 4); }
; #pragma unroll
;                 for (int m = 0; m < 4; ++m) {
;                     const int row = u.pm * 256 + ai * 128 + wr * 64 + m * 16 + fr; float s = 0.f;
; #pragma unroll
;                     for (int bj = 0; bj < 2; ++bj) finish(rv[m][bj][0] + acc[ai][bj][m][0], rv[m][bj][1] + acc[ai][bj][m][1], row, col0 + bj * 128, s);
;                     if (!OUT_F32) { s += __shfl_xor(s, 16); s += __shfl_xor(s, 32); if (fq == 0) atomicAdd(ssq_next + row, s); }
.LBB0_935:
	s_or_b64 exec, exec, s[0:1]
	v_add_u32_e32 v120, 0x80, v190
	v_ashrrev_i32_e32 v121, 31, v120
	s_waitcnt lgkmcnt(0)
	v_lshlrev_b64 v[64:65], 12, v[120:121]
	v_lshl_add_u64 v[64:65], v[192:193], 0, v[64:65]
	global_load_dwordx4 v[124:127], v[64:65], off
	global_load_dwordx4 v[128:131], v[64:65], off offset:16
	global_load_dwordx4 v[132:135], v[64:65], off offset:512
	global_load_dwordx4 v[136:139], v[64:65], off offset:528
	v_add_u32_e32 v118, 0x90, v190
	v_add_u32_e32 v116, 0xa0, v190
	v_add_u32_e32 v114, 0xb0, v190
	v_ashrrev_i32_e32 v119, 31, v118
	v_ashrrev_i32_e32 v117, 31, v116
	v_ashrrev_i32_e32 v115, 31, v114
	v_lshlrev_b64 v[64:65], 12, v[118:119]
	v_lshlrev_b64 v[66:67], 12, v[116:117]
	v_lshlrev_b64 v[68:69], 12, v[114:115]
	v_lshl_add_u64 v[64:65], v[192:193], 0, v[64:65]
	v_lshl_add_u64 v[66:67], v[192:193], 0, v[66:67]
	v_lshl_add_u64 v[68:69], v[192:193], 0, v[68:69]
	global_load_dwordx4 v[106:109], v[64:65], off offset:16
	global_load_dwordx4 v[110:113], v[64:65], off
	global_load_dwordx4 v[98:101], v[64:65], off offset:528
	global_load_dwordx4 v[102:105], v[64:65], off offset:512
	global_load_dwordx4 v[88:91], v[66:67], off offset:16
	global_load_dwordx4 v[92:95], v[66:67], off
	global_load_dwordx4 v[80:83], v[66:67], off offset:528
	global_load_dwordx4 v[84:87], v[66:67], off offset:512
	global_load_dwordx4 v[72:75], v[68:69], off offset:16
	global_load_dwordx4 v[76:79], v[68:69], off
	s_nop 0
	global_load_dwordx4 v[64:67], v[68:69], off offset:528
	s_nop 0
	global_load_dwordx4 v[68:71], v[68:69], off offset:512
	v_lshlrev_b64 v[140:141], 11, v[120:121]
	s_waitcnt vmcnt(0)
	v_pk_add_f32 v[62:63], v[62:63], v[126:127]
	v_pk_add_f32 v[60:61], v[60:61], v[124:125]
	v_pk_add_f32 v[54:55], v[54:55], v[134:135]
	v_pk_add_f32 v[52:53], v[52:53], v[132:133]
	v_pk_add_f32 v[58:59], v[58:59], v[130:131]
	v_pk_add_f32 v[56:57], v[56:57], v[128:129]
	v_pk_add_f32 v[126:127], v[48:49], v[136:137]
	v_cvt_pk_bf16_f32 v48, v60, v61
	v_cvt_pk_bf16_f32 v49, v62, v63
	v_mul_f32_e32 v61, v61, v61
	v_mul_f32_e32 v63, v63, v63
	v_mul_f32_e32 v128, v53, v53
	v_mul_f32_e32 v129, v55, v55
	v_pk_add_f32 v[124:125], v[50:51], v[138:139]
	v_cvt_pk_bf16_f32 v50, v56, v57
	v_cvt_pk_bf16_f32 v51, v58, v59
	v_mul_f32_e32 v57, v57, v57
	v_mul_f32_e32 v59, v59, v59
	v_mul_f32_e32 v130, v127, v127
	v_fmac_f32_e32 v61, v60, v60
	v_fmac_f32_e32 v63, v62, v62
	v_fmac_f32_e32 v128, v52, v52
	v_fmac_f32_e32 v129, v54, v54
	v_mul_f32_e32 v131, v125, v125
	v_fmac_f32_e32 v57, v56, v56
	v_fmac_f32_e32 v59, v58, v58
	v_fmac_f32_e32 v130, v126, v126
	v_add_f32_e32 v56, v61, v63
	v_add_f32_e32 v58, v128, v129
	v_fmac_f32_e32 v131, v124, v124
	v_add_f32_e32 v56, v56, v57
	v_add_f32_e32 v57, v58, v130
	v_add_f32_e32 v56, v59, v56
	v_add_f32_e32 v57, v131, v57
	v_add_f32_e32 v58, v56, v57
	ds_bpermute_b32 v59, v122, v58
	v_lshl_add_u64 v[56:57], s[90:91], 0, v[140:141]
	v_lshl_add_u64 v[56:57], v[188:189], 1, v[56:57]
	global_store_dwordx4 v[56:57], v[48:51], off nt
	s_waitcnt lgkmcnt(0)
	s_nop 0
	v_add_f32_e32 v48, v58, v59
	ds_bpermute_b32 v49, v123, v48
	v_cvt_pk_bf16_f32 v50, v52, v53
	v_cvt_pk_bf16_f32 v51, v54, v55
	v_cvt_pk_bf16_f32 v52, v126, v127
	v_cvt_pk_bf16_f32 v53, v124, v125
	global_store_dwordx4 v[56:57], v[50:53], off offset:256 nt
	s_and_saveexec_b64 s[0:1], vcc
	s_cbranch_execz .LBB0_937
	v_lshl_add_u64 v[50:51], v[120:121], 2, s[2:3]
	s_waitcnt lgkmcnt(0)
	v_add_f32_e32 v48, v48, v49
	global_atomic_add_f32 v[50:51], v48, off
.LBB0_937:
	s_or_b64 exec, exec, s[0:1]
	v_pk_add_f32 v[44:45], v[44:45], v[110:111]
	v_pk_add_f32 v[46:47], v[46:47], v[112:113]
	v_pk_add_f32 v[52:53], v[40:41], v[106:107]
	v_cvt_pk_bf16_f32 v40, v44, v45
	v_mul_f32_e32 v45, v45, v45
	v_fmac_f32_e32 v45, v44, v44
	v_mul_f32_e32 v44, v47, v47
	v_fmac_f32_e32 v44, v46, v46
	v_add_f32_e32 v44, v45, v44
	v_mul_f32_e32 v45, v53, v53
	v_pk_add_f32 v[38:39], v[38:39], v[104:105]
	v_pk_add_f32 v[36:37], v[36:37], v[102:103]
	v_pk_add_f32 v[50:51], v[42:43], v[108:109]
	v_cvt_pk_bf16_f32 v41, v46, v47
	v_fmac_f32_e32 v45, v52, v52
	v_pk_add_f32 v[46:47], v[32:33], v[98:99]
	v_mul_f32_e32 v32, v37, v37
	v_mul_f32_e32 v33, v39, v39
	v_add_f32_e32 v44, v44, v45
	v_mul_f32_e32 v45, v51, v51
	v_fmac_f32_e32 v32, v36, v36
	v_fmac_f32_e32 v33, v38, v38
	v_fmac_f32_e32 v45, v50, v50
	v_add_f32_e32 v32, v32, v33
	v_mul_f32_e32 v33, v47, v47
	v_cvt_pk_bf16_f32 v42, v52, v53
	v_cvt_pk_bf16_f32 v43, v50, v51
	v_add_f32_e32 v50, v45, v44
	v_pk_add_f32 v[44:45], v[34:35], v[100:101]
	v_fmac_f32_e32 v33, v46, v46
	v_add_f32_e32 v32, v32, v33
	v_mul_f32_e32 v33, v45, v45
	v_fmac_f32_e32 v33, v44, v44
	v_add_f32_e32 v32, v33, v32
	v_add_f32_e32 v35, v50, v32
	ds_bpermute_b32 v50, v122, v35
	s_waitcnt lgkmcnt(0)
	v_lshlrev_b64 v[48:49], 11, v[118:119]
	v_lshl_add_u64 v[32:33], s[90:91], 0, v[48:49]
	v_lshl_add_u64 v[48:49], v[188:189], 1, v[32:33]
	global_store_dwordx4 v[48:49], v[40:43], off nt
	v_add_f32_e32 v32, v35, v50
	ds_bpermute_b32 v33, v123, v32
	v_cvt_pk_bf16_f32 v34, v36, v37
	v_cvt_pk_bf16_f32 v35, v38, v39
	v_cvt_pk_bf16_f32 v36, v46, v47
	v_cvt_pk_bf16_f32 v37, v44, v45
	global_store_dwordx4 v[48:49], v[34:37], off offset:256 nt
	s_and_saveexec_b64 s[0:1], vcc
	s_cbranch_execz .LBB0_939
	v_lshl_add_u64 v[34:35], v[118:119], 2, s[2:3]
	s_waitcnt lgkmcnt(0)
	v_add_f32_e32 v32, v32, v33
	global_atomic_add_f32 v[34:35], v32, off
; __device__ __forceinline__ unsigned cvt_pk_bf16(float lo, float hi) { unsigned r; asm volatile("v_cvt_pk_bf16_f32 %0, %1, %2" : "=v"(r) : "v"(lo), "v"(hi)); return r; }
;     __device__ __forceinline__ void finish(const f32x4 x0, const f32x4 x1, int row, int col, float& s) const {
;         if (OUT_F32) { *(f32x4*)(out + (size_t)row * DM + col) = x0; *(f32x4*)(out + (size_t)row * DM + col + 4) = x1; }
;         else { u32x4 w; w.x = cvt_pk_bf16(x0[0], x0[1]); w.y = cvt_pk_bf16(x0[2], x0[3]); w.z = cvt_pk_bf16(x1[0], x1[1]); w.w = cvt_pk_bf16(x1[2], x1[3]); *(u32x4*)(XB + (size_t)row * DM + col) = w; }
;         s += (x0[0] * x0[0] + x0[1] * x0[1]) + (x0[2] * x0[2] + x0[3] * x0[3]) + (x1[0] * x1[0] + x1[1] * x1[1]) + (x1[2] * x1[2] + x1[3] * x1[3]);
;     __device__ __forceinline__ void operator()(AccT& acc, const Unit& u, int wr, int wc, int fr, int fq) const {
;     ...
;                 for (int m = 0; m < 4; ++m) {
;                     const int row = u.pm * 256 + ai * 128 + wr * 64 + m * 16 + fr; float s = 0.f;
; #pragma unroll
;                     for (int bj = 0; bj < 2; ++bj) finish(rv[m][bj][0] + acc[ai][bj][m][0], rv[m][bj][1] + acc[ai][bj][m][1], row, col0 + bj * 128, s);
;                     if (!OUT_F32) { s += __shfl_xor(s, 16); s += __shfl_xor(s, 32); if (fq == 0) atomicAdd(ssq_next + row, s); }
.LBB0_939:
	s_or_b64 exec, exec, s[0:1]
	v_pk_add_f32 v[28:29], v[28:29], v[92:93]
	v_pk_add_f32 v[30:31], v[30:31], v[94:95]
	v_pk_add_f32 v[36:37], v[24:25], v[88:89]
	v_cvt_pk_bf16_f32 v24, v28, v29
	v_mul_f32_e32 v29, v29, v29
	v_fmac_f32_e32 v29, v28, v28
	v_mul_f32_e32 v28, v31, v31
	v_fmac_f32_e32 v28, v30, v30
	v_add_f32_e32 v28, v29, v28
	v_mul_f32_e32 v29, v37, v37
	v_pk_add_f32 v[22:23], v[22:23], v[86:87]
	v_pk_add_f32 v[20:21], v[20:21], v[84:85]
	v_pk_add_f32 v[34:35], v[26:27], v[90:91]
	v_cvt_pk_bf16_f32 v25, v30, v31
	v_fmac_f32_e32 v29, v36, v36
	v_pk_add_f32 v[30:31], v[16:17], v[80:81]
	v_mul_f32_e32 v16, v21, v21
	v_mul_f32_e32 v17, v23, v23
	v_add_f32_e32 v28, v28, v29
	v_mul_f32_e32 v29, v35, v35
	v_fmac_f32_e32 v16, v20, v20
	v_fmac_f32_e32 v17, v22, v22
	v_fmac_f32_e32 v29, v34, v34
	v_add_f32_e32 v16, v16, v17
	v_mul_f32_e32 v17, v31, v31
	v_cvt_pk_bf16_f32 v26, v36, v37
	v_cvt_pk_bf16_f32 v27, v34, v35
	v_add_f32_e32 v34, v29, v28
	v_pk_add_f32 v[28:29], v[18:19], v[82:83]
	v_fmac_f32_e32 v17, v30, v30
	v_add_f32_e32 v16, v16, v17
	v_mul_f32_e32 v17, v29, v29
	v_fmac_f32_e32 v17, v28, v28
	v_add_f32_e32 v16, v17, v16
	v_add_f32_e32 v19, v34, v16
	ds_bpermute_b32 v34, v122, v19
	s_waitcnt lgkmcnt(0)
	v_lshlrev_b64 v[32:33], 11, v[116:117]
	v_lshl_add_u64 v[16:17], s[90:91], 0, v[32:33]
	v_lshl_add_u64 v[32:33], v[188:189], 1, v[16:17]
	global_store_dwordx4 v[32:33], v[24:27], off nt
	v_add_f32_e32 v16, v19, v34
	ds_bpermute_b32 v17, v123, v16
	v_cvt_pk_bf16_f32 v18, v20, v21
	v_cvt_pk_bf16_f32 v19, v22, v23
	v_cvt_pk_bf16_f32 v20, v30, v31
	v_cvt_pk_bf16_f32 v21, v28, v29
	global_store_dwordx4 v[32:33], v[18:21], off offset:256 nt
	s_and_saveexec_b64 s[0:1], vcc
	s_cbranch_execz .LBB0_941
	v_lshl_add_u64 v[18:19], v[116:117], 2, s[2:3]
	s_waitcnt lgkmcnt(0)
	v_add_f32_e32 v16, v16, v17
	global_atomic_add_f32 v[18:19], v16, off
.LBB0_941:
	s_or_b64 exec, exec, s[0:1]
	v_pk_add_f32 v[12:13], v[12:13], v[76:77]
	v_pk_add_f32 v[14:15], v[14:15], v[78:79]
	v_pk_add_f32 v[20:21], v[8:9], v[72:73]
	v_cvt_pk_bf16_f32 v8, v12, v13
	v_mul_f32_e32 v13, v13, v13
	v_fmac_f32_e32 v13, v12, v12
	v_mul_f32_e32 v12, v15, v15
	v_fmac_f32_e32 v12, v14, v14
	v_add_f32_e32 v12, v13, v12
	v_mul_f32_e32 v13, v21, v21
	v_pk_add_f32 v[6:7], v[6:7], v[70:71]
	v_pk_add_f32 v[4:5], v[4:5], v[68:69]
	v_pk_add_f32 v[18:19], v[10:11], v[74:75]
	v_cvt_pk_bf16_f32 v9, v14, v15
	v_fmac_f32_e32 v13, v20, v20
	v_pk_add_f32 v[14:15], v[0:1], v[64:65]
	v_mul_f32_e32 v0, v5, v5
	v_mul_f32_e32 v1, v7, v7
	v_add_f32_e32 v12, v12, v13
	v_mul_f32_e32 v13, v19, v19
	v_fmac_f32_e32 v0, v4, v4
	v_fmac_f32_e32 v1, v6, v6
	v_fmac_f32_e32 v13, v18, v18
	v_add_f32_e32 v0, v0, v1
	v_mul_f32_e32 v1, v15, v15
	v_cvt_pk_bf16_f32 v10, v20, v21
	v_cvt_pk_bf16_f32 v11, v18, v19
	v_add_f32_e32 v18, v13, v12
	v_pk_add_f32 v[12:13], v[2:3], v[66:67]
	v_fmac_f32_e32 v1, v14, v14
	v_add_f32_e32 v0, v0, v1
	v_mul_f32_e32 v1, v13, v13
	v_fmac_f32_e32 v1, v12, v12
	v_add_f32_e32 v0, v1, v0
	v_add_f32_e32 v3, v18, v0
	ds_bpermute_b32 v18, v122, v3
	s_waitcnt lgkmcnt(0)
	v_lshlrev_b64 v[16:17], 11, v[114:115]
	v_lshl_add_u64 v[0:1], s[90:91], 0, v[16:17]
	v_lshl_add_u64 v[16:17], v[188:189], 1, v[0:1]
	global_store_dwordx4 v[16:17], v[8:11], off nt
	v_add_f32_e32 v0, v3, v18
	ds_bpermute_b32 v1, v123, v0
	v_cvt_pk_bf16_f32 v2, v4, v5
	v_cvt_pk_bf16_f32 v3, v6, v7
	v_cvt_pk_bf16_f32 v4, v14, v15
	v_cvt_pk_bf16_f32 v5, v12, v13
	global_store_dwordx4 v[16:17], v[2:5], off offset:256 nt
	s_and_saveexec_b64 s[0:1], vcc
	s_cbranch_execz .LBB0_943
	v_lshl_add_u64 v[2:3], v[114:115], 2, s[2:3]
	s_waitcnt lgkmcnt(0)
	v_add_f32_e32 v0, v0, v1
	global_atomic_add_f32 v[2:3], v0, off

; __device__ __forceinline__ float ror1(float x) { return __builtin_bit_cast(float, __builtin_amdgcn_update_dpp(0, __builtin_bit_cast(int, x), 0x121, 0xf, 0xf, false)); }
; __device__ __forceinline__ float ror2(float x) { return __builtin_bit_cast(float, __builtin_amdgcn_update_dpp(0, __builtin_bit_cast(int, x), 0x122, 0xf, 0xf, false)); }
; template <int KSTEPS  >
; __device__ __forceinline__ void small_mma_ksplit(f32x4 (&acc)[2], const bf16_t* A, int lda, const bf16_t* Bt, int ldb, int n0, LAS unsigned char* lds, const SmallId& id) {
;     ...
;     acc[0] = (f32x4){0.f, 0.f, 0.f, 0.f}; acc[1] = acc[0];
; #pragma unroll
;     for (int w2 = 0; w2 < 8; ++w2) { acc[0] += red[((w2 * 8 + id.w) * 2 + 0) * 64 + lane]; acc[1] += red[((w2 * 8 + id.w) * 2 + 1) * 64 + lane]; }
; __device__ __forceinline__ void small_up(const Params& p, int l, LAS unsigned char* lds, int G, int bx) {
;     ...
;         const float rs = __builtin_amdgcn_rsqf(ssq[id.row] * (1.0f / 1024.0f) + EPS);
;         const int fr = id.fr;
; #pragma unroll
;         for (int nb = 0; nb < 2; ++nb) {
;             const int colg = c0 + 16 * nb + 4 * id.fq, colv = FF + colg;
;             const f32x4 cg_ = acc[nb] * rs, cv_ = acc[2 + nb] * rs;
;             f32x4 hg = (f32x4){0.f, 0.f, 0.f, 0.f}, hv = hg;
;             if (fr >= 14) { const float* sp = sconv + (size_t)(id.w * 2 + (fr - 14)) * FF2; hg = *(const f32x4*)(sp + colg); hv = *(const f32x4*)(sp + colv); }
;             const f32x4 w0g = *(const f32x4*)(cw + colg), w1g = *(const f32x4*)(cw + FF2 + colg), w2g = *(const f32x4*)(cw + 2 * FF2 + colg), bg = *(const f32x4*)(cb + colg);
;             const f32x4 w0v = *(const f32x4*)(cw + colv), w1v = *(const f32x4*)(cw + FF2 + colv), w2v = *(const f32x4*)(cw + 2 * FF2 + colv), bv = *(const f32x4*)(cb + colv);
;             f32x4 p1g, p2g, p1v, p2v;
; #pragma unroll
;             for (int j = 0; j < 4; ++j) {
;                 p1g[j] = ror1(fr == 15 ? hg[j] : cg_[j]); p2g[j] = ror2(fr >= 14 ? hg[j] : cg_[j]);
;                 p1v[j] = ror1(fr == 15 ? hv[j] : cv_[j]); p2v[j] = ror2(fr >= 14 ? hv[j] : cv_[j]);
;             }
;             const f32x4 hcg = bg + w0g * p2g + w1g * p1g + w2g * cg_;
;             const f32x4 hcv = bv + w0v * p2v + w1v * p1v + w2v * cv_;
.LBB0_1008:
	s_or_b64 exec, exec, s[0:1]
	v_pk_add_f32 v[94:95], v[94:95], 0 op_sel_hi:[1,0]
	v_pk_add_f32 v[92:93], v[92:93], 0 op_sel_hi:[1,0]
	v_pk_add_f32 v[90:91], v[94:95], v[90:91]
	v_pk_add_f32 v[88:89], v[92:93], v[88:89]
	v_pk_add_f32 v[86:87], v[90:91], v[86:87]
	v_pk_add_f32 v[84:85], v[88:89], v[84:85]
	v_pk_add_f32 v[82:83], v[86:87], v[82:83]
	v_pk_add_f32 v[80:81], v[84:85], v[80:81]
	v_pk_add_f32 v[78:79], v[82:83], v[78:79]
	v_pk_add_f32 v[76:77], v[80:81], v[76:77]
	v_pk_add_f32 v[74:75], v[78:79], v[74:75]
	v_pk_add_f32 v[72:73], v[76:77], v[72:73]
	v_pk_add_f32 v[70:71], v[74:75], v[70:71]
	v_pk_add_f32 v[68:69], v[72:73], v[68:69]
	v_pk_add_f32 v[66:67], v[70:71], v[66:67]
	v_pk_add_f32 v[70:71], v[106:107], 0 op_sel_hi:[1,0]
	v_pk_add_f32 v[64:65], v[68:69], v[64:65]
	v_pk_add_f32 v[70:71], v[70:71], v[110:111]
	v_pk_add_f32 v[68:69], v[108:109], 0 op_sel_hi:[1,0]
	v_pk_add_f32 v[70:71], v[70:71], v[114:115]
	v_pk_add_f32 v[68:69], v[68:69], v[112:113]
	v_pk_add_f32 v[70:71], v[70:71], v[118:119]
	v_pk_add_f32 v[68:69], v[68:69], v[116:117]
	v_pk_add_f32 v[70:71], v[70:71], v[122:123]
	v_pk_add_f32 v[68:69], v[68:69], v[120:121]
	v_pk_add_f32 v[70:71], v[70:71], v[126:127]
	v_pk_add_f32 v[68:69], v[68:69], v[124:125]
	v_pk_add_f32 v[70:71], v[70:71], v[130:131]
	v_pk_add_f32 v[68:69], v[68:69], v[128:129]
	v_pk_add_f32 v[74:75], v[70:71], v[134:135]
	s_waitcnt vmcnt(0) lgkmcnt(0)
	v_fmamk_f32 v70, v168, 0x3a800000, v223
	v_rsq_f32_e32 v72, v70
	v_pk_add_f32 v[68:69], v[68:69], v[132:133]
	v_lshlrev_b64 v[76:77], 2, v[150:151]
	v_pk_add_f32 v[68:69], v[68:69], v[136:137]
	v_lshl_add_u64 v[82:83], s[42:43], 0, v[76:77]
	v_pk_mul_f32 v[70:71], v[68:69], v[72:73] op_sel_hi:[1,0]
	v_pk_mul_f32 v[68:69], v[74:75], v[72:73] op_sel_hi:[1,0]
	v_lshl_add_u64 v[74:75], s[40:41], 0, v[76:77]
	v_lshl_add_u64 v[86:87], s[94:95], 0, v[76:77]
	v_lshl_add_u64 v[76:77], s[44:45], 0, v[76:77]
	global_load_dwordx4 v[78:81], v[74:75], off
	global_load_dwordx4 v[90:93], v[76:77], off
	v_lshlrev_b64 v[94:95], 2, v[154:155]
	global_load_dwordx4 v[82:85], v[82:83], off
	v_lshl_add_u64 v[106:107], s[40:41], 0, v[94:95]
	global_load_dwordx4 v[86:89], v[86:87], off
	v_lshl_add_u64 v[110:111], s[42:43], 0, v[94:95]
	v_lshl_add_u64 v[114:115], s[94:95], 0, v[94:95]
	v_lshl_add_u64 v[94:95], s[44:45], 0, v[94:95]
	global_load_dwordx4 v[106:109], v[106:107], off
	v_pk_mul_f32 v[64:65], v[64:65], v[72:73] op_sel_hi:[1,0]
	global_load_dwordx4 v[118:121], v[94:95], off
	v_pk_mul_f32 v[66:67], v[66:67], v[72:73] op_sel_hi:[1,0]
	global_load_dwordx4 v[110:113], v[110:111], off
	v_cndmask_b32_e64 v73, v64, v102, s[50:51]
	global_load_dwordx4 v[114:117], v[114:115], off
	v_mov_b32_e32 v94, v97
	v_mov_b32_e32 v122, v97
	v_mov_b32_e32 v95, v97
	v_mov_b32_dpp v94, v73 row_ror:1 row_mask:0xf bank_mask:0xf
	v_cndmask_b32_e64 v73, v64, v102, s[46:47]
	v_mov_b32_e32 v102, v97
	v_mov_b32_e32 v123, v97
	v_mov_b32_e32 v124, v97
	v_mov_b32_dpp v102, v73 row_ror:2 row_mask:0xf bank_mask:0xf
	v_cndmask_b32_e64 v73, v68, v98, s[50:51]
	v_mov_b32_e32 v126, v97
	v_mov_b32_e32 v125, v97
	v_mov_b32_dpp v122, v73 row_ror:1 row_mask:0xf bank_mask:0xf
	v_cndmask_b32_e64 v73, v68, v98, s[46:47]
	v_mov_b32_e32 v98, v97
	s_mov_b32 s0, 0xbf3a00e3
	v_mov_b32_e32 v127, v97
	v_mov_b32_dpp v98, v73 row_ror:2 row_mask:0xf bank_mask:0xf
	v_cndmask_b32_e64 v73, v65, v103, s[50:51]
	s_nop 1
	v_mov_b32_dpp v95, v73 row_ror:1 row_mask:0xf bank_mask:0xf
	v_cndmask_b32_e64 v73, v65, v103, s[46:47]
	v_mov_b32_e32 v103, v97
	s_nop 1
	v_mov_b32_dpp v103, v73 row_ror:2 row_mask:0xf bank_mask:0xf
	v_cndmask_b32_e64 v73, v69, v99, s[50:51]
	s_waitcnt vmcnt(6)
	v_pk_fma_f32 v[78:79], v[78:79], v[102:103], v[90:91]
	v_mov_b32_dpp v123, v73 row_ror:1 row_mask:0xf bank_mask:0xf
	v_cndmask_b32_e64 v73, v69, v99, s[46:47]
	v_mov_b32_e32 v99, v97
	s_waitcnt vmcnt(5)
	v_pk_fma_f32 v[78:79], v[82:83], v[94:95], v[78:79]
	v_mov_b32_dpp v99, v73 row_ror:2 row_mask:0xf bank_mask:0xf
	v_cndmask_b32_e64 v73, v66, v104, s[50:51]
	s_waitcnt vmcnt(4)
; __device__ __forceinline__ unsigned cvt_pk_bf16(float lo, float hi) { unsigned r; asm volatile("v_cvt_pk_bf16_f32 %0, %1, %2" : "=v"(r) : "v"(lo), "v"(hi)); return r; }
; __device__ __forceinline__ void small_up(const Params& p, int l, LAS unsigned char* lds, int G, int bx) {
;     ...
;             const f32x4 hcg = bg + w0g * p2g + w1g * p1g + w2g * cg_;
;             const f32x4 hcv = bv + w0v * p2v + w1v * p1v + w2v * cv_;
;             const f32x2 ga = gelu_pk((f32x2){hcg[0], hcg[1]}), gb2 = gelu_pk((f32x2){hcg[2], hcg[3]});
;             u32x2 w; w.x = cvt_pk_bf16(ga.x * hcv[0], ga.y * hcv[1]); w.y = cvt_pk_bf16(gb2.x * hcv[2], gb2.y * hcv[3]);
;             *(u32x2*)(U + (size_t)id.row * FF + colg) = w;
;             if (fr >= 14) { float* cp = conv_s + (size_t)(id.w * 2 + (fr - 14)) * FF2; *(f32x4*)(cp + colg) = cg_; *(f32x4*)(cp + colv) = cv_; }
	v_pk_fma_f32 v[78:79], v[64:65], v[86:87], v[78:79]
	v_mov_b32_dpp v124, v73 row_ror:1 row_mask:0xf bank_mask:0xf
	v_cndmask_b32_e64 v73, v66, v104, s[46:47]
	v_mov_b32_e32 v104, v97
	v_and_b32_e32 v87, 0x7fffffff, v79
	v_and_b32_e32 v86, 0x7fffffff, v78
	v_mov_b32_dpp v104, v73 row_ror:2 row_mask:0xf bank_mask:0xf
	v_cndmask_b32_e64 v73, v70, v100, s[50:51]
	v_pk_fma_f32 v[86:87], v[86:87], s[6:7], 1.0 op_sel_hi:[1,0,0]
	v_cmp_gt_f32_e32 vcc, 0, v78
	v_mov_b32_dpp v126, v73 row_ror:1 row_mask:0xf bank_mask:0xf
	v_cndmask_b32_e64 v73, v70, v100, s[46:47]
	v_mov_b32_e32 v100, v97
	v_rcp_f32_e32 v86, v86
	v_rcp_f32_e32 v87, v87
	v_mov_b32_dpp v100, v73 row_ror:2 row_mask:0xf bank_mask:0xf
	v_cndmask_b32_e64 v73, v67, v105, s[50:51]
	s_nop 1
	v_mov_b32_dpp v125, v73 row_ror:1 row_mask:0xf bank_mask:0xf
	v_cndmask_b32_e64 v73, v67, v105, s[46:47]
	v_mov_b32_e32 v105, v97
	s_nop 1
	v_mov_b32_dpp v105, v73 row_ror:2 row_mask:0xf bank_mask:0xf
	v_pk_fma_f32 v[80:81], v[80:81], v[104:105], v[92:93]
	v_pk_mul_f32 v[92:93], v[78:79], v[78:79]
	v_pk_fma_f32 v[80:81], v[84:85], v[124:125], v[80:81]
	v_pk_mul_f32 v[92:93], v[92:93], s[36:37] op_sel_hi:[1,0]
	v_pk_fma_f32 v[80:81], v[66:67], v[88:89], v[80:81]
	v_mov_b64_e32 v[88:89], s[0:1]
	v_pk_fma_f32 v[90:91], v[86:87], s[24:25], v[88:89] op_sel_hi:[1,0,0]
	v_exp_f32_e32 v92, v92
	v_pk_fma_f32 v[90:91], v[86:87], v[90:91], s[28:29] op_sel_hi:[1,1,0]
	v_exp_f32_e32 v93, v93
	v_pk_fma_f32 v[90:91], v[86:87], v[90:91], s[30:31] op_sel_hi:[1,1,0]
	v_cndmask_b32_e64 v73, v71, v101, s[50:51]
	v_pk_fma_f32 v[90:91], v[86:87], v[90:91], s[34:35] op_sel_hi:[1,1,0]
	s_waitcnt vmcnt(2)
	v_pk_fma_f32 v[84:85], v[106:107], v[98:99], v[118:119]
	v_pk_mul_f32 v[86:87], v[86:87], v[90:91]
	v_mov_b32_dpp v127, v73 row_ror:1 row_mask:0xf bank_mask:0xf
	v_pk_mul_f32 v[86:87], v[92:93], v[86:87]
	v_cndmask_b32_e64 v73, v71, v101, s[46:47]
	v_mov_b32_e32 v101, v97
	v_pk_mul_f32 v[92:93], v[78:79], v[86:87]
	v_pk_fma_f32 v[86:87], v[78:79], v[86:87], v[78:79] neg_lo:[1,0,0] neg_hi:[1,0,0]
	v_mov_b32_dpp v101, v73 row_ror:2 row_mask:0xf bank_mask:0xf
	v_cndmask_b32_e32 v73, v86, v92, vcc
	v_cmp_gt_f32_e32 vcc, 0, v79
	v_and_b32_e32 v79, 0x7fffffff, v81
	v_and_b32_e32 v78, 0x7fffffff, v80
	v_pk_fma_f32 v[78:79], v[78:79], s[6:7], 1.0 op_sel_hi:[1,0,0]
	v_cndmask_b32_e32 v92, v87, v93, vcc
	v_rcp_f32_e32 v78, v78
	v_rcp_f32_e32 v79, v79
	v_pk_mul_f32 v[90:91], v[80:81], v[80:81]
	v_pk_fma_f32 v[82:83], v[108:109], v[100:101], v[120:121]
	v_cmp_gt_f32_e32 vcc, 0, v80
	v_pk_fma_f32 v[86:87], v[78:79], s[24:25], v[88:89] op_sel_hi:[1,0,0]
	s_waitcnt vmcnt(1)
	v_pk_fma_f32 v[82:83], v[112:113], v[126:127], v[82:83]
	v_pk_fma_f32 v[86:87], v[78:79], v[86:87], s[28:29] op_sel_hi:[1,1,0]
	v_pk_fma_f32 v[84:85], v[110:111], v[122:123], v[84:85]
	v_pk_fma_f32 v[86:87], v[78:79], v[86:87], s[30:31] op_sel_hi:[1,1,0]
	s_waitcnt vmcnt(0)
	v_pk_fma_f32 v[82:83], v[70:71], v[116:117], v[82:83]
	v_pk_fma_f32 v[86:87], v[78:79], v[86:87], s[34:35] op_sel_hi:[1,1,0]
	v_pk_fma_f32 v[84:85], v[68:69], v[114:115], v[84:85]
	v_pk_mul_f32 v[78:79], v[78:79], v[86:87]
	v_pk_mul_f32 v[86:87], v[90:91], s[36:37] op_sel_hi:[1,0]
	v_mul_f32_e32 v73, v84, v73
	v_exp_f32_e32 v86, v86
	v_exp_f32_e32 v87, v87
	s_nop 0
	v_pk_mul_f32 v[78:79], v[86:87], v[78:79]
	s_nop 0
	v_pk_mul_f32 v[86:87], v[80:81], v[78:79]
	v_pk_fma_f32 v[78:79], v[80:81], v[78:79], v[80:81] neg_lo:[1,0,0] neg_hi:[1,0,0]
	s_nop 0
	v_cndmask_b32_e32 v80, v78, v86, vcc
	v_cmp_gt_f32_e32 vcc, 0, v81
	v_mul_f32_e32 v78, v85, v92
	v_cvt_pk_bf16_f32 v78, v73, v78
	v_mul_f32_e32 v73, v82, v80
	v_cndmask_b32_e32 v79, v79, v87, vcc
	v_mul_f32_e32 v79, v83, v79
	v_cvt_pk_bf16_f32 v79, v73, v79
	v_lshl_add_u64 v[80:81], v[150:151], 1, v[142:143]
	global_store_dwordx2 v[80:81], v[78:79], off
	v_lshl_add_u64 v[78:79], v[150:151], 2, v[144:145]
	s_and_saveexec_b64 s[0:1], s[46:47]
	s_cbranch_execz .LBB0_1010
	v_lshl_add_u64 v[82:83], v[154:155], 2, v[144:145]
	global_store_dwordx4 v[78:79], v[64:67], off nt
	global_store_dwordx4 v[82:83], v[68:71], off nt

; __device__ __forceinline__ float ror1(float x) { return __builtin_bit_cast(float, __builtin_amdgcn_update_dpp(0, __builtin_bit_cast(int, x), 0x121, 0xf, 0xf, false)); }
; __device__ __forceinline__ float ror2(float x) { return __builtin_bit_cast(float, __builtin_amdgcn_update_dpp(0, __builtin_bit_cast(int, x), 0x122, 0xf, 0xf, false)); }
; template <int KSTEPS  >
; __device__ __forceinline__ void small_mma_ksplit(f32x4 (&acc)[2], const bf16_t* A, int lda, const bf16_t* Bt, int ldb, int n0, LAS unsigned char* lds, const SmallId& id) {
;     ...
;     acc[0] = (f32x4){0.f, 0.f, 0.f, 0.f}; acc[1] = acc[0];
; #pragma unroll
;     for (int w2 = 0; w2 < 8; ++w2) { acc[0] += red[((w2 * 8 + id.w) * 2 + 0) * 64 + lane]; acc[1] += red[((w2 * 8 + id.w) * 2 + 1) * 64 + lane]; }
; __device__ __forceinline__ void small_up(const Params& p, int l, LAS unsigned char* lds, int G, int bx) {
;     ...
;         for (int nb = 0; nb < 2; ++nb) {
;             const int colg = c0 + 16 * nb + 4 * id.fq, colv = FF + colg;
;             const f32x4 cg_ = acc[nb] * rs, cv_ = acc[2 + nb] * rs;
;             f32x4 hg = (f32x4){0.f, 0.f, 0.f, 0.f}, hv = hg;
;             if (fr >= 14) { const float* sp = sconv + (size_t)(id.w * 2 + (fr - 14)) * FF2; hg = *(const f32x4*)(sp + colg); hv = *(const f32x4*)(sp + colv); }
;             const f32x4 w0g = *(const f32x4*)(cw + colg), w1g = *(const f32x4*)(cw + FF2 + colg), w2g = *(const f32x4*)(cw + 2 * FF2 + colg), bg = *(const f32x4*)(cb + colg);
;             const f32x4 w0v = *(const f32x4*)(cw + colv), w1v = *(const f32x4*)(cw + FF2 + colv), w2v = *(const f32x4*)(cw + 2 * FF2 + colv), bv = *(const f32x4*)(cb + colv);
;             f32x4 p1g, p2g, p1v, p2v;
; #pragma unroll
;             for (int j = 0; j < 4; ++j) {
;                 p1g[j] = ror1(fr == 15 ? hg[j] : cg_[j]); p2g[j] = ror2(fr >= 14 ? hg[j] : cg_[j]);
;                 p1v[j] = ror1(fr == 15 ? hv[j] : cv_[j]); p2v[j] = ror2(fr >= 14 ? hv[j] : cv_[j]);
;             }
;             const f32x4 hcg = bg + w0g * p2g + w1g * p1g + w2g * cg_;
;             const f32x4 hcv = bv + w0v * p2v + w1v * p1v + w2v * cv_;
.LBB0_1014:
	s_or_b64 exec, exec, s[0:1]
	v_pk_add_f32 v[30:31], v[30:31], 0 op_sel_hi:[1,0]
	v_pk_add_f32 v[28:29], v[28:29], 0 op_sel_hi:[1,0]
	v_pk_add_f32 v[26:27], v[30:31], v[26:27]
	v_pk_add_f32 v[24:25], v[28:29], v[24:25]
	v_pk_add_f32 v[22:23], v[26:27], v[22:23]
	v_pk_add_f32 v[20:21], v[24:25], v[20:21]
	v_pk_add_f32 v[18:19], v[22:23], v[18:19]
	v_pk_add_f32 v[16:17], v[20:21], v[16:17]
	v_pk_add_f32 v[14:15], v[18:19], v[14:15]
	v_pk_add_f32 v[12:13], v[16:17], v[12:13]
	v_pk_add_f32 v[10:11], v[14:15], v[10:11]
	v_pk_add_f32 v[8:9], v[12:13], v[8:9]
	v_pk_add_f32 v[6:7], v[10:11], v[6:7]
	v_pk_add_f32 v[4:5], v[8:9], v[4:5]
	v_pk_add_f32 v[2:3], v[6:7], v[2:3]
	v_or_b32_e32 v6, 16, v150
	v_ashrrev_i32_e32 v7, 31, v6
	global_load_dwordx4 v[8:11], v[74:75], off offset:64
	v_lshlrev_b64 v[6:7], 2, v[6:7]
	v_lshl_add_u64 v[16:17], s[42:43], 0, v[6:7]
	v_lshl_add_u64 v[6:7], s[94:95], 0, v[6:7]
	global_load_dwordx4 v[12:15], v[76:77], off offset:64
	s_nop 0
	global_load_dwordx4 v[16:19], v[16:17], off
	s_nop 0
	global_load_dwordx4 v[20:23], v[6:7], off
	v_lshlrev_b64 v[6:7], 2, v[82:83]
	v_lshl_add_u64 v[24:25], s[40:41], 0, v[6:7]
	v_lshl_add_u64 v[28:29], s[44:45], 0, v[6:7]
	global_load_dwordx4 v[24:27], v[24:25], off
	v_pk_add_f32 v[0:1], v[4:5], v[0:1]
	global_load_dwordx4 v[28:31], v[28:29], off
	v_pk_add_f32 v[4:5], v[54:55], 0 op_sel_hi:[1,0]
	v_lshl_add_u64 v[54:55], s[42:43], 0, v[6:7]
	v_pk_add_f32 v[52:53], v[52:53], 0 op_sel_hi:[1,0]
	global_load_dwordx4 v[74:77], v[54:55], off
	v_pk_add_f32 v[52:53], v[52:53], v[56:57]
	v_lshl_add_u64 v[6:7], s[94:95], 0, v[6:7]
	v_pk_add_f32 v[56:57], v[52:53], v[60:61]
	global_load_dwordx4 v[52:55], v[6:7], off
	v_pk_add_f32 v[4:5], v[4:5], v[58:59]
	v_pk_add_f32 v[6:7], v[56:57], v[32:33]
	v_pk_add_f32 v[4:5], v[4:5], v[62:63]
	v_pk_add_f32 v[6:7], v[6:7], v[36:37]
	v_pk_add_f32 v[4:5], v[4:5], v[34:35]
	v_pk_add_f32 v[6:7], v[6:7], v[40:41]
	v_pk_add_f32 v[4:5], v[4:5], v[38:39]
	v_mov_b32_e32 v73, v72
	v_pk_add_f32 v[4:5], v[4:5], v[42:43]
	v_pk_add_f32 v[6:7], v[6:7], v[44:45]
	v_pk_add_f32 v[4:5], v[4:5], v[46:47]
	v_pk_add_f32 v[32:33], v[6:7], v[48:49]
	v_pk_add_f32 v[4:5], v[4:5], v[50:51]
	v_mov_b32_e32 v6, v72
	v_mov_b32_e32 v7, v72
	v_pk_mul_f32 v[0:1], v[0:1], v[72:73]
	v_pk_mul_f32 v[2:3], v[2:3], v[6:7]
	v_pk_mul_f32 v[6:7], v[4:5], v[6:7]
	v_pk_mul_f32 v[4:5], v[32:33], v[72:73]
	s_waitcnt vmcnt(0)
; __device__ __forceinline__ unsigned cvt_pk_bf16(float lo, float hi) { unsigned r; asm volatile("v_cvt_pk_bf16_f32 %0, %1, %2" : "=v"(r) : "v"(lo), "v"(hi)); return r; }
; __device__ __forceinline__ float ror1(float x) { return __builtin_bit_cast(float, __builtin_amdgcn_update_dpp(0, __builtin_bit_cast(int, x), 0x121, 0xf, 0xf, false)); }
; __device__ __forceinline__ float ror2(float x) { return __builtin_bit_cast(float, __builtin_amdgcn_update_dpp(0, __builtin_bit_cast(int, x), 0x122, 0xf, 0xf, false)); }
; __device__ __forceinline__ void small_up(const Params& p, int l, LAS unsigned char* lds, int G, int bx) {
;     ...
;             f32x4 p1g, p2g, p1v, p2v;
; #pragma unroll
;             for (int j = 0; j < 4; ++j) {
;                 p1g[j] = ror1(fr == 15 ? hg[j] : cg_[j]); p2g[j] = ror2(fr >= 14 ? hg[j] : cg_[j]);
;                 p1v[j] = ror1(fr == 15 ? hv[j] : cv_[j]); p2v[j] = ror2(fr >= 14 ? hv[j] : cv_[j]);
;             }
;             const f32x4 hcg = bg + w0g * p2g + w1g * p1g + w2g * cg_;
;             const f32x4 hcv = bv + w0v * p2v + w1v * p1v + w2v * cv_;
;             const f32x2 ga = gelu_pk((f32x2){hcg[0], hcg[1]}), gb2 = gelu_pk((f32x2){hcg[2], hcg[3]});
;             u32x2 w; w.x = cvt_pk_bf16(ga.x * hcv[0], ga.y * hcv[1]); w.y = cvt_pk_bf16(gb2.x * hcv[2], gb2.y * hcv[3]);
;             *(u32x2*)(U + (size_t)id.row * FF + colg) = w;
;             if (fr >= 14) { float* cp = conv_s + (size_t)(id.w * 2 + (fr - 14)) * FF2; *(f32x4*)(cp + colg) = cg_; *(f32x4*)(cp + colv) = cv_; }
	v_cndmask_b32_e64 v33, v0, v68, s[50:51]
	v_mov_b32_e32 v32, v97
	v_mov_b32_e32 v34, v97
	v_mov_b32_e32 v36, v97
	v_mov_b32_dpp v32, v33 row_ror:1 row_mask:0xf bank_mask:0xf
	v_cndmask_b32_e64 v33, v0, v68, s[46:47]
	v_mov_b32_e32 v38, v97
	v_cndmask_b32_e64 v35, v1, v69, s[50:51]
	v_mov_b32_dpp v34, v33 row_ror:2 row_mask:0xf bank_mask:0xf
	v_cndmask_b32_e64 v33, v4, v64, s[50:51]
	v_cndmask_b32_e64 v37, v1, v69, s[46:47]
	v_cndmask_b32_e64 v39, v5, v65, s[50:51]
	v_mov_b32_dpp v36, v33 row_ror:1 row_mask:0xf bank_mask:0xf
	v_cndmask_b32_e64 v33, v4, v64, s[46:47]
	v_cndmask_b32_e64 v40, v5, v65, s[46:47]
	v_cndmask_b32_e64 v41, v2, v70, s[50:51]
	v_mov_b32_dpp v38, v33 row_ror:2 row_mask:0xf bank_mask:0xf
	v_mov_b32_e32 v33, v97
	v_mov_b32_e32 v42, v97
	v_mov_b32_e32 v44, v97
	v_mov_b32_dpp v33, v35 row_ror:1 row_mask:0xf bank_mask:0xf
	v_mov_b32_e32 v35, v97
	v_mov_b32_e32 v46, v97
	v_cndmask_b32_e64 v43, v3, v71, s[50:51]
	v_mov_b32_dpp v35, v37 row_ror:2 row_mask:0xf bank_mask:0xf
	v_mov_b32_e32 v37, v97
	v_cndmask_b32_e64 v45, v3, v71, s[46:47]
	s_mov_b32 s0, 0xbf3a00e3
	v_mov_b32_dpp v37, v39 row_ror:1 row_mask:0xf bank_mask:0xf
	v_mov_b32_e32 v39, v97
	v_cndmask_b32_e64 v47, v7, v67, s[50:51]
	v_cndmask_b32_e64 v48, v7, v67, s[46:47]
	v_mov_b32_dpp v39, v40 row_ror:2 row_mask:0xf bank_mask:0xf
	v_mov_b32_e32 v40, v97
	v_pk_fma_f32 v[8:9], v[8:9], v[34:35], v[12:13]
	s_nop 0
	v_mov_b32_dpp v40, v41 row_ror:1 row_mask:0xf bank_mask:0xf
	v_cndmask_b32_e64 v41, v2, v70, s[46:47]
	v_pk_fma_f32 v[8:9], v[16:17], v[32:33], v[8:9]
	s_nop 0
	v_mov_b32_dpp v42, v41 row_ror:2 row_mask:0xf bank_mask:0xf
	v_cndmask_b32_e64 v41, v6, v66, s[50:51]
	v_pk_fma_f32 v[8:9], v[0:1], v[20:21], v[8:9]
	s_nop 0
	v_mov_b32_dpp v44, v41 row_ror:1 row_mask:0xf bank_mask:0xf
	v_cndmask_b32_e64 v41, v6, v66, s[46:47]
	v_and_b32_e32 v17, 0x7fffffff, v9
	v_and_b32_e32 v16, 0x7fffffff, v8
	v_mov_b32_dpp v46, v41 row_ror:2 row_mask:0xf bank_mask:0xf
	v_mov_b32_e32 v41, v97
	v_pk_fma_f32 v[16:17], v[16:17], s[6:7], 1.0 op_sel_hi:[1,0,0]
	v_cmp_gt_f32_e32 vcc, 0, v8
	v_mov_b32_dpp v41, v43 row_ror:1 row_mask:0xf bank_mask:0xf
	v_mov_b32_e32 v43, v97
	v_rcp_f32_e32 v16, v16
	v_rcp_f32_e32 v17, v17
	v_mov_b32_dpp v43, v45 row_ror:2 row_mask:0xf bank_mask:0xf
	v_pk_fma_f32 v[10:11], v[10:11], v[42:43], v[14:15]
	v_pk_fma_f32 v[14:15], v[24:25], v[38:39], v[28:29]
	v_pk_fma_f32 v[10:11], v[18:19], v[40:41], v[10:11]
	v_mov_b64_e32 v[18:19], s[0:1]
	v_pk_fma_f32 v[10:11], v[2:3], v[22:23], v[10:11]
	v_pk_mul_f32 v[22:23], v[8:9], v[8:9]
	v_pk_fma_f32 v[20:21], v[16:17], s[24:25], v[18:19] op_sel_hi:[1,0,0]
	v_pk_mul_f32 v[22:23], v[22:23], s[36:37] op_sel_hi:[1,0]
	v_pk_fma_f32 v[20:21], v[16:17], v[20:21], s[28:29] op_sel_hi:[1,1,0]
	v_exp_f32_e32 v22, v22
	v_exp_f32_e32 v23, v23
	v_pk_fma_f32 v[20:21], v[16:17], v[20:21], s[30:31] op_sel_hi:[1,1,0]
	v_and_b32_e32 v25, 0x7fffffff, v11
	v_and_b32_e32 v24, 0x7fffffff, v10
	v_pk_fma_f32 v[20:21], v[16:17], v[20:21], s[34:35] op_sel_hi:[1,1,0]
	v_pk_fma_f32 v[24:25], v[24:25], s[6:7], 1.0 op_sel_hi:[1,0,0]
	v_pk_mul_f32 v[16:17], v[16:17], v[20:21]
	v_rcp_f32_e32 v24, v24
	v_rcp_f32_e32 v25, v25
	v_pk_mul_f32 v[16:17], v[22:23], v[16:17]
	v_pk_mul_f32 v[20:21], v[10:11], v[10:11]
	v_pk_mul_f32 v[22:23], v[8:9], v[16:17]
	v_pk_fma_f32 v[16:17], v[8:9], v[16:17], v[8:9] neg_lo:[1,0,0] neg_hi:[1,0,0]
	v_mov_b32_e32 v45, v97
	v_cndmask_b32_e32 v22, v16, v22, vcc
	v_cmp_gt_f32_e32 vcc, 0, v9
	v_pk_fma_f32 v[8:9], v[24:25], s[24:25], v[18:19] op_sel_hi:[1,0,0]
	v_mov_b32_dpp v45, v47 row_ror:1 row_mask:0xf bank_mask:0xf
	v_cndmask_b32_e32 v23, v17, v23, vcc
	v_pk_mul_f32 v[16:17], v[20:21], s[36:37] op_sel_hi:[1,0]
	v_pk_fma_f32 v[8:9], v[24:25], v[8:9], s[28:29] op_sel_hi:[1,1,0]
	v_exp_f32_e32 v16, v16
	v_exp_f32_e32 v17, v17
	v_pk_fma_f32 v[8:9], v[24:25], v[8:9], s[30:31] op_sel_hi:[1,1,0]
	v_mov_b32_e32 v47, v97
	v_pk_fma_f32 v[8:9], v[24:25], v[8:9], s[34:35] op_sel_hi:[1,1,0]
	v_cmp_gt_f32_e32 vcc, 0, v10
	v_pk_mul_f32 v[8:9], v[24:25], v[8:9]
	v_mov_b32_dpp v47, v48 row_ror:2 row_mask:0xf bank_mask:0xf
	v_pk_mul_f32 v[8:9], v[16:17], v[8:9]
	v_pk_fma_f32 v[12:13], v[26:27], v[46:47], v[30:31]
	v_pk_mul_f32 v[16:17], v[10:11], v[8:9]
	v_pk_fma_f32 v[8:9], v[10:11], v[8:9], v[10:11] neg_lo:[1,0,0] neg_hi:[1,0,0]
	v_pk_fma_f32 v[12:13], v[76:77], v[44:45], v[12:13]
	v_pk_fma_f32 v[14:15], v[74:75], v[36:37], v[14:15]
	v_cndmask_b32_e32 v10, v8, v16, vcc
	v_cmp_gt_f32_e32 vcc, 0, v11
	v_pk_fma_f32 v[12:13], v[6:7], v[54:55], v[12:13]
	v_pk_fma_f32 v[14:15], v[4:5], v[52:53], v[14:15]
	v_cndmask_b32_e32 v9, v9, v17, vcc
	v_mul_f32_e32 v8, v14, v22
	v_mul_f32_e32 v9, v13, v9
	v_mul_f32_e32 v11, v15, v23
	v_cvt_pk_bf16_f32 v8, v8, v11
	v_mul_f32_e32 v10, v12, v10
	v_cvt_pk_bf16_f32 v9, v10, v9
	global_store_dwordx2 v[80:81], v[8:9], off offset:32
	s_and_saveexec_b64 s[0:1], s[46:47]
	s_cbranch_execz .LBB0_1001
	v_lshl_add_u64 v[8:9], v[82:83], 2, v[144:145]
	global_store_dwordx4 v[78:79], v[0:3], off offset:64 nt
	global_store_dwordx4 v[8:9], v[4:7], off nt
	s_branch .LBB0_1001

; #define LAS __attribute__((address_space(3)))
; template <int KSTEPS  >
; __device__ __forceinline__ void small_mma_ksplit(f32x4 (&acc)[2], const bf16_t* A, int lda, const bf16_t* Bt, int ldb, int n0, LAS unsigned char* lds, const SmallId& id) {
;     const int lane = id.fq * 16 + id.fr, k0 = id.w * (KSTEPS * 32);
;     f32x4 part[8][2];
; #pragma unroll
;     for (int rb = 0; rb < 8; ++rb) { part[rb][0] = (f32x4){0.f, 0.f, 0.f, 0.f}; part[rb][1] = part[rb][0]; }
;     const bf16_t* ap = A + (size_t)(MP + id.fr) * lda + k0 + 8 * id.fq;
;     const bf16_t* bp = Bt + (size_t)(n0 + id.fr) * ldb + k0 + 8 * id.fq;
; #pragma unroll 1
;     for (int ks = 0; ks < KSTEPS; ++ks) {
;         bf16x8 a[8], b[2];
; #pragma unroll
;         for (int rb = 0; rb < 8; ++rb) a[rb] = *(const bf16x8*)(ap + (size_t)(16 * rb) * lda + 32 * ks);
;         b[0] = *(const bf16x8*)(bp + 32 * ks); b[1] = *(const bf16x8*)(bp + (size_t)16 * ldb + 32 * ks);
; #pragma unroll
;         for (int rb = 0; rb < 8; ++rb) { part[rb][0] = __builtin_amdgcn_mfma_f32_16x16x32_bf16(b[0], a[rb], part[rb][0], 0, 0, 0); part[rb][1] = __builtin_amdgcn_mfma_f32_16x16x32_bf16(b[1], a[rb], part[rb][1], 0, 0, 0); }
;     }
;     LAS f32x4* red = (LAS f32x4*)lds;
; #pragma unroll
;     for (int rb = 0; rb < 8; ++rb) { red[((id.w * 8 + rb) * 2 + 0) * 64 + lane] = part[rb][0]; red[((id.w * 8 + rb) * 2 + 1) * 64 + lane] = part[rb][1]; }
;     asm volatile("s_waitcnt lgkmcnt(0)" ::: "memory"); __syncthreads();
.LBB0_1223:
	v_lshl_or_b32 v218, s2, 5, v84
	v_ashrrev_i32_e32 v219, 31, v218
	v_lshl_add_u64 v[220:221], v[218:219], 1, v[64:65]
	global_load_dwordx2 v[250:251], v[220:221], off
	global_load_dwordx2 v[234:235], v[220:221], off offset:32
	s_waitcnt lgkmcnt(0)
	v_readlane_b32 s0, v246, 8
	v_readfirstlane_b32 s32, v222
	s_bfe_u32 s0, s0, 0x30003
	s_lshr_b32 s32, s32, 6
	s_cmp_eq_u32 s32, s0
	s_cselect_b32 s32, 1, 0
	s_lshl_b32 s1, s0, 11
	v_add_u32_e32 v68, s1, v74
	s_sub_i32 s1, s53, s52
	s_mul_i32 s0, s0, s1
	s_add_i32 s0, s0, s52
	s_mov_b32 s1, 0
	v_lshl_add_u64 v[86:87], v[70:71], 0, s[0:1]
	s_mov_b32 s0, s62
	v_lshl_add_u64 v[88:89], v[72:73], 0, s[0:1]
	s_mov_b32 s0, s63
	v_lshl_add_u64 v[90:91], v[72:73], 0, s[0:1]
	global_load_dwordx4 v[92:95], v[86:87], off
	global_load_dwordx4 v[98:101], v[88:89], off
	global_load_dwordx4 v[102:105], v[90:91], off
	global_load_dwordx4 v[106:109], v[86:87], off offset:64
	global_load_dwordx4 v[110:113], v[88:89], off offset:64
	global_load_dwordx4 v[114:117], v[90:91], off offset:64
	global_load_dwordx4 v[118:121], v[86:87], off offset:128
	global_load_dwordx4 v[122:125], v[88:89], off offset:128
	global_load_dwordx4 v[126:129], v[90:91], off offset:128
	global_load_dwordx4 v[130:133], v[86:87], off offset:192
	global_load_dwordx4 v[134:137], v[88:89], off offset:192
	global_load_dwordx4 v[138:141], v[90:91], off offset:192
	global_load_dwordx4 v[142:145], v[86:87], off offset:256
	global_load_dwordx4 v[146:149], v[88:89], off offset:256
	global_load_dwordx4 v[150:153], v[90:91], off offset:256
	global_load_dwordx4 v[154:157], v[86:87], off offset:320
	global_load_dwordx4 v[158:161], v[88:89], off offset:320
	global_load_dwordx4 v[162:165], v[90:91], off offset:320
	global_load_dwordx4 v[166:169], v[86:87], off offset:384
	global_load_dwordx4 v[170:173], v[88:89], off offset:384
	global_load_dwordx4 v[174:177], v[90:91], off offset:384
	global_load_dwordx4 v[178:181], v[86:87], off offset:448
	global_load_dwordx4 v[182:185], v[88:89], off offset:448
	global_load_dwordx4 v[186:189], v[90:91], off offset:448
	s_waitcnt vmcnt(21)
	v_mfma_f32_16x16x32_bf16 v[36:39], v[98:101], v[92:95], v[36:39]
	v_mfma_f32_16x16x32_bf16 v[24:27], v[102:105], v[92:95], v[24:27]
	global_load_dwordx4 v[92:95], v[86:87], off offset:512
	global_load_dwordx4 v[98:101], v[88:89], off offset:512
	global_load_dwordx4 v[102:105], v[90:91], off offset:512
	s_waitcnt vmcnt(21)
	v_mfma_f32_16x16x32_bf16 v[36:39], v[110:113], v[106:109], v[36:39]
	v_mfma_f32_16x16x32_bf16 v[24:27], v[114:117], v[106:109], v[24:27]
	global_load_dwordx4 v[106:109], v[86:87], off offset:576
	global_load_dwordx4 v[110:113], v[88:89], off offset:576
	global_load_dwordx4 v[114:117], v[90:91], off offset:576
	s_waitcnt vmcnt(21)
	v_mfma_f32_16x16x32_bf16 v[36:39], v[122:125], v[118:121], v[36:39]
	v_mfma_f32_16x16x32_bf16 v[24:27], v[126:129], v[118:121], v[24:27]
	global_load_dwordx4 v[118:121], v[86:87], off offset:640
	global_load_dwordx4 v[122:125], v[88:89], off offset:640
	global_load_dwordx4 v[126:129], v[90:91], off offset:640
	s_waitcnt vmcnt(21)
	v_mfma_f32_16x16x32_bf16 v[36:39], v[134:137], v[130:133], v[36:39]
	v_mfma_f32_16x16x32_bf16 v[24:27], v[138:141], v[130:133], v[24:27]
	s_waitcnt vmcnt(18)
	v_mfma_f32_16x16x32_bf16 v[36:39], v[146:149], v[142:145], v[36:39]
	v_mfma_f32_16x16x32_bf16 v[24:27], v[150:153], v[142:145], v[24:27]
	s_waitcnt vmcnt(15)
	v_mfma_f32_16x16x32_bf16 v[36:39], v[158:161], v[154:157], v[36:39]
	v_mfma_f32_16x16x32_bf16 v[24:27], v[162:165], v[154:157], v[24:27]
	s_waitcnt vmcnt(12)
	v_mfma_f32_16x16x32_bf16 v[36:39], v[170:173], v[166:169], v[36:39]
	v_mfma_f32_16x16x32_bf16 v[24:27], v[174:177], v[166:169], v[24:27]
	s_waitcnt vmcnt(9)
	v_mfma_f32_16x16x32_bf16 v[36:39], v[182:185], v[178:181], v[36:39]
	v_mfma_f32_16x16x32_bf16 v[24:27], v[186:189], v[178:181], v[24:27]
	s_waitcnt vmcnt(6)
	v_mfma_f32_16x16x32_bf16 v[36:39], v[98:101], v[92:95], v[36:39]
	v_mfma_f32_16x16x32_bf16 v[24:27], v[102:105], v[92:95], v[24:27]
	s_waitcnt vmcnt(3)
	v_mfma_f32_16x16x32_bf16 v[36:39], v[110:113], v[106:109], v[36:39]
	v_mfma_f32_16x16x32_bf16 v[24:27], v[114:117], v[106:109], v[24:27]
	s_waitcnt vmcnt(0)
	v_mfma_f32_16x16x32_bf16 v[36:39], v[122:125], v[118:121], v[36:39]
	v_mfma_f32_16x16x32_bf16 v[24:27], v[126:129], v[118:121], v[24:27]
	s_nop 7
	s_nop 1
	ds_write_b128 v68, v[36:39]
	ds_write_b128 v68, v[24:27] offset:1024
	s_waitcnt lgkmcnt(0)
	s_waitcnt lgkmcnt(0)
	s_barrier
; __device__ __forceinline__ unsigned cvt_pk_bf16(float lo, float hi) { unsigned r; asm volatile("v_cvt_pk_bf16_f32 %0, %1, %2" : "=v"(r) : "v"(lo), "v"(hi)); return r; }
; template <int KSTEPS  >
; __device__ __forceinline__ void small_mma_ksplit(f32x4 (&acc)[2], const bf16_t* A, int lda, const bf16_t* Bt, int ldb, int n0, LAS unsigned char* lds, const SmallId& id) {
;     ...
;     asm volatile("s_waitcnt lgkmcnt(0)" ::: "memory"); __syncthreads();
;     acc[0] = (f32x4){0.f, 0.f, 0.f, 0.f}; acc[1] = acc[0];
; #pragma unroll
;     for (int w2 = 0; w2 < 8; ++w2) { acc[0] += red[((w2 * 8 + id.w) * 2 + 0) * 64 + lane]; acc[1] += red[((w2 * 8 + id.w) * 2 + 1) * 64 + lane]; }
; template <bool RES_F32, bool OUT_F32, int KSTEPS>
; __device__ __forceinline__ void small_res(const Params& p, LAS unsigned char* lds, const bf16_t* A, int lda, const bf16_t* Bt, int K, float* ssq_next, int G, int bx) {
;     ...
;         float s = 0.f;
; #pragma unroll
;         for (int nb = 0; nb < 2; ++nb) { const int col = n0 + 16 * nb + 4 * id.fq;
;             f32x4 r;
;             if (RES_F32) r = *(const f32x4*)(p.xs + (size_t)(id.row - MP) * DM + col);
;             else { const u32x2 w = *(const u32x2*)(XB + (size_t)id.row * DM + col); r = (f32x4){bf_lo(w.x), bf_hi(w.x), bf_lo(w.y), bf_hi(w.y)}; }
;             const f32x4 x = r + acc[nb];
;             if (OUT_F32) *(f32x4*)(p.out + (size_t)id.row * DM + col) = x;
;             else { u32x2 w; w.x = cvt_pk_bf16(x[0], x[1]); w.y = cvt_pk_bf16(x[2], x[3]); *(u32x2*)(XB + (size_t)id.row * DM + col) = w; }
	ds_read_b128 v[92:95], v75
	ds_read_b128 v[98:101], v75 offset:1024
	ds_read_b128 v[102:105], v75 offset:16384
	ds_read_b128 v[106:109], v75 offset:17408
	ds_read_b128 v[110:113], v75 offset:32768
	ds_read_b128 v[114:117], v75 offset:33792
	ds_read_b128 v[118:121], v75 offset:49152
	ds_read_b128 v[122:125], v75 offset:50176
	ds_read_b128 v[126:129], v76
	ds_read_b128 v[130:133], v77
	ds_read_b128 v[134:137], v78
	ds_read_b128 v[138:141], v79
	ds_read_b128 v[142:145], v80
	ds_read_b128 v[146:149], v81
	ds_read_b128 v[150:153], v82
	ds_read_b128 v[0:3], v83
	s_waitcnt lgkmcnt(0)
	v_lshl_or_b32 v12, s2, 5, v84
	v_ashrrev_i32_e32 v13, 31, v12
	v_lshl_add_u64 v[14:15], v[12:13], 1, v[64:65]
	s_add_i32 s2, s2, s92
	v_pk_add_f32 v[4:5], v[94:95], 0 op_sel_hi:[1,0]
	v_pk_add_f32 v[6:7], v[92:93], 0 op_sel_hi:[1,0]
	v_add_u32_e32 v85, s37, v85
	s_cmp_lt_i32 s2, 32
	v_pk_add_f32 v[8:9], v[100:101], 0 op_sel_hi:[1,0]
	v_pk_add_f32 v[10:11], v[98:99], 0 op_sel_hi:[1,0]
	v_pk_add_f32 v[4:5], v[4:5], v[104:105]
	v_pk_add_f32 v[6:7], v[6:7], v[102:103]
	v_pk_add_f32 v[8:9], v[8:9], v[108:109]
	v_pk_add_f32 v[10:11], v[10:11], v[106:107]
	v_pk_add_f32 v[4:5], v[4:5], v[112:113]
	v_pk_add_f32 v[6:7], v[6:7], v[110:111]
	v_pk_add_f32 v[8:9], v[8:9], v[116:117]
	v_pk_add_f32 v[10:11], v[10:11], v[114:115]
	v_pk_add_f32 v[4:5], v[4:5], v[120:121]
	v_pk_add_f32 v[6:7], v[6:7], v[118:119]
	v_pk_add_f32 v[8:9], v[8:9], v[124:125]
	v_pk_add_f32 v[10:11], v[10:11], v[122:123]
	v_pk_add_f32 v[4:5], v[4:5], v[128:129]
	v_pk_add_f32 v[6:7], v[6:7], v[126:127]
	v_pk_add_f32 v[8:9], v[8:9], v[132:133]
	v_pk_add_f32 v[10:11], v[10:11], v[130:131]
	v_pk_add_f32 v[4:5], v[4:5], v[136:137]
	v_pk_add_f32 v[6:7], v[6:7], v[134:135]
	v_pk_add_f32 v[8:9], v[8:9], v[140:141]
	v_pk_add_f32 v[10:11], v[10:11], v[138:139]
	v_pk_add_f32 v[4:5], v[4:5], v[144:145]
	v_pk_add_f32 v[6:7], v[6:7], v[142:143]
	v_pk_add_f32 v[8:9], v[8:9], v[148:149]
	v_pk_add_f32 v[10:11], v[10:11], v[146:147]
	v_pk_add_f32 v[4:5], v[4:5], v[152:153]
	v_pk_add_f32 v[6:7], v[6:7], v[150:151]
	s_waitcnt lgkmcnt(0)
	s_waitcnt lgkmcnt(0)
	s_barrier
	s_mul_i32 exec_lo, s32, -1
	s_mov_b32 exec_hi, exec_lo
	v_pk_add_f32 v[10:11], v[10:11], v[0:1]
	v_mov_b64_e32 v[0:1], v[250:251]
	v_pk_add_f32 v[8:9], v[8:9], v[2:3]
	s_waitcnt vmcnt(0) lgkmcnt(0)
	v_lshlrev_b32_e32 v2, 16, v0
	v_and_b32_e32 v3, 0xffff0000, v0
	v_lshlrev_b32_e32 v16, 16, v1
	v_and_b32_e32 v17, 0xffff0000, v1
	v_pk_add_f32 v[0:1], v[6:7], v[2:3]
	v_pk_add_f32 v[2:3], v[4:5], v[16:17]
	v_lshl_add_u64 v[4:5], v[12:13], 2, v[66:67]
	global_store_dwordx4 v[4:5], v[0:3], off nt
	s_waitcnt vmcnt(0) lgkmcnt(0)
	v_lshlrev_b32_e32 v6, 16, v234
	v_and_b32_e32 v7, 0xffff0000, v234
	v_lshlrev_b32_e32 v0, 16, v235
	v_and_b32_e32 v1, 0xffff0000, v235
	v_pk_add_f32 v[2:3], v[8:9], v[0:1]
	v_pk_add_f32 v[0:1], v[10:11], v[6:7]
	global_store_dwordx4 v[4:5], v[0:3], off offset:64 nt
	s_cbranch_scc1 .LBB0_1222

;     __device__ __forceinline__ void finish(const f32x4 x0, const f32x4 x1, int row, int col, float& s) const {
;         if (OUT_F32) { *(f32x4*)(out + (size_t)row * DM + col) = x0; *(f32x4*)(out + (size_t)row * DM + col + 4) = x1; }
;     __device__ __forceinline__ void operator()(AccT& acc, const Unit& u, int wr, int wc, int fr, int fq) const {
;     ...
;             u32x4 rb[2][4][2];
; #pragma unroll
;             for (int ai = 0; ai < 2; ++ai)
; #pragma unroll
;                 for (int m = 0; m < 4; ++m)
; #pragma unroll
;                     for (int bj = 0; bj < 2; ++bj) rb[ai][m][bj] = __builtin_nontemporal_load((const u32x4*)((const char*)XB + (unsigned)(((u.pm * 256 + ai * 128 + wr * 64 + m * 16 + fr) * DM + col0 + bj * 128) * 2)));
; #pragma unroll
;             for (int ai = 0; ai < 2; ++ai)
; #pragma unroll
;                 for (int m = 0; m < 4; ++m) {
;                     const int row = u.pm * 256 + ai * 128 + wr * 64 + m * 16 + fr; float s = 0.f;
; #pragma unroll
;                     for (int bj = 0; bj < 2; ++bj) { const u32x4 w = rb[ai][m][bj];
;                         finish((f32x4){bf_lo(w.x), bf_hi(w.x), bf_lo(w.y), bf_hi(w.y)} + acc[ai][bj][m][0], (f32x4){bf_lo(w.z), bf_hi(w.z), bf_lo(w.w), bf_hi(w.w)} + acc[ai][bj][m][1], row, col0 + bj * 128, s); }
.LBB0_1245:
	s_lshl_b32 s12, s44, 8
	v_mov_b32_e32 v96, v229
	v_mov_b32_e32 v130, v230
	s_or_b32 s12, s12, s31
	s_and_b64 vcc, exec, s[46:47]
	v_lshl_add_u32 v220, v130, 3, s12
	s_lshl_b32 s12, s43, 8
	s_add_i32 s12, s12, s29
	v_add_u32_e32 v218, s12, v96
	v_lshlrev_b32_e32 v96, 11, v218
	v_lshl_add_u32 v96, v220, 1, v96
	v_lshl_add_u64 v[130:131], s[90:91], 0, v[96:97]
	global_load_dwordx4 v[190:193], v[130:131], off nt
	v_add_u32_e32 v130, 0x100, v96
	v_mov_b32_e32 v131, v97
	v_lshl_add_u64 v[130:131], s[90:91], 0, v[130:131]
	global_load_dwordx4 v[186:189], v[130:131], off nt
	v_add_u32_e32 v130, 0x8000, v96
	v_mov_b32_e32 v131, v97
	v_lshl_add_u64 v[130:131], s[90:91], 0, v[130:131]
	global_load_dwordx4 v[182:185], v[130:131], off nt
	v_add_u32_e32 v130, 0x8100, v96
	v_mov_b32_e32 v131, v97
	v_lshl_add_u64 v[130:131], s[90:91], 0, v[130:131]
	global_load_dwordx4 v[178:181], v[130:131], off nt
	v_add_u32_e32 v130, 0x10000, v96
	v_mov_b32_e32 v131, v97
	v_lshl_add_u64 v[130:131], s[90:91], 0, v[130:131]
	global_load_dwordx4 v[174:177], v[130:131], off nt
	v_add_u32_e32 v130, 0x10100, v96
	v_mov_b32_e32 v131, v97
	v_lshl_add_u64 v[130:131], s[90:91], 0, v[130:131]
	global_load_dwordx4 v[170:173], v[130:131], off nt
	v_add_u32_e32 v130, 0x18000, v96
	v_mov_b32_e32 v131, v97
	v_lshl_add_u64 v[130:131], s[90:91], 0, v[130:131]
	global_load_dwordx4 v[166:169], v[130:131], off nt
	v_add_u32_e32 v130, 0x18100, v96
	v_mov_b32_e32 v131, v97
	v_lshl_add_u64 v[130:131], s[90:91], 0, v[130:131]
	global_load_dwordx4 v[162:165], v[130:131], off nt
	v_add_u32_e32 v130, 0x40000, v96
	v_mov_b32_e32 v131, v97
	v_lshl_add_u64 v[130:131], s[90:91], 0, v[130:131]
	global_load_dwordx4 v[158:161], v[130:131], off nt
	v_add_u32_e32 v130, 0x40100, v96
	v_mov_b32_e32 v131, v97
	v_lshl_add_u64 v[130:131], s[90:91], 0, v[130:131]
	global_load_dwordx4 v[154:157], v[130:131], off nt
	v_add_u32_e32 v130, 0x48000, v96
	v_mov_b32_e32 v131, v97
	v_lshl_add_u64 v[130:131], s[90:91], 0, v[130:131]
	global_load_dwordx4 v[150:153], v[130:131], off nt
	v_add_u32_e32 v130, 0x48100, v96
	v_mov_b32_e32 v131, v97
	v_lshl_add_u64 v[130:131], s[90:91], 0, v[130:131]
	global_load_dwordx4 v[146:149], v[130:131], off nt
	v_add_u32_e32 v130, 0x50000, v96
	v_mov_b32_e32 v131, v97
	v_lshl_add_u64 v[130:131], s[90:91], 0, v[130:131]
	global_load_dwordx4 v[142:145], v[130:131], off nt
	v_add_u32_e32 v130, 0x50100, v96
	v_mov_b32_e32 v131, v97
	v_lshl_add_u64 v[130:131], s[90:91], 0, v[130:131]
	global_load_dwordx4 v[138:141], v[130:131], off nt
	v_add_u32_e32 v130, 0x58000, v96
	v_mov_b32_e32 v131, v97
	v_lshl_add_u64 v[130:131], s[90:91], 0, v[130:131]
	global_load_dwordx4 v[134:137], v[130:131], off nt
	v_add_u32_e32 v96, 0x58100, v96
	v_lshl_add_u64 v[130:131], s[90:91], 0, v[96:97]
	global_load_dwordx4 v[130:133], v[130:131], off nt
	v_ashrrev_i32_e32 v219, 31, v218
	v_ashrrev_i32_e32 v221, 31, v220
	s_mov_b64 s[12:13], -1
	s_waitcnt vmcnt(0) lgkmcnt(0)
	v_lshlrev_b32_e32 v234, 16, v190
	v_and_b32_e32 v235, 0xffff0000, v190
	v_lshlrev_b32_e32 v190, 16, v191
	v_and_b32_e32 v191, 0xffff0000, v191
	v_pk_add_f32 v[128:129], v[128:129], v[190:191]
	v_lshlrev_b32_e32 v190, 16, v192
	v_and_b32_e32 v191, 0xffff0000, v192
	v_lshlrev_b32_e32 v192, 16, v193
	v_and_b32_e32 v193, 0xffff0000, v193
	v_pk_add_f32 v[122:123], v[122:123], v[190:191]
	v_lshlrev_b64 v[190:191], 12, v[218:219]
	v_pk_add_f32 v[124:125], v[124:125], v[192:193]
	v_lshl_add_u64 v[192:193], s[64:65], 0, v[190:191]
	v_lshlrev_b64 v[190:191], 2, v[220:221]
	v_pk_add_f32 v[126:127], v[126:127], v[234:235]
	v_lshl_add_u64 v[192:193], v[192:193], 0, v[190:191]
	global_store_dwordx4 v[192:193], v[126:129], off nt
	global_store_dwordx4 v[192:193], v[122:125], off offset:16 nt
	s_nop 1
	v_lshlrev_b32_e32 v122, 16, v186
	v_and_b32_e32 v123, 0xffff0000, v186
	v_lshlrev_b32_e32 v124, 16, v187
	v_and_b32_e32 v125, 0xffff0000, v187
	v_pk_add_f32 v[118:119], v[118:119], v[122:123]
	v_lshlrev_b32_e32 v122, 16, v188
	v_and_b32_e32 v123, 0xffff0000, v188
	v_pk_add_f32 v[120:121], v[120:121], v[124:125]
	v_lshlrev_b32_e32 v124, 16, v189
	v_and_b32_e32 v125, 0xffff0000, v189
	v_pk_add_f32 v[110:111], v[110:111], v[122:123]
	v_pk_add_f32 v[112:113], v[112:113], v[124:125]
	global_store_dwordx4 v[192:193], v[118:121], off offset:512 nt
	global_store_dwordx4 v[192:193], v[110:113], off offset:528 nt
	s_nop 0
	v_add_u32_e32 v118, 16, v218
	v_lshlrev_b32_e32 v110, 16, v182
	v_and_b32_e32 v111, 0xffff0000, v182
	v_ashrrev_i32_e32 v119, 31, v118
	v_pk_add_f32 v[110:111], v[114:115], v[110:111]
	v_lshlrev_b32_e32 v114, 16, v184
	v_and_b32_e32 v115, 0xffff0000, v184
	v_pk_add_f32 v[106:107], v[106:107], v[114:115]
	v_lshlrev_b64 v[114:115], 12, v[118:119]
	v_lshlrev_b32_e32 v112, 16, v183
	v_and_b32_e32 v113, 0xffff0000, v183
	v_lshl_add_u64 v[114:115], s[64:65], 0, v[114:115]
	v_pk_add_f32 v[112:113], v[116:117], v[112:113]
	v_lshlrev_b32_e32 v116, 16, v185
	v_and_b32_e32 v117, 0xffff0000, v185
	v_lshl_add_u64 v[114:115], v[114:115], 0, v[190:191]
	v_pk_add_f32 v[108:109], v[108:109], v[116:117]
	global_store_dwordx4 v[114:115], v[110:113], off nt
	global_store_dwordx4 v[114:115], v[106:109], off offset:16 nt
	s_nop 1
	v_lshlrev_b32_e32 v106, 16, v178
	v_and_b32_e32 v107, 0xffff0000, v178
	v_lshlrev_b32_e32 v108, 16, v179
	v_and_b32_e32 v109, 0xffff0000, v179
	v_pk_add_f32 v[102:103], v[102:103], v[106:107]
	v_lshlrev_b32_e32 v106, 16, v180
	v_and_b32_e32 v107, 0xffff0000, v180
	v_pk_add_f32 v[104:105], v[104:105], v[108:109]
	v_lshlrev_b32_e32 v108, 16, v181
	v_and_b32_e32 v109, 0xffff0000, v181
	v_pk_add_f32 v[92:93], v[92:93], v[106:107]
;     __device__ __forceinline__ void finish(const f32x4 x0, const f32x4 x1, int row, int col, float& s) const {
;         if (OUT_F32) { *(f32x4*)(out + (size_t)row * DM + col) = x0; *(f32x4*)(out + (size_t)row * DM + col + 4) = x1; }
;     __device__ __forceinline__ void operator()(AccT& acc, const Unit& u, int wr, int wc, int fr, int fq) const {
;     ...
;             for (int ai = 0; ai < 2; ++ai)
; #pragma unroll
;                 for (int m = 0; m < 4; ++m) {
;                     const int row = u.pm * 256 + ai * 128 + wr * 64 + m * 16 + fr; float s = 0.f;
; #pragma unroll
;                     for (int bj = 0; bj < 2; ++bj) { const u32x4 w = rb[ai][m][bj];
;                         finish((f32x4){bf_lo(w.x), bf_hi(w.x), bf_lo(w.y), bf_hi(w.y)} + acc[ai][bj][m][0], (f32x4){bf_lo(w.z), bf_hi(w.z), bf_lo(w.w), bf_hi(w.w)} + acc[ai][bj][m][1], row, col0 + bj * 128, s); }
	v_pk_add_f32 v[94:95], v[94:95], v[108:109]
	global_store_dwordx4 v[114:115], v[102:105], off offset:512 nt
	global_store_dwordx4 v[114:115], v[92:95], off offset:528 nt
	s_nop 0
	v_add_u32_e32 v102, 32, v218
	v_lshlrev_b32_e32 v92, 16, v174
	v_and_b32_e32 v93, 0xffff0000, v174
	v_ashrrev_i32_e32 v103, 31, v102
	v_pk_add_f32 v[92:93], v[98:99], v[92:93]
	v_lshlrev_b32_e32 v98, 16, v176
	v_and_b32_e32 v99, 0xffff0000, v176
	v_pk_add_f32 v[88:89], v[88:89], v[98:99]
	v_lshlrev_b64 v[98:99], 12, v[102:103]
	v_lshlrev_b32_e32 v94, 16, v175
	v_and_b32_e32 v95, 0xffff0000, v175
	v_lshl_add_u64 v[98:99], s[64:65], 0, v[98:99]
	v_pk_add_f32 v[94:95], v[100:101], v[94:95]
	v_lshlrev_b32_e32 v100, 16, v177
	v_and_b32_e32 v101, 0xffff0000, v177
	v_lshl_add_u64 v[98:99], v[98:99], 0, v[190:191]
	v_pk_add_f32 v[90:91], v[90:91], v[100:101]
	global_store_dwordx4 v[98:99], v[92:95], off nt
	global_store_dwordx4 v[98:99], v[88:91], off offset:16 nt
	s_nop 1
	v_lshlrev_b32_e32 v88, 16, v170
	v_and_b32_e32 v89, 0xffff0000, v170
	v_lshlrev_b32_e32 v90, 16, v171
	v_and_b32_e32 v91, 0xffff0000, v171
	v_pk_add_f32 v[84:85], v[84:85], v[88:89]
	v_lshlrev_b32_e32 v88, 16, v172
	v_and_b32_e32 v89, 0xffff0000, v172
	v_pk_add_f32 v[86:87], v[86:87], v[90:91]
	v_lshlrev_b32_e32 v90, 16, v173
	v_and_b32_e32 v91, 0xffff0000, v173
	v_pk_add_f32 v[76:77], v[76:77], v[88:89]
	v_pk_add_f32 v[78:79], v[78:79], v[90:91]
	global_store_dwordx4 v[98:99], v[84:87], off offset:512 nt
	global_store_dwordx4 v[98:99], v[76:79], off offset:528 nt
	s_nop 0
	v_add_u32_e32 v84, 48, v218
	v_lshlrev_b32_e32 v76, 16, v166
	v_and_b32_e32 v77, 0xffff0000, v166
	v_ashrrev_i32_e32 v85, 31, v84
	v_pk_add_f32 v[76:77], v[80:81], v[76:77]
	v_lshlrev_b32_e32 v80, 16, v168
	v_and_b32_e32 v81, 0xffff0000, v168
	v_pk_add_f32 v[72:73], v[72:73], v[80:81]
	v_lshlrev_b64 v[80:81], 12, v[84:85]
	v_lshlrev_b32_e32 v78, 16, v167
	v_and_b32_e32 v79, 0xffff0000, v167
	v_lshl_add_u64 v[80:81], s[64:65], 0, v[80:81]
	v_pk_add_f32 v[78:79], v[82:83], v[78:79]
	v_lshlrev_b32_e32 v82, 16, v169
	v_and_b32_e32 v83, 0xffff0000, v169
	v_lshl_add_u64 v[80:81], v[80:81], 0, v[190:191]
	v_pk_add_f32 v[74:75], v[74:75], v[82:83]
	global_store_dwordx4 v[80:81], v[76:79], off nt
	global_store_dwordx4 v[80:81], v[72:75], off offset:16 nt
	s_nop 1
	v_lshlrev_b32_e32 v72, 16, v162
	v_and_b32_e32 v73, 0xffff0000, v162
	v_lshlrev_b32_e32 v74, 16, v163
	v_and_b32_e32 v75, 0xffff0000, v163
	v_pk_add_f32 v[68:69], v[68:69], v[72:73]
	v_lshlrev_b32_e32 v72, 16, v164
	v_and_b32_e32 v73, 0xffff0000, v164
	v_pk_add_f32 v[70:71], v[70:71], v[74:75]
	v_lshlrev_b32_e32 v74, 16, v165
	v_and_b32_e32 v75, 0xffff0000, v165
	v_pk_add_f32 v[64:65], v[64:65], v[72:73]
	v_pk_add_f32 v[66:67], v[66:67], v[74:75]
	global_store_dwordx4 v[80:81], v[68:71], off offset:512 nt
	global_store_dwordx4 v[80:81], v[64:67], off offset:528 nt
	s_nop 0
	v_lshlrev_b32_e32 v68, 16, v159
	v_add_u32_e32 v64, 0x80, v218
	v_ashrrev_i32_e32 v65, 31, v64
	v_lshlrev_b32_e32 v66, 16, v158
	v_and_b32_e32 v67, 0xffff0000, v158
	v_lshlrev_b64 v[64:65], 12, v[64:65]
	v_and_b32_e32 v69, 0xffff0000, v159
	v_pk_add_f32 v[60:61], v[60:61], v[66:67]
	v_lshlrev_b32_e32 v66, 16, v160
	v_and_b32_e32 v67, 0xffff0000, v160
	v_lshl_add_u64 v[64:65], s[64:65], 0, v[64:65]
	v_pk_add_f32 v[62:63], v[62:63], v[68:69]
	v_lshlrev_b32_e32 v68, 16, v161
	v_and_b32_e32 v69, 0xffff0000, v161
	v_pk_add_f32 v[56:57], v[56:57], v[66:67]
	v_lshl_add_u64 v[64:65], v[64:65], 0, v[190:191]
	v_pk_add_f32 v[58:59], v[58:59], v[68:69]
	global_store_dwordx4 v[64:65], v[60:63], off nt
	global_store_dwordx4 v[64:65], v[56:59], off offset:16 nt
	s_nop 1
	v_lshlrev_b32_e32 v56, 16, v154
	v_and_b32_e32 v57, 0xffff0000, v154
	v_lshlrev_b32_e32 v58, 16, v155
	v_and_b32_e32 v59, 0xffff0000, v155
	v_pk_add_f32 v[52:53], v[52:53], v[56:57]
	v_lshlrev_b32_e32 v56, 16, v156
	v_and_b32_e32 v57, 0xffff0000, v156
	v_pk_add_f32 v[54:55], v[54:55], v[58:59]
	v_lshlrev_b32_e32 v58, 16, v157
	v_and_b32_e32 v59, 0xffff0000, v157
	v_pk_add_f32 v[44:45], v[44:45], v[56:57]
	v_pk_add_f32 v[46:47], v[46:47], v[58:59]
	global_store_dwordx4 v[64:65], v[52:55], off offset:512 nt
;     __device__ __forceinline__ void finish(const f32x4 x0, const f32x4 x1, int row, int col, float& s) const {
;         if (OUT_F32) { *(f32x4*)(out + (size_t)row * DM + col) = x0; *(f32x4*)(out + (size_t)row * DM + col + 4) = x1; }
;     __device__ __forceinline__ void operator()(AccT& acc, const Unit& u, int wr, int wc, int fr, int fq) const {
;     ...
;             for (int ai = 0; ai < 2; ++ai)
; #pragma unroll
;                 for (int m = 0; m < 4; ++m) {
;                     const int row = u.pm * 256 + ai * 128 + wr * 64 + m * 16 + fr; float s = 0.f;
; #pragma unroll
;                     for (int bj = 0; bj < 2; ++bj) { const u32x4 w = rb[ai][m][bj];
;                         finish((f32x4){bf_lo(w.x), bf_hi(w.x), bf_lo(w.y), bf_hi(w.y)} + acc[ai][bj][m][0], (f32x4){bf_lo(w.z), bf_hi(w.z), bf_lo(w.w), bf_hi(w.w)} + acc[ai][bj][m][1], row, col0 + bj * 128, s); }
	global_store_dwordx4 v[64:65], v[44:47], off offset:528 nt
	s_nop 0
	v_add_u32_e32 v52, 0x90, v218
	v_lshlrev_b32_e32 v44, 16, v150
	v_and_b32_e32 v45, 0xffff0000, v150
	v_ashrrev_i32_e32 v53, 31, v52
	v_pk_add_f32 v[44:45], v[48:49], v[44:45]
	v_lshlrev_b32_e32 v48, 16, v152
	v_and_b32_e32 v49, 0xffff0000, v152
	v_pk_add_f32 v[40:41], v[40:41], v[48:49]
	v_lshlrev_b64 v[48:49], 12, v[52:53]
	v_lshlrev_b32_e32 v46, 16, v151
	v_and_b32_e32 v47, 0xffff0000, v151
	v_lshl_add_u64 v[48:49], s[64:65], 0, v[48:49]
	v_pk_add_f32 v[46:47], v[50:51], v[46:47]
	v_lshlrev_b32_e32 v50, 16, v153
	v_and_b32_e32 v51, 0xffff0000, v153
	v_lshl_add_u64 v[48:49], v[48:49], 0, v[190:191]
	v_pk_add_f32 v[42:43], v[42:43], v[50:51]
	global_store_dwordx4 v[48:49], v[44:47], off nt
	global_store_dwordx4 v[48:49], v[40:43], off offset:16 nt
	s_nop 1
	v_lshlrev_b32_e32 v40, 16, v146
	v_and_b32_e32 v41, 0xffff0000, v146
	v_lshlrev_b32_e32 v42, 16, v147
	v_and_b32_e32 v43, 0xffff0000, v147
	v_pk_add_f32 v[36:37], v[36:37], v[40:41]
	v_lshlrev_b32_e32 v40, 16, v148
	v_and_b32_e32 v41, 0xffff0000, v148
	v_pk_add_f32 v[38:39], v[38:39], v[42:43]
	v_lshlrev_b32_e32 v42, 16, v149
	v_and_b32_e32 v43, 0xffff0000, v149
	v_pk_add_f32 v[28:29], v[28:29], v[40:41]
	v_pk_add_f32 v[30:31], v[30:31], v[42:43]
	global_store_dwordx4 v[48:49], v[36:39], off offset:512 nt
	global_store_dwordx4 v[48:49], v[28:31], off offset:528 nt
	s_nop 0
	v_add_u32_e32 v36, 0xa0, v218
	v_lshlrev_b32_e32 v28, 16, v142
	v_and_b32_e32 v29, 0xffff0000, v142
	v_ashrrev_i32_e32 v37, 31, v36
	v_pk_add_f32 v[28:29], v[32:33], v[28:29]
	v_lshlrev_b32_e32 v32, 16, v144
	v_and_b32_e32 v33, 0xffff0000, v144
	v_pk_add_f32 v[24:25], v[24:25], v[32:33]
	v_lshlrev_b64 v[32:33], 12, v[36:37]
	v_lshlrev_b32_e32 v30, 16, v143
	v_and_b32_e32 v31, 0xffff0000, v143
	v_lshl_add_u64 v[32:33], s[64:65], 0, v[32:33]
	v_pk_add_f32 v[30:31], v[34:35], v[30:31]
	v_lshlrev_b32_e32 v34, 16, v145
	v_and_b32_e32 v35, 0xffff0000, v145
	v_lshl_add_u64 v[32:33], v[32:33], 0, v[190:191]
	v_pk_add_f32 v[26:27], v[26:27], v[34:35]
	global_store_dwordx4 v[32:33], v[28:31], off nt
	global_store_dwordx4 v[32:33], v[24:27], off offset:16 nt
	s_nop 1
	v_lshlrev_b32_e32 v24, 16, v138
	v_and_b32_e32 v25, 0xffff0000, v138
	v_lshlrev_b32_e32 v26, 16, v139
	v_and_b32_e32 v27, 0xffff0000, v139
	v_pk_add_f32 v[20:21], v[20:21], v[24:25]
	v_lshlrev_b32_e32 v24, 16, v140
	v_and_b32_e32 v25, 0xffff0000, v140
	v_pk_add_f32 v[22:23], v[22:23], v[26:27]
	v_lshlrev_b32_e32 v26, 16, v141
	v_and_b32_e32 v27, 0xffff0000, v141
	v_pk_add_f32 v[12:13], v[12:13], v[24:25]
	v_pk_add_f32 v[14:15], v[14:15], v[26:27]
	global_store_dwordx4 v[32:33], v[20:23], off offset:512 nt
	global_store_dwordx4 v[32:33], v[12:15], off offset:528 nt
	s_nop 0
	v_add_u32_e32 v20, 0xb0, v218
	v_lshlrev_b32_e32 v12, 16, v134
	v_and_b32_e32 v13, 0xffff0000, v134
	v_ashrrev_i32_e32 v21, 31, v20
	v_pk_add_f32 v[12:13], v[16:17], v[12:13]
	v_lshlrev_b32_e32 v16, 16, v136
	v_and_b32_e32 v17, 0xffff0000, v136
	v_lshlrev_b32_e32 v14, 16, v135
	v_and_b32_e32 v15, 0xffff0000, v135
	v_pk_add_f32 v[8:9], v[8:9], v[16:17]
	v_lshlrev_b64 v[16:17], 12, v[20:21]
	v_pk_add_f32 v[14:15], v[18:19], v[14:15]
	v_lshlrev_b32_e32 v18, 16, v137
	v_and_b32_e32 v19, 0xffff0000, v137
	v_lshl_add_u64 v[16:17], s[64:65], 0, v[16:17]
	v_pk_add_f32 v[10:11], v[10:11], v[18:19]
	v_lshl_add_u64 v[16:17], v[16:17], 0, v[190:191]
	global_store_dwordx4 v[16:17], v[12:15], off nt
	global_store_dwordx4 v[16:17], v[8:11], off offset:16 nt
	s_nop 1
	v_lshlrev_b32_e32 v8, 16, v130
	v_and_b32_e32 v9, 0xffff0000, v130
	v_lshlrev_b32_e32 v10, 16, v131
	v_and_b32_e32 v11, 0xffff0000, v131
	v_pk_add_f32 v[6:7], v[6:7], v[10:11]
	v_pk_add_f32 v[4:5], v[4:5], v[8:9]
	v_lshlrev_b32_e32 v8, 16, v132
	v_and_b32_e32 v9, 0xffff0000, v132
	v_lshlrev_b32_e32 v10, 16, v133
	v_and_b32_e32 v11, 0xffff0000, v133
	v_pk_add_f32 v[2:3], v[2:3], v[10:11]
	v_pk_add_f32 v[0:1], v[0:1], v[8:9]
	global_store_dwordx4 v[16:17], v[4:7], off offset:512 nt
	global_store_dwordx4 v[16:17], v[0:3], off offset:528 nt
	s_cbranch_vccnz .LBB0_1230
	s_andn2_b64 vcc, exec, s[2:3]
	s_cbranch_vccnz .LBB0_1229
	s_barrier
	s_branch .LBB0_1229

; __device__ __forceinline__ unsigned cvt_pk_bf16(float lo, float hi) { unsigned r; asm volatile("v_cvt_pk_bf16_f32 %0, %1, %2" : "=v"(r) : "v"(lo), "v"(hi)); return r; }
;     __device__ __forceinline__ void finish(const f32x4 x0, const f32x4 x1, int row, int col, float& s) const {
;         if (OUT_F32) { *(f32x4*)(out + (size_t)row * DM + col) = x0; *(f32x4*)(out + (size_t)row * DM + col + 4) = x1; }
;         else { u32x4 w; w.x = cvt_pk_bf16(x0[0], x0[1]); w.y = cvt_pk_bf16(x0[2], x0[3]); w.z = cvt_pk_bf16(x1[0], x1[1]); w.w = cvt_pk_bf16(x1[2], x1[3]); *(u32x4*)(XB + (size_t)row * DM + col) = w; }
;         s += (x0[0] * x0[0] + x0[1] * x0[1]) + (x0[2] * x0[2] + x0[3] * x0[3]) + (x1[0] * x1[0] + x1[1] * x1[1]) + (x1[2] * x1[2] + x1[3] * x1[3]);
;     }
;     __device__ __forceinline__ void operator()(AccT& acc, const Unit& u, int wr, int wc, int fr, int fq) const {
;         const int col0 = u.pn * 256 + wc * 32 + 8 * fq;
;         if constexpr (!RES_F32) {
;             u32x4 rb[2][4][2];
; #pragma unroll
;             for (int ai = 0; ai < 2; ++ai)
; #pragma unroll
;                 for (int m = 0; m < 4; ++m)
; #pragma unroll
;                     for (int bj = 0; bj < 2; ++bj) rb[ai][m][bj] = __builtin_nontemporal_load((const u32x4*)((const char*)XB + (unsigned)(((u.pm * 256 + ai * 128 + wr * 64 + m * 16 + fr) * DM + col0 + bj * 128) * 2)));
; #pragma unroll
;             for (int ai = 0; ai < 2; ++ai)
; #pragma unroll
;                 for (int m = 0; m < 4; ++m) {
;                     const int row = u.pm * 256 + ai * 128 + wr * 64 + m * 16 + fr; float s = 0.f;
; #pragma unroll
;                     for (int bj = 0; bj < 2; ++bj) { const u32x4 w = rb[ai][m][bj];
;                         finish((f32x4){bf_lo(w.x), bf_hi(w.x), bf_lo(w.y), bf_hi(w.y)} + acc[ai][bj][m][0], (f32x4){bf_lo(w.z), bf_hi(w.z), bf_lo(w.w), bf_hi(w.w)} + acc[ai][bj][m][1], row, col0 + bj * 128, s); }
;                     if (!OUT_F32) { s += __shfl_xor(s, 16); s += __shfl_xor(s, 32); if (fq == 0) atomicAdd(ssq_next + row, s); }
.LBB0_1278:
	s_lshl_b32 s0, s48, 8
	v_mov_b32_e32 v96, v230
	v_mov_b32_e32 v219, v229
	s_or_b32 s0, s0, s37
	s_nop 0
	v_lshl_add_u32 v218, v219, 3, s0
	s_lshl_b32 s0, s47, 8
	s_add_i32 s0, s0, s33
	v_add_u32_e32 v220, s0, v96
	v_lshlrev_b32_e32 v96, 11, v220
	v_lshl_add_u32 v96, v218, 1, v96
	v_lshl_add_u64 v[118:119], s[90:91], 0, v[96:97]
	global_load_dwordx4 v[190:193], v[118:119], off nt
	v_add_u32_e32 v118, 0x100, v96
	v_mov_b32_e32 v119, v97
	v_lshl_add_u64 v[118:119], s[90:91], 0, v[118:119]
	global_load_dwordx4 v[186:189], v[118:119], off nt
	v_add_u32_e32 v118, 0x8000, v96
	v_mov_b32_e32 v119, v97
	v_lshl_add_u64 v[118:119], s[90:91], 0, v[118:119]
	global_load_dwordx4 v[182:185], v[118:119], off nt
	v_add_u32_e32 v118, 0x8100, v96
	v_mov_b32_e32 v119, v97
	v_lshl_add_u64 v[118:119], s[90:91], 0, v[118:119]
	global_load_dwordx4 v[178:181], v[118:119], off nt
	v_add_u32_e32 v118, 0x10000, v96
	v_mov_b32_e32 v119, v97
	v_lshl_add_u64 v[118:119], s[90:91], 0, v[118:119]
	global_load_dwordx4 v[174:177], v[118:119], off nt
	v_add_u32_e32 v118, 0x10100, v96
	v_mov_b32_e32 v119, v97
	v_lshl_add_u64 v[118:119], s[90:91], 0, v[118:119]
	global_load_dwordx4 v[170:173], v[118:119], off nt
	v_add_u32_e32 v118, 0x18000, v96
	v_mov_b32_e32 v119, v97
	v_lshl_add_u64 v[118:119], s[90:91], 0, v[118:119]
	global_load_dwordx4 v[166:169], v[118:119], off nt
	v_add_u32_e32 v118, 0x18100, v96
	v_mov_b32_e32 v119, v97
	v_lshl_add_u64 v[118:119], s[90:91], 0, v[118:119]
	global_load_dwordx4 v[162:165], v[118:119], off nt
	v_add_u32_e32 v118, 0x40000, v96
	v_mov_b32_e32 v119, v97
	v_lshl_add_u64 v[118:119], s[90:91], 0, v[118:119]
	global_load_dwordx4 v[158:161], v[118:119], off nt
	v_add_u32_e32 v118, 0x40100, v96
	v_mov_b32_e32 v119, v97
	v_lshl_add_u64 v[118:119], s[90:91], 0, v[118:119]
	global_load_dwordx4 v[154:157], v[118:119], off nt
	v_add_u32_e32 v118, 0x48000, v96
	v_mov_b32_e32 v119, v97
	v_lshl_add_u64 v[118:119], s[90:91], 0, v[118:119]
	global_load_dwordx4 v[150:153], v[118:119], off nt
	v_add_u32_e32 v118, 0x48100, v96
	v_mov_b32_e32 v119, v97
	v_lshl_add_u64 v[118:119], s[90:91], 0, v[118:119]
	global_load_dwordx4 v[146:149], v[118:119], off nt
	v_add_u32_e32 v118, 0x50000, v96
	v_mov_b32_e32 v119, v97
	v_lshl_add_u64 v[118:119], s[90:91], 0, v[118:119]
	global_load_dwordx4 v[134:137], v[118:119], off nt
	v_add_u32_e32 v118, 0x50100, v96
	v_mov_b32_e32 v119, v97
	v_lshl_add_u64 v[118:119], s[90:91], 0, v[118:119]
	global_load_dwordx4 v[126:129], v[118:119], off nt
	v_add_u32_e32 v118, 0x58000, v96
	v_mov_b32_e32 v119, v97
	v_add_u32_e32 v96, 0x58100, v96
	v_lshl_add_u64 v[118:119], s[90:91], 0, v[118:119]
	v_lshl_add_u64 v[138:139], s[90:91], 0, v[96:97]
	global_load_dwordx4 v[118:121], v[118:119], off nt
	v_ashrrev_i32_e32 v221, 31, v220
	global_load_dwordx4 v[138:141], v[138:139], off nt
	v_lshlrev_b64 v[234:235], 11, v[220:221]
	v_cmp_eq_u32_e32 vcc, 0, v219
	v_lshl_add_u64 v[234:235], s[90:91], 0, v[234:235]
	v_ashrrev_i32_e32 v219, 31, v218
	v_lshl_add_u64 v[234:235], v[218:219], 1, v[234:235]
	s_waitcnt vmcnt(0) lgkmcnt(0)
	v_lshlrev_b32_e32 v236, 16, v190
	v_and_b32_e32 v237, 0xffff0000, v190
	v_lshlrev_b32_e32 v190, 16, v191
	v_and_b32_e32 v191, 0xffff0000, v191
	v_pk_add_f32 v[144:145], v[144:145], v[190:191]
	v_lshlrev_b32_e32 v190, 16, v192
	v_and_b32_e32 v191, 0xffff0000, v192
	v_pk_add_f32 v[142:143], v[142:143], v[236:237]
	v_lshlrev_b32_e32 v192, 16, v193
	v_and_b32_e32 v193, 0xffff0000, v193
	v_pk_add_f32 v[190:191], v[130:131], v[190:191]
	v_cvt_pk_bf16_f32 v130, v142, v143
	v_pk_add_f32 v[192:193], v[132:133], v[192:193]
	v_cvt_pk_bf16_f32 v131, v144, v145
	v_cvt_pk_bf16_f32 v132, v190, v191
	v_mul_f32_e32 v96, v143, v143
	v_cvt_pk_bf16_f32 v133, v192, v193
	global_store_dwordx4 v[234:235], v[130:133], off nt
	v_fmac_f32_e32 v96, v142, v142
	s_nop 0
	v_mul_f32_e32 v130, v145, v145
	v_fmac_f32_e32 v130, v144, v144
	v_add_f32_e32 v96, v96, v130
	v_mul_f32_e32 v130, v191, v191
	v_fmac_f32_e32 v130, v190, v190
	v_add_f32_e32 v96, v130, v96
	v_mul_f32_e32 v130, v193, v193
	v_fmac_f32_e32 v130, v192, v192
	v_add_f32_e32 v96, v130, v96
	v_lshlrev_b32_e32 v130, 16, v186
	v_and_b32_e32 v131, 0xffff0000, v186
	v_lshlrev_b32_e32 v132, 16, v187
	v_and_b32_e32 v133, 0xffff0000, v187
	v_pk_add_f32 v[122:123], v[122:123], v[130:131]
	v_lshlrev_b32_e32 v130, 16, v188
	v_and_b32_e32 v131, 0xffff0000, v188
	v_pk_add_f32 v[124:125], v[124:125], v[132:133]
	v_lshlrev_b32_e32 v132, 16, v189
	v_and_b32_e32 v133, 0xffff0000, v189
	v_pk_add_f32 v[130:131], v[114:115], v[130:131]
	v_cvt_pk_bf16_f32 v114, v122, v123
	v_cvt_pk_bf16_f32 v115, v124, v125
	v_pk_add_f32 v[132:133], v[116:117], v[132:133]
	v_cvt_pk_bf16_f32 v116, v130, v131
	s_nop 0
	v_cvt_pk_bf16_f32 v117, v132, v133
	global_store_dwordx4 v[234:235], v[114:117], off offset:256 nt
	s_nop 1
	v_mul_f32_e32 v114, v123, v123
	v_mul_f32_e32 v115, v125, v125
	v_fmac_f32_e32 v114, v122, v122
	v_fmac_f32_e32 v115, v124, v124
	v_add_f32_e32 v114, v114, v115
	v_mul_f32_e32 v115, v131, v131
	v_fmac_f32_e32 v115, v130, v130
	v_add_f32_e32 v114, v115, v114
	v_mul_f32_e32 v115, v133, v133
	v_fmac_f32_e32 v115, v132, v132
	v_add_f32_e32 v114, v115, v114
	v_and_b32_e32 v115, 64, v225
	v_add_f32_e32 v114, v96, v114
	v_xor_b32_e32 v96, 16, v225
	v_add_u32_e32 v115, 64, v115
	v_cmp_lt_i32_e64 s[0:1], v96, v115
	s_nop 1
	v_cndmask_b32_e64 v96, v225, v96, s[0:1]
	v_lshlrev_b32_e32 v96, 2, v96
	ds_bpermute_b32 v116, v96, v114
	s_waitcnt lgkmcnt(0)
	v_add_f32_e32 v114, v114, v116
	v_xor_b32_e32 v116, 32, v225
	v_cmp_lt_i32_e64 s[0:1], v116, v115
	s_nop 1
	v_cndmask_b32_e64 v115, v225, v116, s[0:1]
	v_lshlrev_b32_e32 v116, 2, v115
	ds_bpermute_b32 v115, v116, v114
	s_and_saveexec_b64 s[0:1], vcc
	s_cbranch_execz .LBB0_1280
	v_lshl_add_u64 v[122:123], v[220:221], 2, s[2:3]
	s_waitcnt lgkmcnt(0)
	v_add_f32_e32 v114, v114, v115
	global_atomic_add_f32 v[122:123], v114, off
